# v3 + all s_setprio removed from the GEMM phases (loading wave no longer starved by the MFMA wave: DMA issues earlier)
# speedup vs baseline: 1.0017x; 1.0017x over previous
; template <class Epi, class Sched, bool ALIGN_EPI = false, bool SP2 = false, bool A_TILED = false>
; __device__ __forceinline__ void gemm_phase(PG8_LAS unsigned char* lds, const Gemm g, const Sched& S, const Epi& E, const int wave_s) {
;     ...
;         const bool has_next = Epi::AFTER_DRAIN ? false : S.next(ui + 1, nxt);
;         const char* nA = has_next ? (const char*)g.A + (size_t)nxt.pm * tstepA : cA; const char* nB = has_next ? (const char*)g.Bt + (size_t)nxt.pn * tstep : cB;
;         constexpr bool PEEL = SP2 && !Epi::AFTER_DRAIN;
;         if constexpr (PEEL) {
;             const char* a1 = cA + kstepA; const char* a2 = cA + 2 * kstepA; const char* b2 = cB + 2 * kstep; const char* a3 = a2 + kstepA; const char* b3 = b2 + kstep;
;             PG8_ITER(PG8_MMAZ)
.LBB0_776:
	s_ashr_i32 s73, s72, 31
	ds_read_b128 v[0:3], v149
	ds_read_b128 v[4:7], v149 offset:1024
	ds_read_b128 v[8:11], v149 offset:2048
	ds_read_b128 v[12:15], v149 offset:3072
	ds_read_b128 v[16:19], v150
	ds_read_b128 v[20:23], v150 offset:1024
	ds_read_b128 v[24:27], v150 offset:2048
	ds_read_b128 v[28:31], v150 offset:3072
	s_lshl_b64 s[52:53], s[72:73], 20
	s_add_u32 s74, s7, s52
	s_addc_u32 s75, s8, s53
	s_and_b64 s[52:53], s[0:1], exec
	s_cselect_b32 s51, s75, s83
	s_cselect_b32 s52, s74, s82
	s_ashr_i32 s71, s70, 31
	s_lshl_b64 s[54:55], s[70:71], 20
	s_add_u32 s76, s9, s54
	s_addc_u32 s77, s14, s55
	s_and_b64 s[54:55], s[0:1], exec
	s_cselect_b32 s53, s77, s81
	s_cselect_b32 s54, s76, s80
	s_add_u32 s56, s82, 0x80080
	s_addc_u32 s57, s83, 0
	s_mov_b32 m0, s48
	v_lshl_add_u64 v[64:65], s[56:57], 0, v[134:135]
	ds_read_b128 v[32:35], v151
	ds_read_b128 v[36:39], v151 offset:1024
	ds_read_b128 v[40:43], v151 offset:2048
	ds_read_b128 v[44:47], v151 offset:3072
	ds_read_b128 v[48:51], v151 offset:4096
	ds_read_b128 v[52:55], v151 offset:5120
	ds_read_b128 v[56:59], v151 offset:6144
	ds_read_b128 v[60:63], v151 offset:7168
	global_load_lds_dwordx4 v[64:65], off
	v_lshl_add_u64 v[64:65], s[56:57], 0, v[132:133]
	s_mov_b32 m0, s49
	s_nop 0
	global_load_lds_dwordx4 v[64:65], off
	s_waitcnt vmcnt(8) lgkmcnt(0)
	s_barrier
	v_mfma_f32_16x16x32_bf16 v[88:91], v[0:3], v[56:59], 0
	v_mfma_f32_16x16x32_bf16 v[64:67], v[0:3], v[32:35], 0
	v_mfma_f32_16x16x32_bf16 v[68:71], v[8:11], v[32:35], 0
	v_mfma_f32_16x16x32_bf16 v[72:75], v[0:3], v[40:43], 0
	v_mfma_f32_16x16x32_bf16 v[76:79], v[8:11], v[40:43], 0
	v_mfma_f32_16x16x32_bf16 v[80:83], v[0:3], v[48:51], 0
	v_mfma_f32_16x16x32_bf16 v[84:87], v[8:11], v[48:51], 0
	v_mfma_f32_16x16x32_bf16 v[92:95], v[4:7], v[60:63], v[88:91]
	v_mfma_f32_16x16x32_bf16 v[88:91], v[8:11], v[56:59], 0
	v_mfma_f32_16x16x32_bf16 v[64:67], v[4:7], v[36:39], v[64:67]
	v_mfma_f32_16x16x32_bf16 v[68:71], v[12:15], v[36:39], v[68:71]
	v_mfma_f32_16x16x32_bf16 v[72:75], v[4:7], v[44:47], v[72:75]
	v_mfma_f32_16x16x32_bf16 v[76:79], v[12:15], v[44:47], v[76:79]
	v_mfma_f32_16x16x32_bf16 v[80:83], v[4:7], v[52:55], v[80:83]
	v_mfma_f32_16x16x32_bf16 v[84:87], v[12:15], v[52:55], v[84:87]
	v_mfma_f32_16x16x32_bf16 v[100:103], v[12:15], v[60:63], v[88:91]
	v_mfma_f32_16x16x32_bf16 v[88:91], v[16:19], v[32:35], 0
	v_mfma_f32_16x16x32_bf16 v[32:35], v[24:27], v[32:35], 0
	v_mfma_f32_16x16x32_bf16 v[108:111], v[20:23], v[36:39], v[88:91]
	v_mfma_f32_16x16x32_bf16 v[32:35], v[28:31], v[36:39], v[32:35]
	v_mfma_f32_16x16x32_bf16 v[36:39], v[16:19], v[40:43], 0
	v_mfma_f32_16x16x32_bf16 v[40:43], v[24:27], v[40:43], 0
	v_mfma_f32_16x16x32_bf16 v[36:39], v[20:23], v[44:47], v[36:39]
	v_mfma_f32_16x16x32_bf16 v[40:43], v[28:31], v[44:47], v[40:43]
	v_mfma_f32_16x16x32_bf16 v[44:47], v[16:19], v[48:51], 0
	v_mfma_f32_16x16x32_bf16 v[48:51], v[24:27], v[48:51], 0
	v_mfma_f32_16x16x32_bf16 v[44:47], v[20:23], v[52:55], v[44:47]
	v_mfma_f32_16x16x32_bf16 v[52:55], v[28:31], v[52:55], v[48:51]
	v_mfma_f32_16x16x32_bf16 v[48:51], v[16:19], v[56:59], 0
	v_mfma_f32_16x16x32_bf16 v[152:155], v[20:23], v[60:63], v[48:51]
	v_mfma_f32_16x16x32_bf16 v[48:51], v[24:27], v[56:59], 0
	v_mfma_f32_16x16x32_bf16 v[156:159], v[28:31], v[60:63], v[48:51]
	s_barrier
	s_add_i32 s55, s45, s15
	v_lshl_add_u64 v[146:147], s[80:81], 0, v[128:129]
	s_add_i32 s56, s55, 0x2000
	v_lshl_add_u64 v[120:121], v[146:147], 0, s[68:69]
	s_mov_b32 m0, s55
	v_lshl_add_u64 v[252:253], s[80:81], 0, v[130:131]
	s_add_u32 s58, s80, 0x80100
	ds_read_b128 v[48:51], v151 offset:16384
	ds_read_b128 v[56:59], v151 offset:17408
	ds_read_b128 v[60:63], v151 offset:18432
	ds_read_b128 v[88:91], v151 offset:19456
	ds_read_b128 v[96:99], v151 offset:20480
	ds_read_b128 v[104:107], v151 offset:21504
	ds_read_b128 v[112:115], v151 offset:22528
	ds_read_b128 v[116:119], v151 offset:23552
	global_load_lds_dwordx4 v[120:121], off
	v_lshl_add_u64 v[120:121], v[252:253], 0, s[68:69]
	s_mov_b32 m0, s56
	s_addc_u32 s59, s81, 0
	s_add_i32 s57, s46, s15
	global_load_lds_dwordx4 v[120:121], off
	v_lshl_add_u64 v[120:121], s[58:59], 0, v[128:129]
	s_mov_b32 m0, s57
	v_lshl_add_u64 v[140:141], s[82:83], 0, v[134:135]
	global_load_lds_dwordx4 v[120:121], off
	v_lshl_add_u64 v[120:121], s[58:59], 0, v[130:131]
	s_add_i32 s58, s57, 0x2000
	s_mov_b32 m0, s58
	v_lshl_add_u64 v[142:143], s[82:83], 0, v[132:133]
	global_load_lds_dwordx4 v[120:121], off
	v_lshl_add_u64 v[120:121], v[140:141], 0, s[68:69]
	s_mov_b32 m0, s23
	s_nop 0
	global_load_lds_dwordx4 v[120:121], off
	v_lshl_add_u64 v[120:121], v[142:143], 0, s[68:69]
	s_mov_b32 m0, s36
	s_nop 0
	global_load_lds_dwordx4 v[120:121], off
	s_waitcnt vmcnt(8) lgkmcnt(0)
	s_barrier
; template <class Epi, class Sched, bool ALIGN_EPI = false, bool SP2 = false, bool A_TILED = false>
; __device__ __forceinline__ void gemm_phase(PG8_LAS unsigned char* lds, const Gemm g, const Sched& S, const Epi& E, const int wave_s) {
;     ...
;         const bool has_next = Epi::AFTER_DRAIN ? false : S.next(ui + 1, nxt);
;         const char* nA = has_next ? (const char*)g.A + (size_t)nxt.pm * tstepA : cA; const char* nB = has_next ? (const char*)g.Bt + (size_t)nxt.pn * tstep : cB;
;         constexpr bool PEEL = SP2 && !Epi::AFTER_DRAIN;
;         if constexpr (PEEL) {
;             const char* a1 = cA + kstepA; const char* a2 = cA + 2 * kstepA; const char* b2 = cB + 2 * kstep; const char* a3 = a2 + kstepA; const char* b3 = b2 + kstep;
;             PG8_ITER(PG8_MMAZ)
	v_mfma_f32_16x16x32_bf16 v[120:123], v[0:3], v[48:51], 0
	v_mfma_f32_16x16x32_bf16 v[160:163], v[4:7], v[56:59], v[120:123]
	v_mfma_f32_16x16x32_bf16 v[120:123], v[8:11], v[48:51], 0
	v_mfma_f32_16x16x32_bf16 v[164:167], v[12:15], v[56:59], v[120:123]
	v_mfma_f32_16x16x32_bf16 v[120:123], v[0:3], v[60:63], 0
	v_mfma_f32_16x16x32_bf16 v[168:171], v[4:7], v[88:91], v[120:123]
	v_mfma_f32_16x16x32_bf16 v[120:123], v[8:11], v[60:63], 0
	v_mfma_f32_16x16x32_bf16 v[172:175], v[12:15], v[88:91], v[120:123]
	v_mfma_f32_16x16x32_bf16 v[120:123], v[0:3], v[96:99], 0
	v_mfma_f32_16x16x32_bf16 v[0:3], v[0:3], v[112:115], 0
	v_mfma_f32_16x16x32_bf16 v[176:179], v[4:7], v[104:107], v[120:123]
	v_mfma_f32_16x16x32_bf16 v[0:3], v[4:7], v[116:119], v[0:3]
	v_mfma_f32_16x16x32_bf16 v[4:7], v[8:11], v[112:115], 0
	v_mfma_f32_16x16x32_bf16 v[120:123], v[8:11], v[96:99], 0
	v_mfma_f32_16x16x32_bf16 v[4:7], v[12:15], v[116:119], v[4:7]
	v_mfma_f32_16x16x32_bf16 v[180:183], v[12:15], v[104:107], v[120:123]
	v_mfma_f32_16x16x32_bf16 v[8:11], v[16:19], v[48:51], 0
	v_mfma_f32_16x16x32_bf16 v[12:15], v[20:23], v[56:59], v[8:11]
	v_mfma_f32_16x16x32_bf16 v[8:11], v[24:27], v[48:51], 0
	v_mfma_f32_16x16x32_bf16 v[184:187], v[28:31], v[56:59], v[8:11]
	v_mfma_f32_16x16x32_bf16 v[8:11], v[16:19], v[60:63], 0
	v_mfma_f32_16x16x32_bf16 v[188:191], v[20:23], v[88:91], v[8:11]
	v_mfma_f32_16x16x32_bf16 v[8:11], v[24:27], v[60:63], 0
	v_mfma_f32_16x16x32_bf16 v[192:195], v[28:31], v[88:91], v[8:11]
	v_mfma_f32_16x16x32_bf16 v[8:11], v[16:19], v[96:99], 0
	v_mfma_f32_16x16x32_bf16 v[196:199], v[20:23], v[104:107], v[8:11]
	v_mfma_f32_16x16x32_bf16 v[8:11], v[24:27], v[96:99], 0
	v_mfma_f32_16x16x32_bf16 v[200:203], v[28:31], v[104:107], v[8:11]
	v_mfma_f32_16x16x32_bf16 v[8:11], v[16:19], v[112:115], 0
	v_mfma_f32_16x16x32_bf16 v[204:207], v[20:23], v[116:119], v[8:11]
	v_mfma_f32_16x16x32_bf16 v[8:11], v[24:27], v[112:115], 0
	v_mfma_f32_16x16x32_bf16 v[208:211], v[28:31], v[116:119], v[8:11]
	s_barrier
	s_add_i32 s59, 0, 0x18000
	s_add_i32 s73, 0, 0x1c000
	v_add_u32_e32 v144, s59, v148
	v_add_u32_e32 v145, s73, v148
	s_nop 0
	ds_read_b128 v[8:11], v144
	ds_read_b128 v[20:23], v144 offset:1024
	ds_read_b128 v[28:31], v144 offset:2048
	ds_read_b128 v[212:215], v144 offset:3072
	ds_read_b128 v[216:219], v145
	ds_read_b128 v[220:223], v145 offset:1024
	ds_read_b128 v[224:227], v145 offset:2048
	ds_read_b128 v[228:231], v145 offset:3072
	s_add_u32 s84, s82, 0x80100
	s_addc_u32 s85, s83, 0
	s_mov_b32 m0, s37
	v_lshl_add_u64 v[48:49], s[84:85], 0, v[134:135]
	ds_read_b128 v[16:19], v151 offset:32768
	ds_read_b128 v[24:27], v151 offset:33792
	ds_read_b128 v[60:63], v151 offset:34816
	ds_read_b128 v[232:235], v151 offset:35840
	ds_read_b128 v[236:239], v151 offset:36864
	ds_read_b128 v[240:243], v151 offset:37888
	ds_read_b128 v[244:247], v151 offset:38912
	ds_read_b128 v[248:251], v151 offset:39936
	global_load_lds_dwordx4 v[48:49], off
	v_lshl_add_u64 v[48:49], s[84:85], 0, v[132:133]
	s_mov_b32 m0, s38
	s_nop 0
	global_load_lds_dwordx4 v[48:49], off
	s_waitcnt vmcnt(8) lgkmcnt(0)
	s_barrier
	v_mfma_f32_16x16x32_bf16 v[48:51], v[8:11], v[16:19], v[64:67]
	v_mfma_f32_16x16x32_bf16 v[120:123], v[20:23], v[24:27], v[48:51]
	v_mfma_f32_16x16x32_bf16 v[48:51], v[28:31], v[16:19], v[68:71]
	v_mfma_f32_16x16x32_bf16 v[112:115], v[212:215], v[24:27], v[48:51]
	v_mfma_f32_16x16x32_bf16 v[48:51], v[8:11], v[60:63], v[72:75]
	v_mfma_f32_16x16x32_bf16 v[104:107], v[20:23], v[232:235], v[48:51]
	v_mfma_f32_16x16x32_bf16 v[48:51], v[28:31], v[60:63], v[76:79]
	v_mfma_f32_16x16x32_bf16 v[96:99], v[212:215], v[232:235], v[48:51]
	v_mfma_f32_16x16x32_bf16 v[48:51], v[8:11], v[236:239], v[80:83]
	v_mfma_f32_16x16x32_bf16 v[88:91], v[20:23], v[240:243], v[48:51]
	v_mfma_f32_16x16x32_bf16 v[48:51], v[28:31], v[236:239], v[84:87]
	v_mfma_f32_16x16x32_bf16 v[80:83], v[212:215], v[240:243], v[48:51]
	v_mfma_f32_16x16x32_bf16 v[48:51], v[8:11], v[244:247], v[92:95]
	v_mfma_f32_16x16x32_bf16 v[56:59], v[20:23], v[248:251], v[48:51]
	v_mfma_f32_16x16x32_bf16 v[48:51], v[28:31], v[244:247], v[100:103]
	v_mfma_f32_16x16x32_bf16 v[48:51], v[212:215], v[248:251], v[48:51]
	v_mfma_f32_16x16x32_bf16 v[64:67], v[216:219], v[16:19], v[108:111]
	v_mfma_f32_16x16x32_bf16 v[16:19], v[224:227], v[16:19], v[32:35]
	v_mfma_f32_16x16x32_bf16 v[116:119], v[228:231], v[24:27], v[16:19]
	v_mfma_f32_16x16x32_bf16 v[16:19], v[216:219], v[60:63], v[36:39]
	v_mfma_f32_16x16x32_bf16 v[108:111], v[220:223], v[232:235], v[16:19]
	v_mfma_f32_16x16x32_bf16 v[16:19], v[224:227], v[60:63], v[40:43]
	v_mfma_f32_16x16x32_bf16 v[100:103], v[228:231], v[232:235], v[16:19]
	v_mfma_f32_16x16x32_bf16 v[16:19], v[216:219], v[236:239], v[44:47]
	v_mfma_f32_16x16x32_bf16 v[92:95], v[220:223], v[240:243], v[16:19]
	v_mfma_f32_16x16x32_bf16 v[16:19], v[224:227], v[236:239], v[52:55]
	v_mfma_f32_16x16x32_bf16 v[84:87], v[228:231], v[240:243], v[16:19]
	v_mfma_f32_16x16x32_bf16 v[16:19], v[216:219], v[244:247], v[152:155]
	v_mfma_f32_16x16x32_bf16 v[60:63], v[220:223], v[248:251], v[16:19]
	v_mfma_f32_16x16x32_bf16 v[16:19], v[224:227], v[244:247], v[156:159]
	v_mfma_f32_16x16x32_bf16 v[124:127], v[220:223], v[24:27], v[64:67]
	v_mfma_f32_16x16x32_bf16 v[52:55], v[228:231], v[248:251], v[16:19]
	s_barrier
	s_add_i32 s59, s59, s15
	s_add_i32 s71, s59, 0x2000
	s_nop 1
	v_lshl_add_u64 v[16:17], v[146:147], 0, s[66:67]
	s_mov_b32 m0, s59
	s_add_u32 s84, s80, 0x80180
	ds_read_b128 v[36:39], v151 offset:49152
	ds_read_b128 v[44:47], v151 offset:50176
	ds_read_b128 v[152:155], v151 offset:51200
	ds_read_b128 v[156:159], v151 offset:52224
	ds_read_b128 v[232:235], v151 offset:53248
	ds_read_b128 v[236:239], v151 offset:54272
	ds_read_b128 v[240:243], v151 offset:55296
	ds_read_b128 v[244:247], v151 offset:56320
	global_load_lds_dwordx4 v[16:17], off
	v_lshl_add_u64 v[16:17], v[252:253], 0, s[66:67]
	s_mov_b32 m0, s71
	s_addc_u32 s85, s81, 0
	s_add_i32 s73, s73, s15
	global_load_lds_dwordx4 v[16:17], off
	v_lshl_add_u64 v[16:17], s[84:85], 0, v[128:129]
	s_mov_b32 m0, s73
	s_add_i32 s79, s73, 0x2000
	global_load_lds_dwordx4 v[16:17], off
	v_lshl_add_u64 v[16:17], s[84:85], 0, v[130:131]
	s_mov_b32 m0, s79
	s_nop 0
	global_load_lds_dwordx4 v[16:17], off
	v_lshl_add_u64 v[16:17], v[140:141], 0, s[66:67]
	s_mov_b32 m0, s43
	s_nop 0
	global_load_lds_dwordx4 v[16:17], off
	v_lshl_add_u64 v[16:17], v[142:143], 0, s[66:67]
	s_mov_b32 m0, s44
	s_nop 0
	global_load_lds_dwordx4 v[16:17], off
	s_waitcnt vmcnt(8) lgkmcnt(0)
	s_barrier
	v_mfma_f32_16x16x32_bf16 v[16:19], v[8:11], v[36:39], v[160:163]
	v_mfma_f32_16x16x32_bf16 v[72:75], v[20:23], v[44:47], v[16:19]
	v_mfma_f32_16x16x32_bf16 v[16:19], v[28:31], v[36:39], v[164:167]
	v_mfma_f32_16x16x32_bf16 v[64:67], v[212:215], v[44:47], v[16:19]
	v_mfma_f32_16x16x32_bf16 v[16:19], v[8:11], v[152:155], v[168:171]
	v_mfma_f32_16x16x32_bf16 v[40:43], v[20:23], v[156:159], v[16:19]
	v_mfma_f32_16x16x32_bf16 v[16:19], v[28:31], v[152:155], v[172:175]
	v_mfma_f32_16x16x32_bf16 v[32:35], v[212:215], v[156:159], v[16:19]
	v_mfma_f32_16x16x32_bf16 v[16:19], v[8:11], v[232:235], v[176:179]
	v_mfma_f32_16x16x32_bf16 v[0:3], v[8:11], v[240:243], v[0:3]
	v_mfma_f32_16x16x32_bf16 v[24:27], v[20:23], v[236:239], v[16:19]
	v_mfma_f32_16x16x32_bf16 v[16:19], v[28:31], v[232:235], v[180:183]
	v_mfma_f32_16x16x32_bf16 v[8:11], v[20:23], v[244:247], v[0:3]
	v_mfma_f32_16x16x32_bf16 v[0:3], v[28:31], v[240:243], v[4:7]
	v_mfma_f32_16x16x32_bf16 v[16:19], v[212:215], v[236:239], v[16:19]
	v_mfma_f32_16x16x32_bf16 v[0:3], v[212:215], v[244:247], v[0:3]
	v_mfma_f32_16x16x32_bf16 v[4:7], v[216:219], v[36:39], v[12:15]
	v_mfma_f32_16x16x32_bf16 v[76:79], v[220:223], v[44:47], v[4:7]
	v_mfma_f32_16x16x32_bf16 v[4:7], v[224:227], v[36:39], v[184:187]
	v_mfma_f32_16x16x32_bf16 v[68:71], v[228:231], v[44:47], v[4:7]
	v_mfma_f32_16x16x32_bf16 v[4:7], v[216:219], v[152:155], v[188:191]
	v_mfma_f32_16x16x32_bf16 v[44:47], v[220:223], v[156:159], v[4:7]
	v_mfma_f32_16x16x32_bf16 v[4:7], v[224:227], v[152:155], v[192:195]
	v_mfma_f32_16x16x32_bf16 v[36:39], v[228:231], v[156:159], v[4:7]
	v_mfma_f32_16x16x32_bf16 v[4:7], v[216:219], v[232:235], v[196:199]
	v_mfma_f32_16x16x32_bf16 v[28:31], v[220:223], v[236:239], v[4:7]
	v_mfma_f32_16x16x32_bf16 v[4:7], v[224:227], v[232:235], v[200:203]
	v_mfma_f32_16x16x32_bf16 v[20:23], v[228:231], v[236:239], v[4:7]
	v_mfma_f32_16x16x32_bf16 v[4:7], v[216:219], v[240:243], v[204:207]
	v_mfma_f32_16x16x32_bf16 v[12:15], v[220:223], v[244:247], v[4:7]
	v_mfma_f32_16x16x32_bf16 v[4:7], v[224:227], v[240:243], v[208:211]
	v_mfma_f32_16x16x32_bf16 v[4:7], v[228:231], v[244:247], v[4:7]
	s_barrier
	s_add_u32 s88, s80, 0x200
	s_addc_u32 s89, s81, 0
	s_add_u32 s80, s82, 0x80180
	s_addc_u32 s81, s83, 0
	s_mov_b32 s90, 0
.LBB0_777:
	ds_read_b128 v[152:155], v149
	ds_read_b128 v[156:159], v149 offset:1024
	ds_read_b128 v[160:163], v149 offset:2048
	ds_read_b128 v[164:167], v149 offset:3072
	ds_read_b128 v[168:171], v150
	ds_read_b128 v[172:175], v150 offset:1024
	ds_read_b128 v[176:179], v150 offset:2048
	ds_read_b128 v[180:183], v150 offset:3072
	s_add_u32 s82, s80, 0xfff80080
	s_addc_u32 s83, s81, -1
	s_cmp_eq_u32 s90, 28
	s_cselect_b32 s85, s51, s83
	s_cselect_b32 s84, s52, s82
	s_cselect_b32 s83, s53, s89
	s_cselect_b32 s82, s54, s88
	s_mov_b32 m0, s48
	v_lshl_add_u64 v[140:141], s[80:81], 0, v[138:139]
	ds_read_b128 v[184:187], v151
	ds_read_b128 v[188:191], v151 offset:1024
	ds_read_b128 v[192:195], v151 offset:2048
	ds_read_b128 v[196:199], v151 offset:3072
	ds_read_b128 v[200:203], v151 offset:4096
	ds_read_b128 v[204:207], v151 offset:5120
	ds_read_b128 v[208:211], v151 offset:6144
	ds_read_b128 v[212:215], v151 offset:7168
	global_load_lds_dwordx4 v[140:141], off
	v_lshl_add_u64 v[140:141], s[80:81], 0, v[136:137]
	s_mov_b32 m0, s49
	s_nop 0
	global_load_lds_dwordx4 v[140:141], off
	s_waitcnt vmcnt(8) lgkmcnt(0)
	s_barrier
	v_mfma_f32_16x16x32_bf16 v[120:123], v[152:155], v[184:187], v[120:123]
	v_mfma_f32_16x16x32_bf16 v[112:115], v[160:163], v[184:187], v[112:115]
	v_mfma_f32_16x16x32_bf16 v[104:107], v[152:155], v[192:195], v[104:107]
	v_mfma_f32_16x16x32_bf16 v[96:99], v[160:163], v[192:195], v[96:99]
	v_mfma_f32_16x16x32_bf16 v[88:91], v[152:155], v[200:203], v[88:91]
	v_mfma_f32_16x16x32_bf16 v[80:83], v[160:163], v[200:203], v[80:83]
	v_mfma_f32_16x16x32_bf16 v[56:59], v[152:155], v[208:211], v[56:59]
	v_mfma_f32_16x16x32_bf16 v[48:51], v[160:163], v[208:211], v[48:51]
	v_mfma_f32_16x16x32_bf16 v[120:123], v[156:159], v[188:191], v[120:123]
	v_mfma_f32_16x16x32_bf16 v[112:115], v[164:167], v[188:191], v[112:115]
	v_mfma_f32_16x16x32_bf16 v[104:107], v[156:159], v[196:199], v[104:107]
	v_mfma_f32_16x16x32_bf16 v[96:99], v[164:167], v[196:199], v[96:99]
	v_mfma_f32_16x16x32_bf16 v[88:91], v[156:159], v[204:207], v[88:91]
	v_mfma_f32_16x16x32_bf16 v[80:83], v[164:167], v[204:207], v[80:83]
	v_mfma_f32_16x16x32_bf16 v[56:59], v[156:159], v[212:215], v[56:59]
	v_mfma_f32_16x16x32_bf16 v[48:51], v[164:167], v[212:215], v[48:51]
	v_mfma_f32_16x16x32_bf16 v[124:127], v[168:171], v[184:187], v[124:127]
	v_mfma_f32_16x16x32_bf16 v[116:119], v[176:179], v[184:187], v[116:119]
	v_mfma_f32_16x16x32_bf16 v[108:111], v[168:171], v[192:195], v[108:111]
	v_mfma_f32_16x16x32_bf16 v[100:103], v[176:179], v[192:195], v[100:103]
	v_mfma_f32_16x16x32_bf16 v[92:95], v[168:171], v[200:203], v[92:95]
	v_mfma_f32_16x16x32_bf16 v[84:87], v[176:179], v[200:203], v[84:87]
	v_mfma_f32_16x16x32_bf16 v[60:63], v[168:171], v[208:211], v[60:63]
	v_mfma_f32_16x16x32_bf16 v[52:55], v[176:179], v[208:211], v[52:55]
	v_mfma_f32_16x16x32_bf16 v[124:127], v[172:175], v[188:191], v[124:127]
	v_mfma_f32_16x16x32_bf16 v[116:119], v[180:183], v[188:191], v[116:119]
	v_mfma_f32_16x16x32_bf16 v[108:111], v[172:175], v[196:199], v[108:111]
	v_mfma_f32_16x16x32_bf16 v[100:103], v[180:183], v[196:199], v[100:103]
	v_mfma_f32_16x16x32_bf16 v[92:95], v[172:175], v[204:207], v[92:95]
	v_mfma_f32_16x16x32_bf16 v[84:87], v[180:183], v[204:207], v[84:87]
	v_mfma_f32_16x16x32_bf16 v[60:63], v[172:175], v[212:215], v[60:63]
	v_mfma_f32_16x16x32_bf16 v[52:55], v[180:183], v[212:215], v[52:55]
	s_barrier
	s_mov_b32 m0, s55
	v_lshl_add_u64 v[140:141], s[82:83], 0, v[128:129]
	s_add_u32 s94, s82, 0x80000
	ds_read_b128 v[184:187], v151 offset:16384
	ds_read_b128 v[188:191], v151 offset:17408
	ds_read_b128 v[192:195], v151 offset:18432
	ds_read_b128 v[196:199], v151 offset:19456
	ds_read_b128 v[200:203], v151 offset:20480
	ds_read_b128 v[204:207], v151 offset:21504
	ds_read_b128 v[208:211], v151 offset:22528
	ds_read_b128 v[212:215], v151 offset:23552
	global_load_lds_dwordx4 v[140:141], off
	v_lshl_add_u64 v[142:143], s[82:83], 0, v[130:131]
	s_mov_b32 m0, s56
	s_addc_u32 s95, s83, 0
	global_load_lds_dwordx4 v[142:143], off
	v_lshl_add_u64 v[146:147], s[94:95], 0, v[128:129]
	s_mov_b32 m0, s57
	v_lshl_add_u64 v[216:217], s[84:85], 0, v[132:133]
	global_load_lds_dwordx4 v[146:147], off
	v_lshl_add_u64 v[146:147], s[94:95], 0, v[130:131]
	s_mov_b32 m0, s58
	s_nop 0
	global_load_lds_dwordx4 v[146:147], off
	v_lshl_add_u64 v[146:147], s[84:85], 0, v[134:135]
	s_mov_b32 m0, s23
	s_nop 0
	global_load_lds_dwordx4 v[146:147], off
	s_mov_b32 m0, s36
	s_nop 0
	global_load_lds_dwordx4 v[216:217], off
	s_waitcnt vmcnt(8) lgkmcnt(0)
	s_barrier
	v_mfma_f32_16x16x32_bf16 v[72:75], v[152:155], v[184:187], v[72:75]
	v_mfma_f32_16x16x32_bf16 v[64:67], v[160:163], v[184:187], v[64:67]
	v_mfma_f32_16x16x32_bf16 v[40:43], v[152:155], v[192:195], v[40:43]
	v_mfma_f32_16x16x32_bf16 v[32:35], v[160:163], v[192:195], v[32:35]
	v_mfma_f32_16x16x32_bf16 v[24:27], v[152:155], v[200:203], v[24:27]
	v_mfma_f32_16x16x32_bf16 v[16:19], v[160:163], v[200:203], v[16:19]
	v_mfma_f32_16x16x32_bf16 v[8:11], v[152:155], v[208:211], v[8:11]
	v_mfma_f32_16x16x32_bf16 v[0:3], v[160:163], v[208:211], v[0:3]
	v_mfma_f32_16x16x32_bf16 v[72:75], v[156:159], v[188:191], v[72:75]
	v_mfma_f32_16x16x32_bf16 v[64:67], v[164:167], v[188:191], v[64:67]
	v_mfma_f32_16x16x32_bf16 v[40:43], v[156:159], v[196:199], v[40:43]
	v_mfma_f32_16x16x32_bf16 v[32:35], v[164:167], v[196:199], v[32:35]
	v_mfma_f32_16x16x32_bf16 v[24:27], v[156:159], v[204:207], v[24:27]
	v_mfma_f32_16x16x32_bf16 v[16:19], v[164:167], v[204:207], v[16:19]
	v_mfma_f32_16x16x32_bf16 v[8:11], v[156:159], v[212:215], v[8:11]
	v_mfma_f32_16x16x32_bf16 v[0:3], v[164:167], v[212:215], v[0:3]
	v_mfma_f32_16x16x32_bf16 v[76:79], v[168:171], v[184:187], v[76:79]
	v_mfma_f32_16x16x32_bf16 v[68:71], v[176:179], v[184:187], v[68:71]
	v_mfma_f32_16x16x32_bf16 v[44:47], v[168:171], v[192:195], v[44:47]
	v_mfma_f32_16x16x32_bf16 v[36:39], v[176:179], v[192:195], v[36:39]
	v_mfma_f32_16x16x32_bf16 v[28:31], v[168:171], v[200:203], v[28:31]
	v_mfma_f32_16x16x32_bf16 v[20:23], v[176:179], v[200:203], v[20:23]
	v_mfma_f32_16x16x32_bf16 v[12:15], v[168:171], v[208:211], v[12:15]
	v_mfma_f32_16x16x32_bf16 v[4:7], v[176:179], v[208:211], v[4:7]
	v_mfma_f32_16x16x32_bf16 v[76:79], v[172:175], v[188:191], v[76:79]
	v_mfma_f32_16x16x32_bf16 v[68:71], v[180:183], v[188:191], v[68:71]
	v_mfma_f32_16x16x32_bf16 v[44:47], v[172:175], v[196:199], v[44:47]
	v_mfma_f32_16x16x32_bf16 v[36:39], v[180:183], v[196:199], v[36:39]
	v_mfma_f32_16x16x32_bf16 v[28:31], v[172:175], v[204:207], v[28:31]
	v_mfma_f32_16x16x32_bf16 v[20:23], v[180:183], v[204:207], v[20:23]
	v_mfma_f32_16x16x32_bf16 v[12:15], v[172:175], v[212:215], v[12:15]
	v_mfma_f32_16x16x32_bf16 v[4:7], v[180:183], v[212:215], v[4:7]
	s_barrier
; #define PG8_BAR __builtin_amdgcn_s_barrier()
; template <class Epi, class Sched, bool ALIGN_EPI = false, bool SP2 = false, bool A_TILED = false>
; __device__ __forceinline__ void gemm_phase(PG8_LAS unsigned char* lds, const Gemm g, const Sched& S, const Epi& E, const int wave_s) {
;     ...
;         if constexpr (ALIGN_EPI) { if (wr == 0) PG8_BAR; }
	ds_read_b128 v[152:155], v144
	ds_read_b128 v[156:159], v144 offset:1024
	ds_read_b128 v[160:163], v144 offset:2048
	ds_read_b128 v[164:167], v144 offset:3072
	ds_read_b128 v[168:171], v145
	ds_read_b128 v[172:175], v145 offset:1024
	ds_read_b128 v[176:179], v145 offset:2048
	ds_read_b128 v[180:183], v145 offset:3072
	s_add_u32 s84, s84, 0x80000
	s_addc_u32 s85, s85, 0
	s_mov_b32 m0, s37
	v_lshl_add_u64 v[218:219], s[84:85], 0, v[134:135]
	ds_read_b128 v[184:187], v151 offset:32768
	ds_read_b128 v[188:191], v151 offset:33792
	ds_read_b128 v[192:195], v151 offset:34816
	ds_read_b128 v[196:199], v151 offset:35840
	ds_read_b128 v[200:203], v151 offset:36864
	ds_read_b128 v[204:207], v151 offset:37888
	ds_read_b128 v[208:211], v151 offset:38912
	ds_read_b128 v[212:215], v151 offset:39936
	global_load_lds_dwordx4 v[218:219], off
	v_lshl_add_u64 v[218:219], s[84:85], 0, v[132:133]
	s_mov_b32 m0, s38
	s_nop 0
	global_load_lds_dwordx4 v[218:219], off
	s_waitcnt vmcnt(8) lgkmcnt(0)
	s_barrier
	v_mfma_f32_16x16x32_bf16 v[120:123], v[152:155], v[184:187], v[120:123]
	v_mfma_f32_16x16x32_bf16 v[112:115], v[160:163], v[184:187], v[112:115]
	v_mfma_f32_16x16x32_bf16 v[104:107], v[152:155], v[192:195], v[104:107]
	v_mfma_f32_16x16x32_bf16 v[96:99], v[160:163], v[192:195], v[96:99]
	v_mfma_f32_16x16x32_bf16 v[88:91], v[152:155], v[200:203], v[88:91]
	v_mfma_f32_16x16x32_bf16 v[80:83], v[160:163], v[200:203], v[80:83]
	v_mfma_f32_16x16x32_bf16 v[56:59], v[152:155], v[208:211], v[56:59]
	v_mfma_f32_16x16x32_bf16 v[48:51], v[160:163], v[208:211], v[48:51]
	v_mfma_f32_16x16x32_bf16 v[120:123], v[156:159], v[188:191], v[120:123]
	v_mfma_f32_16x16x32_bf16 v[112:115], v[164:167], v[188:191], v[112:115]
	v_mfma_f32_16x16x32_bf16 v[104:107], v[156:159], v[196:199], v[104:107]
	v_mfma_f32_16x16x32_bf16 v[96:99], v[164:167], v[196:199], v[96:99]
	v_mfma_f32_16x16x32_bf16 v[88:91], v[156:159], v[204:207], v[88:91]
	v_mfma_f32_16x16x32_bf16 v[80:83], v[164:167], v[204:207], v[80:83]
	v_mfma_f32_16x16x32_bf16 v[56:59], v[156:159], v[212:215], v[56:59]
	v_mfma_f32_16x16x32_bf16 v[48:51], v[164:167], v[212:215], v[48:51]
	v_mfma_f32_16x16x32_bf16 v[124:127], v[168:171], v[184:187], v[124:127]
	v_mfma_f32_16x16x32_bf16 v[116:119], v[176:179], v[184:187], v[116:119]
	v_mfma_f32_16x16x32_bf16 v[108:111], v[168:171], v[192:195], v[108:111]
	v_mfma_f32_16x16x32_bf16 v[100:103], v[176:179], v[192:195], v[100:103]
	v_mfma_f32_16x16x32_bf16 v[92:95], v[168:171], v[200:203], v[92:95]
	v_mfma_f32_16x16x32_bf16 v[84:87], v[176:179], v[200:203], v[84:87]
	v_mfma_f32_16x16x32_bf16 v[60:63], v[168:171], v[208:211], v[60:63]
	v_mfma_f32_16x16x32_bf16 v[52:55], v[176:179], v[208:211], v[52:55]
	v_mfma_f32_16x16x32_bf16 v[124:127], v[172:175], v[188:191], v[124:127]
	v_mfma_f32_16x16x32_bf16 v[116:119], v[180:183], v[188:191], v[116:119]
	v_mfma_f32_16x16x32_bf16 v[108:111], v[172:175], v[196:199], v[108:111]
	v_mfma_f32_16x16x32_bf16 v[100:103], v[180:183], v[196:199], v[100:103]
	v_mfma_f32_16x16x32_bf16 v[92:95], v[172:175], v[204:207], v[92:95]
	v_mfma_f32_16x16x32_bf16 v[84:87], v[180:183], v[204:207], v[84:87]
	v_mfma_f32_16x16x32_bf16 v[60:63], v[172:175], v[212:215], v[60:63]
	v_mfma_f32_16x16x32_bf16 v[52:55], v[180:183], v[212:215], v[52:55]
	s_barrier
	s_mov_b32 m0, s59
	v_lshl_add_u64 v[140:141], v[140:141], 0, s[62:63]
	s_add_u32 s82, s82, 0x80080
	ds_read_b128 v[184:187], v151 offset:49152
	ds_read_b128 v[188:191], v151 offset:50176
	ds_read_b128 v[192:195], v151 offset:51200
	ds_read_b128 v[196:199], v151 offset:52224
	ds_read_b128 v[200:203], v151 offset:53248
	ds_read_b128 v[204:207], v151 offset:54272
	ds_read_b128 v[208:211], v151 offset:55296
	ds_read_b128 v[212:215], v151 offset:56320
	global_load_lds_dwordx4 v[140:141], off
	v_lshl_add_u64 v[140:141], v[142:143], 0, s[62:63]
	s_mov_b32 m0, s71
	s_addc_u32 s83, s83, 0
	global_load_lds_dwordx4 v[140:141], off
	v_lshl_add_u64 v[140:141], s[82:83], 0, v[128:129]
	s_mov_b32 m0, s73
	s_nop 0
	global_load_lds_dwordx4 v[140:141], off
	v_lshl_add_u64 v[140:141], s[82:83], 0, v[130:131]
	s_mov_b32 m0, s79
	s_nop 0
	global_load_lds_dwordx4 v[140:141], off
	v_lshl_add_u64 v[140:141], v[146:147], 0, s[62:63]
	s_mov_b32 m0, s43
	s_nop 0
	global_load_lds_dwordx4 v[140:141], off
	v_lshl_add_u64 v[140:141], v[216:217], 0, s[62:63]
	s_mov_b32 m0, s44
	s_nop 0
	global_load_lds_dwordx4 v[140:141], off
	s_waitcnt vmcnt(8) lgkmcnt(0)
	s_barrier
	v_mfma_f32_16x16x32_bf16 v[72:75], v[152:155], v[184:187], v[72:75]
	v_mfma_f32_16x16x32_bf16 v[64:67], v[160:163], v[184:187], v[64:67]
	v_mfma_f32_16x16x32_bf16 v[40:43], v[152:155], v[192:195], v[40:43]
	v_mfma_f32_16x16x32_bf16 v[32:35], v[160:163], v[192:195], v[32:35]
	v_mfma_f32_16x16x32_bf16 v[24:27], v[152:155], v[200:203], v[24:27]
	v_mfma_f32_16x16x32_bf16 v[16:19], v[160:163], v[200:203], v[16:19]
	v_mfma_f32_16x16x32_bf16 v[8:11], v[152:155], v[208:211], v[8:11]
	v_mfma_f32_16x16x32_bf16 v[0:3], v[160:163], v[208:211], v[0:3]
	v_mfma_f32_16x16x32_bf16 v[72:75], v[156:159], v[188:191], v[72:75]
	v_mfma_f32_16x16x32_bf16 v[64:67], v[164:167], v[188:191], v[64:67]
	v_mfma_f32_16x16x32_bf16 v[40:43], v[156:159], v[196:199], v[40:43]
	v_mfma_f32_16x16x32_bf16 v[32:35], v[164:167], v[196:199], v[32:35]
	v_mfma_f32_16x16x32_bf16 v[24:27], v[156:159], v[204:207], v[24:27]
	v_mfma_f32_16x16x32_bf16 v[16:19], v[164:167], v[204:207], v[16:19]
	v_mfma_f32_16x16x32_bf16 v[8:11], v[156:159], v[212:215], v[8:11]
	v_mfma_f32_16x16x32_bf16 v[0:3], v[164:167], v[212:215], v[0:3]
	v_mfma_f32_16x16x32_bf16 v[76:79], v[168:171], v[184:187], v[76:79]
	v_mfma_f32_16x16x32_bf16 v[68:71], v[176:179], v[184:187], v[68:71]
	v_mfma_f32_16x16x32_bf16 v[44:47], v[168:171], v[192:195], v[44:47]
	v_mfma_f32_16x16x32_bf16 v[36:39], v[176:179], v[192:195], v[36:39]
	v_mfma_f32_16x16x32_bf16 v[28:31], v[168:171], v[200:203], v[28:31]
	v_mfma_f32_16x16x32_bf16 v[20:23], v[176:179], v[200:203], v[20:23]
	v_mfma_f32_16x16x32_bf16 v[12:15], v[168:171], v[208:211], v[12:15]
	v_mfma_f32_16x16x32_bf16 v[4:7], v[176:179], v[208:211], v[4:7]
	v_mfma_f32_16x16x32_bf16 v[76:79], v[172:175], v[188:191], v[76:79]
	v_mfma_f32_16x16x32_bf16 v[68:71], v[180:183], v[188:191], v[68:71]
	v_mfma_f32_16x16x32_bf16 v[44:47], v[172:175], v[196:199], v[44:47]
	v_mfma_f32_16x16x32_bf16 v[36:39], v[180:183], v[196:199], v[36:39]
	v_mfma_f32_16x16x32_bf16 v[28:31], v[172:175], v[204:207], v[28:31]
	v_mfma_f32_16x16x32_bf16 v[20:23], v[180:183], v[204:207], v[20:23]
	v_mfma_f32_16x16x32_bf16 v[12:15], v[172:175], v[212:215], v[12:15]
	v_mfma_f32_16x16x32_bf16 v[4:7], v[180:183], v[212:215], v[4:7]
	s_barrier
	s_add_i32 s90, s90, 2
	s_add_u32 s88, s88, 0x100
	s_addc_u32 s89, s89, 0
	s_add_u32 s80, s80, 0x100
	s_addc_u32 s81, s81, 0
	s_cmp_gt_u32 s90, 29
	s_cbranch_scc0 .LBB0_777
	s_and_b64 vcc, exec, s[64:65]
	s_cbranch_vccz .LBB0_780
	s_barrier

.LBB0_1043:
	ds_read_b128 v[146:149], v140
	ds_read_b128 v[150:153], v140 offset:1024
	ds_read_b128 v[154:157], v140 offset:2048
	ds_read_b128 v[158:161], v140 offset:3072
	ds_read_b128 v[162:165], v141
	ds_read_b128 v[166:169], v141 offset:1024
	ds_read_b128 v[170:173], v141 offset:2048
	ds_read_b128 v[174:177], v141 offset:3072
	s_add_u32 s52, s62, s39
	s_addc_u32 s53, s63, s40
	s_add_u32 s54, s62, s37
	s_addc_u32 s55, s63, s38
	s_cmp_eq_u32 s41, 28
	s_cselect_b32 s73, s5, s53
	s_cselect_b32 s72, s4, s52
	s_cselect_b32 s71, s1, s55
	s_cselect_b32 s70, s0, s54
	s_mov_b32 m0, s42
	v_lshl_add_u64 v[210:211], s[62:63], 0, v[138:139]
	ds_read_b128 v[178:181], v142
	ds_read_b128 v[182:185], v142 offset:1024
	ds_read_b128 v[186:189], v142 offset:2048
	ds_read_b128 v[190:193], v142 offset:3072
	ds_read_b128 v[194:197], v142 offset:4096
	ds_read_b128 v[198:201], v142 offset:5120
	ds_read_b128 v[202:205], v142 offset:6144
	ds_read_b128 v[206:209], v142 offset:7168
	global_load_lds_dwordx4 v[210:211], off
	v_lshl_add_u64 v[210:211], s[62:63], 0, v[136:137]
	s_mov_b32 m0, s43
	s_nop 0
	global_load_lds_dwordx4 v[210:211], off
	s_waitcnt vmcnt(8) lgkmcnt(0)
	s_barrier
	v_mfma_f32_16x16x32_bf16 v[8:11], v[146:149], v[178:181], v[8:11]
	v_mfma_f32_16x16x32_bf16 v[12:15], v[154:157], v[178:181], v[12:15]
	v_mfma_f32_16x16x32_bf16 v[36:39], v[146:149], v[186:189], v[36:39]
	v_mfma_f32_16x16x32_bf16 v[32:35], v[154:157], v[186:189], v[32:35]
	v_mfma_f32_16x16x32_bf16 v[60:63], v[146:149], v[194:197], v[60:63]
	v_mfma_f32_16x16x32_bf16 v[56:59], v[154:157], v[194:197], v[56:59]
	v_mfma_f32_16x16x32_bf16 v[80:83], v[146:149], v[202:205], v[80:83]
	v_mfma_f32_16x16x32_bf16 v[72:75], v[154:157], v[202:205], v[72:75]
	v_mfma_f32_16x16x32_bf16 v[8:11], v[150:153], v[182:185], v[8:11]
	v_mfma_f32_16x16x32_bf16 v[12:15], v[158:161], v[182:185], v[12:15]
	v_mfma_f32_16x16x32_bf16 v[36:39], v[150:153], v[190:193], v[36:39]
	v_mfma_f32_16x16x32_bf16 v[32:35], v[158:161], v[190:193], v[32:35]
	v_mfma_f32_16x16x32_bf16 v[60:63], v[150:153], v[198:201], v[60:63]
	v_mfma_f32_16x16x32_bf16 v[56:59], v[158:161], v[198:201], v[56:59]
	v_mfma_f32_16x16x32_bf16 v[80:83], v[150:153], v[206:209], v[80:83]
	v_mfma_f32_16x16x32_bf16 v[72:75], v[158:161], v[206:209], v[72:75]
	v_mfma_f32_16x16x32_bf16 v[44:47], v[162:165], v[178:181], v[44:47]
	v_mfma_f32_16x16x32_bf16 v[40:43], v[170:173], v[178:181], v[40:43]
	v_mfma_f32_16x16x32_bf16 v[52:55], v[162:165], v[186:189], v[52:55]
	v_mfma_f32_16x16x32_bf16 v[48:51], v[170:173], v[186:189], v[48:51]
	v_mfma_f32_16x16x32_bf16 v[68:71], v[162:165], v[194:197], v[68:71]
	v_mfma_f32_16x16x32_bf16 v[64:67], v[170:173], v[194:197], v[64:67]
	v_mfma_f32_16x16x32_bf16 v[100:103], v[162:165], v[202:205], v[100:103]
	v_mfma_f32_16x16x32_bf16 v[96:99], v[170:173], v[202:205], v[96:99]
	v_mfma_f32_16x16x32_bf16 v[44:47], v[166:169], v[182:185], v[44:47]
	v_mfma_f32_16x16x32_bf16 v[40:43], v[174:177], v[182:185], v[40:43]
	v_mfma_f32_16x16x32_bf16 v[52:55], v[166:169], v[190:193], v[52:55]
	v_mfma_f32_16x16x32_bf16 v[48:51], v[174:177], v[190:193], v[48:51]
	v_mfma_f32_16x16x32_bf16 v[68:71], v[166:169], v[198:201], v[68:71]
	v_mfma_f32_16x16x32_bf16 v[64:67], v[174:177], v[198:201], v[64:67]
	v_mfma_f32_16x16x32_bf16 v[100:103], v[166:169], v[206:209], v[100:103]
	v_mfma_f32_16x16x32_bf16 v[96:99], v[174:177], v[206:209], v[96:99]
	s_barrier
	s_mov_b32 m0, s44
	v_lshl_add_u64 v[210:211], s[70:71], 0, v[130:131]
	s_add_u32 s52, s70, 0x80000
	ds_read_b128 v[178:181], v142 offset:16384
	ds_read_b128 v[182:185], v142 offset:17408
	ds_read_b128 v[186:189], v142 offset:18432
	ds_read_b128 v[190:193], v142 offset:19456
	ds_read_b128 v[194:197], v142 offset:20480
	ds_read_b128 v[198:201], v142 offset:21504
	ds_read_b128 v[202:205], v142 offset:22528
	ds_read_b128 v[206:209], v142 offset:23552
	global_load_lds_dwordx4 v[210:211], off
	v_lshl_add_u64 v[212:213], s[70:71], 0, v[134:135]
	s_mov_b32 m0, s45
	s_addc_u32 s53, s71, 0
	global_load_lds_dwordx4 v[212:213], off
	v_lshl_add_u64 v[214:215], s[52:53], 0, v[130:131]
	s_mov_b32 m0, s46
	v_lshl_add_u64 v[216:217], s[72:73], 0, v[132:133]
	global_load_lds_dwordx4 v[214:215], off
	v_lshl_add_u64 v[214:215], s[52:53], 0, v[134:135]
	s_mov_b32 m0, s47
	s_nop 0
	global_load_lds_dwordx4 v[214:215], off
	v_lshl_add_u64 v[214:215], s[72:73], 0, v[128:129]
	s_mov_b32 m0, s14
	s_nop 0
	global_load_lds_dwordx4 v[214:215], off
	s_mov_b32 m0, s15
	s_nop 0
	global_load_lds_dwordx4 v[216:217], off
	s_waitcnt vmcnt(8) lgkmcnt(0)
	s_barrier
	v_mfma_f32_16x16x32_bf16 v[108:111], v[146:149], v[178:181], v[108:111]
	v_mfma_f32_16x16x32_bf16 v[104:107], v[154:157], v[178:181], v[104:107]
	v_mfma_f32_16x16x32_bf16 v[124:127], v[146:149], v[186:189], v[124:127]
	v_mfma_f32_16x16x32_bf16 v[120:123], v[154:157], v[186:189], v[120:123]
	v_mfma_f32_16x16x32_bf16 v[84:87], v[146:149], v[194:197], v[84:87]
	v_mfma_f32_16x16x32_bf16 v[76:79], v[154:157], v[194:197], v[76:79]
	v_mfma_f32_16x16x32_bf16 v[20:23], v[146:149], v[202:205], v[20:23]
	v_mfma_f32_16x16x32_bf16 v[16:19], v[154:157], v[202:205], v[16:19]
	v_mfma_f32_16x16x32_bf16 v[108:111], v[150:153], v[182:185], v[108:111]
	v_mfma_f32_16x16x32_bf16 v[104:107], v[158:161], v[182:185], v[104:107]
	v_mfma_f32_16x16x32_bf16 v[124:127], v[150:153], v[190:193], v[124:127]
	v_mfma_f32_16x16x32_bf16 v[120:123], v[158:161], v[190:193], v[120:123]
	v_mfma_f32_16x16x32_bf16 v[84:87], v[150:153], v[198:201], v[84:87]
	v_mfma_f32_16x16x32_bf16 v[76:79], v[158:161], v[198:201], v[76:79]
	v_mfma_f32_16x16x32_bf16 v[20:23], v[150:153], v[206:209], v[20:23]
	v_mfma_f32_16x16x32_bf16 v[16:19], v[158:161], v[206:209], v[16:19]
	v_mfma_f32_16x16x32_bf16 v[116:119], v[162:165], v[178:181], v[116:119]
	v_mfma_f32_16x16x32_bf16 v[112:115], v[170:173], v[178:181], v[112:115]
	v_mfma_f32_16x16x32_bf16 v[92:95], v[162:165], v[186:189], v[92:95]
	v_mfma_f32_16x16x32_bf16 v[88:91], v[170:173], v[186:189], v[88:91]
	v_mfma_f32_16x16x32_bf16 v[28:31], v[162:165], v[194:197], v[28:31]
	v_mfma_f32_16x16x32_bf16 v[24:27], v[170:173], v[194:197], v[24:27]
	v_mfma_f32_16x16x32_bf16 v[4:7], v[162:165], v[202:205], v[4:7]
	v_mfma_f32_16x16x32_bf16 v[0:3], v[170:173], v[202:205], v[0:3]
	v_mfma_f32_16x16x32_bf16 v[116:119], v[166:169], v[182:185], v[116:119]
	v_mfma_f32_16x16x32_bf16 v[112:115], v[174:177], v[182:185], v[112:115]
	v_mfma_f32_16x16x32_bf16 v[92:95], v[166:169], v[190:193], v[92:95]
	v_mfma_f32_16x16x32_bf16 v[88:91], v[174:177], v[190:193], v[88:91]
	v_mfma_f32_16x16x32_bf16 v[28:31], v[166:169], v[198:201], v[28:31]
	v_mfma_f32_16x16x32_bf16 v[24:27], v[174:177], v[198:201], v[24:27]
	v_mfma_f32_16x16x32_bf16 v[4:7], v[166:169], v[206:209], v[4:7]
	v_mfma_f32_16x16x32_bf16 v[0:3], v[174:177], v[206:209], v[0:3]
	s_barrier
	ds_read_b128 v[146:149], v143
	ds_read_b128 v[150:153], v143 offset:1024
	ds_read_b128 v[154:157], v143 offset:2048
	ds_read_b128 v[158:161], v143 offset:3072
	ds_read_b128 v[162:165], v144
	ds_read_b128 v[166:169], v144 offset:1024
	ds_read_b128 v[170:173], v144 offset:2048
	ds_read_b128 v[174:177], v144 offset:3072
	s_add_u32 s52, s72, 0x80000
	s_addc_u32 s53, s73, 0
	s_mov_b32 m0, s21
	v_lshl_add_u64 v[218:219], s[52:53], 0, v[128:129]
	ds_read_b128 v[178:181], v142 offset:32768
	ds_read_b128 v[182:185], v142 offset:33792
	ds_read_b128 v[186:189], v142 offset:34816
	ds_read_b128 v[190:193], v142 offset:35840
	ds_read_b128 v[194:197], v142 offset:36864
	ds_read_b128 v[198:201], v142 offset:37888
	ds_read_b128 v[202:205], v142 offset:38912
	ds_read_b128 v[206:209], v142 offset:39936
	global_load_lds_dwordx4 v[218:219], off
	v_lshl_add_u64 v[218:219], s[52:53], 0, v[132:133]
	s_mov_b32 m0, s22
	s_nop 0
	global_load_lds_dwordx4 v[218:219], off
	s_waitcnt vmcnt(8) lgkmcnt(0)
	s_barrier
	v_mfma_f32_16x16x32_bf16 v[8:11], v[146:149], v[178:181], v[8:11]
	v_mfma_f32_16x16x32_bf16 v[12:15], v[154:157], v[178:181], v[12:15]
	v_mfma_f32_16x16x32_bf16 v[36:39], v[146:149], v[186:189], v[36:39]
	v_mfma_f32_16x16x32_bf16 v[32:35], v[154:157], v[186:189], v[32:35]
	v_mfma_f32_16x16x32_bf16 v[60:63], v[146:149], v[194:197], v[60:63]
	v_mfma_f32_16x16x32_bf16 v[56:59], v[154:157], v[194:197], v[56:59]
	v_mfma_f32_16x16x32_bf16 v[80:83], v[146:149], v[202:205], v[80:83]
	v_mfma_f32_16x16x32_bf16 v[72:75], v[154:157], v[202:205], v[72:75]
	v_mfma_f32_16x16x32_bf16 v[8:11], v[150:153], v[182:185], v[8:11]
	v_mfma_f32_16x16x32_bf16 v[12:15], v[158:161], v[182:185], v[12:15]
	v_mfma_f32_16x16x32_bf16 v[36:39], v[150:153], v[190:193], v[36:39]
	v_mfma_f32_16x16x32_bf16 v[32:35], v[158:161], v[190:193], v[32:35]
	v_mfma_f32_16x16x32_bf16 v[60:63], v[150:153], v[198:201], v[60:63]
	v_mfma_f32_16x16x32_bf16 v[56:59], v[158:161], v[198:201], v[56:59]
	v_mfma_f32_16x16x32_bf16 v[80:83], v[150:153], v[206:209], v[80:83]
	v_mfma_f32_16x16x32_bf16 v[72:75], v[158:161], v[206:209], v[72:75]
	v_mfma_f32_16x16x32_bf16 v[44:47], v[162:165], v[178:181], v[44:47]
	v_mfma_f32_16x16x32_bf16 v[40:43], v[170:173], v[178:181], v[40:43]
	v_mfma_f32_16x16x32_bf16 v[52:55], v[162:165], v[186:189], v[52:55]
	v_mfma_f32_16x16x32_bf16 v[48:51], v[170:173], v[186:189], v[48:51]
	v_mfma_f32_16x16x32_bf16 v[68:71], v[162:165], v[194:197], v[68:71]
	v_mfma_f32_16x16x32_bf16 v[64:67], v[170:173], v[194:197], v[64:67]
	v_mfma_f32_16x16x32_bf16 v[100:103], v[162:165], v[202:205], v[100:103]
	v_mfma_f32_16x16x32_bf16 v[96:99], v[170:173], v[202:205], v[96:99]
	v_mfma_f32_16x16x32_bf16 v[44:47], v[166:169], v[182:185], v[44:47]
	v_mfma_f32_16x16x32_bf16 v[40:43], v[174:177], v[182:185], v[40:43]
	v_mfma_f32_16x16x32_bf16 v[52:55], v[166:169], v[190:193], v[52:55]
	v_mfma_f32_16x16x32_bf16 v[48:51], v[174:177], v[190:193], v[48:51]
	v_mfma_f32_16x16x32_bf16 v[68:71], v[166:169], v[198:201], v[68:71]
	v_mfma_f32_16x16x32_bf16 v[64:67], v[174:177], v[198:201], v[64:67]
	v_mfma_f32_16x16x32_bf16 v[100:103], v[166:169], v[206:209], v[100:103]
	v_mfma_f32_16x16x32_bf16 v[96:99], v[174:177], v[206:209], v[96:99]
	s_barrier
; #define PG8_WAIT_V(n) asm volatile("s_waitcnt vmcnt(" #n ")" ::: "memory")
; #define PG8_BAR __builtin_amdgcn_s_barrier()
; template <class Epi, class Sched, bool ALIGN_EPI = false, bool SP2 = false, bool A_TILED = false>
; __device__ __forceinline__ void gemm_phase(PG8_LAS unsigned char* lds, const Gemm g, const Sched& S, const Epi& E, const int wave_s) {
;     ...
;     PG8_WAIT_V(0);
;     if constexpr (!ALIGN_EPI) { if (wr == 0) PG8_BAR; }
	s_mov_b32 m0, s48
	v_lshl_add_u64 v[210:211], v[210:211], 0, s[66:67]
	s_add_u32 s52, s70, 0x80080
	ds_read_b128 v[178:181], v142 offset:49152
	ds_read_b128 v[182:185], v142 offset:50176
	ds_read_b128 v[186:189], v142 offset:51200
	ds_read_b128 v[190:193], v142 offset:52224
	ds_read_b128 v[194:197], v142 offset:53248
	ds_read_b128 v[198:201], v142 offset:54272
	ds_read_b128 v[202:205], v142 offset:55296
	ds_read_b128 v[206:209], v142 offset:56320
	global_load_lds_dwordx4 v[210:211], off
	v_lshl_add_u64 v[210:211], v[212:213], 0, s[66:67]
	s_mov_b32 m0, s49
	s_addc_u32 s53, s71, 0
	global_load_lds_dwordx4 v[210:211], off
	v_lshl_add_u64 v[210:211], s[52:53], 0, v[130:131]
	s_mov_b32 m0, s50
	s_nop 0
	global_load_lds_dwordx4 v[210:211], off
	v_lshl_add_u64 v[210:211], s[52:53], 0, v[134:135]
	s_mov_b32 m0, s51
	s_nop 0
	global_load_lds_dwordx4 v[210:211], off
	v_lshl_add_u64 v[210:211], v[214:215], 0, s[66:67]
	s_mov_b32 m0, s23
	s_nop 0
	global_load_lds_dwordx4 v[210:211], off
	v_lshl_add_u64 v[210:211], v[216:217], 0, s[66:67]
	s_mov_b32 m0, s36
	s_nop 0
	global_load_lds_dwordx4 v[210:211], off
	s_waitcnt vmcnt(8) lgkmcnt(0)
	s_barrier
	v_mfma_f32_16x16x32_bf16 v[108:111], v[146:149], v[178:181], v[108:111]
	v_mfma_f32_16x16x32_bf16 v[104:107], v[154:157], v[178:181], v[104:107]
	v_mfma_f32_16x16x32_bf16 v[124:127], v[146:149], v[186:189], v[124:127]
	v_mfma_f32_16x16x32_bf16 v[120:123], v[154:157], v[186:189], v[120:123]
	v_mfma_f32_16x16x32_bf16 v[84:87], v[146:149], v[194:197], v[84:87]
	v_mfma_f32_16x16x32_bf16 v[76:79], v[154:157], v[194:197], v[76:79]
	v_mfma_f32_16x16x32_bf16 v[20:23], v[146:149], v[202:205], v[20:23]
	v_mfma_f32_16x16x32_bf16 v[16:19], v[154:157], v[202:205], v[16:19]
	v_mfma_f32_16x16x32_bf16 v[108:111], v[150:153], v[182:185], v[108:111]
	v_mfma_f32_16x16x32_bf16 v[104:107], v[158:161], v[182:185], v[104:107]
	v_mfma_f32_16x16x32_bf16 v[124:127], v[150:153], v[190:193], v[124:127]
	v_mfma_f32_16x16x32_bf16 v[120:123], v[158:161], v[190:193], v[120:123]
	v_mfma_f32_16x16x32_bf16 v[84:87], v[150:153], v[198:201], v[84:87]
	v_mfma_f32_16x16x32_bf16 v[76:79], v[158:161], v[198:201], v[76:79]
	v_mfma_f32_16x16x32_bf16 v[20:23], v[150:153], v[206:209], v[20:23]
	v_mfma_f32_16x16x32_bf16 v[16:19], v[158:161], v[206:209], v[16:19]
	v_mfma_f32_16x16x32_bf16 v[116:119], v[162:165], v[178:181], v[116:119]
	v_mfma_f32_16x16x32_bf16 v[112:115], v[170:173], v[178:181], v[112:115]
	v_mfma_f32_16x16x32_bf16 v[92:95], v[162:165], v[186:189], v[92:95]
	v_mfma_f32_16x16x32_bf16 v[88:91], v[170:173], v[186:189], v[88:91]
	v_mfma_f32_16x16x32_bf16 v[28:31], v[162:165], v[194:197], v[28:31]
	v_mfma_f32_16x16x32_bf16 v[24:27], v[170:173], v[194:197], v[24:27]
	v_mfma_f32_16x16x32_bf16 v[4:7], v[162:165], v[202:205], v[4:7]
	v_mfma_f32_16x16x32_bf16 v[0:3], v[170:173], v[202:205], v[0:3]
	v_mfma_f32_16x16x32_bf16 v[116:119], v[166:169], v[182:185], v[116:119]
	v_mfma_f32_16x16x32_bf16 v[112:115], v[174:177], v[182:185], v[112:115]
	v_mfma_f32_16x16x32_bf16 v[92:95], v[166:169], v[190:193], v[92:95]
	v_mfma_f32_16x16x32_bf16 v[88:91], v[174:177], v[190:193], v[88:91]
	v_mfma_f32_16x16x32_bf16 v[28:31], v[166:169], v[198:201], v[28:31]
	v_mfma_f32_16x16x32_bf16 v[24:27], v[174:177], v[198:201], v[24:27]
	v_mfma_f32_16x16x32_bf16 v[4:7], v[166:169], v[206:209], v[4:7]
	v_mfma_f32_16x16x32_bf16 v[0:3], v[174:177], v[206:209], v[0:3]
	s_barrier
	s_add_i32 s41, s41, 2
	s_add_u32 s37, s37, 0x100
	s_addc_u32 s38, s38, 0
	s_add_u32 s39, s39, 0x100
	s_addc_u32 s40, s40, 0
	v_lshl_add_u64 v[136:137], v[136:137], 0, s[68:69]
	s_cmp_gt_u32 s41, 29
	v_lshl_add_u64 v[138:139], v[138:139], 0, s[68:69]
	s_cbranch_scc0 .LBB0_1043
	s_waitcnt vmcnt(0)
	s_cmpk_lt_u32 s6, 0x100
	s_cbranch_scc0 .LBB0_1046
	s_barrier

; template <class Epi, class Sched, bool ALIGN_EPI = false, bool SP2 = false, bool A_TILED = false>
; __device__ __forceinline__ void gemm_phase(PG8_LAS unsigned char* lds, const Gemm g, const Sched& S, const Epi& E, const int wave_s) {
;     ...
;         const bool has_next = Epi::AFTER_DRAIN ? false : S.next(ui + 1, nxt);
;         const char* nA = has_next ? (const char*)g.A + (size_t)nxt.pm * tstepA : cA; const char* nB = has_next ? (const char*)g.Bt + (size_t)nxt.pn * tstep : cB;
;         constexpr bool PEEL = SP2 && !Epi::AFTER_DRAIN;
;         if constexpr (PEEL) {
;             const char* a1 = cA + kstepA; const char* a2 = cA + 2 * kstepA; const char* b2 = cB + 2 * kstep; const char* a3 = a2 + kstepA; const char* b3 = b2 + kstep;
;             PG8_ITER(PG8_MMAZ)
.LBB0_1154:
	s_ashr_i32 s69, s68, 31
	s_lshl_b64 s[50:51], s[68:69], 20
	s_add_u32 s70, s7, s50
	ds_read_b128 v[0:3], v145
	ds_read_b128 v[4:7], v145 offset:1024
	ds_read_b128 v[8:11], v145 offset:2048
	ds_read_b128 v[12:15], v145 offset:3072
	ds_read_b128 v[16:19], v146
	ds_read_b128 v[20:23], v146 offset:1024
	ds_read_b128 v[24:27], v146 offset:2048
	ds_read_b128 v[28:31], v146 offset:3072
	s_addc_u32 s71, s8, s51
	s_ashr_i32 s67, s66, 31
	s_lshl_b64 s[50:51], s[66:67], 20
	s_add_u32 s72, s9, s50
	s_addc_u32 s73, s14, s51
	s_and_b64 s[50:51], s[0:1], exec
	s_cselect_b32 s50, s71, s79
	s_cselect_b32 s51, s70, s78
	s_cselect_b32 s52, s73, s77
	s_cselect_b32 s53, s72, s76
	s_add_u32 s56, s78, 0x80080
	s_addc_u32 s57, s79, 0
	s_add_i32 s54, s22, 0xc000
	v_lshl_add_u64 v[64:65], s[56:57], 0, v[134:135]
	s_mov_b32 m0, s54
	s_add_i32 s55, s22, 0xe000
	ds_read_b128 v[32:35], v147
	ds_read_b128 v[36:39], v147 offset:1024
	ds_read_b128 v[40:43], v147 offset:2048
	ds_read_b128 v[44:47], v147 offset:3072
	ds_read_b128 v[48:51], v147 offset:4096
	ds_read_b128 v[52:55], v147 offset:5120
	ds_read_b128 v[56:59], v147 offset:6144
	ds_read_b128 v[60:63], v147 offset:7168
	global_load_lds_dwordx4 v[64:65], off
	v_lshl_add_u64 v[64:65], s[56:57], 0, v[132:133]
	s_mov_b32 m0, s55
	s_nop 0
	global_load_lds_dwordx4 v[64:65], off
	s_waitcnt vmcnt(8) lgkmcnt(0)
	s_barrier
	v_mfma_f32_16x16x32_bf16 v[88:91], v[0:3], v[56:59], 0
	v_mfma_f32_16x16x32_bf16 v[64:67], v[0:3], v[32:35], 0
	v_mfma_f32_16x16x32_bf16 v[68:71], v[8:11], v[32:35], 0
	v_mfma_f32_16x16x32_bf16 v[72:75], v[0:3], v[40:43], 0
	v_mfma_f32_16x16x32_bf16 v[76:79], v[8:11], v[40:43], 0
	v_mfma_f32_16x16x32_bf16 v[80:83], v[0:3], v[48:51], 0
	v_mfma_f32_16x16x32_bf16 v[84:87], v[8:11], v[48:51], 0
	v_mfma_f32_16x16x32_bf16 v[96:99], v[4:7], v[60:63], v[88:91]
	v_mfma_f32_16x16x32_bf16 v[88:91], v[8:11], v[56:59], 0
	v_mfma_f32_16x16x32_bf16 v[64:67], v[4:7], v[36:39], v[64:67]
	v_mfma_f32_16x16x32_bf16 v[68:71], v[12:15], v[36:39], v[68:71]
	v_mfma_f32_16x16x32_bf16 v[72:75], v[4:7], v[44:47], v[72:75]
	v_mfma_f32_16x16x32_bf16 v[76:79], v[12:15], v[44:47], v[76:79]
	v_mfma_f32_16x16x32_bf16 v[80:83], v[4:7], v[52:55], v[80:83]
	v_mfma_f32_16x16x32_bf16 v[84:87], v[12:15], v[52:55], v[84:87]
	v_mfma_f32_16x16x32_bf16 v[100:103], v[12:15], v[60:63], v[88:91]
	v_mfma_f32_16x16x32_bf16 v[88:91], v[16:19], v[32:35], 0
	v_mfma_f32_16x16x32_bf16 v[32:35], v[24:27], v[32:35], 0
	v_mfma_f32_16x16x32_bf16 v[112:115], v[20:23], v[36:39], v[88:91]
	v_mfma_f32_16x16x32_bf16 v[32:35], v[28:31], v[36:39], v[32:35]
	v_mfma_f32_16x16x32_bf16 v[36:39], v[16:19], v[40:43], 0
	v_mfma_f32_16x16x32_bf16 v[40:43], v[24:27], v[40:43], 0
	v_mfma_f32_16x16x32_bf16 v[36:39], v[20:23], v[44:47], v[36:39]
	v_mfma_f32_16x16x32_bf16 v[40:43], v[28:31], v[44:47], v[40:43]
	v_mfma_f32_16x16x32_bf16 v[44:47], v[16:19], v[48:51], 0
	v_mfma_f32_16x16x32_bf16 v[48:51], v[24:27], v[48:51], 0
	v_mfma_f32_16x16x32_bf16 v[44:47], v[20:23], v[52:55], v[44:47]
	v_mfma_f32_16x16x32_bf16 v[48:51], v[28:31], v[52:55], v[48:51]
	v_mfma_f32_16x16x32_bf16 v[52:55], v[16:19], v[56:59], 0
	v_mfma_f32_16x16x32_bf16 v[56:59], v[24:27], v[56:59], 0
	v_mfma_f32_16x16x32_bf16 v[52:55], v[20:23], v[60:63], v[52:55]
	v_mfma_f32_16x16x32_bf16 v[56:59], v[28:31], v[60:63], v[56:59]
	s_barrier
	s_add_i32 s56, s47, s15
	v_lshl_add_u64 v[242:243], s[76:77], 0, v[128:129]
	s_add_i32 s57, s56, 0x2000
	v_lshl_add_u64 v[148:149], v[242:243], 0, s[62:63]
	s_mov_b32 m0, s56
	v_lshl_add_u64 v[244:245], s[76:77], 0, v[130:131]
	s_add_u32 s80, s76, 0x80100
	ds_read_b128 v[60:63], v147 offset:16384
	ds_read_b128 v[88:91], v147 offset:17408
	ds_read_b128 v[92:95], v147 offset:18432
	ds_read_b128 v[104:107], v147 offset:19456
	ds_read_b128 v[108:111], v147 offset:20480
	ds_read_b128 v[116:119], v147 offset:21504
	ds_read_b128 v[120:123], v147 offset:22528
	ds_read_b128 v[124:127], v147 offset:23552
	global_load_lds_dwordx4 v[148:149], off
	v_lshl_add_u64 v[148:149], v[244:245], 0, s[62:63]
	s_mov_b32 m0, s57
	s_addc_u32 s81, s77, 0
	s_add_i32 s58, s48, s15
	global_load_lds_dwordx4 v[148:149], off
	v_lshl_add_u64 v[148:149], s[80:81], 0, v[128:129]
	s_mov_b32 m0, s58
	s_add_i32 s59, s58, 0x2000
	global_load_lds_dwordx4 v[148:149], off
	v_lshl_add_u64 v[148:149], s[80:81], 0, v[130:131]
	s_mov_b32 m0, s59
	v_lshl_add_u64 v[246:247], s[78:79], 0, v[134:135]
	global_load_lds_dwordx4 v[148:149], off
	v_lshl_add_u64 v[148:149], v[246:247], 0, s[62:63]
	s_mov_b32 m0, s22
	v_lshl_add_u64 v[248:249], s[78:79], 0, v[132:133]
	global_load_lds_dwordx4 v[148:149], off
	v_lshl_add_u64 v[148:149], v[248:249], 0, s[62:63]
	s_mov_b32 m0, s23
	s_nop 0
	global_load_lds_dwordx4 v[148:149], off
	s_waitcnt vmcnt(8) lgkmcnt(0)
	s_barrier
; template <class Epi, class Sched, bool ALIGN_EPI = false, bool SP2 = false, bool A_TILED = false>
; __device__ __forceinline__ void gemm_phase(PG8_LAS unsigned char* lds, const Gemm g, const Sched& S, const Epi& E, const int wave_s) {
;     ...
;         const bool has_next = Epi::AFTER_DRAIN ? false : S.next(ui + 1, nxt);
;         const char* nA = has_next ? (const char*)g.A + (size_t)nxt.pm * tstepA : cA; const char* nB = has_next ? (const char*)g.Bt + (size_t)nxt.pn * tstep : cB;
;         constexpr bool PEEL = SP2 && !Epi::AFTER_DRAIN;
;         if constexpr (PEEL) {
;             const char* a1 = cA + kstepA; const char* a2 = cA + 2 * kstepA; const char* b2 = cB + 2 * kstep; const char* a3 = a2 + kstepA; const char* b3 = b2 + kstep;
;             PG8_ITER(PG8_MMAZ)
	v_mfma_f32_16x16x32_bf16 v[148:151], v[0:3], v[60:63], 0
	v_mfma_f32_16x16x32_bf16 v[158:161], v[0:3], v[92:95], 0
	v_mfma_f32_16x16x32_bf16 v[166:169], v[0:3], v[108:111], 0
	v_mfma_f32_16x16x32_bf16 v[0:3], v[0:3], v[120:123], 0
	v_mfma_f32_16x16x32_bf16 v[150:153], v[4:7], v[88:91], v[148:151]
	v_mfma_f32_16x16x32_bf16 v[158:161], v[4:7], v[104:107], v[158:161]
	v_mfma_f32_16x16x32_bf16 v[166:169], v[4:7], v[116:119], v[166:169]
	v_mfma_f32_16x16x32_bf16 v[0:3], v[4:7], v[124:127], v[0:3]
	v_mfma_f32_16x16x32_bf16 v[4:7], v[8:11], v[120:123], 0
	v_mfma_f32_16x16x32_bf16 v[154:157], v[8:11], v[60:63], 0
	v_mfma_f32_16x16x32_bf16 v[162:165], v[8:11], v[92:95], 0
	v_mfma_f32_16x16x32_bf16 v[170:173], v[8:11], v[108:111], 0
	v_mfma_f32_16x16x32_bf16 v[4:7], v[12:15], v[124:127], v[4:7]
	v_mfma_f32_16x16x32_bf16 v[154:157], v[12:15], v[88:91], v[154:157]
	v_mfma_f32_16x16x32_bf16 v[162:165], v[12:15], v[104:107], v[162:165]
	v_mfma_f32_16x16x32_bf16 v[170:173], v[12:15], v[116:119], v[170:173]
	v_mfma_f32_16x16x32_bf16 v[8:11], v[16:19], v[60:63], 0
	v_mfma_f32_16x16x32_bf16 v[174:177], v[20:23], v[88:91], v[8:11]
	v_mfma_f32_16x16x32_bf16 v[8:11], v[24:27], v[60:63], 0
	v_mfma_f32_16x16x32_bf16 v[60:63], v[28:31], v[88:91], v[8:11]
	v_mfma_f32_16x16x32_bf16 v[8:11], v[16:19], v[92:95], 0
	v_mfma_f32_16x16x32_bf16 v[178:181], v[20:23], v[104:107], v[8:11]
	v_mfma_f32_16x16x32_bf16 v[8:11], v[24:27], v[92:95], 0
	v_mfma_f32_16x16x32_bf16 v[182:185], v[28:31], v[104:107], v[8:11]
	v_mfma_f32_16x16x32_bf16 v[8:11], v[16:19], v[108:111], 0
	v_mfma_f32_16x16x32_bf16 v[186:189], v[20:23], v[116:119], v[8:11]
	v_mfma_f32_16x16x32_bf16 v[8:11], v[24:27], v[108:111], 0
	v_mfma_f32_16x16x32_bf16 v[190:193], v[28:31], v[116:119], v[8:11]
	v_mfma_f32_16x16x32_bf16 v[8:11], v[16:19], v[120:123], 0
	v_mfma_f32_16x16x32_bf16 v[194:197], v[20:23], v[124:127], v[8:11]
	v_mfma_f32_16x16x32_bf16 v[8:11], v[24:27], v[120:123], 0
	v_mfma_f32_16x16x32_bf16 v[198:201], v[28:31], v[124:127], v[8:11]
	s_barrier
	s_add_i32 s67, 0, 0x18000
	s_add_i32 s75, 0, 0x1c000
	v_add_u32_e32 v148, s67, v144
	v_add_u32_e32 v149, s75, v144
	s_nop 0
	ds_read_b128 v[8:11], v148
	ds_read_b128 v[12:15], v148 offset:1024
	ds_read_b128 v[16:19], v148 offset:2048
	ds_read_b128 v[20:23], v148 offset:3072
	ds_read_b128 v[202:205], v149
	ds_read_b128 v[206:209], v149 offset:1024
	ds_read_b128 v[210:213], v149 offset:2048
	ds_read_b128 v[214:217], v149 offset:3072
	s_add_u32 s80, s78, 0x80100
	s_addc_u32 s81, s79, 0
	s_mov_b32 m0, s36
	v_lshl_add_u64 v[88:89], s[80:81], 0, v[134:135]
	ds_read_b128 v[24:27], v147 offset:32768
	ds_read_b128 v[28:31], v147 offset:33792
	ds_read_b128 v[218:221], v147 offset:34816
	ds_read_b128 v[222:225], v147 offset:35840
	ds_read_b128 v[226:229], v147 offset:36864
	ds_read_b128 v[230:233], v147 offset:37888
	ds_read_b128 v[234:237], v147 offset:38912
	ds_read_b128 v[238:241], v147 offset:39936
	global_load_lds_dwordx4 v[88:89], off
	v_lshl_add_u64 v[88:89], s[80:81], 0, v[132:133]
	s_mov_b32 m0, s37
	s_nop 0
	global_load_lds_dwordx4 v[88:89], off
	s_waitcnt vmcnt(8) lgkmcnt(0)
	s_barrier
	v_mfma_f32_16x16x32_bf16 v[64:67], v[8:11], v[24:27], v[64:67]
	v_mfma_f32_16x16x32_bf16 v[120:123], v[12:15], v[28:31], v[64:67]
	v_mfma_f32_16x16x32_bf16 v[64:67], v[16:19], v[24:27], v[68:71]
	v_mfma_f32_16x16x32_bf16 v[124:127], v[20:23], v[28:31], v[64:67]
	v_mfma_f32_16x16x32_bf16 v[64:67], v[8:11], v[218:221], v[72:75]
	v_mfma_f32_16x16x32_bf16 v[104:107], v[12:15], v[222:225], v[64:67]
	v_mfma_f32_16x16x32_bf16 v[64:67], v[16:19], v[218:221], v[76:79]
	v_mfma_f32_16x16x32_bf16 v[108:111], v[20:23], v[222:225], v[64:67]
	v_mfma_f32_16x16x32_bf16 v[64:67], v[8:11], v[226:229], v[80:83]
	v_mfma_f32_16x16x32_bf16 v[88:91], v[12:15], v[230:233], v[64:67]
	v_mfma_f32_16x16x32_bf16 v[64:67], v[16:19], v[226:229], v[84:87]
	v_mfma_f32_16x16x32_bf16 v[92:95], v[20:23], v[230:233], v[64:67]
	v_mfma_f32_16x16x32_bf16 v[64:67], v[8:11], v[234:237], v[96:99]
	v_mfma_f32_16x16x32_bf16 v[68:71], v[16:19], v[234:237], v[100:103]
	v_mfma_f32_16x16x32_bf16 v[64:67], v[12:15], v[238:241], v[64:67]
	v_mfma_f32_16x16x32_bf16 v[68:71], v[20:23], v[238:241], v[68:71]
	v_mfma_f32_16x16x32_bf16 v[72:75], v[202:205], v[24:27], v[112:115]
	v_mfma_f32_16x16x32_bf16 v[24:27], v[210:213], v[24:27], v[32:35]
	v_mfma_f32_16x16x32_bf16 v[116:119], v[214:217], v[28:31], v[24:27]
	v_mfma_f32_16x16x32_bf16 v[24:27], v[202:205], v[218:221], v[36:39]
	v_mfma_f32_16x16x32_bf16 v[96:99], v[206:209], v[222:225], v[24:27]
	v_mfma_f32_16x16x32_bf16 v[24:27], v[210:213], v[218:221], v[40:43]
	v_mfma_f32_16x16x32_bf16 v[100:103], v[214:217], v[222:225], v[24:27]
	v_mfma_f32_16x16x32_bf16 v[24:27], v[202:205], v[226:229], v[44:47]
	v_mfma_f32_16x16x32_bf16 v[80:83], v[206:209], v[230:233], v[24:27]
	v_mfma_f32_16x16x32_bf16 v[24:27], v[210:213], v[226:229], v[48:51]
	v_mfma_f32_16x16x32_bf16 v[84:87], v[214:217], v[230:233], v[24:27]
	v_mfma_f32_16x16x32_bf16 v[24:27], v[202:205], v[234:237], v[52:55]
	v_mfma_f32_16x16x32_bf16 v[48:51], v[206:209], v[238:241], v[24:27]
	v_mfma_f32_16x16x32_bf16 v[24:27], v[210:213], v[234:237], v[56:59]
	v_mfma_f32_16x16x32_bf16 v[112:115], v[206:209], v[28:31], v[72:75]
	v_mfma_f32_16x16x32_bf16 v[52:55], v[214:217], v[238:241], v[24:27]
	s_barrier
	s_add_i32 s67, s67, s15
	s_add_i32 s69, s67, 0x2000
	s_nop 1
	v_lshl_add_u64 v[24:25], v[242:243], 0, s[64:65]
	s_mov_b32 m0, s67
	s_add_u32 s80, s76, 0x80180
	ds_read_b128 v[32:35], v147 offset:49152
	ds_read_b128 v[36:39], v147 offset:50176
	ds_read_b128 v[218:221], v147 offset:51200
	ds_read_b128 v[222:225], v147 offset:52224
	ds_read_b128 v[226:229], v147 offset:53248
	ds_read_b128 v[230:233], v147 offset:54272
	ds_read_b128 v[234:237], v147 offset:55296
	ds_read_b128 v[238:241], v147 offset:56320
	global_load_lds_dwordx4 v[24:25], off
	v_lshl_add_u64 v[24:25], v[244:245], 0, s[64:65]
	s_mov_b32 m0, s69
	s_addc_u32 s81, s77, 0
	s_add_i32 s75, s75, s15
	global_load_lds_dwordx4 v[24:25], off
	v_lshl_add_u64 v[24:25], s[80:81], 0, v[128:129]
	s_mov_b32 m0, s75
	s_add_i32 s82, s75, 0x2000
	global_load_lds_dwordx4 v[24:25], off
	v_lshl_add_u64 v[24:25], s[80:81], 0, v[130:131]
	s_mov_b32 m0, s82
	s_nop 0
	global_load_lds_dwordx4 v[24:25], off
	v_lshl_add_u64 v[24:25], v[246:247], 0, s[64:65]
	s_mov_b32 m0, s43
	s_nop 0
	global_load_lds_dwordx4 v[24:25], off
	v_lshl_add_u64 v[24:25], v[248:249], 0, s[64:65]
	s_mov_b32 m0, s44
	s_nop 0
	global_load_lds_dwordx4 v[24:25], off
	s_waitcnt vmcnt(8) lgkmcnt(0)
	s_barrier
	v_mfma_f32_16x16x32_bf16 v[24:27], v[8:11], v[32:35], v[150:153]
	v_mfma_f32_16x16x32_bf16 v[72:75], v[12:15], v[36:39], v[24:27]
	v_mfma_f32_16x16x32_bf16 v[24:27], v[16:19], v[32:35], v[154:157]
	v_mfma_f32_16x16x32_bf16 v[76:79], v[20:23], v[36:39], v[24:27]
	v_mfma_f32_16x16x32_bf16 v[24:27], v[8:11], v[218:221], v[158:161]
	v_mfma_f32_16x16x32_bf16 v[40:43], v[12:15], v[222:225], v[24:27]
	v_mfma_f32_16x16x32_bf16 v[24:27], v[16:19], v[218:221], v[162:165]
	v_mfma_f32_16x16x32_bf16 v[0:3], v[8:11], v[234:237], v[0:3]
	v_mfma_f32_16x16x32_bf16 v[44:47], v[20:23], v[222:225], v[24:27]
	v_mfma_f32_16x16x32_bf16 v[24:27], v[8:11], v[226:229], v[166:169]
	v_mfma_f32_16x16x32_bf16 v[28:31], v[16:19], v[226:229], v[170:173]
	v_mfma_f32_16x16x32_bf16 v[8:11], v[12:15], v[238:241], v[0:3]
	v_mfma_f32_16x16x32_bf16 v[0:3], v[16:19], v[234:237], v[4:7]
	v_mfma_f32_16x16x32_bf16 v[24:27], v[12:15], v[230:233], v[24:27]
	v_mfma_f32_16x16x32_bf16 v[28:31], v[20:23], v[230:233], v[28:31]
	v_mfma_f32_16x16x32_bf16 v[12:15], v[20:23], v[238:241], v[0:3]
	v_mfma_f32_16x16x32_bf16 v[0:3], v[202:205], v[32:35], v[174:177]
	v_mfma_f32_16x16x32_bf16 v[56:59], v[206:209], v[36:39], v[0:3]
	v_mfma_f32_16x16x32_bf16 v[0:3], v[210:213], v[32:35], v[60:63]
	v_mfma_f32_16x16x32_bf16 v[60:63], v[214:217], v[36:39], v[0:3]
	v_mfma_f32_16x16x32_bf16 v[0:3], v[202:205], v[218:221], v[178:181]
	v_mfma_f32_16x16x32_bf16 v[32:35], v[206:209], v[222:225], v[0:3]
	v_mfma_f32_16x16x32_bf16 v[0:3], v[210:213], v[218:221], v[182:185]
	v_mfma_f32_16x16x32_bf16 v[36:39], v[214:217], v[222:225], v[0:3]
	v_mfma_f32_16x16x32_bf16 v[0:3], v[202:205], v[226:229], v[186:189]
	v_mfma_f32_16x16x32_bf16 v[16:19], v[206:209], v[230:233], v[0:3]
	v_mfma_f32_16x16x32_bf16 v[0:3], v[210:213], v[226:229], v[190:193]
	v_mfma_f32_16x16x32_bf16 v[20:23], v[214:217], v[230:233], v[0:3]
	v_mfma_f32_16x16x32_bf16 v[0:3], v[202:205], v[234:237], v[194:197]
	v_mfma_f32_16x16x32_bf16 v[4:7], v[210:213], v[234:237], v[198:201]
	v_mfma_f32_16x16x32_bf16 v[0:3], v[206:209], v[238:241], v[0:3]
	v_mfma_f32_16x16x32_bf16 v[4:7], v[214:217], v[238:241], v[4:7]
	s_barrier
	s_add_u32 s83, s76, 0x200
	s_addc_u32 s84, s77, 0
	s_add_u32 s76, s78, 0x80180
	s_addc_u32 s77, s79, 0
	s_mov_b32 s85, 0
.LBB0_1155:
	ds_read_b128 v[150:153], v145
	ds_read_b128 v[154:157], v145 offset:1024
	ds_read_b128 v[158:161], v145 offset:2048
	ds_read_b128 v[162:165], v145 offset:3072
	ds_read_b128 v[166:169], v146
	ds_read_b128 v[170:173], v146 offset:1024
	ds_read_b128 v[174:177], v146 offset:2048
	ds_read_b128 v[178:181], v146 offset:3072
	s_add_u32 s78, s76, 0xfff80080
	s_addc_u32 s79, s77, -1
	s_cmp_eq_u32 s85, 28
	s_cselect_b32 s81, s50, s79
	s_cselect_b32 s80, s51, s78
	s_cselect_b32 s79, s52, s84
	s_cselect_b32 s78, s53, s83
	s_mov_b32 m0, s54
	v_lshl_add_u64 v[214:215], s[76:77], 0, v[138:139]
	ds_read_b128 v[182:185], v147
	ds_read_b128 v[186:189], v147 offset:1024
	ds_read_b128 v[190:193], v147 offset:2048
	ds_read_b128 v[194:197], v147 offset:3072
	ds_read_b128 v[198:201], v147 offset:4096
	ds_read_b128 v[202:205], v147 offset:5120
	ds_read_b128 v[206:209], v147 offset:6144
	ds_read_b128 v[210:213], v147 offset:7168
	global_load_lds_dwordx4 v[214:215], off
	v_lshl_add_u64 v[214:215], s[76:77], 0, v[136:137]
	s_mov_b32 m0, s55
	s_nop 0
	global_load_lds_dwordx4 v[214:215], off
	s_waitcnt vmcnt(8) lgkmcnt(0)
	s_barrier
	v_mfma_f32_16x16x32_bf16 v[120:123], v[150:153], v[182:185], v[120:123]
	v_mfma_f32_16x16x32_bf16 v[124:127], v[158:161], v[182:185], v[124:127]
	v_mfma_f32_16x16x32_bf16 v[104:107], v[150:153], v[190:193], v[104:107]
	v_mfma_f32_16x16x32_bf16 v[108:111], v[158:161], v[190:193], v[108:111]
	v_mfma_f32_16x16x32_bf16 v[88:91], v[150:153], v[198:201], v[88:91]
	v_mfma_f32_16x16x32_bf16 v[92:95], v[158:161], v[198:201], v[92:95]
	v_mfma_f32_16x16x32_bf16 v[64:67], v[150:153], v[206:209], v[64:67]
	v_mfma_f32_16x16x32_bf16 v[68:71], v[158:161], v[206:209], v[68:71]
	v_mfma_f32_16x16x32_bf16 v[120:123], v[154:157], v[186:189], v[120:123]
	v_mfma_f32_16x16x32_bf16 v[124:127], v[162:165], v[186:189], v[124:127]
	v_mfma_f32_16x16x32_bf16 v[104:107], v[154:157], v[194:197], v[104:107]
	v_mfma_f32_16x16x32_bf16 v[108:111], v[162:165], v[194:197], v[108:111]
	v_mfma_f32_16x16x32_bf16 v[88:91], v[154:157], v[202:205], v[88:91]
	v_mfma_f32_16x16x32_bf16 v[92:95], v[162:165], v[202:205], v[92:95]
	v_mfma_f32_16x16x32_bf16 v[64:67], v[154:157], v[210:213], v[64:67]
	v_mfma_f32_16x16x32_bf16 v[68:71], v[162:165], v[210:213], v[68:71]
	v_mfma_f32_16x16x32_bf16 v[112:115], v[166:169], v[182:185], v[112:115]
	v_mfma_f32_16x16x32_bf16 v[116:119], v[174:177], v[182:185], v[116:119]
	v_mfma_f32_16x16x32_bf16 v[96:99], v[166:169], v[190:193], v[96:99]
	v_mfma_f32_16x16x32_bf16 v[100:103], v[174:177], v[190:193], v[100:103]
	v_mfma_f32_16x16x32_bf16 v[80:83], v[166:169], v[198:201], v[80:83]
	v_mfma_f32_16x16x32_bf16 v[84:87], v[174:177], v[198:201], v[84:87]
	v_mfma_f32_16x16x32_bf16 v[48:51], v[166:169], v[206:209], v[48:51]
	v_mfma_f32_16x16x32_bf16 v[52:55], v[174:177], v[206:209], v[52:55]
	v_mfma_f32_16x16x32_bf16 v[112:115], v[170:173], v[186:189], v[112:115]
	v_mfma_f32_16x16x32_bf16 v[116:119], v[178:181], v[186:189], v[116:119]
	v_mfma_f32_16x16x32_bf16 v[96:99], v[170:173], v[194:197], v[96:99]
	v_mfma_f32_16x16x32_bf16 v[100:103], v[178:181], v[194:197], v[100:103]
	v_mfma_f32_16x16x32_bf16 v[80:83], v[170:173], v[202:205], v[80:83]
	v_mfma_f32_16x16x32_bf16 v[84:87], v[178:181], v[202:205], v[84:87]
	v_mfma_f32_16x16x32_bf16 v[48:51], v[170:173], v[210:213], v[48:51]
	v_mfma_f32_16x16x32_bf16 v[52:55], v[178:181], v[210:213], v[52:55]
	s_barrier
	s_mov_b32 m0, s56
	v_lshl_add_u64 v[214:215], s[78:79], 0, v[128:129]
	s_add_u32 s88, s78, 0x80000
	ds_read_b128 v[182:185], v147 offset:16384
	ds_read_b128 v[186:189], v147 offset:17408
	ds_read_b128 v[190:193], v147 offset:18432
	ds_read_b128 v[194:197], v147 offset:19456
	ds_read_b128 v[198:201], v147 offset:20480
	ds_read_b128 v[202:205], v147 offset:21504
	ds_read_b128 v[206:209], v147 offset:22528
	ds_read_b128 v[210:213], v147 offset:23552
	global_load_lds_dwordx4 v[214:215], off
	v_lshl_add_u64 v[216:217], s[78:79], 0, v[130:131]
	s_mov_b32 m0, s57
	s_addc_u32 s89, s79, 0
	global_load_lds_dwordx4 v[216:217], off
	v_lshl_add_u64 v[218:219], s[88:89], 0, v[128:129]
	s_mov_b32 m0, s58
	v_lshl_add_u64 v[220:221], s[80:81], 0, v[132:133]
	global_load_lds_dwordx4 v[218:219], off
	v_lshl_add_u64 v[218:219], s[88:89], 0, v[130:131]
	s_mov_b32 m0, s59
	s_nop 0
	global_load_lds_dwordx4 v[218:219], off
	v_lshl_add_u64 v[218:219], s[80:81], 0, v[134:135]
	s_mov_b32 m0, s22
	s_nop 0
	global_load_lds_dwordx4 v[218:219], off
	s_mov_b32 m0, s23
	s_nop 0
	global_load_lds_dwordx4 v[220:221], off
	s_waitcnt vmcnt(8) lgkmcnt(0)
	s_barrier
	v_mfma_f32_16x16x32_bf16 v[72:75], v[150:153], v[182:185], v[72:75]
	v_mfma_f32_16x16x32_bf16 v[76:79], v[158:161], v[182:185], v[76:79]
	v_mfma_f32_16x16x32_bf16 v[40:43], v[150:153], v[190:193], v[40:43]
	v_mfma_f32_16x16x32_bf16 v[44:47], v[158:161], v[190:193], v[44:47]
	v_mfma_f32_16x16x32_bf16 v[24:27], v[150:153], v[198:201], v[24:27]
	v_mfma_f32_16x16x32_bf16 v[28:31], v[158:161], v[198:201], v[28:31]
	v_mfma_f32_16x16x32_bf16 v[8:11], v[150:153], v[206:209], v[8:11]
	v_mfma_f32_16x16x32_bf16 v[12:15], v[158:161], v[206:209], v[12:15]
	v_mfma_f32_16x16x32_bf16 v[72:75], v[154:157], v[186:189], v[72:75]
	v_mfma_f32_16x16x32_bf16 v[76:79], v[162:165], v[186:189], v[76:79]
	v_mfma_f32_16x16x32_bf16 v[40:43], v[154:157], v[194:197], v[40:43]
	v_mfma_f32_16x16x32_bf16 v[44:47], v[162:165], v[194:197], v[44:47]
	v_mfma_f32_16x16x32_bf16 v[24:27], v[154:157], v[202:205], v[24:27]
	v_mfma_f32_16x16x32_bf16 v[28:31], v[162:165], v[202:205], v[28:31]
	v_mfma_f32_16x16x32_bf16 v[8:11], v[154:157], v[210:213], v[8:11]
	v_mfma_f32_16x16x32_bf16 v[12:15], v[162:165], v[210:213], v[12:15]
	v_mfma_f32_16x16x32_bf16 v[56:59], v[166:169], v[182:185], v[56:59]
	v_mfma_f32_16x16x32_bf16 v[60:63], v[174:177], v[182:185], v[60:63]
	v_mfma_f32_16x16x32_bf16 v[32:35], v[166:169], v[190:193], v[32:35]
	v_mfma_f32_16x16x32_bf16 v[36:39], v[174:177], v[190:193], v[36:39]
	v_mfma_f32_16x16x32_bf16 v[16:19], v[166:169], v[198:201], v[16:19]
	v_mfma_f32_16x16x32_bf16 v[20:23], v[174:177], v[198:201], v[20:23]
	v_mfma_f32_16x16x32_bf16 v[0:3], v[166:169], v[206:209], v[0:3]
	v_mfma_f32_16x16x32_bf16 v[4:7], v[174:177], v[206:209], v[4:7]
	v_mfma_f32_16x16x32_bf16 v[56:59], v[170:173], v[186:189], v[56:59]
	v_mfma_f32_16x16x32_bf16 v[60:63], v[178:181], v[186:189], v[60:63]
	v_mfma_f32_16x16x32_bf16 v[32:35], v[170:173], v[194:197], v[32:35]
	v_mfma_f32_16x16x32_bf16 v[36:39], v[178:181], v[194:197], v[36:39]
	v_mfma_f32_16x16x32_bf16 v[16:19], v[170:173], v[202:205], v[16:19]
	v_mfma_f32_16x16x32_bf16 v[20:23], v[178:181], v[202:205], v[20:23]
	v_mfma_f32_16x16x32_bf16 v[0:3], v[170:173], v[210:213], v[0:3]
	v_mfma_f32_16x16x32_bf16 v[4:7], v[178:181], v[210:213], v[4:7]
	s_barrier
; #define PG8_BAR __builtin_amdgcn_s_barrier()
; template <class Epi, class Sched, bool ALIGN_EPI = false, bool SP2 = false, bool A_TILED = false>
; __device__ __forceinline__ void gemm_phase(PG8_LAS unsigned char* lds, const Gemm g, const Sched& S, const Epi& E, const int wave_s) {
;     ...
;         if constexpr (ALIGN_EPI) { if (wr == 0) PG8_BAR; }
	ds_read_b128 v[150:153], v148
	ds_read_b128 v[154:157], v148 offset:1024
	ds_read_b128 v[158:161], v148 offset:2048
	ds_read_b128 v[162:165], v148 offset:3072
	ds_read_b128 v[166:169], v149
	ds_read_b128 v[170:173], v149 offset:1024
	ds_read_b128 v[174:177], v149 offset:2048
	ds_read_b128 v[178:181], v149 offset:3072
	s_add_u32 s80, s80, 0x80000
	s_addc_u32 s81, s81, 0
	s_mov_b32 m0, s36
	v_lshl_add_u64 v[222:223], s[80:81], 0, v[134:135]
	ds_read_b128 v[182:185], v147 offset:32768
	ds_read_b128 v[186:189], v147 offset:33792
	ds_read_b128 v[190:193], v147 offset:34816
	ds_read_b128 v[194:197], v147 offset:35840
	ds_read_b128 v[198:201], v147 offset:36864
	ds_read_b128 v[202:205], v147 offset:37888
	ds_read_b128 v[206:209], v147 offset:38912
	ds_read_b128 v[210:213], v147 offset:39936
	global_load_lds_dwordx4 v[222:223], off
	v_lshl_add_u64 v[222:223], s[80:81], 0, v[132:133]
	s_mov_b32 m0, s37
	s_nop 0
	global_load_lds_dwordx4 v[222:223], off
	s_waitcnt vmcnt(8) lgkmcnt(0)
	s_barrier
	v_mfma_f32_16x16x32_bf16 v[120:123], v[150:153], v[182:185], v[120:123]
	v_mfma_f32_16x16x32_bf16 v[124:127], v[158:161], v[182:185], v[124:127]
	v_mfma_f32_16x16x32_bf16 v[104:107], v[150:153], v[190:193], v[104:107]
	v_mfma_f32_16x16x32_bf16 v[108:111], v[158:161], v[190:193], v[108:111]
	v_mfma_f32_16x16x32_bf16 v[88:91], v[150:153], v[198:201], v[88:91]
	v_mfma_f32_16x16x32_bf16 v[92:95], v[158:161], v[198:201], v[92:95]
	v_mfma_f32_16x16x32_bf16 v[64:67], v[150:153], v[206:209], v[64:67]
	v_mfma_f32_16x16x32_bf16 v[68:71], v[158:161], v[206:209], v[68:71]
	v_mfma_f32_16x16x32_bf16 v[120:123], v[154:157], v[186:189], v[120:123]
	v_mfma_f32_16x16x32_bf16 v[124:127], v[162:165], v[186:189], v[124:127]
	v_mfma_f32_16x16x32_bf16 v[104:107], v[154:157], v[194:197], v[104:107]
	v_mfma_f32_16x16x32_bf16 v[108:111], v[162:165], v[194:197], v[108:111]
	v_mfma_f32_16x16x32_bf16 v[88:91], v[154:157], v[202:205], v[88:91]
	v_mfma_f32_16x16x32_bf16 v[92:95], v[162:165], v[202:205], v[92:95]
	v_mfma_f32_16x16x32_bf16 v[64:67], v[154:157], v[210:213], v[64:67]
	v_mfma_f32_16x16x32_bf16 v[68:71], v[162:165], v[210:213], v[68:71]
	v_mfma_f32_16x16x32_bf16 v[112:115], v[166:169], v[182:185], v[112:115]
	v_mfma_f32_16x16x32_bf16 v[116:119], v[174:177], v[182:185], v[116:119]
	v_mfma_f32_16x16x32_bf16 v[96:99], v[166:169], v[190:193], v[96:99]
	v_mfma_f32_16x16x32_bf16 v[100:103], v[174:177], v[190:193], v[100:103]
	v_mfma_f32_16x16x32_bf16 v[80:83], v[166:169], v[198:201], v[80:83]
	v_mfma_f32_16x16x32_bf16 v[84:87], v[174:177], v[198:201], v[84:87]
	v_mfma_f32_16x16x32_bf16 v[48:51], v[166:169], v[206:209], v[48:51]
	v_mfma_f32_16x16x32_bf16 v[52:55], v[174:177], v[206:209], v[52:55]
	v_mfma_f32_16x16x32_bf16 v[112:115], v[170:173], v[186:189], v[112:115]
	v_mfma_f32_16x16x32_bf16 v[116:119], v[178:181], v[186:189], v[116:119]
	v_mfma_f32_16x16x32_bf16 v[96:99], v[170:173], v[194:197], v[96:99]
	v_mfma_f32_16x16x32_bf16 v[100:103], v[178:181], v[194:197], v[100:103]
	v_mfma_f32_16x16x32_bf16 v[80:83], v[170:173], v[202:205], v[80:83]
	v_mfma_f32_16x16x32_bf16 v[84:87], v[178:181], v[202:205], v[84:87]
	v_mfma_f32_16x16x32_bf16 v[48:51], v[170:173], v[210:213], v[48:51]
	v_mfma_f32_16x16x32_bf16 v[52:55], v[178:181], v[210:213], v[52:55]
	s_barrier
	s_mov_b32 m0, s67
	v_lshl_add_u64 v[214:215], v[214:215], 0, s[12:13]
	s_add_u32 s78, s78, 0x80080
	ds_read_b128 v[182:185], v147 offset:49152
	ds_read_b128 v[186:189], v147 offset:50176
	ds_read_b128 v[190:193], v147 offset:51200
	ds_read_b128 v[194:197], v147 offset:52224
	ds_read_b128 v[198:201], v147 offset:53248
	ds_read_b128 v[202:205], v147 offset:54272
	ds_read_b128 v[206:209], v147 offset:55296
	ds_read_b128 v[210:213], v147 offset:56320
	global_load_lds_dwordx4 v[214:215], off
	v_lshl_add_u64 v[214:215], v[216:217], 0, s[12:13]
	s_mov_b32 m0, s69
	s_addc_u32 s79, s79, 0
	global_load_lds_dwordx4 v[214:215], off
	v_lshl_add_u64 v[214:215], s[78:79], 0, v[128:129]
	s_mov_b32 m0, s75
	s_nop 0
	global_load_lds_dwordx4 v[214:215], off
	v_lshl_add_u64 v[214:215], s[78:79], 0, v[130:131]
	s_mov_b32 m0, s82
	s_nop 0
	global_load_lds_dwordx4 v[214:215], off
	v_lshl_add_u64 v[214:215], v[218:219], 0, s[12:13]
	s_mov_b32 m0, s43
	s_nop 0
	global_load_lds_dwordx4 v[214:215], off
	v_lshl_add_u64 v[214:215], v[220:221], 0, s[12:13]
	s_mov_b32 m0, s44
	s_nop 0
	global_load_lds_dwordx4 v[214:215], off
	s_waitcnt vmcnt(8) lgkmcnt(0)
	s_barrier
	v_mfma_f32_16x16x32_bf16 v[72:75], v[150:153], v[182:185], v[72:75]
	v_mfma_f32_16x16x32_bf16 v[76:79], v[158:161], v[182:185], v[76:79]
	v_mfma_f32_16x16x32_bf16 v[40:43], v[150:153], v[190:193], v[40:43]
	v_mfma_f32_16x16x32_bf16 v[44:47], v[158:161], v[190:193], v[44:47]
	v_mfma_f32_16x16x32_bf16 v[24:27], v[150:153], v[198:201], v[24:27]
	v_mfma_f32_16x16x32_bf16 v[28:31], v[158:161], v[198:201], v[28:31]
	v_mfma_f32_16x16x32_bf16 v[8:11], v[150:153], v[206:209], v[8:11]
	v_mfma_f32_16x16x32_bf16 v[12:15], v[158:161], v[206:209], v[12:15]
	v_mfma_f32_16x16x32_bf16 v[72:75], v[154:157], v[186:189], v[72:75]
	v_mfma_f32_16x16x32_bf16 v[76:79], v[162:165], v[186:189], v[76:79]
	v_mfma_f32_16x16x32_bf16 v[40:43], v[154:157], v[194:197], v[40:43]
	v_mfma_f32_16x16x32_bf16 v[44:47], v[162:165], v[194:197], v[44:47]
	v_mfma_f32_16x16x32_bf16 v[24:27], v[154:157], v[202:205], v[24:27]
	v_mfma_f32_16x16x32_bf16 v[28:31], v[162:165], v[202:205], v[28:31]
	v_mfma_f32_16x16x32_bf16 v[8:11], v[154:157], v[210:213], v[8:11]
	v_mfma_f32_16x16x32_bf16 v[12:15], v[162:165], v[210:213], v[12:15]
	v_mfma_f32_16x16x32_bf16 v[56:59], v[166:169], v[182:185], v[56:59]
	v_mfma_f32_16x16x32_bf16 v[60:63], v[174:177], v[182:185], v[60:63]
	v_mfma_f32_16x16x32_bf16 v[32:35], v[166:169], v[190:193], v[32:35]
	v_mfma_f32_16x16x32_bf16 v[36:39], v[174:177], v[190:193], v[36:39]
	v_mfma_f32_16x16x32_bf16 v[16:19], v[166:169], v[198:201], v[16:19]
	v_mfma_f32_16x16x32_bf16 v[20:23], v[174:177], v[198:201], v[20:23]
	v_mfma_f32_16x16x32_bf16 v[0:3], v[166:169], v[206:209], v[0:3]
	v_mfma_f32_16x16x32_bf16 v[4:7], v[174:177], v[206:209], v[4:7]
	v_mfma_f32_16x16x32_bf16 v[56:59], v[170:173], v[186:189], v[56:59]
	v_mfma_f32_16x16x32_bf16 v[60:63], v[178:181], v[186:189], v[60:63]
	v_mfma_f32_16x16x32_bf16 v[32:35], v[170:173], v[194:197], v[32:35]
	v_mfma_f32_16x16x32_bf16 v[36:39], v[178:181], v[194:197], v[36:39]
	v_mfma_f32_16x16x32_bf16 v[16:19], v[170:173], v[202:205], v[16:19]
	v_mfma_f32_16x16x32_bf16 v[20:23], v[178:181], v[202:205], v[20:23]
	v_mfma_f32_16x16x32_bf16 v[0:3], v[170:173], v[210:213], v[0:3]
	v_mfma_f32_16x16x32_bf16 v[4:7], v[178:181], v[210:213], v[4:7]
	s_barrier
	s_add_i32 s85, s85, 2
	s_add_u32 s83, s83, 0x100
	s_addc_u32 s84, s84, 0
	s_add_u32 s76, s76, 0x100
	s_addc_u32 s77, s77, 0
	s_cmp_gt_u32 s85, 29
	s_cbranch_scc0 .LBB0_1155
	s_and_b64 vcc, exec, s[60:61]
	s_cbranch_vccz .LBB0_1158
	s_barrier

; template <class Epi, class Sched, bool ALIGN_EPI = false, bool SP2 = false, bool A_TILED = false>
; __device__ __forceinline__ void gemm_phase(PG8_LAS unsigned char* lds, const Gemm g, const Sched& S, const Epi& E, const int wave_s) {
;     ...
;             const bool last = (t == nt - 2);
;             const char* a1 = cA + (size_t)(t + 1) * kstepA;
;             const char* a2 = last ? nA : cA + (size_t)(t + 2) * kstepA; const char* b2 = last ? nB : cB + (size_t)(t + 2) * kstep;
;             const char* a3 = a2 + kstepA; const char* b3 = b2 + kstep;
.LBB0_1228:
	ds_read_b128 v[146:149], v140
	ds_read_b128 v[150:153], v140 offset:1024
	ds_read_b128 v[154:157], v140 offset:2048
	ds_read_b128 v[158:161], v140 offset:3072
	ds_read_b128 v[162:165], v141
	ds_read_b128 v[166:169], v141 offset:1024
	ds_read_b128 v[170:173], v141 offset:2048
	ds_read_b128 v[174:177], v141 offset:3072
	s_add_u32 s52, s12, s39
	s_addc_u32 s53, s13, s40
	s_add_u32 s54, s12, s37
	s_addc_u32 s55, s13, s38
	s_cmpk_eq_i32 s41, 0x7c
	s_cselect_b32 s72, s4, s52
	s_cselect_b32 s73, s5, s53
	s_cselect_b32 s70, s0, s54
	s_cselect_b32 s71, s1, s55
	s_add_u32 s68, s72, 0x8000
	s_addc_u32 s69, s73, 0
	s_mov_b32 m0, s42
	v_lshl_add_u64 v[210:211], s[12:13], 0, v[138:139]
	ds_read_b128 v[178:181], v142
	ds_read_b128 v[182:185], v142 offset:1024
	ds_read_b128 v[186:189], v142 offset:2048
	ds_read_b128 v[190:193], v142 offset:3072
	ds_read_b128 v[194:197], v142 offset:4096
	ds_read_b128 v[198:201], v142 offset:5120
	ds_read_b128 v[202:205], v142 offset:6144
	ds_read_b128 v[206:209], v142 offset:7168
	global_load_lds_dwordx4 v[210:211], off
	v_lshl_add_u64 v[210:211], s[12:13], 0, v[136:137]
	s_mov_b32 m0, s43
	s_nop 0
	global_load_lds_dwordx4 v[210:211], off
	s_waitcnt vmcnt(8) lgkmcnt(0)
	s_barrier
	v_mfma_f32_16x16x32_bf16 v[8:11], v[146:149], v[178:181], v[8:11]
	v_mfma_f32_16x16x32_bf16 v[12:15], v[154:157], v[178:181], v[12:15]
	v_mfma_f32_16x16x32_bf16 v[60:63], v[146:149], v[186:189], v[60:63]
	v_mfma_f32_16x16x32_bf16 v[20:23], v[154:157], v[186:189], v[20:23]
	v_mfma_f32_16x16x32_bf16 v[76:79], v[146:149], v[194:197], v[76:79]
	v_mfma_f32_16x16x32_bf16 v[52:55], v[154:157], v[194:197], v[52:55]
	v_mfma_f32_16x16x32_bf16 v[128:131], v[146:149], v[202:205], v[128:131]
	v_mfma_f32_16x16x32_bf16 v[68:71], v[154:157], v[202:205], v[68:71]
	v_mfma_f32_16x16x32_bf16 v[8:11], v[150:153], v[182:185], v[8:11]
	v_mfma_f32_16x16x32_bf16 v[12:15], v[158:161], v[182:185], v[12:15]
	v_mfma_f32_16x16x32_bf16 v[60:63], v[150:153], v[190:193], v[60:63]
	v_mfma_f32_16x16x32_bf16 v[20:23], v[158:161], v[190:193], v[20:23]
	v_mfma_f32_16x16x32_bf16 v[76:79], v[150:153], v[198:201], v[76:79]
	v_mfma_f32_16x16x32_bf16 v[52:55], v[158:161], v[198:201], v[52:55]
	v_mfma_f32_16x16x32_bf16 v[128:131], v[150:153], v[206:209], v[128:131]
	v_mfma_f32_16x16x32_bf16 v[68:71], v[158:161], v[206:209], v[68:71]
	v_mfma_f32_16x16x32_bf16 v[28:31], v[162:165], v[178:181], v[28:31]
	v_mfma_f32_16x16x32_bf16 v[16:19], v[170:173], v[178:181], v[16:19]
	v_mfma_f32_16x16x32_bf16 v[56:59], v[162:165], v[186:189], v[56:59]
	v_mfma_f32_16x16x32_bf16 v[48:51], v[170:173], v[186:189], v[48:51]
	v_mfma_f32_16x16x32_bf16 v[72:75], v[162:165], v[194:197], v[72:75]
	v_mfma_f32_16x16x32_bf16 v[64:67], v[170:173], v[194:197], v[64:67]
	v_mfma_f32_16x16x32_bf16 v[108:111], v[162:165], v[202:205], v[108:111]
	v_mfma_f32_16x16x32_bf16 v[96:99], v[170:173], v[202:205], v[96:99]
	v_mfma_f32_16x16x32_bf16 v[28:31], v[166:169], v[182:185], v[28:31]
	v_mfma_f32_16x16x32_bf16 v[16:19], v[174:177], v[182:185], v[16:19]
	v_mfma_f32_16x16x32_bf16 v[56:59], v[166:169], v[190:193], v[56:59]
	v_mfma_f32_16x16x32_bf16 v[48:51], v[174:177], v[190:193], v[48:51]
	v_mfma_f32_16x16x32_bf16 v[72:75], v[166:169], v[198:201], v[72:75]
	v_mfma_f32_16x16x32_bf16 v[64:67], v[174:177], v[198:201], v[64:67]
	v_mfma_f32_16x16x32_bf16 v[108:111], v[166:169], v[206:209], v[108:111]
	v_mfma_f32_16x16x32_bf16 v[96:99], v[174:177], v[206:209], v[96:99]
	s_barrier
	s_mov_b32 m0, s44
	v_lshl_add_u64 v[210:211], s[70:71], 0, v[34:35]
	s_add_u32 s52, s70, 0x200000
	ds_read_b128 v[178:181], v142 offset:16384
	ds_read_b128 v[182:185], v142 offset:17408
	ds_read_b128 v[186:189], v142 offset:18432
	ds_read_b128 v[190:193], v142 offset:19456
	ds_read_b128 v[194:197], v142 offset:20480
	ds_read_b128 v[198:201], v142 offset:21504
	ds_read_b128 v[202:205], v142 offset:22528
	ds_read_b128 v[206:209], v142 offset:23552
	global_load_lds_dwordx4 v[210:211], off
	v_lshl_add_u64 v[212:213], s[70:71], 0, v[134:135]
	s_mov_b32 m0, s45
	s_addc_u32 s53, s71, 0
	global_load_lds_dwordx4 v[212:213], off
	v_lshl_add_u64 v[214:215], s[52:53], 0, v[34:35]
	s_mov_b32 m0, s46
	s_nop 0
	global_load_lds_dwordx4 v[214:215], off
	v_lshl_add_u64 v[214:215], s[52:53], 0, v[134:135]
	s_mov_b32 m0, s47
	s_nop 0
	global_load_lds_dwordx4 v[214:215], off
	v_lshl_add_u64 v[214:215], s[72:73], 0, v[32:33]
	s_mov_b32 m0, s14
	s_nop 0
	global_load_lds_dwordx4 v[214:215], off
	v_lshl_add_u64 v[214:215], s[72:73], 0, v[132:133]
	s_mov_b32 m0, s15
	s_nop 0
	global_load_lds_dwordx4 v[214:215], off
	s_waitcnt vmcnt(8) lgkmcnt(0)
	s_barrier
	v_mfma_f32_16x16x32_bf16 v[100:103], v[146:149], v[178:181], v[100:103]
	v_mfma_f32_16x16x32_bf16 v[104:107], v[154:157], v[178:181], v[104:107]
	v_mfma_f32_16x16x32_bf16 v[116:119], v[146:149], v[186:189], v[116:119]
	v_mfma_f32_16x16x32_bf16 v[120:123], v[154:157], v[186:189], v[120:123]
	v_mfma_f32_16x16x32_bf16 v[84:87], v[146:149], v[194:197], v[84:87]
	v_mfma_f32_16x16x32_bf16 v[80:83], v[154:157], v[194:197], v[80:83]
	v_mfma_f32_16x16x32_bf16 v[36:39], v[146:149], v[202:205], v[36:39]
	v_mfma_f32_16x16x32_bf16 v[24:27], v[154:157], v[202:205], v[24:27]
	v_mfma_f32_16x16x32_bf16 v[100:103], v[150:153], v[182:185], v[100:103]
	v_mfma_f32_16x16x32_bf16 v[104:107], v[158:161], v[182:185], v[104:107]
	v_mfma_f32_16x16x32_bf16 v[116:119], v[150:153], v[190:193], v[116:119]
	v_mfma_f32_16x16x32_bf16 v[120:123], v[158:161], v[190:193], v[120:123]
	v_mfma_f32_16x16x32_bf16 v[84:87], v[150:153], v[198:201], v[84:87]
	v_mfma_f32_16x16x32_bf16 v[80:83], v[158:161], v[198:201], v[80:83]
	v_mfma_f32_16x16x32_bf16 v[36:39], v[150:153], v[206:209], v[36:39]
	v_mfma_f32_16x16x32_bf16 v[24:27], v[158:161], v[206:209], v[24:27]
	v_mfma_f32_16x16x32_bf16 v[124:127], v[162:165], v[178:181], v[124:127]
	v_mfma_f32_16x16x32_bf16 v[112:115], v[170:173], v[178:181], v[112:115]
	v_mfma_f32_16x16x32_bf16 v[92:95], v[162:165], v[186:189], v[92:95]
	v_mfma_f32_16x16x32_bf16 v[88:91], v[170:173], v[186:189], v[88:91]
	v_mfma_f32_16x16x32_bf16 v[44:47], v[162:165], v[194:197], v[44:47]
	v_mfma_f32_16x16x32_bf16 v[40:43], v[170:173], v[194:197], v[40:43]
	v_mfma_f32_16x16x32_bf16 v[4:7], v[162:165], v[202:205], v[4:7]
	v_mfma_f32_16x16x32_bf16 v[0:3], v[170:173], v[202:205], v[0:3]
	v_mfma_f32_16x16x32_bf16 v[124:127], v[166:169], v[182:185], v[124:127]
	v_mfma_f32_16x16x32_bf16 v[112:115], v[174:177], v[182:185], v[112:115]
	v_mfma_f32_16x16x32_bf16 v[92:95], v[166:169], v[190:193], v[92:95]
	v_mfma_f32_16x16x32_bf16 v[88:91], v[174:177], v[190:193], v[88:91]
	v_mfma_f32_16x16x32_bf16 v[44:47], v[166:169], v[198:201], v[44:47]
	v_mfma_f32_16x16x32_bf16 v[40:43], v[174:177], v[198:201], v[40:43]
	v_mfma_f32_16x16x32_bf16 v[4:7], v[166:169], v[206:209], v[4:7]
	v_mfma_f32_16x16x32_bf16 v[0:3], v[174:177], v[206:209], v[0:3]
	s_barrier
	ds_read_b128 v[146:149], v143
	ds_read_b128 v[150:153], v143 offset:1024
	ds_read_b128 v[154:157], v143 offset:2048
	ds_read_b128 v[158:161], v143 offset:3072
	ds_read_b128 v[162:165], v144
	ds_read_b128 v[166:169], v144 offset:1024
	ds_read_b128 v[170:173], v144 offset:2048
	ds_read_b128 v[174:177], v144 offset:3072
	s_add_u32 s52, s72, 0x4000
	s_addc_u32 s53, s73, 0
	s_mov_b32 m0, s21
	v_lshl_add_u64 v[214:215], s[52:53], 0, v[32:33]
	ds_read_b128 v[178:181], v142 offset:32768
	ds_read_b128 v[182:185], v142 offset:33792
	ds_read_b128 v[186:189], v142 offset:34816
	ds_read_b128 v[190:193], v142 offset:35840
	ds_read_b128 v[194:197], v142 offset:36864
	ds_read_b128 v[198:201], v142 offset:37888
	ds_read_b128 v[202:205], v142 offset:38912
	ds_read_b128 v[206:209], v142 offset:39936
	global_load_lds_dwordx4 v[214:215], off
	v_lshl_add_u64 v[214:215], s[52:53], 0, v[132:133]
	s_mov_b32 m0, s22
	s_nop 0
	global_load_lds_dwordx4 v[214:215], off
	s_waitcnt vmcnt(8) lgkmcnt(0)
	s_barrier
	v_mfma_f32_16x16x32_bf16 v[8:11], v[146:149], v[178:181], v[8:11]
	v_mfma_f32_16x16x32_bf16 v[12:15], v[154:157], v[178:181], v[12:15]
	v_mfma_f32_16x16x32_bf16 v[60:63], v[146:149], v[186:189], v[60:63]
	v_mfma_f32_16x16x32_bf16 v[20:23], v[154:157], v[186:189], v[20:23]
	v_mfma_f32_16x16x32_bf16 v[76:79], v[146:149], v[194:197], v[76:79]
	v_mfma_f32_16x16x32_bf16 v[52:55], v[154:157], v[194:197], v[52:55]
	v_mfma_f32_16x16x32_bf16 v[128:131], v[146:149], v[202:205], v[128:131]
	v_mfma_f32_16x16x32_bf16 v[68:71], v[154:157], v[202:205], v[68:71]
	v_mfma_f32_16x16x32_bf16 v[8:11], v[150:153], v[182:185], v[8:11]
	v_mfma_f32_16x16x32_bf16 v[12:15], v[158:161], v[182:185], v[12:15]
	v_mfma_f32_16x16x32_bf16 v[60:63], v[150:153], v[190:193], v[60:63]
	v_mfma_f32_16x16x32_bf16 v[20:23], v[158:161], v[190:193], v[20:23]
	v_mfma_f32_16x16x32_bf16 v[76:79], v[150:153], v[198:201], v[76:79]
	v_mfma_f32_16x16x32_bf16 v[52:55], v[158:161], v[198:201], v[52:55]
	v_mfma_f32_16x16x32_bf16 v[128:131], v[150:153], v[206:209], v[128:131]
	v_mfma_f32_16x16x32_bf16 v[68:71], v[158:161], v[206:209], v[68:71]
	v_mfma_f32_16x16x32_bf16 v[28:31], v[162:165], v[178:181], v[28:31]
	v_mfma_f32_16x16x32_bf16 v[16:19], v[170:173], v[178:181], v[16:19]
	v_mfma_f32_16x16x32_bf16 v[56:59], v[162:165], v[186:189], v[56:59]
	v_mfma_f32_16x16x32_bf16 v[48:51], v[170:173], v[186:189], v[48:51]
	v_mfma_f32_16x16x32_bf16 v[72:75], v[162:165], v[194:197], v[72:75]
	v_mfma_f32_16x16x32_bf16 v[64:67], v[170:173], v[194:197], v[64:67]
	v_mfma_f32_16x16x32_bf16 v[108:111], v[162:165], v[202:205], v[108:111]
	v_mfma_f32_16x16x32_bf16 v[96:99], v[170:173], v[202:205], v[96:99]
	v_mfma_f32_16x16x32_bf16 v[28:31], v[166:169], v[182:185], v[28:31]
	v_mfma_f32_16x16x32_bf16 v[16:19], v[174:177], v[182:185], v[16:19]
	v_mfma_f32_16x16x32_bf16 v[56:59], v[166:169], v[190:193], v[56:59]
	v_mfma_f32_16x16x32_bf16 v[48:51], v[174:177], v[190:193], v[48:51]
	v_mfma_f32_16x16x32_bf16 v[72:75], v[166:169], v[198:201], v[72:75]
	v_mfma_f32_16x16x32_bf16 v[64:67], v[174:177], v[198:201], v[64:67]
	v_mfma_f32_16x16x32_bf16 v[108:111], v[166:169], v[206:209], v[108:111]
	v_mfma_f32_16x16x32_bf16 v[96:99], v[174:177], v[206:209], v[96:99]
	s_barrier
; #define PG8_WAIT_V(n) asm volatile("s_waitcnt vmcnt(" #n ")" ::: "memory")
; #define PG8_BAR __builtin_amdgcn_s_barrier()
; template <class Epi, class Sched, bool ALIGN_EPI = false, bool SP2 = false, bool A_TILED = false>
; __device__ __forceinline__ void gemm_phase(PG8_LAS unsigned char* lds, const Gemm g, const Sched& S, const Epi& E, const int wave_s) {
;     ...
;     PG8_WAIT_V(0);
;     if constexpr (!ALIGN_EPI) { if (wr == 0) PG8_BAR; }
	s_mov_b32 m0, s48
	v_lshl_add_u64 v[210:211], v[210:211], 0, s[64:65]
	s_add_u32 s52, s70, 0x200080
	ds_read_b128 v[178:181], v142 offset:49152
	ds_read_b128 v[182:185], v142 offset:50176
	ds_read_b128 v[186:189], v142 offset:51200
	ds_read_b128 v[190:193], v142 offset:52224
	ds_read_b128 v[194:197], v142 offset:53248
	ds_read_b128 v[198:201], v142 offset:54272
	ds_read_b128 v[202:205], v142 offset:55296
	ds_read_b128 v[206:209], v142 offset:56320
	global_load_lds_dwordx4 v[210:211], off
	v_lshl_add_u64 v[210:211], v[212:213], 0, s[64:65]
	s_mov_b32 m0, s49
	s_addc_u32 s53, s71, 0
	global_load_lds_dwordx4 v[210:211], off
	v_lshl_add_u64 v[210:211], s[52:53], 0, v[34:35]
	s_mov_b32 m0, s50
	s_nop 0
	global_load_lds_dwordx4 v[210:211], off
	v_lshl_add_u64 v[210:211], s[52:53], 0, v[134:135]
	s_mov_b32 m0, s51
	s_nop 0
	global_load_lds_dwordx4 v[210:211], off
	v_lshl_add_u64 v[210:211], s[68:69], 0, v[32:33]
	s_mov_b32 m0, s23
	s_nop 0
	global_load_lds_dwordx4 v[210:211], off
	v_lshl_add_u64 v[210:211], s[68:69], 0, v[132:133]
	s_mov_b32 m0, s36
	s_nop 0
	global_load_lds_dwordx4 v[210:211], off
	s_waitcnt vmcnt(8) lgkmcnt(0)
	s_barrier
	v_mfma_f32_16x16x32_bf16 v[100:103], v[146:149], v[178:181], v[100:103]
	v_mfma_f32_16x16x32_bf16 v[104:107], v[154:157], v[178:181], v[104:107]
	v_mfma_f32_16x16x32_bf16 v[116:119], v[146:149], v[186:189], v[116:119]
	v_mfma_f32_16x16x32_bf16 v[120:123], v[154:157], v[186:189], v[120:123]
	v_mfma_f32_16x16x32_bf16 v[84:87], v[146:149], v[194:197], v[84:87]
	v_mfma_f32_16x16x32_bf16 v[80:83], v[154:157], v[194:197], v[80:83]
	v_mfma_f32_16x16x32_bf16 v[36:39], v[146:149], v[202:205], v[36:39]
	v_mfma_f32_16x16x32_bf16 v[24:27], v[154:157], v[202:205], v[24:27]
	v_mfma_f32_16x16x32_bf16 v[100:103], v[150:153], v[182:185], v[100:103]
	v_mfma_f32_16x16x32_bf16 v[104:107], v[158:161], v[182:185], v[104:107]
	v_mfma_f32_16x16x32_bf16 v[116:119], v[150:153], v[190:193], v[116:119]
	v_mfma_f32_16x16x32_bf16 v[120:123], v[158:161], v[190:193], v[120:123]
	v_mfma_f32_16x16x32_bf16 v[84:87], v[150:153], v[198:201], v[84:87]
	v_mfma_f32_16x16x32_bf16 v[80:83], v[158:161], v[198:201], v[80:83]
	v_mfma_f32_16x16x32_bf16 v[36:39], v[150:153], v[206:209], v[36:39]
	v_mfma_f32_16x16x32_bf16 v[24:27], v[158:161], v[206:209], v[24:27]
	v_mfma_f32_16x16x32_bf16 v[124:127], v[162:165], v[178:181], v[124:127]
	v_mfma_f32_16x16x32_bf16 v[112:115], v[170:173], v[178:181], v[112:115]
	v_mfma_f32_16x16x32_bf16 v[92:95], v[162:165], v[186:189], v[92:95]
	v_mfma_f32_16x16x32_bf16 v[88:91], v[170:173], v[186:189], v[88:91]
	v_mfma_f32_16x16x32_bf16 v[44:47], v[162:165], v[194:197], v[44:47]
	v_mfma_f32_16x16x32_bf16 v[40:43], v[170:173], v[194:197], v[40:43]
	v_mfma_f32_16x16x32_bf16 v[4:7], v[162:165], v[202:205], v[4:7]
	v_mfma_f32_16x16x32_bf16 v[0:3], v[170:173], v[202:205], v[0:3]
	v_mfma_f32_16x16x32_bf16 v[124:127], v[166:169], v[182:185], v[124:127]
	v_mfma_f32_16x16x32_bf16 v[112:115], v[174:177], v[182:185], v[112:115]
	v_mfma_f32_16x16x32_bf16 v[92:95], v[166:169], v[190:193], v[92:95]
	v_mfma_f32_16x16x32_bf16 v[88:91], v[174:177], v[190:193], v[88:91]
	v_mfma_f32_16x16x32_bf16 v[44:47], v[166:169], v[198:201], v[44:47]
	v_mfma_f32_16x16x32_bf16 v[40:43], v[174:177], v[198:201], v[40:43]
	v_mfma_f32_16x16x32_bf16 v[4:7], v[166:169], v[206:209], v[4:7]
	v_mfma_f32_16x16x32_bf16 v[0:3], v[174:177], v[206:209], v[0:3]
	s_barrier
	s_add_i32 s41, s41, 2
	s_add_u32 s37, s37, 0x100
	s_addc_u32 s38, s38, 0
	s_add_u32 s39, s39, 0x10000
	s_addc_u32 s40, s40, 0
	v_lshl_add_u64 v[136:137], v[136:137], 0, s[66:67]
	s_cmpk_gt_u32 s41, 0x7d
	v_lshl_add_u64 v[138:139], v[138:139], 0, s[66:67]
	s_cbranch_scc0 .LBB0_1228
	s_waitcnt vmcnt(0)
	s_cmpk_lt_u32 s8, 0x100
	s_cbranch_scc0 .LBB0_1231
	s_barrier

; template <class Epi, class Sched, bool ALIGN_EPI = false, bool SP2 = false, bool A_TILED = false>
; __device__ __forceinline__ void gemm_phase(PG8_LAS unsigned char* lds, const Gemm g, const Sched& S, const Epi& E, const int wave_s) {
;     ...
;         const char* nA = has_next ? (const char*)g.A + (size_t)nxt.pm * tstepA : cA; const char* nB = has_next ? (const char*)g.Bt + (size_t)nxt.pn * tstep : cB;
;         constexpr bool PEEL = SP2 && !Epi::AFTER_DRAIN;
;         if constexpr (PEEL) {
;             const char* a1 = cA + kstepA; const char* a2 = cA + 2 * kstepA; const char* b2 = cB + 2 * kstep; const char* a3 = a2 + kstepA; const char* b3 = b2 + kstep;
;             PG8_ITER(PG8_MMAZ)
.LBB0_1618:
	s_ashr_i32 s71, s70, 31
	s_lshl_b64 s[52:53], s[70:71], 20
	s_add_u32 s72, s1, s52
	ds_read_b128 v[0:3], v149
	ds_read_b128 v[4:7], v149 offset:1024
	ds_read_b128 v[8:11], v149 offset:2048
	ds_read_b128 v[12:15], v149 offset:3072
	ds_read_b128 v[16:19], v150
	ds_read_b128 v[20:23], v150 offset:1024
	ds_read_b128 v[24:27], v150 offset:2048
	ds_read_b128 v[28:31], v150 offset:3072
	s_addc_u32 s73, s8, s53
	s_ashr_i32 s69, s68, 31
	s_lshl_b64 s[52:53], s[68:69], 20
	s_add_u32 s74, s9, s52
	s_addc_u32 s75, s14, s53
	s_and_b64 s[52:53], s[2:3], exec
	s_cselect_b32 s51, s73, s81
	s_cselect_b32 s52, s72, s80
	s_cselect_b32 s53, s75, s79
	s_cselect_b32 s54, s74, s78
	s_add_u32 s56, s80, 0x80080
	s_addc_u32 s57, s81, 0
	s_add_i32 s55, s23, 0xc000
	v_lshl_add_u64 v[64:65], s[56:57], 0, v[134:135]
	s_mov_b32 m0, s55
	ds_read_b128 v[32:35], v151
	ds_read_b128 v[36:39], v151 offset:1024
	ds_read_b128 v[40:43], v151 offset:2048
	ds_read_b128 v[44:47], v151 offset:3072
	ds_read_b128 v[48:51], v151 offset:4096
	ds_read_b128 v[52:55], v151 offset:5120
	ds_read_b128 v[56:59], v151 offset:6144
	ds_read_b128 v[60:63], v151 offset:7168
	global_load_lds_dwordx4 v[64:65], off
	v_lshl_add_u64 v[64:65], s[56:57], 0, v[132:133]
	s_add_i32 s56, s23, 0xe000
	s_mov_b32 m0, s56
	s_nop 0
	global_load_lds_dwordx4 v[64:65], off
	s_waitcnt vmcnt(8) lgkmcnt(0)
	s_barrier
	v_mfma_f32_16x16x32_bf16 v[88:91], v[0:3], v[56:59], 0
	v_mfma_f32_16x16x32_bf16 v[64:67], v[0:3], v[32:35], 0
	v_mfma_f32_16x16x32_bf16 v[68:71], v[8:11], v[32:35], 0
	v_mfma_f32_16x16x32_bf16 v[72:75], v[0:3], v[40:43], 0
	v_mfma_f32_16x16x32_bf16 v[76:79], v[8:11], v[40:43], 0
	v_mfma_f32_16x16x32_bf16 v[80:83], v[0:3], v[48:51], 0
	v_mfma_f32_16x16x32_bf16 v[84:87], v[8:11], v[48:51], 0
	v_mfma_f32_16x16x32_bf16 v[96:99], v[4:7], v[60:63], v[88:91]
	v_mfma_f32_16x16x32_bf16 v[88:91], v[8:11], v[56:59], 0
	v_mfma_f32_16x16x32_bf16 v[64:67], v[4:7], v[36:39], v[64:67]
	v_mfma_f32_16x16x32_bf16 v[68:71], v[12:15], v[36:39], v[68:71]
	v_mfma_f32_16x16x32_bf16 v[72:75], v[4:7], v[44:47], v[72:75]
	v_mfma_f32_16x16x32_bf16 v[76:79], v[12:15], v[44:47], v[76:79]
	v_mfma_f32_16x16x32_bf16 v[80:83], v[4:7], v[52:55], v[80:83]
	v_mfma_f32_16x16x32_bf16 v[84:87], v[12:15], v[52:55], v[84:87]
	v_mfma_f32_16x16x32_bf16 v[100:103], v[12:15], v[60:63], v[88:91]
	v_mfma_f32_16x16x32_bf16 v[88:91], v[16:19], v[32:35], 0
	v_mfma_f32_16x16x32_bf16 v[32:35], v[24:27], v[32:35], 0
	v_mfma_f32_16x16x32_bf16 v[112:115], v[20:23], v[36:39], v[88:91]
	v_mfma_f32_16x16x32_bf16 v[32:35], v[28:31], v[36:39], v[32:35]
	v_mfma_f32_16x16x32_bf16 v[36:39], v[16:19], v[40:43], 0
	v_mfma_f32_16x16x32_bf16 v[40:43], v[24:27], v[40:43], 0
	v_mfma_f32_16x16x32_bf16 v[36:39], v[20:23], v[44:47], v[36:39]
	v_mfma_f32_16x16x32_bf16 v[40:43], v[28:31], v[44:47], v[40:43]
	v_mfma_f32_16x16x32_bf16 v[44:47], v[16:19], v[48:51], 0
	v_mfma_f32_16x16x32_bf16 v[48:51], v[24:27], v[48:51], 0
	v_mfma_f32_16x16x32_bf16 v[44:47], v[20:23], v[52:55], v[44:47]
	v_mfma_f32_16x16x32_bf16 v[48:51], v[28:31], v[52:55], v[48:51]
	v_mfma_f32_16x16x32_bf16 v[52:55], v[16:19], v[56:59], 0
	v_mfma_f32_16x16x32_bf16 v[56:59], v[24:27], v[56:59], 0
	v_mfma_f32_16x16x32_bf16 v[52:55], v[20:23], v[60:63], v[52:55]
	v_mfma_f32_16x16x32_bf16 v[56:59], v[28:31], v[60:63], v[56:59]
	s_barrier
	s_add_i32 s57, s46, s15
	v_lshl_add_u64 v[250:251], s[78:79], 0, v[128:129]
	s_add_i32 s58, s57, 0x2000
	v_lshl_add_u64 v[144:145], v[250:251], 0, s[64:65]
	s_mov_b32 m0, s57
	v_lshl_add_u64 v[252:253], s[78:79], 0, v[130:131]
	s_add_u32 s82, s78, 0x80100
	ds_read_b128 v[60:63], v151 offset:16384
	ds_read_b128 v[88:91], v151 offset:17408
	ds_read_b128 v[92:95], v151 offset:18432
	ds_read_b128 v[104:107], v151 offset:19456
	ds_read_b128 v[108:111], v151 offset:20480
	ds_read_b128 v[116:119], v151 offset:21504
	ds_read_b128 v[120:123], v151 offset:22528
	ds_read_b128 v[124:127], v151 offset:23552
	global_load_lds_dwordx4 v[144:145], off
	v_lshl_add_u64 v[144:145], v[252:253], 0, s[64:65]
	s_mov_b32 m0, s58
	s_addc_u32 s83, s79, 0
	s_add_i32 s59, s47, s15
	global_load_lds_dwordx4 v[144:145], off
	v_lshl_add_u64 v[144:145], s[82:83], 0, v[128:129]
	s_mov_b32 m0, s59
	s_add_i32 s69, s59, 0x2000
	global_load_lds_dwordx4 v[144:145], off
	v_lshl_add_u64 v[144:145], s[82:83], 0, v[130:131]
	s_mov_b32 m0, s69
	v_lshl_add_u64 v[140:141], s[80:81], 0, v[134:135]
	global_load_lds_dwordx4 v[144:145], off
	v_lshl_add_u64 v[144:145], v[140:141], 0, s[64:65]
	s_mov_b32 m0, s23
	v_lshl_add_u64 v[142:143], s[80:81], 0, v[132:133]
	global_load_lds_dwordx4 v[144:145], off
	v_lshl_add_u64 v[144:145], v[142:143], 0, s[64:65]
	s_mov_b32 m0, s36
	s_nop 0
	global_load_lds_dwordx4 v[144:145], off
	s_waitcnt vmcnt(8) lgkmcnt(0)
	s_barrier
	v_mfma_f32_16x16x32_bf16 v[144:147], v[0:3], v[60:63], 0
	v_mfma_f32_16x16x32_bf16 v[154:157], v[4:7], v[88:91], v[144:147]
	v_mfma_f32_16x16x32_bf16 v[144:147], v[8:11], v[60:63], 0
	v_mfma_f32_16x16x32_bf16 v[158:161], v[12:15], v[88:91], v[144:147]
	v_mfma_f32_16x16x32_bf16 v[144:147], v[0:3], v[92:95], 0
	v_mfma_f32_16x16x32_bf16 v[162:165], v[4:7], v[104:107], v[144:147]
	v_mfma_f32_16x16x32_bf16 v[144:147], v[8:11], v[92:95], 0
	v_mfma_f32_16x16x32_bf16 v[166:169], v[12:15], v[104:107], v[144:147]
	v_mfma_f32_16x16x32_bf16 v[144:147], v[0:3], v[108:111], 0
	v_mfma_f32_16x16x32_bf16 v[0:3], v[0:3], v[120:123], 0
	v_mfma_f32_16x16x32_bf16 v[170:173], v[4:7], v[116:119], v[144:147]
	v_mfma_f32_16x16x32_bf16 v[0:3], v[4:7], v[124:127], v[0:3]
	v_mfma_f32_16x16x32_bf16 v[4:7], v[8:11], v[120:123], 0
	v_mfma_f32_16x16x32_bf16 v[144:147], v[8:11], v[108:111], 0
	v_mfma_f32_16x16x32_bf16 v[4:7], v[12:15], v[124:127], v[4:7]
	v_mfma_f32_16x16x32_bf16 v[174:177], v[12:15], v[116:119], v[144:147]
	v_mfma_f32_16x16x32_bf16 v[8:11], v[16:19], v[60:63], 0
	v_mfma_f32_16x16x32_bf16 v[178:181], v[20:23], v[88:91], v[8:11]
	v_mfma_f32_16x16x32_bf16 v[8:11], v[24:27], v[60:63], 0
	v_mfma_f32_16x16x32_bf16 v[182:185], v[28:31], v[88:91], v[8:11]
	v_mfma_f32_16x16x32_bf16 v[8:11], v[16:19], v[92:95], 0
	v_mfma_f32_16x16x32_bf16 v[186:189], v[20:23], v[104:107], v[8:11]
	v_mfma_f32_16x16x32_bf16 v[8:11], v[24:27], v[92:95], 0
	v_mfma_f32_16x16x32_bf16 v[190:193], v[28:31], v[104:107], v[8:11]
	v_mfma_f32_16x16x32_bf16 v[8:11], v[16:19], v[108:111], 0
	v_mfma_f32_16x16x32_bf16 v[194:197], v[20:23], v[116:119], v[8:11]
	v_mfma_f32_16x16x32_bf16 v[8:11], v[24:27], v[108:111], 0
	v_mfma_f32_16x16x32_bf16 v[198:201], v[28:31], v[116:119], v[8:11]
	v_mfma_f32_16x16x32_bf16 v[8:11], v[16:19], v[120:123], 0
	v_mfma_f32_16x16x32_bf16 v[202:205], v[20:23], v[124:127], v[8:11]
	v_mfma_f32_16x16x32_bf16 v[8:11], v[24:27], v[120:123], 0
	v_mfma_f32_16x16x32_bf16 v[206:209], v[28:31], v[124:127], v[8:11]
	s_barrier
	s_add_i32 s71, 0, 0x18000
	s_add_i32 s88, 0, 0x1c000
	v_add_u32_e32 v144, s71, v148
	v_add_u32_e32 v145, s88, v148
	s_nop 0
	ds_read_b128 v[8:11], v144
	ds_read_b128 v[12:15], v144 offset:1024
	ds_read_b128 v[16:19], v144 offset:2048
	ds_read_b128 v[20:23], v144 offset:3072
	ds_read_b128 v[210:213], v145
	ds_read_b128 v[214:217], v145 offset:1024
	ds_read_b128 v[218:221], v145 offset:2048
	ds_read_b128 v[222:225], v145 offset:3072
	s_add_u32 s82, s80, 0x80100
	s_addc_u32 s83, s81, 0
	s_mov_b32 m0, s37
	v_lshl_add_u64 v[88:89], s[82:83], 0, v[134:135]
	ds_read_b128 v[24:27], v151 offset:32768
	ds_read_b128 v[28:31], v151 offset:33792
	ds_read_b128 v[60:63], v151 offset:34816
	ds_read_b128 v[226:229], v151 offset:35840
	ds_read_b128 v[230:233], v151 offset:36864
	ds_read_b128 v[234:237], v151 offset:37888
	ds_read_b128 v[238:241], v151 offset:38912
	ds_read_b128 v[242:245], v151 offset:39936
	global_load_lds_dwordx4 v[88:89], off
	v_lshl_add_u64 v[88:89], s[82:83], 0, v[132:133]
	s_mov_b32 m0, s38
	s_nop 0
	global_load_lds_dwordx4 v[88:89], off
	s_waitcnt vmcnt(8) lgkmcnt(0)
	s_barrier
	v_mfma_f32_16x16x32_bf16 v[64:67], v[8:11], v[24:27], v[64:67]
	v_mfma_f32_16x16x32_bf16 v[124:127], v[12:15], v[28:31], v[64:67]
	v_mfma_f32_16x16x32_bf16 v[64:67], v[16:19], v[24:27], v[68:71]
	v_mfma_f32_16x16x32_bf16 v[120:123], v[20:23], v[28:31], v[64:67]
	v_mfma_f32_16x16x32_bf16 v[64:67], v[8:11], v[60:63], v[72:75]
	v_mfma_f32_16x16x32_bf16 v[108:111], v[12:15], v[226:229], v[64:67]
	v_mfma_f32_16x16x32_bf16 v[64:67], v[16:19], v[60:63], v[76:79]
	v_mfma_f32_16x16x32_bf16 v[104:107], v[20:23], v[226:229], v[64:67]
	v_mfma_f32_16x16x32_bf16 v[64:67], v[8:11], v[230:233], v[80:83]
	v_mfma_f32_16x16x32_bf16 v[92:95], v[12:15], v[234:237], v[64:67]
	v_mfma_f32_16x16x32_bf16 v[64:67], v[16:19], v[230:233], v[84:87]
	v_mfma_f32_16x16x32_bf16 v[88:91], v[20:23], v[234:237], v[64:67]
	v_mfma_f32_16x16x32_bf16 v[64:67], v[8:11], v[238:241], v[96:99]
	v_mfma_f32_16x16x32_bf16 v[76:79], v[12:15], v[242:245], v[64:67]
	v_mfma_f32_16x16x32_bf16 v[64:67], v[16:19], v[238:241], v[100:103]
	v_mfma_f32_16x16x32_bf16 v[72:75], v[20:23], v[242:245], v[64:67]
	v_mfma_f32_16x16x32_bf16 v[64:67], v[210:213], v[24:27], v[112:115]
	v_mfma_f32_16x16x32_bf16 v[24:27], v[218:221], v[24:27], v[32:35]
	v_mfma_f32_16x16x32_bf16 v[112:115], v[222:225], v[28:31], v[24:27]
	v_mfma_f32_16x16x32_bf16 v[24:27], v[210:213], v[60:63], v[36:39]
	v_mfma_f32_16x16x32_bf16 v[100:103], v[214:217], v[226:229], v[24:27]
	v_mfma_f32_16x16x32_bf16 v[24:27], v[218:221], v[60:63], v[40:43]
	v_mfma_f32_16x16x32_bf16 v[96:99], v[222:225], v[226:229], v[24:27]
	v_mfma_f32_16x16x32_bf16 v[24:27], v[210:213], v[230:233], v[44:47]
	v_mfma_f32_16x16x32_bf16 v[84:87], v[214:217], v[234:237], v[24:27]
	v_mfma_f32_16x16x32_bf16 v[24:27], v[218:221], v[230:233], v[48:51]
	v_mfma_f32_16x16x32_bf16 v[80:83], v[222:225], v[234:237], v[24:27]
	v_mfma_f32_16x16x32_bf16 v[24:27], v[210:213], v[238:241], v[52:55]
	v_mfma_f32_16x16x32_bf16 v[68:71], v[214:217], v[242:245], v[24:27]
	v_mfma_f32_16x16x32_bf16 v[24:27], v[218:221], v[238:241], v[56:59]
	v_mfma_f32_16x16x32_bf16 v[116:119], v[214:217], v[28:31], v[64:67]
	v_mfma_f32_16x16x32_bf16 v[64:67], v[222:225], v[242:245], v[24:27]
	s_barrier
; #define PG8_MMA(ai, bj, At, Bt) do { __builtin_amdgcn_s_setprio(1); _Pragma("unroll") for (int m = 0; m < 4; ++m) _Pragma("unroll") for (int n = 0; n < 2; ++n) _Pragma("unroll") for (int k = 0; k < 2; ++k) \
;         acc[ai][bj][m][n] = __builtin_amdgcn_mfma_f32_16x16x32_bf16(Bt[n][k], At[m][k], acc[ai][bj][m][n], 0, 0, 0); __builtin_amdgcn_s_setprio(0); } while (0)
; template <class Epi, class Sched, bool ALIGN_EPI = false, bool SP2 = false, bool A_TILED = false>
; __device__ __forceinline__ void gemm_phase(PG8_LAS unsigned char* lds, const Gemm g, const Sched& S, const Epi& E, const int wave_s) {
;     ...
;         for (int t = PEEL ? 2 : 0; t < nt; t += 2) {
;             const bool last = (t == nt - 2);
;             const char* a1 = cA + (size_t)(t + 1) * kstepA;
;             const char* a2 = last ? nA : cA + (size_t)(t + 2) * kstepA; const char* b2 = last ? nB : cB + (size_t)(t + 2) * kstep;
;             const char* a3 = a2 + kstepA; const char* b3 = b2 + kstep;
;             if (last && has_next) S.a_ready(nxt);
;             if constexpr (SP2) {
;             PG8_ITER(PG8_MMA)
	s_add_i32 s71, s71, s15
	s_add_i32 s77, s71, 0x2000
	s_nop 1
	v_lshl_add_u64 v[24:25], v[250:251], 0, s[66:67]
	s_mov_b32 m0, s71
	s_add_u32 s82, s78, 0x80180
	ds_read_b128 v[32:35], v151 offset:49152
	ds_read_b128 v[36:39], v151 offset:50176
	ds_read_b128 v[226:229], v151 offset:51200
	ds_read_b128 v[230:233], v151 offset:52224
	ds_read_b128 v[234:237], v151 offset:53248
	ds_read_b128 v[238:241], v151 offset:54272
	ds_read_b128 v[242:245], v151 offset:55296
	ds_read_b128 v[246:249], v151 offset:56320
	global_load_lds_dwordx4 v[24:25], off
	v_lshl_add_u64 v[24:25], v[252:253], 0, s[66:67]
	s_mov_b32 m0, s77
	s_addc_u32 s83, s79, 0
	s_add_i32 s88, s88, s15
	global_load_lds_dwordx4 v[24:25], off
	v_lshl_add_u64 v[24:25], s[82:83], 0, v[128:129]
	s_mov_b32 m0, s88
	s_add_i32 s89, s88, 0x2000
	global_load_lds_dwordx4 v[24:25], off
	v_lshl_add_u64 v[24:25], s[82:83], 0, v[130:131]
	s_mov_b32 m0, s89
	s_nop 0
	global_load_lds_dwordx4 v[24:25], off
	v_lshl_add_u64 v[24:25], v[140:141], 0, s[66:67]
	s_mov_b32 m0, s43
	s_nop 0
	global_load_lds_dwordx4 v[24:25], off
	v_lshl_add_u64 v[24:25], v[142:143], 0, s[66:67]
	s_mov_b32 m0, s44
	s_nop 0
	global_load_lds_dwordx4 v[24:25], off
	s_waitcnt vmcnt(8) lgkmcnt(0)
	s_barrier
	v_mfma_f32_16x16x32_bf16 v[24:27], v[8:11], v[32:35], v[154:157]
	v_mfma_f32_16x16x32_bf16 v[60:63], v[12:15], v[36:39], v[24:27]
	v_mfma_f32_16x16x32_bf16 v[24:27], v[16:19], v[32:35], v[158:161]
	v_mfma_f32_16x16x32_bf16 v[56:59], v[20:23], v[36:39], v[24:27]
	v_mfma_f32_16x16x32_bf16 v[24:27], v[8:11], v[226:229], v[162:165]
	v_mfma_f32_16x16x32_bf16 v[44:47], v[12:15], v[230:233], v[24:27]
	v_mfma_f32_16x16x32_bf16 v[24:27], v[16:19], v[226:229], v[166:169]
	v_mfma_f32_16x16x32_bf16 v[40:43], v[20:23], v[230:233], v[24:27]
	v_mfma_f32_16x16x32_bf16 v[24:27], v[8:11], v[234:237], v[170:173]
	v_mfma_f32_16x16x32_bf16 v[0:3], v[8:11], v[242:245], v[0:3]
	v_mfma_f32_16x16x32_bf16 v[28:31], v[12:15], v[238:241], v[24:27]
	v_mfma_f32_16x16x32_bf16 v[24:27], v[16:19], v[234:237], v[174:177]
	v_mfma_f32_16x16x32_bf16 v[12:15], v[12:15], v[246:249], v[0:3]
	v_mfma_f32_16x16x32_bf16 v[0:3], v[16:19], v[242:245], v[4:7]
	v_mfma_f32_16x16x32_bf16 v[24:27], v[20:23], v[238:241], v[24:27]
	v_mfma_f32_16x16x32_bf16 v[8:11], v[20:23], v[246:249], v[0:3]
	v_mfma_f32_16x16x32_bf16 v[0:3], v[210:213], v[32:35], v[178:181]
	v_mfma_f32_16x16x32_bf16 v[52:55], v[214:217], v[36:39], v[0:3]
	v_mfma_f32_16x16x32_bf16 v[0:3], v[218:221], v[32:35], v[182:185]
	v_mfma_f32_16x16x32_bf16 v[48:51], v[222:225], v[36:39], v[0:3]
	v_mfma_f32_16x16x32_bf16 v[0:3], v[210:213], v[226:229], v[186:189]
	v_mfma_f32_16x16x32_bf16 v[36:39], v[214:217], v[230:233], v[0:3]
	v_mfma_f32_16x16x32_bf16 v[0:3], v[218:221], v[226:229], v[190:193]
	v_mfma_f32_16x16x32_bf16 v[32:35], v[222:225], v[230:233], v[0:3]
	v_mfma_f32_16x16x32_bf16 v[0:3], v[210:213], v[234:237], v[194:197]
	v_mfma_f32_16x16x32_bf16 v[20:23], v[214:217], v[238:241], v[0:3]
	v_mfma_f32_16x16x32_bf16 v[0:3], v[218:221], v[234:237], v[198:201]
	v_mfma_f32_16x16x32_bf16 v[16:19], v[222:225], v[238:241], v[0:3]
	v_mfma_f32_16x16x32_bf16 v[0:3], v[210:213], v[242:245], v[202:205]
	v_mfma_f32_16x16x32_bf16 v[4:7], v[214:217], v[246:249], v[0:3]
	v_mfma_f32_16x16x32_bf16 v[0:3], v[218:221], v[242:245], v[206:209]
	v_mfma_f32_16x16x32_bf16 v[0:3], v[222:225], v[246:249], v[0:3]
	s_barrier
	s_add_u32 s90, s78, 0x200
	s_addc_u32 s85, s79, 0
	s_add_u32 s78, s80, 0x80180
	s_addc_u32 s79, s81, 0
	s_mov_b32 s91, 0
.LBB0_1619:
	ds_read_b128 v[154:157], v149
	ds_read_b128 v[158:161], v149 offset:1024
	ds_read_b128 v[162:165], v149 offset:2048
	ds_read_b128 v[166:169], v149 offset:3072
	ds_read_b128 v[170:173], v150
	ds_read_b128 v[174:177], v150 offset:1024
	ds_read_b128 v[178:181], v150 offset:2048
	ds_read_b128 v[182:185], v150 offset:3072
	s_add_u32 s80, s78, 0xfff80080
	s_addc_u32 s81, s79, -1
	s_cmp_eq_u32 s91, 28
	s_cselect_b32 s83, s51, s81
	s_cselect_b32 s82, s52, s80
	s_cselect_b32 s81, s53, s85
	s_cselect_b32 s80, s54, s90
	s_mov_b32 m0, s55
	v_lshl_add_u64 v[140:141], s[78:79], 0, v[138:139]
	ds_read_b128 v[186:189], v151
	ds_read_b128 v[190:193], v151 offset:1024
	ds_read_b128 v[194:197], v151 offset:2048
	ds_read_b128 v[198:201], v151 offset:3072
	ds_read_b128 v[202:205], v151 offset:4096
	ds_read_b128 v[206:209], v151 offset:5120
	ds_read_b128 v[210:213], v151 offset:6144
	ds_read_b128 v[214:217], v151 offset:7168
	global_load_lds_dwordx4 v[140:141], off
	v_lshl_add_u64 v[140:141], s[78:79], 0, v[136:137]
	s_mov_b32 m0, s56
	s_nop 0
	global_load_lds_dwordx4 v[140:141], off
	s_waitcnt vmcnt(8) lgkmcnt(0)
	s_barrier
	v_mfma_f32_16x16x32_bf16 v[124:127], v[154:157], v[186:189], v[124:127]
	v_mfma_f32_16x16x32_bf16 v[120:123], v[162:165], v[186:189], v[120:123]
	v_mfma_f32_16x16x32_bf16 v[108:111], v[154:157], v[194:197], v[108:111]
	v_mfma_f32_16x16x32_bf16 v[104:107], v[162:165], v[194:197], v[104:107]
	v_mfma_f32_16x16x32_bf16 v[92:95], v[154:157], v[202:205], v[92:95]
	v_mfma_f32_16x16x32_bf16 v[88:91], v[162:165], v[202:205], v[88:91]
	v_mfma_f32_16x16x32_bf16 v[76:79], v[154:157], v[210:213], v[76:79]
	v_mfma_f32_16x16x32_bf16 v[72:75], v[162:165], v[210:213], v[72:75]
	v_mfma_f32_16x16x32_bf16 v[124:127], v[158:161], v[190:193], v[124:127]
	v_mfma_f32_16x16x32_bf16 v[120:123], v[166:169], v[190:193], v[120:123]
	v_mfma_f32_16x16x32_bf16 v[108:111], v[158:161], v[198:201], v[108:111]
	v_mfma_f32_16x16x32_bf16 v[104:107], v[166:169], v[198:201], v[104:107]
	v_mfma_f32_16x16x32_bf16 v[92:95], v[158:161], v[206:209], v[92:95]
	v_mfma_f32_16x16x32_bf16 v[88:91], v[166:169], v[206:209], v[88:91]
	v_mfma_f32_16x16x32_bf16 v[76:79], v[158:161], v[214:217], v[76:79]
	v_mfma_f32_16x16x32_bf16 v[72:75], v[166:169], v[214:217], v[72:75]
	v_mfma_f32_16x16x32_bf16 v[116:119], v[170:173], v[186:189], v[116:119]
	v_mfma_f32_16x16x32_bf16 v[112:115], v[178:181], v[186:189], v[112:115]
	v_mfma_f32_16x16x32_bf16 v[100:103], v[170:173], v[194:197], v[100:103]
	v_mfma_f32_16x16x32_bf16 v[96:99], v[178:181], v[194:197], v[96:99]
	v_mfma_f32_16x16x32_bf16 v[84:87], v[170:173], v[202:205], v[84:87]
	v_mfma_f32_16x16x32_bf16 v[80:83], v[178:181], v[202:205], v[80:83]
	v_mfma_f32_16x16x32_bf16 v[68:71], v[170:173], v[210:213], v[68:71]
	v_mfma_f32_16x16x32_bf16 v[64:67], v[178:181], v[210:213], v[64:67]
	v_mfma_f32_16x16x32_bf16 v[116:119], v[174:177], v[190:193], v[116:119]
	v_mfma_f32_16x16x32_bf16 v[112:115], v[182:185], v[190:193], v[112:115]
	v_mfma_f32_16x16x32_bf16 v[100:103], v[174:177], v[198:201], v[100:103]
	v_mfma_f32_16x16x32_bf16 v[96:99], v[182:185], v[198:201], v[96:99]
	v_mfma_f32_16x16x32_bf16 v[84:87], v[174:177], v[206:209], v[84:87]
	v_mfma_f32_16x16x32_bf16 v[80:83], v[182:185], v[206:209], v[80:83]
	v_mfma_f32_16x16x32_bf16 v[68:71], v[174:177], v[214:217], v[68:71]
	v_mfma_f32_16x16x32_bf16 v[64:67], v[182:185], v[214:217], v[64:67]
	s_barrier
	s_mov_b32 m0, s57
	v_lshl_add_u64 v[140:141], s[80:81], 0, v[128:129]
	s_add_u32 s94, s80, 0x80000
	ds_read_b128 v[186:189], v151 offset:16384
	ds_read_b128 v[190:193], v151 offset:17408
	ds_read_b128 v[194:197], v151 offset:18432
	ds_read_b128 v[198:201], v151 offset:19456
	ds_read_b128 v[202:205], v151 offset:20480
	ds_read_b128 v[206:209], v151 offset:21504
	ds_read_b128 v[210:213], v151 offset:22528
	ds_read_b128 v[214:217], v151 offset:23552
	global_load_lds_dwordx4 v[140:141], off
	v_lshl_add_u64 v[142:143], s[80:81], 0, v[130:131]
	s_mov_b32 m0, s58
	s_addc_u32 s95, s81, 0
	global_load_lds_dwordx4 v[142:143], off
	v_lshl_add_u64 v[146:147], s[94:95], 0, v[128:129]
	s_mov_b32 m0, s59
	v_lshl_add_u64 v[218:219], s[82:83], 0, v[132:133]
	global_load_lds_dwordx4 v[146:147], off
	v_lshl_add_u64 v[146:147], s[94:95], 0, v[130:131]
	s_mov_b32 m0, s69
	s_nop 0
	global_load_lds_dwordx4 v[146:147], off
	v_lshl_add_u64 v[146:147], s[82:83], 0, v[134:135]
	s_mov_b32 m0, s23
	s_nop 0
	global_load_lds_dwordx4 v[146:147], off
	s_mov_b32 m0, s36
	s_nop 0
	global_load_lds_dwordx4 v[218:219], off
	s_waitcnt vmcnt(8) lgkmcnt(0)
	s_barrier
	v_mfma_f32_16x16x32_bf16 v[60:63], v[154:157], v[186:189], v[60:63]
	v_mfma_f32_16x16x32_bf16 v[56:59], v[162:165], v[186:189], v[56:59]
	v_mfma_f32_16x16x32_bf16 v[44:47], v[154:157], v[194:197], v[44:47]
	v_mfma_f32_16x16x32_bf16 v[40:43], v[162:165], v[194:197], v[40:43]
	v_mfma_f32_16x16x32_bf16 v[28:31], v[154:157], v[202:205], v[28:31]
	v_mfma_f32_16x16x32_bf16 v[24:27], v[162:165], v[202:205], v[24:27]
	v_mfma_f32_16x16x32_bf16 v[12:15], v[154:157], v[210:213], v[12:15]
	v_mfma_f32_16x16x32_bf16 v[8:11], v[162:165], v[210:213], v[8:11]
	v_mfma_f32_16x16x32_bf16 v[60:63], v[158:161], v[190:193], v[60:63]
	v_mfma_f32_16x16x32_bf16 v[56:59], v[166:169], v[190:193], v[56:59]
	v_mfma_f32_16x16x32_bf16 v[44:47], v[158:161], v[198:201], v[44:47]
	v_mfma_f32_16x16x32_bf16 v[40:43], v[166:169], v[198:201], v[40:43]
	v_mfma_f32_16x16x32_bf16 v[28:31], v[158:161], v[206:209], v[28:31]
	v_mfma_f32_16x16x32_bf16 v[24:27], v[166:169], v[206:209], v[24:27]
	v_mfma_f32_16x16x32_bf16 v[12:15], v[158:161], v[214:217], v[12:15]
	v_mfma_f32_16x16x32_bf16 v[8:11], v[166:169], v[214:217], v[8:11]
	v_mfma_f32_16x16x32_bf16 v[52:55], v[170:173], v[186:189], v[52:55]
	v_mfma_f32_16x16x32_bf16 v[48:51], v[178:181], v[186:189], v[48:51]
	v_mfma_f32_16x16x32_bf16 v[36:39], v[170:173], v[194:197], v[36:39]
	v_mfma_f32_16x16x32_bf16 v[32:35], v[178:181], v[194:197], v[32:35]
	v_mfma_f32_16x16x32_bf16 v[20:23], v[170:173], v[202:205], v[20:23]
	v_mfma_f32_16x16x32_bf16 v[16:19], v[178:181], v[202:205], v[16:19]
	v_mfma_f32_16x16x32_bf16 v[4:7], v[170:173], v[210:213], v[4:7]
	v_mfma_f32_16x16x32_bf16 v[0:3], v[178:181], v[210:213], v[0:3]
	v_mfma_f32_16x16x32_bf16 v[52:55], v[174:177], v[190:193], v[52:55]
	v_mfma_f32_16x16x32_bf16 v[48:51], v[182:185], v[190:193], v[48:51]
	v_mfma_f32_16x16x32_bf16 v[36:39], v[174:177], v[198:201], v[36:39]
	v_mfma_f32_16x16x32_bf16 v[32:35], v[182:185], v[198:201], v[32:35]
	v_mfma_f32_16x16x32_bf16 v[20:23], v[174:177], v[206:209], v[20:23]
	v_mfma_f32_16x16x32_bf16 v[16:19], v[182:185], v[206:209], v[16:19]
	v_mfma_f32_16x16x32_bf16 v[4:7], v[174:177], v[214:217], v[4:7]
	v_mfma_f32_16x16x32_bf16 v[0:3], v[182:185], v[214:217], v[0:3]
	s_barrier
; #define PG8_BAR __builtin_amdgcn_s_barrier()
; template <class Epi, class Sched, bool ALIGN_EPI = false, bool SP2 = false, bool A_TILED = false>
; __device__ __forceinline__ void gemm_phase(PG8_LAS unsigned char* lds, const Gemm g, const Sched& S, const Epi& E, const int wave_s) {
;     ...
;         if constexpr (ALIGN_EPI) { if (wr == 0) PG8_BAR; }
	ds_read_b128 v[154:157], v144
	ds_read_b128 v[158:161], v144 offset:1024
	ds_read_b128 v[162:165], v144 offset:2048
	ds_read_b128 v[166:169], v144 offset:3072
	ds_read_b128 v[170:173], v145
	ds_read_b128 v[174:177], v145 offset:1024
	ds_read_b128 v[178:181], v145 offset:2048
	ds_read_b128 v[182:185], v145 offset:3072
	s_add_u32 s82, s82, 0x80000
	s_addc_u32 s83, s83, 0
	s_mov_b32 m0, s37
	v_lshl_add_u64 v[220:221], s[82:83], 0, v[134:135]
	ds_read_b128 v[186:189], v151 offset:32768
	ds_read_b128 v[190:193], v151 offset:33792
	ds_read_b128 v[194:197], v151 offset:34816
	ds_read_b128 v[198:201], v151 offset:35840
	ds_read_b128 v[202:205], v151 offset:36864
	ds_read_b128 v[206:209], v151 offset:37888
	ds_read_b128 v[210:213], v151 offset:38912
	ds_read_b128 v[214:217], v151 offset:39936
	global_load_lds_dwordx4 v[220:221], off
	v_lshl_add_u64 v[220:221], s[82:83], 0, v[132:133]
	s_mov_b32 m0, s38
	s_nop 0
	global_load_lds_dwordx4 v[220:221], off
	s_waitcnt vmcnt(8) lgkmcnt(0)
	s_barrier
	v_mfma_f32_16x16x32_bf16 v[124:127], v[154:157], v[186:189], v[124:127]
	v_mfma_f32_16x16x32_bf16 v[120:123], v[162:165], v[186:189], v[120:123]
	v_mfma_f32_16x16x32_bf16 v[108:111], v[154:157], v[194:197], v[108:111]
	v_mfma_f32_16x16x32_bf16 v[104:107], v[162:165], v[194:197], v[104:107]
	v_mfma_f32_16x16x32_bf16 v[92:95], v[154:157], v[202:205], v[92:95]
	v_mfma_f32_16x16x32_bf16 v[88:91], v[162:165], v[202:205], v[88:91]
	v_mfma_f32_16x16x32_bf16 v[76:79], v[154:157], v[210:213], v[76:79]
	v_mfma_f32_16x16x32_bf16 v[72:75], v[162:165], v[210:213], v[72:75]
	v_mfma_f32_16x16x32_bf16 v[124:127], v[158:161], v[190:193], v[124:127]
	v_mfma_f32_16x16x32_bf16 v[120:123], v[166:169], v[190:193], v[120:123]
	v_mfma_f32_16x16x32_bf16 v[108:111], v[158:161], v[198:201], v[108:111]
	v_mfma_f32_16x16x32_bf16 v[104:107], v[166:169], v[198:201], v[104:107]
	v_mfma_f32_16x16x32_bf16 v[92:95], v[158:161], v[206:209], v[92:95]
	v_mfma_f32_16x16x32_bf16 v[88:91], v[166:169], v[206:209], v[88:91]
	v_mfma_f32_16x16x32_bf16 v[76:79], v[158:161], v[214:217], v[76:79]
	v_mfma_f32_16x16x32_bf16 v[72:75], v[166:169], v[214:217], v[72:75]
	v_mfma_f32_16x16x32_bf16 v[116:119], v[170:173], v[186:189], v[116:119]
	v_mfma_f32_16x16x32_bf16 v[112:115], v[178:181], v[186:189], v[112:115]
	v_mfma_f32_16x16x32_bf16 v[100:103], v[170:173], v[194:197], v[100:103]
	v_mfma_f32_16x16x32_bf16 v[96:99], v[178:181], v[194:197], v[96:99]
	v_mfma_f32_16x16x32_bf16 v[84:87], v[170:173], v[202:205], v[84:87]
	v_mfma_f32_16x16x32_bf16 v[80:83], v[178:181], v[202:205], v[80:83]
	v_mfma_f32_16x16x32_bf16 v[68:71], v[170:173], v[210:213], v[68:71]
	v_mfma_f32_16x16x32_bf16 v[64:67], v[178:181], v[210:213], v[64:67]
	v_mfma_f32_16x16x32_bf16 v[116:119], v[174:177], v[190:193], v[116:119]
	v_mfma_f32_16x16x32_bf16 v[112:115], v[182:185], v[190:193], v[112:115]
	v_mfma_f32_16x16x32_bf16 v[100:103], v[174:177], v[198:201], v[100:103]
	v_mfma_f32_16x16x32_bf16 v[96:99], v[182:185], v[198:201], v[96:99]
	v_mfma_f32_16x16x32_bf16 v[84:87], v[174:177], v[206:209], v[84:87]
	v_mfma_f32_16x16x32_bf16 v[80:83], v[182:185], v[206:209], v[80:83]
	v_mfma_f32_16x16x32_bf16 v[68:71], v[174:177], v[214:217], v[68:71]
	v_mfma_f32_16x16x32_bf16 v[64:67], v[182:185], v[214:217], v[64:67]
	s_barrier
	s_mov_b32 m0, s71
	v_lshl_add_u64 v[140:141], v[140:141], 0, s[60:61]
	s_add_u32 s80, s80, 0x80080
	ds_read_b128 v[186:189], v151 offset:49152
	ds_read_b128 v[190:193], v151 offset:50176
	ds_read_b128 v[194:197], v151 offset:51200
	ds_read_b128 v[198:201], v151 offset:52224
	ds_read_b128 v[202:205], v151 offset:53248
	ds_read_b128 v[206:209], v151 offset:54272
	ds_read_b128 v[210:213], v151 offset:55296
	ds_read_b128 v[214:217], v151 offset:56320
	global_load_lds_dwordx4 v[140:141], off
	v_lshl_add_u64 v[140:141], v[142:143], 0, s[60:61]
	s_mov_b32 m0, s77
	s_addc_u32 s81, s81, 0
	global_load_lds_dwordx4 v[140:141], off
	v_lshl_add_u64 v[140:141], s[80:81], 0, v[128:129]
	s_mov_b32 m0, s88
	s_nop 0
	global_load_lds_dwordx4 v[140:141], off
	v_lshl_add_u64 v[140:141], s[80:81], 0, v[130:131]
	s_mov_b32 m0, s89
	s_nop 0
	global_load_lds_dwordx4 v[140:141], off
	v_lshl_add_u64 v[140:141], v[146:147], 0, s[60:61]
	s_mov_b32 m0, s43
	s_nop 0
	global_load_lds_dwordx4 v[140:141], off
	v_lshl_add_u64 v[140:141], v[218:219], 0, s[60:61]
	s_mov_b32 m0, s44
	s_nop 0
	global_load_lds_dwordx4 v[140:141], off
	s_waitcnt vmcnt(8) lgkmcnt(0)
	s_barrier
	v_mfma_f32_16x16x32_bf16 v[60:63], v[154:157], v[186:189], v[60:63]
	v_mfma_f32_16x16x32_bf16 v[56:59], v[162:165], v[186:189], v[56:59]
	v_mfma_f32_16x16x32_bf16 v[44:47], v[154:157], v[194:197], v[44:47]
	v_mfma_f32_16x16x32_bf16 v[40:43], v[162:165], v[194:197], v[40:43]
	v_mfma_f32_16x16x32_bf16 v[28:31], v[154:157], v[202:205], v[28:31]
	v_mfma_f32_16x16x32_bf16 v[24:27], v[162:165], v[202:205], v[24:27]
	v_mfma_f32_16x16x32_bf16 v[12:15], v[154:157], v[210:213], v[12:15]
	v_mfma_f32_16x16x32_bf16 v[8:11], v[162:165], v[210:213], v[8:11]
	v_mfma_f32_16x16x32_bf16 v[60:63], v[158:161], v[190:193], v[60:63]
	v_mfma_f32_16x16x32_bf16 v[56:59], v[166:169], v[190:193], v[56:59]
	v_mfma_f32_16x16x32_bf16 v[44:47], v[158:161], v[198:201], v[44:47]
	v_mfma_f32_16x16x32_bf16 v[40:43], v[166:169], v[198:201], v[40:43]
	v_mfma_f32_16x16x32_bf16 v[28:31], v[158:161], v[206:209], v[28:31]
	v_mfma_f32_16x16x32_bf16 v[24:27], v[166:169], v[206:209], v[24:27]
	v_mfma_f32_16x16x32_bf16 v[12:15], v[158:161], v[214:217], v[12:15]
	v_mfma_f32_16x16x32_bf16 v[8:11], v[166:169], v[214:217], v[8:11]
	v_mfma_f32_16x16x32_bf16 v[52:55], v[170:173], v[186:189], v[52:55]
	v_mfma_f32_16x16x32_bf16 v[48:51], v[178:181], v[186:189], v[48:51]
	v_mfma_f32_16x16x32_bf16 v[36:39], v[170:173], v[194:197], v[36:39]
	v_mfma_f32_16x16x32_bf16 v[32:35], v[178:181], v[194:197], v[32:35]
	v_mfma_f32_16x16x32_bf16 v[20:23], v[170:173], v[202:205], v[20:23]
	v_mfma_f32_16x16x32_bf16 v[16:19], v[178:181], v[202:205], v[16:19]
	v_mfma_f32_16x16x32_bf16 v[4:7], v[170:173], v[210:213], v[4:7]
	v_mfma_f32_16x16x32_bf16 v[0:3], v[178:181], v[210:213], v[0:3]
	v_mfma_f32_16x16x32_bf16 v[52:55], v[174:177], v[190:193], v[52:55]
	v_mfma_f32_16x16x32_bf16 v[48:51], v[182:185], v[190:193], v[48:51]
	v_mfma_f32_16x16x32_bf16 v[36:39], v[174:177], v[198:201], v[36:39]
	v_mfma_f32_16x16x32_bf16 v[32:35], v[182:185], v[198:201], v[32:35]
	v_mfma_f32_16x16x32_bf16 v[20:23], v[174:177], v[206:209], v[20:23]
	v_mfma_f32_16x16x32_bf16 v[16:19], v[182:185], v[206:209], v[16:19]
	v_mfma_f32_16x16x32_bf16 v[4:7], v[174:177], v[214:217], v[4:7]
	v_mfma_f32_16x16x32_bf16 v[0:3], v[182:185], v[214:217], v[0:3]
	s_barrier
	s_add_i32 s91, s91, 2
	s_add_u32 s90, s90, 0x100
	s_addc_u32 s85, s85, 0
	s_add_u32 s78, s78, 0x100
	s_addc_u32 s79, s79, 0
	s_cmp_gt_u32 s91, 29
	s_cbranch_scc0 .LBB0_1619
	s_and_b64 vcc, exec, s[62:63]
	s_cbranch_vccz .LBB0_1622
	s_barrier

; template <class Epi, class Sched, bool ALIGN_EPI = false, bool SP2 = false, bool A_TILED = false>
; __device__ __forceinline__ void gemm_phase(PG8_LAS unsigned char* lds, const Gemm g, const Sched& S, const Epi& E, const int wave_s) {
;     ...
;             const bool last = (t == nt - 2);
;             const char* a1 = cA + (size_t)(t + 1) * kstepA;
;             const char* a2 = last ? nA : cA + (size_t)(t + 2) * kstepA; const char* b2 = last ? nB : cB + (size_t)(t + 2) * kstep;
;             const char* a3 = a2 + kstepA; const char* b3 = b2 + kstep;
.LBB0_1841:
	ds_read_b128 v[146:149], v140
	ds_read_b128 v[150:153], v140 offset:1024
	ds_read_b128 v[154:157], v140 offset:2048
	ds_read_b128 v[158:161], v140 offset:3072
	ds_read_b128 v[162:165], v141
	ds_read_b128 v[166:169], v141 offset:1024
	ds_read_b128 v[170:173], v141 offset:2048
	ds_read_b128 v[174:177], v141 offset:3072
	s_add_u32 s52, s60, s39
	s_addc_u32 s53, s61, s40
	s_add_u32 s54, s60, s37
	s_addc_u32 s55, s61, s38
	s_cmp_eq_u32 s41, 28
	s_cselect_b32 s71, s7, s53
	s_cselect_b32 s70, s6, s52
	s_cselect_b32 s69, s3, s55
	s_cselect_b32 s68, s2, s54
	s_mov_b32 m0, s42
	v_lshl_add_u64 v[210:211], s[60:61], 0, v[138:139]
	ds_read_b128 v[178:181], v142
	ds_read_b128 v[182:185], v142 offset:1024
	ds_read_b128 v[186:189], v142 offset:2048
	ds_read_b128 v[190:193], v142 offset:3072
	ds_read_b128 v[194:197], v142 offset:4096
	ds_read_b128 v[198:201], v142 offset:5120
	ds_read_b128 v[202:205], v142 offset:6144
	ds_read_b128 v[206:209], v142 offset:7168
	global_load_lds_dwordx4 v[210:211], off
	v_lshl_add_u64 v[210:211], s[60:61], 0, v[136:137]
	s_mov_b32 m0, s43
	s_nop 0
	global_load_lds_dwordx4 v[210:211], off
	s_waitcnt vmcnt(8) lgkmcnt(0)
	s_barrier
	v_mfma_f32_16x16x32_bf16 v[8:11], v[146:149], v[178:181], v[8:11]
	v_mfma_f32_16x16x32_bf16 v[12:15], v[154:157], v[178:181], v[12:15]
	v_mfma_f32_16x16x32_bf16 v[60:63], v[146:149], v[186:189], v[60:63]
	v_mfma_f32_16x16x32_bf16 v[20:23], v[154:157], v[186:189], v[20:23]
	v_mfma_f32_16x16x32_bf16 v[76:79], v[146:149], v[194:197], v[76:79]
	v_mfma_f32_16x16x32_bf16 v[52:55], v[154:157], v[194:197], v[52:55]
	v_mfma_f32_16x16x32_bf16 v[128:131], v[146:149], v[202:205], v[128:131]
	v_mfma_f32_16x16x32_bf16 v[68:71], v[154:157], v[202:205], v[68:71]
	v_mfma_f32_16x16x32_bf16 v[8:11], v[150:153], v[182:185], v[8:11]
	v_mfma_f32_16x16x32_bf16 v[12:15], v[158:161], v[182:185], v[12:15]
	v_mfma_f32_16x16x32_bf16 v[60:63], v[150:153], v[190:193], v[60:63]
	v_mfma_f32_16x16x32_bf16 v[20:23], v[158:161], v[190:193], v[20:23]
	v_mfma_f32_16x16x32_bf16 v[76:79], v[150:153], v[198:201], v[76:79]
	v_mfma_f32_16x16x32_bf16 v[52:55], v[158:161], v[198:201], v[52:55]
	v_mfma_f32_16x16x32_bf16 v[128:131], v[150:153], v[206:209], v[128:131]
	v_mfma_f32_16x16x32_bf16 v[68:71], v[158:161], v[206:209], v[68:71]
	v_mfma_f32_16x16x32_bf16 v[24:27], v[162:165], v[178:181], v[24:27]
	v_mfma_f32_16x16x32_bf16 v[16:19], v[170:173], v[178:181], v[16:19]
	v_mfma_f32_16x16x32_bf16 v[56:59], v[162:165], v[186:189], v[56:59]
	v_mfma_f32_16x16x32_bf16 v[48:51], v[170:173], v[186:189], v[48:51]
	v_mfma_f32_16x16x32_bf16 v[72:75], v[162:165], v[194:197], v[72:75]
	v_mfma_f32_16x16x32_bf16 v[64:67], v[170:173], v[194:197], v[64:67]
	v_mfma_f32_16x16x32_bf16 v[108:111], v[162:165], v[202:205], v[108:111]
	v_mfma_f32_16x16x32_bf16 v[96:99], v[170:173], v[202:205], v[96:99]
	v_mfma_f32_16x16x32_bf16 v[24:27], v[166:169], v[182:185], v[24:27]
	v_mfma_f32_16x16x32_bf16 v[16:19], v[174:177], v[182:185], v[16:19]
	v_mfma_f32_16x16x32_bf16 v[56:59], v[166:169], v[190:193], v[56:59]
	v_mfma_f32_16x16x32_bf16 v[48:51], v[174:177], v[190:193], v[48:51]
	v_mfma_f32_16x16x32_bf16 v[72:75], v[166:169], v[198:201], v[72:75]
	v_mfma_f32_16x16x32_bf16 v[64:67], v[174:177], v[198:201], v[64:67]
	v_mfma_f32_16x16x32_bf16 v[108:111], v[166:169], v[206:209], v[108:111]
	v_mfma_f32_16x16x32_bf16 v[96:99], v[174:177], v[206:209], v[96:99]
	s_barrier
	s_mov_b32 m0, s44
	v_lshl_add_u64 v[210:211], s[68:69], 0, v[34:35]
	s_add_u32 s52, s68, 0x80000
	ds_read_b128 v[178:181], v142 offset:16384
	ds_read_b128 v[182:185], v142 offset:17408
	ds_read_b128 v[186:189], v142 offset:18432
	ds_read_b128 v[190:193], v142 offset:19456
	ds_read_b128 v[194:197], v142 offset:20480
	ds_read_b128 v[198:201], v142 offset:21504
	ds_read_b128 v[202:205], v142 offset:22528
	ds_read_b128 v[206:209], v142 offset:23552
	global_load_lds_dwordx4 v[210:211], off
	v_lshl_add_u64 v[212:213], s[68:69], 0, v[134:135]
	s_mov_b32 m0, s45
	s_addc_u32 s53, s69, 0
	global_load_lds_dwordx4 v[212:213], off
	v_lshl_add_u64 v[214:215], s[52:53], 0, v[34:35]
	s_mov_b32 m0, s46
	v_lshl_add_u64 v[216:217], s[70:71], 0, v[132:133]
	global_load_lds_dwordx4 v[214:215], off
	v_lshl_add_u64 v[214:215], s[52:53], 0, v[134:135]
	s_mov_b32 m0, s47
	s_nop 0
	global_load_lds_dwordx4 v[214:215], off
	v_lshl_add_u64 v[214:215], s[70:71], 0, v[32:33]
	s_mov_b32 m0, s14
	s_nop 0
	global_load_lds_dwordx4 v[214:215], off
	s_mov_b32 m0, s15
	s_nop 0
	global_load_lds_dwordx4 v[216:217], off
	s_waitcnt vmcnt(8) lgkmcnt(0)
	s_barrier
	v_mfma_f32_16x16x32_bf16 v[100:103], v[146:149], v[178:181], v[100:103]
	v_mfma_f32_16x16x32_bf16 v[104:107], v[154:157], v[178:181], v[104:107]
	v_mfma_f32_16x16x32_bf16 v[116:119], v[146:149], v[186:189], v[116:119]
	v_mfma_f32_16x16x32_bf16 v[120:123], v[154:157], v[186:189], v[120:123]
	v_mfma_f32_16x16x32_bf16 v[84:87], v[146:149], v[194:197], v[84:87]
	v_mfma_f32_16x16x32_bf16 v[80:83], v[154:157], v[194:197], v[80:83]
	v_mfma_f32_16x16x32_bf16 v[36:39], v[146:149], v[202:205], v[36:39]
	v_mfma_f32_16x16x32_bf16 v[28:31], v[154:157], v[202:205], v[28:31]
	v_mfma_f32_16x16x32_bf16 v[100:103], v[150:153], v[182:185], v[100:103]
	v_mfma_f32_16x16x32_bf16 v[104:107], v[158:161], v[182:185], v[104:107]
	v_mfma_f32_16x16x32_bf16 v[116:119], v[150:153], v[190:193], v[116:119]
	v_mfma_f32_16x16x32_bf16 v[120:123], v[158:161], v[190:193], v[120:123]
	v_mfma_f32_16x16x32_bf16 v[84:87], v[150:153], v[198:201], v[84:87]
	v_mfma_f32_16x16x32_bf16 v[80:83], v[158:161], v[198:201], v[80:83]
	v_mfma_f32_16x16x32_bf16 v[36:39], v[150:153], v[206:209], v[36:39]
	v_mfma_f32_16x16x32_bf16 v[28:31], v[158:161], v[206:209], v[28:31]
	v_mfma_f32_16x16x32_bf16 v[124:127], v[162:165], v[178:181], v[124:127]
	v_mfma_f32_16x16x32_bf16 v[112:115], v[170:173], v[178:181], v[112:115]
	v_mfma_f32_16x16x32_bf16 v[92:95], v[162:165], v[186:189], v[92:95]
	v_mfma_f32_16x16x32_bf16 v[88:91], v[170:173], v[186:189], v[88:91]
	v_mfma_f32_16x16x32_bf16 v[44:47], v[162:165], v[194:197], v[44:47]
	v_mfma_f32_16x16x32_bf16 v[40:43], v[170:173], v[194:197], v[40:43]
	v_mfma_f32_16x16x32_bf16 v[4:7], v[162:165], v[202:205], v[4:7]
	v_mfma_f32_16x16x32_bf16 v[0:3], v[170:173], v[202:205], v[0:3]
	v_mfma_f32_16x16x32_bf16 v[124:127], v[166:169], v[182:185], v[124:127]
	v_mfma_f32_16x16x32_bf16 v[112:115], v[174:177], v[182:185], v[112:115]
	v_mfma_f32_16x16x32_bf16 v[92:95], v[166:169], v[190:193], v[92:95]
	v_mfma_f32_16x16x32_bf16 v[88:91], v[174:177], v[190:193], v[88:91]
	v_mfma_f32_16x16x32_bf16 v[44:47], v[166:169], v[198:201], v[44:47]
	v_mfma_f32_16x16x32_bf16 v[40:43], v[174:177], v[198:201], v[40:43]
	v_mfma_f32_16x16x32_bf16 v[4:7], v[166:169], v[206:209], v[4:7]
	v_mfma_f32_16x16x32_bf16 v[0:3], v[174:177], v[206:209], v[0:3]
	s_barrier
	ds_read_b128 v[146:149], v143
	ds_read_b128 v[150:153], v143 offset:1024
	ds_read_b128 v[154:157], v143 offset:2048
	ds_read_b128 v[158:161], v143 offset:3072
	ds_read_b128 v[162:165], v144
	ds_read_b128 v[166:169], v144 offset:1024
	ds_read_b128 v[170:173], v144 offset:2048
	ds_read_b128 v[174:177], v144 offset:3072
	s_add_u32 s52, s70, 0x80000
	s_addc_u32 s53, s71, 0
	s_mov_b32 m0, s21
	v_lshl_add_u64 v[218:219], s[52:53], 0, v[32:33]
	ds_read_b128 v[178:181], v142 offset:32768
	ds_read_b128 v[182:185], v142 offset:33792
	ds_read_b128 v[186:189], v142 offset:34816
	ds_read_b128 v[190:193], v142 offset:35840
	ds_read_b128 v[194:197], v142 offset:36864
	ds_read_b128 v[198:201], v142 offset:37888
	ds_read_b128 v[202:205], v142 offset:38912
	ds_read_b128 v[206:209], v142 offset:39936
	global_load_lds_dwordx4 v[218:219], off
	v_lshl_add_u64 v[218:219], s[52:53], 0, v[132:133]
	s_mov_b32 m0, s22
	s_nop 0
	global_load_lds_dwordx4 v[218:219], off
	s_waitcnt vmcnt(8) lgkmcnt(0)
	s_barrier
	v_mfma_f32_16x16x32_bf16 v[8:11], v[146:149], v[178:181], v[8:11]
	v_mfma_f32_16x16x32_bf16 v[12:15], v[154:157], v[178:181], v[12:15]
	v_mfma_f32_16x16x32_bf16 v[60:63], v[146:149], v[186:189], v[60:63]
	v_mfma_f32_16x16x32_bf16 v[20:23], v[154:157], v[186:189], v[20:23]
	v_mfma_f32_16x16x32_bf16 v[76:79], v[146:149], v[194:197], v[76:79]
	v_mfma_f32_16x16x32_bf16 v[52:55], v[154:157], v[194:197], v[52:55]
	v_mfma_f32_16x16x32_bf16 v[128:131], v[146:149], v[202:205], v[128:131]
	v_mfma_f32_16x16x32_bf16 v[68:71], v[154:157], v[202:205], v[68:71]
	v_mfma_f32_16x16x32_bf16 v[8:11], v[150:153], v[182:185], v[8:11]
	v_mfma_f32_16x16x32_bf16 v[12:15], v[158:161], v[182:185], v[12:15]
	v_mfma_f32_16x16x32_bf16 v[60:63], v[150:153], v[190:193], v[60:63]
	v_mfma_f32_16x16x32_bf16 v[20:23], v[158:161], v[190:193], v[20:23]
	v_mfma_f32_16x16x32_bf16 v[76:79], v[150:153], v[198:201], v[76:79]
	v_mfma_f32_16x16x32_bf16 v[52:55], v[158:161], v[198:201], v[52:55]
	v_mfma_f32_16x16x32_bf16 v[128:131], v[150:153], v[206:209], v[128:131]
	v_mfma_f32_16x16x32_bf16 v[68:71], v[158:161], v[206:209], v[68:71]
	v_mfma_f32_16x16x32_bf16 v[24:27], v[162:165], v[178:181], v[24:27]
	v_mfma_f32_16x16x32_bf16 v[16:19], v[170:173], v[178:181], v[16:19]
	v_mfma_f32_16x16x32_bf16 v[56:59], v[162:165], v[186:189], v[56:59]
	v_mfma_f32_16x16x32_bf16 v[48:51], v[170:173], v[186:189], v[48:51]
	v_mfma_f32_16x16x32_bf16 v[72:75], v[162:165], v[194:197], v[72:75]
	v_mfma_f32_16x16x32_bf16 v[64:67], v[170:173], v[194:197], v[64:67]
	v_mfma_f32_16x16x32_bf16 v[108:111], v[162:165], v[202:205], v[108:111]
	v_mfma_f32_16x16x32_bf16 v[96:99], v[170:173], v[202:205], v[96:99]
	v_mfma_f32_16x16x32_bf16 v[24:27], v[166:169], v[182:185], v[24:27]
	v_mfma_f32_16x16x32_bf16 v[16:19], v[174:177], v[182:185], v[16:19]
	v_mfma_f32_16x16x32_bf16 v[56:59], v[166:169], v[190:193], v[56:59]
	v_mfma_f32_16x16x32_bf16 v[48:51], v[174:177], v[190:193], v[48:51]
	v_mfma_f32_16x16x32_bf16 v[72:75], v[166:169], v[198:201], v[72:75]
	v_mfma_f32_16x16x32_bf16 v[64:67], v[174:177], v[198:201], v[64:67]
	v_mfma_f32_16x16x32_bf16 v[108:111], v[166:169], v[206:209], v[108:111]
	v_mfma_f32_16x16x32_bf16 v[96:99], v[174:177], v[206:209], v[96:99]
	s_barrier
; #define PG8_WAIT_V(n) asm volatile("s_waitcnt vmcnt(" #n ")" ::: "memory")
; #define PG8_BAR __builtin_amdgcn_s_barrier()
; template <class Epi, class Sched, bool ALIGN_EPI = false, bool SP2 = false, bool A_TILED = false>
; __device__ __forceinline__ void gemm_phase(PG8_LAS unsigned char* lds, const Gemm g, const Sched& S, const Epi& E, const int wave_s) {
;     ...
;     PG8_WAIT_V(0);
;     if constexpr (!ALIGN_EPI) { if (wr == 0) PG8_BAR; }
	s_mov_b32 m0, s48
	v_lshl_add_u64 v[210:211], v[210:211], 0, s[64:65]
	s_add_u32 s52, s68, 0x80080
	ds_read_b128 v[178:181], v142 offset:49152
	ds_read_b128 v[182:185], v142 offset:50176
	ds_read_b128 v[186:189], v142 offset:51200
	ds_read_b128 v[190:193], v142 offset:52224
	ds_read_b128 v[194:197], v142 offset:53248
	ds_read_b128 v[198:201], v142 offset:54272
	ds_read_b128 v[202:205], v142 offset:55296
	ds_read_b128 v[206:209], v142 offset:56320
	global_load_lds_dwordx4 v[210:211], off
	v_lshl_add_u64 v[210:211], v[212:213], 0, s[64:65]
	s_mov_b32 m0, s49
	s_addc_u32 s53, s69, 0
	global_load_lds_dwordx4 v[210:211], off
	v_lshl_add_u64 v[210:211], s[52:53], 0, v[34:35]
	s_mov_b32 m0, s50
	s_nop 0
	global_load_lds_dwordx4 v[210:211], off
	v_lshl_add_u64 v[210:211], s[52:53], 0, v[134:135]
	s_mov_b32 m0, s51
	s_nop 0
	global_load_lds_dwordx4 v[210:211], off
	v_lshl_add_u64 v[210:211], v[214:215], 0, s[64:65]
	s_mov_b32 m0, s23
	s_nop 0
	global_load_lds_dwordx4 v[210:211], off
	v_lshl_add_u64 v[210:211], v[216:217], 0, s[64:65]
	s_mov_b32 m0, s36
	s_nop 0
	global_load_lds_dwordx4 v[210:211], off
	s_waitcnt vmcnt(8) lgkmcnt(0)
	s_barrier
	v_mfma_f32_16x16x32_bf16 v[100:103], v[146:149], v[178:181], v[100:103]
	v_mfma_f32_16x16x32_bf16 v[104:107], v[154:157], v[178:181], v[104:107]
	v_mfma_f32_16x16x32_bf16 v[116:119], v[146:149], v[186:189], v[116:119]
	v_mfma_f32_16x16x32_bf16 v[120:123], v[154:157], v[186:189], v[120:123]
	v_mfma_f32_16x16x32_bf16 v[84:87], v[146:149], v[194:197], v[84:87]
	v_mfma_f32_16x16x32_bf16 v[80:83], v[154:157], v[194:197], v[80:83]
	v_mfma_f32_16x16x32_bf16 v[36:39], v[146:149], v[202:205], v[36:39]
	v_mfma_f32_16x16x32_bf16 v[28:31], v[154:157], v[202:205], v[28:31]
	v_mfma_f32_16x16x32_bf16 v[100:103], v[150:153], v[182:185], v[100:103]
	v_mfma_f32_16x16x32_bf16 v[104:107], v[158:161], v[182:185], v[104:107]
	v_mfma_f32_16x16x32_bf16 v[116:119], v[150:153], v[190:193], v[116:119]
	v_mfma_f32_16x16x32_bf16 v[120:123], v[158:161], v[190:193], v[120:123]
	v_mfma_f32_16x16x32_bf16 v[84:87], v[150:153], v[198:201], v[84:87]
	v_mfma_f32_16x16x32_bf16 v[80:83], v[158:161], v[198:201], v[80:83]
	v_mfma_f32_16x16x32_bf16 v[36:39], v[150:153], v[206:209], v[36:39]
	v_mfma_f32_16x16x32_bf16 v[28:31], v[158:161], v[206:209], v[28:31]
	v_mfma_f32_16x16x32_bf16 v[124:127], v[162:165], v[178:181], v[124:127]
	v_mfma_f32_16x16x32_bf16 v[112:115], v[170:173], v[178:181], v[112:115]
	v_mfma_f32_16x16x32_bf16 v[92:95], v[162:165], v[186:189], v[92:95]
	v_mfma_f32_16x16x32_bf16 v[88:91], v[170:173], v[186:189], v[88:91]
	v_mfma_f32_16x16x32_bf16 v[44:47], v[162:165], v[194:197], v[44:47]
	v_mfma_f32_16x16x32_bf16 v[40:43], v[170:173], v[194:197], v[40:43]
	v_mfma_f32_16x16x32_bf16 v[4:7], v[162:165], v[202:205], v[4:7]
	v_mfma_f32_16x16x32_bf16 v[0:3], v[170:173], v[202:205], v[0:3]
	v_mfma_f32_16x16x32_bf16 v[124:127], v[166:169], v[182:185], v[124:127]
	v_mfma_f32_16x16x32_bf16 v[112:115], v[174:177], v[182:185], v[112:115]
	v_mfma_f32_16x16x32_bf16 v[92:95], v[166:169], v[190:193], v[92:95]
	v_mfma_f32_16x16x32_bf16 v[88:91], v[174:177], v[190:193], v[88:91]
	v_mfma_f32_16x16x32_bf16 v[44:47], v[166:169], v[198:201], v[44:47]
	v_mfma_f32_16x16x32_bf16 v[40:43], v[174:177], v[198:201], v[40:43]
	v_mfma_f32_16x16x32_bf16 v[4:7], v[166:169], v[206:209], v[4:7]
	v_mfma_f32_16x16x32_bf16 v[0:3], v[174:177], v[206:209], v[0:3]
	s_barrier
	s_add_i32 s41, s41, 2
	s_add_u32 s37, s37, 0x100
	s_addc_u32 s38, s38, 0
	s_add_u32 s39, s39, 0x100
	s_addc_u32 s40, s40, 0
	v_lshl_add_u64 v[136:137], v[136:137], 0, s[66:67]
	s_cmp_gt_u32 s41, 29
	v_lshl_add_u64 v[138:139], v[138:139], 0, s[66:67]
	s_cbranch_scc0 .LBB0_1841
	s_waitcnt vmcnt(0)
	s_cmpk_lt_u32 s0, 0x100
	s_cbranch_scc0 .LBB0_1844
	s_barrier

; template <class Epi, class Sched, bool ALIGN_EPI = false, bool SP2 = false, bool A_TILED = false>
; __device__ __forceinline__ void gemm_phase(PG8_LAS unsigned char* lds, const Gemm g, const Sched& S, const Epi& E, const int wave_s) {
;     ...
;         const char* nA = has_next ? (const char*)g.A + (size_t)nxt.pm * tstepA : cA; const char* nB = has_next ? (const char*)g.Bt + (size_t)nxt.pn * tstep : cB;
;         constexpr bool PEEL = SP2 && !Epi::AFTER_DRAIN;
;         if constexpr (PEEL) {
;             const char* a1 = cA + kstepA; const char* a2 = cA + 2 * kstepA; const char* b2 = cB + 2 * kstep; const char* a3 = a2 + kstepA; const char* b3 = b2 + kstep;
;             PG8_ITER(PG8_MMAZ)
.LBB0_1952:
	s_ashr_i32 s69, s68, 31
	s_lshl_b64 s[50:51], s[68:69], 20
	s_add_u32 s70, s1, s50
	ds_read_b128 v[0:3], v145
	ds_read_b128 v[4:7], v145 offset:1024
	ds_read_b128 v[8:11], v145 offset:2048
	ds_read_b128 v[12:15], v145 offset:3072
	ds_read_b128 v[16:19], v146
	ds_read_b128 v[20:23], v146 offset:1024
	ds_read_b128 v[24:27], v146 offset:2048
	ds_read_b128 v[28:31], v146 offset:3072
	s_addc_u32 s71, s8, s51
	s_ashr_i32 s67, s66, 31
	s_lshl_b64 s[50:51], s[66:67], 20
	s_add_u32 s72, s9, s50
	s_addc_u32 s73, s14, s51
	s_and_b64 s[50:51], s[2:3], exec
	s_cselect_b32 s50, s71, s79
	s_cselect_b32 s51, s70, s78
	s_cselect_b32 s52, s73, s77
	s_cselect_b32 s53, s72, s76
	s_add_u32 s56, s78, 0x80080
	s_addc_u32 s57, s79, 0
	s_add_i32 s54, s22, 0xc000
	v_lshl_add_u64 v[64:65], s[56:57], 0, v[134:135]
	s_mov_b32 m0, s54
	s_add_i32 s55, s22, 0xe000
	ds_read_b128 v[32:35], v147
	ds_read_b128 v[36:39], v147 offset:1024
	ds_read_b128 v[40:43], v147 offset:2048
	ds_read_b128 v[44:47], v147 offset:3072
	ds_read_b128 v[48:51], v147 offset:4096
	ds_read_b128 v[52:55], v147 offset:5120
	ds_read_b128 v[56:59], v147 offset:6144
	ds_read_b128 v[60:63], v147 offset:7168
	global_load_lds_dwordx4 v[64:65], off
	v_lshl_add_u64 v[64:65], s[56:57], 0, v[132:133]
	s_mov_b32 m0, s55
	s_nop 0
	global_load_lds_dwordx4 v[64:65], off
	s_waitcnt vmcnt(8) lgkmcnt(0)
	s_barrier
	v_mfma_f32_16x16x32_bf16 v[88:91], v[0:3], v[56:59], 0
	v_mfma_f32_16x16x32_bf16 v[64:67], v[0:3], v[32:35], 0
	v_mfma_f32_16x16x32_bf16 v[68:71], v[8:11], v[32:35], 0
	v_mfma_f32_16x16x32_bf16 v[72:75], v[0:3], v[40:43], 0
	v_mfma_f32_16x16x32_bf16 v[76:79], v[8:11], v[40:43], 0
	v_mfma_f32_16x16x32_bf16 v[80:83], v[0:3], v[48:51], 0
	v_mfma_f32_16x16x32_bf16 v[84:87], v[8:11], v[48:51], 0
	v_mfma_f32_16x16x32_bf16 v[96:99], v[4:7], v[60:63], v[88:91]
	v_mfma_f32_16x16x32_bf16 v[88:91], v[8:11], v[56:59], 0
	v_mfma_f32_16x16x32_bf16 v[64:67], v[4:7], v[36:39], v[64:67]
	v_mfma_f32_16x16x32_bf16 v[68:71], v[12:15], v[36:39], v[68:71]
	v_mfma_f32_16x16x32_bf16 v[72:75], v[4:7], v[44:47], v[72:75]
	v_mfma_f32_16x16x32_bf16 v[76:79], v[12:15], v[44:47], v[76:79]
	v_mfma_f32_16x16x32_bf16 v[80:83], v[4:7], v[52:55], v[80:83]
	v_mfma_f32_16x16x32_bf16 v[84:87], v[12:15], v[52:55], v[84:87]
	v_mfma_f32_16x16x32_bf16 v[100:103], v[12:15], v[60:63], v[88:91]
	v_mfma_f32_16x16x32_bf16 v[88:91], v[16:19], v[32:35], 0
	v_mfma_f32_16x16x32_bf16 v[32:35], v[24:27], v[32:35], 0
	v_mfma_f32_16x16x32_bf16 v[112:115], v[20:23], v[36:39], v[88:91]
	v_mfma_f32_16x16x32_bf16 v[32:35], v[28:31], v[36:39], v[32:35]
	v_mfma_f32_16x16x32_bf16 v[36:39], v[16:19], v[40:43], 0
	v_mfma_f32_16x16x32_bf16 v[40:43], v[24:27], v[40:43], 0
	v_mfma_f32_16x16x32_bf16 v[36:39], v[20:23], v[44:47], v[36:39]
	v_mfma_f32_16x16x32_bf16 v[40:43], v[28:31], v[44:47], v[40:43]
	v_mfma_f32_16x16x32_bf16 v[44:47], v[16:19], v[48:51], 0
	v_mfma_f32_16x16x32_bf16 v[48:51], v[24:27], v[48:51], 0
	v_mfma_f32_16x16x32_bf16 v[44:47], v[20:23], v[52:55], v[44:47]
	v_mfma_f32_16x16x32_bf16 v[48:51], v[28:31], v[52:55], v[48:51]
	v_mfma_f32_16x16x32_bf16 v[52:55], v[16:19], v[56:59], 0
	v_mfma_f32_16x16x32_bf16 v[56:59], v[24:27], v[56:59], 0
	v_mfma_f32_16x16x32_bf16 v[52:55], v[20:23], v[60:63], v[52:55]
	v_mfma_f32_16x16x32_bf16 v[56:59], v[28:31], v[60:63], v[56:59]
	s_barrier
	s_add_i32 s56, s47, s15
	v_lshl_add_u64 v[242:243], s[76:77], 0, v[128:129]
	s_add_i32 s57, s56, 0x2000
	v_lshl_add_u64 v[148:149], v[242:243], 0, s[62:63]
	s_mov_b32 m0, s56
	v_lshl_add_u64 v[244:245], s[76:77], 0, v[130:131]
	s_add_u32 s80, s76, 0x80100
	ds_read_b128 v[60:63], v147 offset:16384
	ds_read_b128 v[88:91], v147 offset:17408
	ds_read_b128 v[92:95], v147 offset:18432
	ds_read_b128 v[104:107], v147 offset:19456
	ds_read_b128 v[108:111], v147 offset:20480
	ds_read_b128 v[116:119], v147 offset:21504
	ds_read_b128 v[120:123], v147 offset:22528
	ds_read_b128 v[124:127], v147 offset:23552
	global_load_lds_dwordx4 v[148:149], off
	v_lshl_add_u64 v[148:149], v[244:245], 0, s[62:63]
	s_mov_b32 m0, s57
	s_addc_u32 s81, s77, 0
	s_add_i32 s58, s48, s15
	global_load_lds_dwordx4 v[148:149], off
	v_lshl_add_u64 v[148:149], s[80:81], 0, v[128:129]
	s_mov_b32 m0, s58
	s_add_i32 s59, s58, 0x2000
	global_load_lds_dwordx4 v[148:149], off
	v_lshl_add_u64 v[148:149], s[80:81], 0, v[130:131]
	s_mov_b32 m0, s59
	v_lshl_add_u64 v[246:247], s[78:79], 0, v[134:135]
	global_load_lds_dwordx4 v[148:149], off
	v_lshl_add_u64 v[148:149], v[246:247], 0, s[62:63]
	s_mov_b32 m0, s22
	v_lshl_add_u64 v[248:249], s[78:79], 0, v[132:133]
	global_load_lds_dwordx4 v[148:149], off
	v_lshl_add_u64 v[148:149], v[248:249], 0, s[62:63]
	s_mov_b32 m0, s23
	s_nop 0
	global_load_lds_dwordx4 v[148:149], off
	s_waitcnt vmcnt(8) lgkmcnt(0)
	s_barrier
	v_mfma_f32_16x16x32_bf16 v[148:151], v[0:3], v[60:63], 0
	v_mfma_f32_16x16x32_bf16 v[158:161], v[0:3], v[92:95], 0
	v_mfma_f32_16x16x32_bf16 v[166:169], v[0:3], v[108:111], 0
	v_mfma_f32_16x16x32_bf16 v[0:3], v[0:3], v[120:123], 0
	v_mfma_f32_16x16x32_bf16 v[150:153], v[4:7], v[88:91], v[148:151]
	v_mfma_f32_16x16x32_bf16 v[158:161], v[4:7], v[104:107], v[158:161]
	v_mfma_f32_16x16x32_bf16 v[166:169], v[4:7], v[116:119], v[166:169]
	v_mfma_f32_16x16x32_bf16 v[0:3], v[4:7], v[124:127], v[0:3]
	v_mfma_f32_16x16x32_bf16 v[4:7], v[8:11], v[120:123], 0
	v_mfma_f32_16x16x32_bf16 v[154:157], v[8:11], v[60:63], 0
	v_mfma_f32_16x16x32_bf16 v[162:165], v[8:11], v[92:95], 0
	v_mfma_f32_16x16x32_bf16 v[170:173], v[8:11], v[108:111], 0
	v_mfma_f32_16x16x32_bf16 v[4:7], v[12:15], v[124:127], v[4:7]
	v_mfma_f32_16x16x32_bf16 v[154:157], v[12:15], v[88:91], v[154:157]
	v_mfma_f32_16x16x32_bf16 v[162:165], v[12:15], v[104:107], v[162:165]
	v_mfma_f32_16x16x32_bf16 v[170:173], v[12:15], v[116:119], v[170:173]
	v_mfma_f32_16x16x32_bf16 v[8:11], v[16:19], v[60:63], 0
	v_mfma_f32_16x16x32_bf16 v[174:177], v[20:23], v[88:91], v[8:11]
	v_mfma_f32_16x16x32_bf16 v[8:11], v[24:27], v[60:63], 0
	v_mfma_f32_16x16x32_bf16 v[60:63], v[28:31], v[88:91], v[8:11]
	v_mfma_f32_16x16x32_bf16 v[8:11], v[16:19], v[92:95], 0
	v_mfma_f32_16x16x32_bf16 v[178:181], v[20:23], v[104:107], v[8:11]
	v_mfma_f32_16x16x32_bf16 v[8:11], v[24:27], v[92:95], 0
	v_mfma_f32_16x16x32_bf16 v[182:185], v[28:31], v[104:107], v[8:11]
	v_mfma_f32_16x16x32_bf16 v[8:11], v[16:19], v[108:111], 0
	v_mfma_f32_16x16x32_bf16 v[186:189], v[20:23], v[116:119], v[8:11]
	v_mfma_f32_16x16x32_bf16 v[8:11], v[24:27], v[108:111], 0
	v_mfma_f32_16x16x32_bf16 v[190:193], v[28:31], v[116:119], v[8:11]
	v_mfma_f32_16x16x32_bf16 v[8:11], v[16:19], v[120:123], 0
	v_mfma_f32_16x16x32_bf16 v[194:197], v[20:23], v[124:127], v[8:11]
	v_mfma_f32_16x16x32_bf16 v[8:11], v[24:27], v[120:123], 0
	v_mfma_f32_16x16x32_bf16 v[198:201], v[28:31], v[124:127], v[8:11]
	s_barrier
	s_add_i32 s67, 0, 0x18000
	s_add_i32 s75, 0, 0x1c000
	v_add_u32_e32 v148, s67, v144
	v_add_u32_e32 v149, s75, v144
	s_nop 0
	ds_read_b128 v[8:11], v148
	ds_read_b128 v[12:15], v148 offset:1024
	ds_read_b128 v[16:19], v148 offset:2048
	ds_read_b128 v[20:23], v148 offset:3072
	ds_read_b128 v[202:205], v149
	ds_read_b128 v[206:209], v149 offset:1024
	ds_read_b128 v[210:213], v149 offset:2048
	ds_read_b128 v[214:217], v149 offset:3072
	s_add_u32 s80, s78, 0x80100
	s_addc_u32 s81, s79, 0
	s_mov_b32 m0, s36
	v_lshl_add_u64 v[88:89], s[80:81], 0, v[134:135]
	ds_read_b128 v[24:27], v147 offset:32768
	ds_read_b128 v[28:31], v147 offset:33792
	ds_read_b128 v[218:221], v147 offset:34816
	ds_read_b128 v[222:225], v147 offset:35840
	ds_read_b128 v[226:229], v147 offset:36864
	ds_read_b128 v[230:233], v147 offset:37888
	ds_read_b128 v[234:237], v147 offset:38912
	ds_read_b128 v[238:241], v147 offset:39936
	global_load_lds_dwordx4 v[88:89], off
	v_lshl_add_u64 v[88:89], s[80:81], 0, v[132:133]
	s_mov_b32 m0, s37
	s_nop 0
	global_load_lds_dwordx4 v[88:89], off
	s_waitcnt vmcnt(8) lgkmcnt(0)
	s_barrier
	v_mfma_f32_16x16x32_bf16 v[64:67], v[8:11], v[24:27], v[64:67]
	v_mfma_f32_16x16x32_bf16 v[120:123], v[12:15], v[28:31], v[64:67]
	v_mfma_f32_16x16x32_bf16 v[64:67], v[16:19], v[24:27], v[68:71]
	v_mfma_f32_16x16x32_bf16 v[124:127], v[20:23], v[28:31], v[64:67]
	v_mfma_f32_16x16x32_bf16 v[64:67], v[8:11], v[218:221], v[72:75]
	v_mfma_f32_16x16x32_bf16 v[104:107], v[12:15], v[222:225], v[64:67]
	v_mfma_f32_16x16x32_bf16 v[64:67], v[16:19], v[218:221], v[76:79]
	v_mfma_f32_16x16x32_bf16 v[108:111], v[20:23], v[222:225], v[64:67]
	v_mfma_f32_16x16x32_bf16 v[64:67], v[8:11], v[226:229], v[80:83]
	v_mfma_f32_16x16x32_bf16 v[88:91], v[12:15], v[230:233], v[64:67]
	v_mfma_f32_16x16x32_bf16 v[64:67], v[16:19], v[226:229], v[84:87]
	v_mfma_f32_16x16x32_bf16 v[92:95], v[20:23], v[230:233], v[64:67]
	v_mfma_f32_16x16x32_bf16 v[64:67], v[8:11], v[234:237], v[96:99]
	v_mfma_f32_16x16x32_bf16 v[68:71], v[16:19], v[234:237], v[100:103]
	v_mfma_f32_16x16x32_bf16 v[64:67], v[12:15], v[238:241], v[64:67]
	v_mfma_f32_16x16x32_bf16 v[68:71], v[20:23], v[238:241], v[68:71]
	v_mfma_f32_16x16x32_bf16 v[72:75], v[202:205], v[24:27], v[112:115]
	v_mfma_f32_16x16x32_bf16 v[24:27], v[210:213], v[24:27], v[32:35]
	v_mfma_f32_16x16x32_bf16 v[116:119], v[214:217], v[28:31], v[24:27]
	v_mfma_f32_16x16x32_bf16 v[24:27], v[202:205], v[218:221], v[36:39]
	v_mfma_f32_16x16x32_bf16 v[96:99], v[206:209], v[222:225], v[24:27]
	v_mfma_f32_16x16x32_bf16 v[24:27], v[210:213], v[218:221], v[40:43]
	v_mfma_f32_16x16x32_bf16 v[100:103], v[214:217], v[222:225], v[24:27]
	v_mfma_f32_16x16x32_bf16 v[24:27], v[202:205], v[226:229], v[44:47]
	v_mfma_f32_16x16x32_bf16 v[80:83], v[206:209], v[230:233], v[24:27]
	v_mfma_f32_16x16x32_bf16 v[24:27], v[210:213], v[226:229], v[48:51]
	v_mfma_f32_16x16x32_bf16 v[84:87], v[214:217], v[230:233], v[24:27]
	v_mfma_f32_16x16x32_bf16 v[24:27], v[202:205], v[234:237], v[52:55]
	v_mfma_f32_16x16x32_bf16 v[48:51], v[206:209], v[238:241], v[24:27]
	v_mfma_f32_16x16x32_bf16 v[24:27], v[210:213], v[234:237], v[56:59]
	v_mfma_f32_16x16x32_bf16 v[112:115], v[206:209], v[28:31], v[72:75]
	v_mfma_f32_16x16x32_bf16 v[52:55], v[214:217], v[238:241], v[24:27]
	s_barrier
; #define PG8_MMA(ai, bj, At, Bt) do { __builtin_amdgcn_s_setprio(1); _Pragma("unroll") for (int m = 0; m < 4; ++m) _Pragma("unroll") for (int n = 0; n < 2; ++n) _Pragma("unroll") for (int k = 0; k < 2; ++k) \
;         acc[ai][bj][m][n] = __builtin_amdgcn_mfma_f32_16x16x32_bf16(Bt[n][k], At[m][k], acc[ai][bj][m][n], 0, 0, 0); __builtin_amdgcn_s_setprio(0); } while (0)
; template <class Epi, class Sched, bool ALIGN_EPI = false, bool SP2 = false, bool A_TILED = false>
; __device__ __forceinline__ void gemm_phase(PG8_LAS unsigned char* lds, const Gemm g, const Sched& S, const Epi& E, const int wave_s) {
;     ...
;         for (int t = PEEL ? 2 : 0; t < nt; t += 2) {
;             const bool last = (t == nt - 2);
;             const char* a1 = cA + (size_t)(t + 1) * kstepA;
;             const char* a2 = last ? nA : cA + (size_t)(t + 2) * kstepA; const char* b2 = last ? nB : cB + (size_t)(t + 2) * kstep;
;             const char* a3 = a2 + kstepA; const char* b3 = b2 + kstep;
;             if (last && has_next) S.a_ready(nxt);
;             if constexpr (SP2) {
;             PG8_ITER(PG8_MMA)
	s_add_i32 s67, s67, s15
	s_add_i32 s69, s67, 0x2000
	s_nop 1
	v_lshl_add_u64 v[24:25], v[242:243], 0, s[64:65]
	s_mov_b32 m0, s67
	s_add_u32 s80, s76, 0x80180
	ds_read_b128 v[32:35], v147 offset:49152
	ds_read_b128 v[36:39], v147 offset:50176
	ds_read_b128 v[218:221], v147 offset:51200
	ds_read_b128 v[222:225], v147 offset:52224
	ds_read_b128 v[226:229], v147 offset:53248
	ds_read_b128 v[230:233], v147 offset:54272
	ds_read_b128 v[234:237], v147 offset:55296
	ds_read_b128 v[238:241], v147 offset:56320
	global_load_lds_dwordx4 v[24:25], off
	v_lshl_add_u64 v[24:25], v[244:245], 0, s[64:65]
	s_mov_b32 m0, s69
	s_addc_u32 s81, s77, 0
	s_add_i32 s75, s75, s15
	global_load_lds_dwordx4 v[24:25], off
	v_lshl_add_u64 v[24:25], s[80:81], 0, v[128:129]
	s_mov_b32 m0, s75
	s_add_i32 s82, s75, 0x2000
	global_load_lds_dwordx4 v[24:25], off
	v_lshl_add_u64 v[24:25], s[80:81], 0, v[130:131]
	s_mov_b32 m0, s82
	s_nop 0
	global_load_lds_dwordx4 v[24:25], off
	v_lshl_add_u64 v[24:25], v[246:247], 0, s[64:65]
	s_mov_b32 m0, s43
	s_nop 0
	global_load_lds_dwordx4 v[24:25], off
	v_lshl_add_u64 v[24:25], v[248:249], 0, s[64:65]
	s_mov_b32 m0, s44
	s_nop 0
	global_load_lds_dwordx4 v[24:25], off
	s_waitcnt vmcnt(8) lgkmcnt(0)
	s_barrier
	v_mfma_f32_16x16x32_bf16 v[24:27], v[8:11], v[32:35], v[150:153]
	v_mfma_f32_16x16x32_bf16 v[72:75], v[12:15], v[36:39], v[24:27]
	v_mfma_f32_16x16x32_bf16 v[24:27], v[16:19], v[32:35], v[154:157]
	v_mfma_f32_16x16x32_bf16 v[76:79], v[20:23], v[36:39], v[24:27]
	v_mfma_f32_16x16x32_bf16 v[24:27], v[8:11], v[218:221], v[158:161]
	v_mfma_f32_16x16x32_bf16 v[40:43], v[12:15], v[222:225], v[24:27]
	v_mfma_f32_16x16x32_bf16 v[24:27], v[16:19], v[218:221], v[162:165]
	v_mfma_f32_16x16x32_bf16 v[0:3], v[8:11], v[234:237], v[0:3]
	v_mfma_f32_16x16x32_bf16 v[44:47], v[20:23], v[222:225], v[24:27]
	v_mfma_f32_16x16x32_bf16 v[24:27], v[8:11], v[226:229], v[166:169]
	v_mfma_f32_16x16x32_bf16 v[28:31], v[16:19], v[226:229], v[170:173]
	v_mfma_f32_16x16x32_bf16 v[8:11], v[12:15], v[238:241], v[0:3]
	v_mfma_f32_16x16x32_bf16 v[0:3], v[16:19], v[234:237], v[4:7]
	v_mfma_f32_16x16x32_bf16 v[24:27], v[12:15], v[230:233], v[24:27]
	v_mfma_f32_16x16x32_bf16 v[28:31], v[20:23], v[230:233], v[28:31]
	v_mfma_f32_16x16x32_bf16 v[12:15], v[20:23], v[238:241], v[0:3]
	v_mfma_f32_16x16x32_bf16 v[0:3], v[202:205], v[32:35], v[174:177]
	v_mfma_f32_16x16x32_bf16 v[56:59], v[206:209], v[36:39], v[0:3]
	v_mfma_f32_16x16x32_bf16 v[0:3], v[210:213], v[32:35], v[60:63]
	v_mfma_f32_16x16x32_bf16 v[60:63], v[214:217], v[36:39], v[0:3]
	v_mfma_f32_16x16x32_bf16 v[0:3], v[202:205], v[218:221], v[178:181]
	v_mfma_f32_16x16x32_bf16 v[32:35], v[206:209], v[222:225], v[0:3]
	v_mfma_f32_16x16x32_bf16 v[0:3], v[210:213], v[218:221], v[182:185]
	v_mfma_f32_16x16x32_bf16 v[36:39], v[214:217], v[222:225], v[0:3]
	v_mfma_f32_16x16x32_bf16 v[0:3], v[202:205], v[226:229], v[186:189]
	v_mfma_f32_16x16x32_bf16 v[16:19], v[206:209], v[230:233], v[0:3]
	v_mfma_f32_16x16x32_bf16 v[0:3], v[210:213], v[226:229], v[190:193]
	v_mfma_f32_16x16x32_bf16 v[20:23], v[214:217], v[230:233], v[0:3]
	v_mfma_f32_16x16x32_bf16 v[0:3], v[202:205], v[234:237], v[194:197]
	v_mfma_f32_16x16x32_bf16 v[4:7], v[210:213], v[234:237], v[198:201]
	v_mfma_f32_16x16x32_bf16 v[0:3], v[206:209], v[238:241], v[0:3]
	v_mfma_f32_16x16x32_bf16 v[4:7], v[214:217], v[238:241], v[4:7]
	s_barrier
	s_add_u32 s83, s76, 0x200
	s_addc_u32 s85, s77, 0
	s_add_u32 s76, s78, 0x80180
	s_addc_u32 s77, s79, 0
	s_mov_b32 s88, 0
.LBB0_1953:
	ds_read_b128 v[150:153], v145
	ds_read_b128 v[154:157], v145 offset:1024
	ds_read_b128 v[158:161], v145 offset:2048
	ds_read_b128 v[162:165], v145 offset:3072
	ds_read_b128 v[166:169], v146
	ds_read_b128 v[170:173], v146 offset:1024
	ds_read_b128 v[174:177], v146 offset:2048
	ds_read_b128 v[178:181], v146 offset:3072
	s_add_u32 s78, s76, 0xfff80080
	s_addc_u32 s79, s77, -1
	s_cmp_eq_u32 s88, 28
	s_cselect_b32 s81, s50, s79
	s_cselect_b32 s80, s51, s78
	s_cselect_b32 s79, s52, s85
	s_cselect_b32 s78, s53, s83
	s_mov_b32 m0, s54
	v_lshl_add_u64 v[214:215], s[76:77], 0, v[138:139]
	ds_read_b128 v[182:185], v147
	ds_read_b128 v[186:189], v147 offset:1024
	ds_read_b128 v[190:193], v147 offset:2048
	ds_read_b128 v[194:197], v147 offset:3072
	ds_read_b128 v[198:201], v147 offset:4096
	ds_read_b128 v[202:205], v147 offset:5120
	ds_read_b128 v[206:209], v147 offset:6144
	ds_read_b128 v[210:213], v147 offset:7168
	global_load_lds_dwordx4 v[214:215], off
	v_lshl_add_u64 v[214:215], s[76:77], 0, v[136:137]
	s_mov_b32 m0, s55
	s_nop 0
	global_load_lds_dwordx4 v[214:215], off
	s_waitcnt vmcnt(8) lgkmcnt(0)
	s_barrier
	v_mfma_f32_16x16x32_bf16 v[120:123], v[150:153], v[182:185], v[120:123]
	v_mfma_f32_16x16x32_bf16 v[124:127], v[158:161], v[182:185], v[124:127]
	v_mfma_f32_16x16x32_bf16 v[104:107], v[150:153], v[190:193], v[104:107]
	v_mfma_f32_16x16x32_bf16 v[108:111], v[158:161], v[190:193], v[108:111]
	v_mfma_f32_16x16x32_bf16 v[88:91], v[150:153], v[198:201], v[88:91]
	v_mfma_f32_16x16x32_bf16 v[92:95], v[158:161], v[198:201], v[92:95]
	v_mfma_f32_16x16x32_bf16 v[64:67], v[150:153], v[206:209], v[64:67]
	v_mfma_f32_16x16x32_bf16 v[68:71], v[158:161], v[206:209], v[68:71]
	v_mfma_f32_16x16x32_bf16 v[120:123], v[154:157], v[186:189], v[120:123]
	v_mfma_f32_16x16x32_bf16 v[124:127], v[162:165], v[186:189], v[124:127]
	v_mfma_f32_16x16x32_bf16 v[104:107], v[154:157], v[194:197], v[104:107]
	v_mfma_f32_16x16x32_bf16 v[108:111], v[162:165], v[194:197], v[108:111]
	v_mfma_f32_16x16x32_bf16 v[88:91], v[154:157], v[202:205], v[88:91]
	v_mfma_f32_16x16x32_bf16 v[92:95], v[162:165], v[202:205], v[92:95]
	v_mfma_f32_16x16x32_bf16 v[64:67], v[154:157], v[210:213], v[64:67]
	v_mfma_f32_16x16x32_bf16 v[68:71], v[162:165], v[210:213], v[68:71]
	v_mfma_f32_16x16x32_bf16 v[112:115], v[166:169], v[182:185], v[112:115]
	v_mfma_f32_16x16x32_bf16 v[116:119], v[174:177], v[182:185], v[116:119]
	v_mfma_f32_16x16x32_bf16 v[96:99], v[166:169], v[190:193], v[96:99]
	v_mfma_f32_16x16x32_bf16 v[100:103], v[174:177], v[190:193], v[100:103]
	v_mfma_f32_16x16x32_bf16 v[80:83], v[166:169], v[198:201], v[80:83]
	v_mfma_f32_16x16x32_bf16 v[84:87], v[174:177], v[198:201], v[84:87]
	v_mfma_f32_16x16x32_bf16 v[48:51], v[166:169], v[206:209], v[48:51]
	v_mfma_f32_16x16x32_bf16 v[52:55], v[174:177], v[206:209], v[52:55]
	v_mfma_f32_16x16x32_bf16 v[112:115], v[170:173], v[186:189], v[112:115]
	v_mfma_f32_16x16x32_bf16 v[116:119], v[178:181], v[186:189], v[116:119]
	v_mfma_f32_16x16x32_bf16 v[96:99], v[170:173], v[194:197], v[96:99]
	v_mfma_f32_16x16x32_bf16 v[100:103], v[178:181], v[194:197], v[100:103]
	v_mfma_f32_16x16x32_bf16 v[80:83], v[170:173], v[202:205], v[80:83]
	v_mfma_f32_16x16x32_bf16 v[84:87], v[178:181], v[202:205], v[84:87]
	v_mfma_f32_16x16x32_bf16 v[48:51], v[170:173], v[210:213], v[48:51]
	v_mfma_f32_16x16x32_bf16 v[52:55], v[178:181], v[210:213], v[52:55]
	s_barrier
	s_mov_b32 m0, s56
	v_lshl_add_u64 v[214:215], s[78:79], 0, v[128:129]
	s_add_u32 s90, s78, 0x80000
	ds_read_b128 v[182:185], v147 offset:16384
	ds_read_b128 v[186:189], v147 offset:17408
	ds_read_b128 v[190:193], v147 offset:18432
	ds_read_b128 v[194:197], v147 offset:19456
	ds_read_b128 v[198:201], v147 offset:20480
	ds_read_b128 v[202:205], v147 offset:21504
	ds_read_b128 v[206:209], v147 offset:22528
	ds_read_b128 v[210:213], v147 offset:23552
	global_load_lds_dwordx4 v[214:215], off
	v_lshl_add_u64 v[216:217], s[78:79], 0, v[130:131]
	s_mov_b32 m0, s57
	s_addc_u32 s91, s79, 0
	global_load_lds_dwordx4 v[216:217], off
	v_lshl_add_u64 v[218:219], s[90:91], 0, v[128:129]
	s_mov_b32 m0, s58
	v_lshl_add_u64 v[220:221], s[80:81], 0, v[132:133]
	global_load_lds_dwordx4 v[218:219], off
	v_lshl_add_u64 v[218:219], s[90:91], 0, v[130:131]
	s_mov_b32 m0, s59
	s_nop 0
	global_load_lds_dwordx4 v[218:219], off
	v_lshl_add_u64 v[218:219], s[80:81], 0, v[134:135]
	s_mov_b32 m0, s22
	s_nop 0
	global_load_lds_dwordx4 v[218:219], off
	s_mov_b32 m0, s23
	s_nop 0
	global_load_lds_dwordx4 v[220:221], off
	s_waitcnt vmcnt(8) lgkmcnt(0)
	s_barrier
	v_mfma_f32_16x16x32_bf16 v[72:75], v[150:153], v[182:185], v[72:75]
	v_mfma_f32_16x16x32_bf16 v[76:79], v[158:161], v[182:185], v[76:79]
	v_mfma_f32_16x16x32_bf16 v[40:43], v[150:153], v[190:193], v[40:43]
	v_mfma_f32_16x16x32_bf16 v[44:47], v[158:161], v[190:193], v[44:47]
	v_mfma_f32_16x16x32_bf16 v[24:27], v[150:153], v[198:201], v[24:27]
	v_mfma_f32_16x16x32_bf16 v[28:31], v[158:161], v[198:201], v[28:31]
	v_mfma_f32_16x16x32_bf16 v[8:11], v[150:153], v[206:209], v[8:11]
	v_mfma_f32_16x16x32_bf16 v[12:15], v[158:161], v[206:209], v[12:15]
	v_mfma_f32_16x16x32_bf16 v[72:75], v[154:157], v[186:189], v[72:75]
	v_mfma_f32_16x16x32_bf16 v[76:79], v[162:165], v[186:189], v[76:79]
	v_mfma_f32_16x16x32_bf16 v[40:43], v[154:157], v[194:197], v[40:43]
	v_mfma_f32_16x16x32_bf16 v[44:47], v[162:165], v[194:197], v[44:47]
	v_mfma_f32_16x16x32_bf16 v[24:27], v[154:157], v[202:205], v[24:27]
	v_mfma_f32_16x16x32_bf16 v[28:31], v[162:165], v[202:205], v[28:31]
	v_mfma_f32_16x16x32_bf16 v[8:11], v[154:157], v[210:213], v[8:11]
	v_mfma_f32_16x16x32_bf16 v[12:15], v[162:165], v[210:213], v[12:15]
	v_mfma_f32_16x16x32_bf16 v[56:59], v[166:169], v[182:185], v[56:59]
	v_mfma_f32_16x16x32_bf16 v[60:63], v[174:177], v[182:185], v[60:63]
	v_mfma_f32_16x16x32_bf16 v[32:35], v[166:169], v[190:193], v[32:35]
	v_mfma_f32_16x16x32_bf16 v[36:39], v[174:177], v[190:193], v[36:39]
	v_mfma_f32_16x16x32_bf16 v[16:19], v[166:169], v[198:201], v[16:19]
	v_mfma_f32_16x16x32_bf16 v[20:23], v[174:177], v[198:201], v[20:23]
	v_mfma_f32_16x16x32_bf16 v[0:3], v[166:169], v[206:209], v[0:3]
	v_mfma_f32_16x16x32_bf16 v[4:7], v[174:177], v[206:209], v[4:7]
	v_mfma_f32_16x16x32_bf16 v[56:59], v[170:173], v[186:189], v[56:59]
	v_mfma_f32_16x16x32_bf16 v[60:63], v[178:181], v[186:189], v[60:63]
	v_mfma_f32_16x16x32_bf16 v[32:35], v[170:173], v[194:197], v[32:35]
	v_mfma_f32_16x16x32_bf16 v[36:39], v[178:181], v[194:197], v[36:39]
	v_mfma_f32_16x16x32_bf16 v[16:19], v[170:173], v[202:205], v[16:19]
	v_mfma_f32_16x16x32_bf16 v[20:23], v[178:181], v[202:205], v[20:23]
	v_mfma_f32_16x16x32_bf16 v[0:3], v[170:173], v[210:213], v[0:3]
	v_mfma_f32_16x16x32_bf16 v[4:7], v[178:181], v[210:213], v[4:7]
	s_barrier
; #define PG8_BAR __builtin_amdgcn_s_barrier()
; template <class Epi, class Sched, bool ALIGN_EPI = false, bool SP2 = false, bool A_TILED = false>
; __device__ __forceinline__ void gemm_phase(PG8_LAS unsigned char* lds, const Gemm g, const Sched& S, const Epi& E, const int wave_s) {
;     ...
;         if constexpr (ALIGN_EPI) { if (wr == 0) PG8_BAR; }
	ds_read_b128 v[150:153], v148
	ds_read_b128 v[154:157], v148 offset:1024
	ds_read_b128 v[158:161], v148 offset:2048
	ds_read_b128 v[162:165], v148 offset:3072
	ds_read_b128 v[166:169], v149
	ds_read_b128 v[170:173], v149 offset:1024
	ds_read_b128 v[174:177], v149 offset:2048
	ds_read_b128 v[178:181], v149 offset:3072
	s_add_u32 s80, s80, 0x80000
	s_addc_u32 s81, s81, 0
	s_mov_b32 m0, s36
	v_lshl_add_u64 v[222:223], s[80:81], 0, v[134:135]
	ds_read_b128 v[182:185], v147 offset:32768
	ds_read_b128 v[186:189], v147 offset:33792
	ds_read_b128 v[190:193], v147 offset:34816
	ds_read_b128 v[194:197], v147 offset:35840
	ds_read_b128 v[198:201], v147 offset:36864
	ds_read_b128 v[202:205], v147 offset:37888
	ds_read_b128 v[206:209], v147 offset:38912
	ds_read_b128 v[210:213], v147 offset:39936
	global_load_lds_dwordx4 v[222:223], off
	v_lshl_add_u64 v[222:223], s[80:81], 0, v[132:133]
	s_mov_b32 m0, s37
	s_nop 0
	global_load_lds_dwordx4 v[222:223], off
	s_waitcnt vmcnt(8) lgkmcnt(0)
	s_barrier
	v_mfma_f32_16x16x32_bf16 v[120:123], v[150:153], v[182:185], v[120:123]
	v_mfma_f32_16x16x32_bf16 v[124:127], v[158:161], v[182:185], v[124:127]
	v_mfma_f32_16x16x32_bf16 v[104:107], v[150:153], v[190:193], v[104:107]
	v_mfma_f32_16x16x32_bf16 v[108:111], v[158:161], v[190:193], v[108:111]
	v_mfma_f32_16x16x32_bf16 v[88:91], v[150:153], v[198:201], v[88:91]
	v_mfma_f32_16x16x32_bf16 v[92:95], v[158:161], v[198:201], v[92:95]
	v_mfma_f32_16x16x32_bf16 v[64:67], v[150:153], v[206:209], v[64:67]
	v_mfma_f32_16x16x32_bf16 v[68:71], v[158:161], v[206:209], v[68:71]
	v_mfma_f32_16x16x32_bf16 v[120:123], v[154:157], v[186:189], v[120:123]
	v_mfma_f32_16x16x32_bf16 v[124:127], v[162:165], v[186:189], v[124:127]
	v_mfma_f32_16x16x32_bf16 v[104:107], v[154:157], v[194:197], v[104:107]
	v_mfma_f32_16x16x32_bf16 v[108:111], v[162:165], v[194:197], v[108:111]
	v_mfma_f32_16x16x32_bf16 v[88:91], v[154:157], v[202:205], v[88:91]
	v_mfma_f32_16x16x32_bf16 v[92:95], v[162:165], v[202:205], v[92:95]
	v_mfma_f32_16x16x32_bf16 v[64:67], v[154:157], v[210:213], v[64:67]
	v_mfma_f32_16x16x32_bf16 v[68:71], v[162:165], v[210:213], v[68:71]
	v_mfma_f32_16x16x32_bf16 v[112:115], v[166:169], v[182:185], v[112:115]
	v_mfma_f32_16x16x32_bf16 v[116:119], v[174:177], v[182:185], v[116:119]
	v_mfma_f32_16x16x32_bf16 v[96:99], v[166:169], v[190:193], v[96:99]
	v_mfma_f32_16x16x32_bf16 v[100:103], v[174:177], v[190:193], v[100:103]
	v_mfma_f32_16x16x32_bf16 v[80:83], v[166:169], v[198:201], v[80:83]
	v_mfma_f32_16x16x32_bf16 v[84:87], v[174:177], v[198:201], v[84:87]
	v_mfma_f32_16x16x32_bf16 v[48:51], v[166:169], v[206:209], v[48:51]
	v_mfma_f32_16x16x32_bf16 v[52:55], v[174:177], v[206:209], v[52:55]
	v_mfma_f32_16x16x32_bf16 v[112:115], v[170:173], v[186:189], v[112:115]
	v_mfma_f32_16x16x32_bf16 v[116:119], v[178:181], v[186:189], v[116:119]
	v_mfma_f32_16x16x32_bf16 v[96:99], v[170:173], v[194:197], v[96:99]
	v_mfma_f32_16x16x32_bf16 v[100:103], v[178:181], v[194:197], v[100:103]
	v_mfma_f32_16x16x32_bf16 v[80:83], v[170:173], v[202:205], v[80:83]
	v_mfma_f32_16x16x32_bf16 v[84:87], v[178:181], v[202:205], v[84:87]
	v_mfma_f32_16x16x32_bf16 v[48:51], v[170:173], v[210:213], v[48:51]
	v_mfma_f32_16x16x32_bf16 v[52:55], v[178:181], v[210:213], v[52:55]
	s_barrier
	s_mov_b32 m0, s67
	v_lshl_add_u64 v[214:215], v[214:215], 0, s[12:13]
	s_add_u32 s78, s78, 0x80080
	ds_read_b128 v[182:185], v147 offset:49152
	ds_read_b128 v[186:189], v147 offset:50176
	ds_read_b128 v[190:193], v147 offset:51200
	ds_read_b128 v[194:197], v147 offset:52224
	ds_read_b128 v[198:201], v147 offset:53248
	ds_read_b128 v[202:205], v147 offset:54272
	ds_read_b128 v[206:209], v147 offset:55296
	ds_read_b128 v[210:213], v147 offset:56320
	global_load_lds_dwordx4 v[214:215], off
	v_lshl_add_u64 v[214:215], v[216:217], 0, s[12:13]
	s_mov_b32 m0, s69
	s_addc_u32 s79, s79, 0
	global_load_lds_dwordx4 v[214:215], off
	v_lshl_add_u64 v[214:215], s[78:79], 0, v[128:129]
	s_mov_b32 m0, s75
	s_nop 0
	global_load_lds_dwordx4 v[214:215], off
	v_lshl_add_u64 v[214:215], s[78:79], 0, v[130:131]
	s_mov_b32 m0, s82
	s_nop 0
	global_load_lds_dwordx4 v[214:215], off
	v_lshl_add_u64 v[214:215], v[218:219], 0, s[12:13]
	s_mov_b32 m0, s43
	s_nop 0
	global_load_lds_dwordx4 v[214:215], off
	v_lshl_add_u64 v[214:215], v[220:221], 0, s[12:13]
	s_mov_b32 m0, s44
	s_nop 0
	global_load_lds_dwordx4 v[214:215], off
	s_waitcnt vmcnt(8) lgkmcnt(0)
	s_barrier
	v_mfma_f32_16x16x32_bf16 v[72:75], v[150:153], v[182:185], v[72:75]
	v_mfma_f32_16x16x32_bf16 v[76:79], v[158:161], v[182:185], v[76:79]
	v_mfma_f32_16x16x32_bf16 v[40:43], v[150:153], v[190:193], v[40:43]
	v_mfma_f32_16x16x32_bf16 v[44:47], v[158:161], v[190:193], v[44:47]
	v_mfma_f32_16x16x32_bf16 v[24:27], v[150:153], v[198:201], v[24:27]
	v_mfma_f32_16x16x32_bf16 v[28:31], v[158:161], v[198:201], v[28:31]
	v_mfma_f32_16x16x32_bf16 v[8:11], v[150:153], v[206:209], v[8:11]
	v_mfma_f32_16x16x32_bf16 v[12:15], v[158:161], v[206:209], v[12:15]
	v_mfma_f32_16x16x32_bf16 v[72:75], v[154:157], v[186:189], v[72:75]
	v_mfma_f32_16x16x32_bf16 v[76:79], v[162:165], v[186:189], v[76:79]
	v_mfma_f32_16x16x32_bf16 v[40:43], v[154:157], v[194:197], v[40:43]
	v_mfma_f32_16x16x32_bf16 v[44:47], v[162:165], v[194:197], v[44:47]
	v_mfma_f32_16x16x32_bf16 v[24:27], v[154:157], v[202:205], v[24:27]
	v_mfma_f32_16x16x32_bf16 v[28:31], v[162:165], v[202:205], v[28:31]
	v_mfma_f32_16x16x32_bf16 v[8:11], v[154:157], v[210:213], v[8:11]
	v_mfma_f32_16x16x32_bf16 v[12:15], v[162:165], v[210:213], v[12:15]
	v_mfma_f32_16x16x32_bf16 v[56:59], v[166:169], v[182:185], v[56:59]
	v_mfma_f32_16x16x32_bf16 v[60:63], v[174:177], v[182:185], v[60:63]
	v_mfma_f32_16x16x32_bf16 v[32:35], v[166:169], v[190:193], v[32:35]
	v_mfma_f32_16x16x32_bf16 v[36:39], v[174:177], v[190:193], v[36:39]
	v_mfma_f32_16x16x32_bf16 v[16:19], v[166:169], v[198:201], v[16:19]
	v_mfma_f32_16x16x32_bf16 v[20:23], v[174:177], v[198:201], v[20:23]
	v_mfma_f32_16x16x32_bf16 v[0:3], v[166:169], v[206:209], v[0:3]
	v_mfma_f32_16x16x32_bf16 v[4:7], v[174:177], v[206:209], v[4:7]
	v_mfma_f32_16x16x32_bf16 v[56:59], v[170:173], v[186:189], v[56:59]
	v_mfma_f32_16x16x32_bf16 v[60:63], v[178:181], v[186:189], v[60:63]
	v_mfma_f32_16x16x32_bf16 v[32:35], v[170:173], v[194:197], v[32:35]
	v_mfma_f32_16x16x32_bf16 v[36:39], v[178:181], v[194:197], v[36:39]
	v_mfma_f32_16x16x32_bf16 v[16:19], v[170:173], v[202:205], v[16:19]
	v_mfma_f32_16x16x32_bf16 v[20:23], v[178:181], v[202:205], v[20:23]
	v_mfma_f32_16x16x32_bf16 v[0:3], v[170:173], v[210:213], v[0:3]
	v_mfma_f32_16x16x32_bf16 v[4:7], v[178:181], v[210:213], v[4:7]
	s_barrier
	s_add_i32 s88, s88, 2
	s_add_u32 s83, s83, 0x100
	s_addc_u32 s85, s85, 0
	s_add_u32 s76, s76, 0x100
	s_addc_u32 s77, s77, 0
	s_cmp_gt_u32 s88, 29
	s_cbranch_scc0 .LBB0_1953
	s_and_b64 vcc, exec, s[60:61]
	s_cbranch_vccz .LBB0_1956
	s_barrier

; template <class Epi, class Sched, bool ALIGN_EPI = false, bool SP2 = false, bool A_TILED = false>
; __device__ __forceinline__ void gemm_phase(PG8_LAS unsigned char* lds, const Gemm g, const Sched& S, const Epi& E, const int wave_s) {
;     ...
;             const bool last = (t == nt - 2);
;             const char* a1 = cA + (size_t)(t + 1) * kstepA;
;             const char* a2 = last ? nA : cA + (size_t)(t + 2) * kstepA; const char* b2 = last ? nB : cB + (size_t)(t + 2) * kstep;
;             const char* a3 = a2 + kstepA; const char* b3 = b2 + kstep;
.LBB0_2026:
	ds_read_b128 v[146:149], v140
	ds_read_b128 v[150:153], v140 offset:1024
	ds_read_b128 v[154:157], v140 offset:2048
	ds_read_b128 v[158:161], v140 offset:3072
	ds_read_b128 v[162:165], v141
	ds_read_b128 v[166:169], v141 offset:1024
	ds_read_b128 v[170:173], v141 offset:2048
	ds_read_b128 v[174:177], v141 offset:3072
	s_add_u32 s52, s60, s39
	s_addc_u32 s53, s61, s40
	s_add_u32 s54, s60, s37
	s_addc_u32 s55, s61, s38
	s_cmpk_eq_i32 s41, 0x7c
	s_cselect_b32 s72, s6, s52
	s_cselect_b32 s73, s7, s53
	s_cselect_b32 s70, s2, s54
	s_cselect_b32 s71, s3, s55
	s_add_u32 s68, s72, 0x8000
	s_addc_u32 s69, s73, 0
	s_mov_b32 m0, s42
	v_lshl_add_u64 v[210:211], s[60:61], 0, v[138:139]
	ds_read_b128 v[178:181], v142
	ds_read_b128 v[182:185], v142 offset:1024
	ds_read_b128 v[186:189], v142 offset:2048
	ds_read_b128 v[190:193], v142 offset:3072
	ds_read_b128 v[194:197], v142 offset:4096
	ds_read_b128 v[198:201], v142 offset:5120
	ds_read_b128 v[202:205], v142 offset:6144
	ds_read_b128 v[206:209], v142 offset:7168
	global_load_lds_dwordx4 v[210:211], off
	v_lshl_add_u64 v[210:211], s[60:61], 0, v[136:137]
	s_mov_b32 m0, s43
	s_nop 0
	global_load_lds_dwordx4 v[210:211], off
	s_waitcnt vmcnt(8) lgkmcnt(0)
	s_barrier
	v_mfma_f32_16x16x32_bf16 v[8:11], v[146:149], v[178:181], v[8:11]
	v_mfma_f32_16x16x32_bf16 v[12:15], v[154:157], v[178:181], v[12:15]
	v_mfma_f32_16x16x32_bf16 v[60:63], v[146:149], v[186:189], v[60:63]
	v_mfma_f32_16x16x32_bf16 v[20:23], v[154:157], v[186:189], v[20:23]
	v_mfma_f32_16x16x32_bf16 v[76:79], v[146:149], v[194:197], v[76:79]
	v_mfma_f32_16x16x32_bf16 v[52:55], v[154:157], v[194:197], v[52:55]
	v_mfma_f32_16x16x32_bf16 v[128:131], v[146:149], v[202:205], v[128:131]
	v_mfma_f32_16x16x32_bf16 v[68:71], v[154:157], v[202:205], v[68:71]
	v_mfma_f32_16x16x32_bf16 v[8:11], v[150:153], v[182:185], v[8:11]
	v_mfma_f32_16x16x32_bf16 v[12:15], v[158:161], v[182:185], v[12:15]
	v_mfma_f32_16x16x32_bf16 v[60:63], v[150:153], v[190:193], v[60:63]
	v_mfma_f32_16x16x32_bf16 v[20:23], v[158:161], v[190:193], v[20:23]
	v_mfma_f32_16x16x32_bf16 v[76:79], v[150:153], v[198:201], v[76:79]
	v_mfma_f32_16x16x32_bf16 v[52:55], v[158:161], v[198:201], v[52:55]
	v_mfma_f32_16x16x32_bf16 v[128:131], v[150:153], v[206:209], v[128:131]
	v_mfma_f32_16x16x32_bf16 v[68:71], v[158:161], v[206:209], v[68:71]
	v_mfma_f32_16x16x32_bf16 v[28:31], v[162:165], v[178:181], v[28:31]
	v_mfma_f32_16x16x32_bf16 v[16:19], v[170:173], v[178:181], v[16:19]
	v_mfma_f32_16x16x32_bf16 v[56:59], v[162:165], v[186:189], v[56:59]
	v_mfma_f32_16x16x32_bf16 v[48:51], v[170:173], v[186:189], v[48:51]
	v_mfma_f32_16x16x32_bf16 v[72:75], v[162:165], v[194:197], v[72:75]
	v_mfma_f32_16x16x32_bf16 v[64:67], v[170:173], v[194:197], v[64:67]
	v_mfma_f32_16x16x32_bf16 v[108:111], v[162:165], v[202:205], v[108:111]
	v_mfma_f32_16x16x32_bf16 v[96:99], v[170:173], v[202:205], v[96:99]
	v_mfma_f32_16x16x32_bf16 v[28:31], v[166:169], v[182:185], v[28:31]
	v_mfma_f32_16x16x32_bf16 v[16:19], v[174:177], v[182:185], v[16:19]
	v_mfma_f32_16x16x32_bf16 v[56:59], v[166:169], v[190:193], v[56:59]
	v_mfma_f32_16x16x32_bf16 v[48:51], v[174:177], v[190:193], v[48:51]
	v_mfma_f32_16x16x32_bf16 v[72:75], v[166:169], v[198:201], v[72:75]
	v_mfma_f32_16x16x32_bf16 v[64:67], v[174:177], v[198:201], v[64:67]
	v_mfma_f32_16x16x32_bf16 v[108:111], v[166:169], v[206:209], v[108:111]
	v_mfma_f32_16x16x32_bf16 v[96:99], v[174:177], v[206:209], v[96:99]
	s_barrier
	s_mov_b32 m0, s44
	v_lshl_add_u64 v[210:211], s[70:71], 0, v[34:35]
	s_add_u32 s52, s70, 0x200000
	ds_read_b128 v[178:181], v142 offset:16384
	ds_read_b128 v[182:185], v142 offset:17408
	ds_read_b128 v[186:189], v142 offset:18432
	ds_read_b128 v[190:193], v142 offset:19456
	ds_read_b128 v[194:197], v142 offset:20480
	ds_read_b128 v[198:201], v142 offset:21504
	ds_read_b128 v[202:205], v142 offset:22528
	ds_read_b128 v[206:209], v142 offset:23552
	global_load_lds_dwordx4 v[210:211], off
	v_lshl_add_u64 v[212:213], s[70:71], 0, v[134:135]
	s_mov_b32 m0, s45
	s_addc_u32 s53, s71, 0
	global_load_lds_dwordx4 v[212:213], off
	v_lshl_add_u64 v[214:215], s[52:53], 0, v[34:35]
	s_mov_b32 m0, s46
	s_nop 0
	global_load_lds_dwordx4 v[214:215], off
	v_lshl_add_u64 v[214:215], s[52:53], 0, v[134:135]
	s_mov_b32 m0, s47
	s_nop 0
	global_load_lds_dwordx4 v[214:215], off
	v_lshl_add_u64 v[214:215], s[72:73], 0, v[32:33]
	s_mov_b32 m0, s14
	s_nop 0
	global_load_lds_dwordx4 v[214:215], off
	v_lshl_add_u64 v[214:215], s[72:73], 0, v[132:133]
	s_mov_b32 m0, s15
	s_nop 0
	global_load_lds_dwordx4 v[214:215], off
	s_waitcnt vmcnt(8) lgkmcnt(0)
	s_barrier
	v_mfma_f32_16x16x32_bf16 v[100:103], v[146:149], v[178:181], v[100:103]
	v_mfma_f32_16x16x32_bf16 v[104:107], v[154:157], v[178:181], v[104:107]
	v_mfma_f32_16x16x32_bf16 v[116:119], v[146:149], v[186:189], v[116:119]
	v_mfma_f32_16x16x32_bf16 v[120:123], v[154:157], v[186:189], v[120:123]
	v_mfma_f32_16x16x32_bf16 v[84:87], v[146:149], v[194:197], v[84:87]
	v_mfma_f32_16x16x32_bf16 v[80:83], v[154:157], v[194:197], v[80:83]
	v_mfma_f32_16x16x32_bf16 v[36:39], v[146:149], v[202:205], v[36:39]
	v_mfma_f32_16x16x32_bf16 v[24:27], v[154:157], v[202:205], v[24:27]
	v_mfma_f32_16x16x32_bf16 v[100:103], v[150:153], v[182:185], v[100:103]
	v_mfma_f32_16x16x32_bf16 v[104:107], v[158:161], v[182:185], v[104:107]
	v_mfma_f32_16x16x32_bf16 v[116:119], v[150:153], v[190:193], v[116:119]
	v_mfma_f32_16x16x32_bf16 v[120:123], v[158:161], v[190:193], v[120:123]
	v_mfma_f32_16x16x32_bf16 v[84:87], v[150:153], v[198:201], v[84:87]
	v_mfma_f32_16x16x32_bf16 v[80:83], v[158:161], v[198:201], v[80:83]
	v_mfma_f32_16x16x32_bf16 v[36:39], v[150:153], v[206:209], v[36:39]
	v_mfma_f32_16x16x32_bf16 v[24:27], v[158:161], v[206:209], v[24:27]
	v_mfma_f32_16x16x32_bf16 v[124:127], v[162:165], v[178:181], v[124:127]
	v_mfma_f32_16x16x32_bf16 v[112:115], v[170:173], v[178:181], v[112:115]
	v_mfma_f32_16x16x32_bf16 v[92:95], v[162:165], v[186:189], v[92:95]
	v_mfma_f32_16x16x32_bf16 v[88:91], v[170:173], v[186:189], v[88:91]
	v_mfma_f32_16x16x32_bf16 v[44:47], v[162:165], v[194:197], v[44:47]
	v_mfma_f32_16x16x32_bf16 v[40:43], v[170:173], v[194:197], v[40:43]
	v_mfma_f32_16x16x32_bf16 v[4:7], v[162:165], v[202:205], v[4:7]
	v_mfma_f32_16x16x32_bf16 v[0:3], v[170:173], v[202:205], v[0:3]
	v_mfma_f32_16x16x32_bf16 v[124:127], v[166:169], v[182:185], v[124:127]
	v_mfma_f32_16x16x32_bf16 v[112:115], v[174:177], v[182:185], v[112:115]
	v_mfma_f32_16x16x32_bf16 v[92:95], v[166:169], v[190:193], v[92:95]
	v_mfma_f32_16x16x32_bf16 v[88:91], v[174:177], v[190:193], v[88:91]
	v_mfma_f32_16x16x32_bf16 v[44:47], v[166:169], v[198:201], v[44:47]
	v_mfma_f32_16x16x32_bf16 v[40:43], v[174:177], v[198:201], v[40:43]
	v_mfma_f32_16x16x32_bf16 v[4:7], v[166:169], v[206:209], v[4:7]
	v_mfma_f32_16x16x32_bf16 v[0:3], v[174:177], v[206:209], v[0:3]
	s_barrier
	ds_read_b128 v[146:149], v143
	ds_read_b128 v[150:153], v143 offset:1024
	ds_read_b128 v[154:157], v143 offset:2048
	ds_read_b128 v[158:161], v143 offset:3072
	ds_read_b128 v[162:165], v144
	ds_read_b128 v[166:169], v144 offset:1024
	ds_read_b128 v[170:173], v144 offset:2048
	ds_read_b128 v[174:177], v144 offset:3072
	s_add_u32 s52, s72, 0x4000
	s_addc_u32 s53, s73, 0
	s_mov_b32 m0, s21
	v_lshl_add_u64 v[214:215], s[52:53], 0, v[32:33]
	ds_read_b128 v[178:181], v142 offset:32768
	ds_read_b128 v[182:185], v142 offset:33792
	ds_read_b128 v[186:189], v142 offset:34816
	ds_read_b128 v[190:193], v142 offset:35840
	ds_read_b128 v[194:197], v142 offset:36864
	ds_read_b128 v[198:201], v142 offset:37888
	ds_read_b128 v[202:205], v142 offset:38912
	ds_read_b128 v[206:209], v142 offset:39936
	global_load_lds_dwordx4 v[214:215], off
	v_lshl_add_u64 v[214:215], s[52:53], 0, v[132:133]
	s_mov_b32 m0, s22
	s_nop 0
	global_load_lds_dwordx4 v[214:215], off
	s_waitcnt vmcnt(8) lgkmcnt(0)
	s_barrier
	v_mfma_f32_16x16x32_bf16 v[8:11], v[146:149], v[178:181], v[8:11]
	v_mfma_f32_16x16x32_bf16 v[12:15], v[154:157], v[178:181], v[12:15]
	v_mfma_f32_16x16x32_bf16 v[60:63], v[146:149], v[186:189], v[60:63]
	v_mfma_f32_16x16x32_bf16 v[20:23], v[154:157], v[186:189], v[20:23]
	v_mfma_f32_16x16x32_bf16 v[76:79], v[146:149], v[194:197], v[76:79]
	v_mfma_f32_16x16x32_bf16 v[52:55], v[154:157], v[194:197], v[52:55]
	v_mfma_f32_16x16x32_bf16 v[128:131], v[146:149], v[202:205], v[128:131]
	v_mfma_f32_16x16x32_bf16 v[68:71], v[154:157], v[202:205], v[68:71]
	v_mfma_f32_16x16x32_bf16 v[8:11], v[150:153], v[182:185], v[8:11]
	v_mfma_f32_16x16x32_bf16 v[12:15], v[158:161], v[182:185], v[12:15]
	v_mfma_f32_16x16x32_bf16 v[60:63], v[150:153], v[190:193], v[60:63]
	v_mfma_f32_16x16x32_bf16 v[20:23], v[158:161], v[190:193], v[20:23]
	v_mfma_f32_16x16x32_bf16 v[76:79], v[150:153], v[198:201], v[76:79]
	v_mfma_f32_16x16x32_bf16 v[52:55], v[158:161], v[198:201], v[52:55]
	v_mfma_f32_16x16x32_bf16 v[128:131], v[150:153], v[206:209], v[128:131]
	v_mfma_f32_16x16x32_bf16 v[68:71], v[158:161], v[206:209], v[68:71]
	v_mfma_f32_16x16x32_bf16 v[28:31], v[162:165], v[178:181], v[28:31]
	v_mfma_f32_16x16x32_bf16 v[16:19], v[170:173], v[178:181], v[16:19]
	v_mfma_f32_16x16x32_bf16 v[56:59], v[162:165], v[186:189], v[56:59]
	v_mfma_f32_16x16x32_bf16 v[48:51], v[170:173], v[186:189], v[48:51]
	v_mfma_f32_16x16x32_bf16 v[72:75], v[162:165], v[194:197], v[72:75]
	v_mfma_f32_16x16x32_bf16 v[64:67], v[170:173], v[194:197], v[64:67]
	v_mfma_f32_16x16x32_bf16 v[108:111], v[162:165], v[202:205], v[108:111]
	v_mfma_f32_16x16x32_bf16 v[96:99], v[170:173], v[202:205], v[96:99]
	v_mfma_f32_16x16x32_bf16 v[28:31], v[166:169], v[182:185], v[28:31]
	v_mfma_f32_16x16x32_bf16 v[16:19], v[174:177], v[182:185], v[16:19]
	v_mfma_f32_16x16x32_bf16 v[56:59], v[166:169], v[190:193], v[56:59]
	v_mfma_f32_16x16x32_bf16 v[48:51], v[174:177], v[190:193], v[48:51]
	v_mfma_f32_16x16x32_bf16 v[72:75], v[166:169], v[198:201], v[72:75]
	v_mfma_f32_16x16x32_bf16 v[64:67], v[174:177], v[198:201], v[64:67]
	v_mfma_f32_16x16x32_bf16 v[108:111], v[166:169], v[206:209], v[108:111]
	v_mfma_f32_16x16x32_bf16 v[96:99], v[174:177], v[206:209], v[96:99]
	s_barrier
; #define PG8_WAIT_V(n) asm volatile("s_waitcnt vmcnt(" #n ")" ::: "memory")
; #define PG8_BAR __builtin_amdgcn_s_barrier()
; template <class Epi, class Sched, bool ALIGN_EPI = false, bool SP2 = false, bool A_TILED = false>
; __device__ __forceinline__ void gemm_phase(PG8_LAS unsigned char* lds, const Gemm g, const Sched& S, const Epi& E, const int wave_s) {
;     ...
;     PG8_WAIT_V(0);
;     if constexpr (!ALIGN_EPI) { if (wr == 0) PG8_BAR; }
	s_mov_b32 m0, s48
	v_lshl_add_u64 v[210:211], v[210:211], 0, s[64:65]
	s_add_u32 s52, s70, 0x200080
	ds_read_b128 v[178:181], v142 offset:49152
	ds_read_b128 v[182:185], v142 offset:50176
	ds_read_b128 v[186:189], v142 offset:51200
	ds_read_b128 v[190:193], v142 offset:52224
	ds_read_b128 v[194:197], v142 offset:53248
	ds_read_b128 v[198:201], v142 offset:54272
	ds_read_b128 v[202:205], v142 offset:55296
	ds_read_b128 v[206:209], v142 offset:56320
	global_load_lds_dwordx4 v[210:211], off
	v_lshl_add_u64 v[210:211], v[212:213], 0, s[64:65]
	s_mov_b32 m0, s49
	s_addc_u32 s53, s71, 0
	global_load_lds_dwordx4 v[210:211], off
	v_lshl_add_u64 v[210:211], s[52:53], 0, v[34:35]
	s_mov_b32 m0, s50
	s_nop 0
	global_load_lds_dwordx4 v[210:211], off
	v_lshl_add_u64 v[210:211], s[52:53], 0, v[134:135]
	s_mov_b32 m0, s51
	s_nop 0
	global_load_lds_dwordx4 v[210:211], off
	v_lshl_add_u64 v[210:211], s[68:69], 0, v[32:33]
	s_mov_b32 m0, s23
	s_nop 0
	global_load_lds_dwordx4 v[210:211], off
	v_lshl_add_u64 v[210:211], s[68:69], 0, v[132:133]
	s_mov_b32 m0, s36
	s_nop 0
	global_load_lds_dwordx4 v[210:211], off
	s_waitcnt vmcnt(8) lgkmcnt(0)
	s_barrier
	v_mfma_f32_16x16x32_bf16 v[100:103], v[146:149], v[178:181], v[100:103]
	v_mfma_f32_16x16x32_bf16 v[104:107], v[154:157], v[178:181], v[104:107]
	v_mfma_f32_16x16x32_bf16 v[116:119], v[146:149], v[186:189], v[116:119]
	v_mfma_f32_16x16x32_bf16 v[120:123], v[154:157], v[186:189], v[120:123]
	v_mfma_f32_16x16x32_bf16 v[84:87], v[146:149], v[194:197], v[84:87]
	v_mfma_f32_16x16x32_bf16 v[80:83], v[154:157], v[194:197], v[80:83]
	v_mfma_f32_16x16x32_bf16 v[36:39], v[146:149], v[202:205], v[36:39]
	v_mfma_f32_16x16x32_bf16 v[24:27], v[154:157], v[202:205], v[24:27]
	v_mfma_f32_16x16x32_bf16 v[100:103], v[150:153], v[182:185], v[100:103]
	v_mfma_f32_16x16x32_bf16 v[104:107], v[158:161], v[182:185], v[104:107]
	v_mfma_f32_16x16x32_bf16 v[116:119], v[150:153], v[190:193], v[116:119]
	v_mfma_f32_16x16x32_bf16 v[120:123], v[158:161], v[190:193], v[120:123]
	v_mfma_f32_16x16x32_bf16 v[84:87], v[150:153], v[198:201], v[84:87]
	v_mfma_f32_16x16x32_bf16 v[80:83], v[158:161], v[198:201], v[80:83]
	v_mfma_f32_16x16x32_bf16 v[36:39], v[150:153], v[206:209], v[36:39]
	v_mfma_f32_16x16x32_bf16 v[24:27], v[158:161], v[206:209], v[24:27]
	v_mfma_f32_16x16x32_bf16 v[124:127], v[162:165], v[178:181], v[124:127]
	v_mfma_f32_16x16x32_bf16 v[112:115], v[170:173], v[178:181], v[112:115]
	v_mfma_f32_16x16x32_bf16 v[92:95], v[162:165], v[186:189], v[92:95]
	v_mfma_f32_16x16x32_bf16 v[88:91], v[170:173], v[186:189], v[88:91]
	v_mfma_f32_16x16x32_bf16 v[44:47], v[162:165], v[194:197], v[44:47]
	v_mfma_f32_16x16x32_bf16 v[40:43], v[170:173], v[194:197], v[40:43]
	v_mfma_f32_16x16x32_bf16 v[4:7], v[162:165], v[202:205], v[4:7]
	v_mfma_f32_16x16x32_bf16 v[0:3], v[170:173], v[202:205], v[0:3]
	v_mfma_f32_16x16x32_bf16 v[124:127], v[166:169], v[182:185], v[124:127]
	v_mfma_f32_16x16x32_bf16 v[112:115], v[174:177], v[182:185], v[112:115]
	v_mfma_f32_16x16x32_bf16 v[92:95], v[166:169], v[190:193], v[92:95]
	v_mfma_f32_16x16x32_bf16 v[88:91], v[174:177], v[190:193], v[88:91]
	v_mfma_f32_16x16x32_bf16 v[44:47], v[166:169], v[198:201], v[44:47]
	v_mfma_f32_16x16x32_bf16 v[40:43], v[174:177], v[198:201], v[40:43]
	v_mfma_f32_16x16x32_bf16 v[4:7], v[166:169], v[206:209], v[4:7]
	v_mfma_f32_16x16x32_bf16 v[0:3], v[174:177], v[206:209], v[0:3]
	s_barrier
	s_add_i32 s41, s41, 2
	s_add_u32 s37, s37, 0x100
	s_addc_u32 s38, s38, 0
	s_add_u32 s39, s39, 0x10000
	s_addc_u32 s40, s40, 0
	v_lshl_add_u64 v[136:137], v[136:137], 0, s[66:67]
	s_cmpk_gt_u32 s41, 0x7d
	v_lshl_add_u64 v[138:139], v[138:139], 0, s[66:67]
	s_cbranch_scc0 .LBB0_2026
	s_waitcnt vmcnt(0)
	s_cmpk_lt_u32 s0, 0x100
	s_cbranch_scc0 .LBB0_2029
	s_barrier

; template <class Epi, class Sched, bool ALIGN_EPI = false, bool SP2 = false, bool A_TILED = false>
; __device__ __forceinline__ void gemm_phase(PG8_LAS unsigned char* lds, const Gemm g, const Sched& S, const Epi& E, const int wave_s) {
;     ...
;         const char* nA = has_next ? (const char*)g.A + (size_t)nxt.pm * tstepA : cA; const char* nB = has_next ? (const char*)g.Bt + (size_t)nxt.pn * tstep : cB;
;         constexpr bool PEEL = SP2 && !Epi::AFTER_DRAIN;
;         if constexpr (PEEL) {
;             const char* a1 = cA + kstepA; const char* a2 = cA + 2 * kstepA; const char* b2 = cB + 2 * kstep; const char* a3 = a2 + kstepA; const char* b3 = b2 + kstep;
;             PG8_ITER(PG8_MMAZ)
.LBB0_2416:
	s_ashr_i32 s73, s72, 31
	s_lshl_b64 s[50:51], s[72:73], 20
	s_add_u32 s74, s1, s50
	ds_read_b128 v[0:3], v141
	ds_read_b128 v[4:7], v141 offset:1024
	ds_read_b128 v[8:11], v141 offset:2048
	ds_read_b128 v[12:15], v141 offset:3072
	ds_read_b128 v[16:19], v142
	ds_read_b128 v[20:23], v142 offset:1024
	ds_read_b128 v[24:27], v142 offset:2048
	ds_read_b128 v[28:31], v142 offset:3072
	s_addc_u32 s75, s8, s51
	s_ashr_i32 s71, s70, 31
	s_lshl_b64 s[50:51], s[70:71], 20
	s_add_u32 s76, s9, s50
	s_addc_u32 s77, s14, s51
	s_and_b64 s[50:51], s[2:3], exec
	s_cselect_b32 s50, s75, s81
	s_cselect_b32 s51, s74, s80
	s_cselect_b32 s52, s77, s79
	s_cselect_b32 s53, s76, s78
	s_add_u32 s54, s80, 0x80080
	s_addc_u32 s55, s81, 0
	s_mov_b32 m0, s48
	v_lshl_add_u64 v[64:65], s[54:55], 0, v[128:129]
	ds_read_b128 v[32:35], v143
	ds_read_b128 v[36:39], v143 offset:1024
	ds_read_b128 v[40:43], v143 offset:2048
	ds_read_b128 v[44:47], v143 offset:3072
	ds_read_b128 v[48:51], v143 offset:4096
	ds_read_b128 v[52:55], v143 offset:5120
	ds_read_b128 v[56:59], v143 offset:6144
	ds_read_b128 v[60:63], v143 offset:7168
	global_load_lds_dwordx4 v[64:65], off
	v_lshl_add_u64 v[64:65], s[54:55], 0, v[130:131]
	s_mov_b32 m0, s49
	s_nop 0
	global_load_lds_dwordx4 v[64:65], off
	s_waitcnt vmcnt(8) lgkmcnt(0)
	s_barrier
	v_mfma_f32_16x16x32_bf16 v[64:67], v[0:3], v[32:35], 0
	v_mfma_f32_16x16x32_bf16 v[68:71], v[8:11], v[32:35], 0
	v_mfma_f32_16x16x32_bf16 v[72:75], v[0:3], v[40:43], 0
	v_mfma_f32_16x16x32_bf16 v[76:79], v[8:11], v[40:43], 0
	v_mfma_f32_16x16x32_bf16 v[80:83], v[0:3], v[48:51], 0
	v_mfma_f32_16x16x32_bf16 v[84:87], v[8:11], v[48:51], 0
	v_mfma_f32_16x16x32_bf16 v[88:91], v[0:3], v[56:59], 0
	v_mfma_f32_16x16x32_bf16 v[92:95], v[8:11], v[56:59], 0
	v_mfma_f32_16x16x32_bf16 v[64:67], v[4:7], v[36:39], v[64:67]
	v_mfma_f32_16x16x32_bf16 v[68:71], v[12:15], v[36:39], v[68:71]
	v_mfma_f32_16x16x32_bf16 v[72:75], v[4:7], v[44:47], v[72:75]
	v_mfma_f32_16x16x32_bf16 v[76:79], v[12:15], v[44:47], v[76:79]
	v_mfma_f32_16x16x32_bf16 v[80:83], v[4:7], v[52:55], v[80:83]
	v_mfma_f32_16x16x32_bf16 v[84:87], v[12:15], v[52:55], v[84:87]
	v_mfma_f32_16x16x32_bf16 v[88:91], v[4:7], v[60:63], v[88:91]
	v_mfma_f32_16x16x32_bf16 v[92:95], v[12:15], v[60:63], v[92:95]
	v_mfma_f32_16x16x32_bf16 v[96:99], v[16:19], v[32:35], 0
	v_mfma_f32_16x16x32_bf16 v[32:35], v[24:27], v[32:35], 0
	v_mfma_f32_16x16x32_bf16 v[96:99], v[20:23], v[36:39], v[96:99]
	v_mfma_f32_16x16x32_bf16 v[32:35], v[28:31], v[36:39], v[32:35]
	v_mfma_f32_16x16x32_bf16 v[36:39], v[16:19], v[40:43], 0
	v_mfma_f32_16x16x32_bf16 v[40:43], v[24:27], v[40:43], 0
	v_mfma_f32_16x16x32_bf16 v[36:39], v[20:23], v[44:47], v[36:39]
	v_mfma_f32_16x16x32_bf16 v[40:43], v[28:31], v[44:47], v[40:43]
	v_mfma_f32_16x16x32_bf16 v[44:47], v[16:19], v[48:51], 0
	v_mfma_f32_16x16x32_bf16 v[48:51], v[24:27], v[48:51], 0
	v_mfma_f32_16x16x32_bf16 v[100:103], v[28:31], v[52:55], v[48:51]
	v_mfma_f32_16x16x32_bf16 v[48:51], v[16:19], v[56:59], 0
	v_mfma_f32_16x16x32_bf16 v[104:107], v[20:23], v[60:63], v[48:51]
	v_mfma_f32_16x16x32_bf16 v[48:51], v[24:27], v[56:59], 0
	v_mfma_f32_16x16x32_bf16 v[44:47], v[20:23], v[52:55], v[44:47]
	v_mfma_f32_16x16x32_bf16 v[108:111], v[28:31], v[60:63], v[48:51]
	s_barrier
	s_add_i32 s54, s45, s15
	v_lshl_add_u64 v[250:251], s[78:79], 0, v[128:129]
	s_add_i32 s55, s54, 0x2000
	v_lshl_add_u64 v[144:145], v[250:251], 0, s[66:67]
	s_mov_b32 m0, s54
	v_lshl_add_u64 v[252:253], s[78:79], 0, v[130:131]
	s_add_u32 s58, s78, 0x80100
	ds_read_b128 v[48:51], v143 offset:16384
	ds_read_b128 v[52:55], v143 offset:17408
	ds_read_b128 v[56:59], v143 offset:18432
	ds_read_b128 v[60:63], v143 offset:19456
	ds_read_b128 v[112:115], v143 offset:20480
	ds_read_b128 v[116:119], v143 offset:21504
	ds_read_b128 v[120:123], v143 offset:22528
	ds_read_b128 v[124:127], v143 offset:23552
	global_load_lds_dwordx4 v[144:145], off
	v_lshl_add_u64 v[144:145], v[252:253], 0, s[66:67]
	s_mov_b32 m0, s55
	s_addc_u32 s59, s79, 0
	s_add_i32 s56, s46, s15
	global_load_lds_dwordx4 v[144:145], off
	v_lshl_add_u64 v[144:145], s[58:59], 0, v[128:129]
	s_mov_b32 m0, s56
	s_add_i32 s57, s56, 0x2000
	global_load_lds_dwordx4 v[144:145], off
	v_lshl_add_u64 v[144:145], s[58:59], 0, v[130:131]
	s_mov_b32 m0, s57
	v_lshl_add_u64 v[136:137], s[80:81], 0, v[128:129]
	global_load_lds_dwordx4 v[144:145], off
	v_lshl_add_u64 v[144:145], v[136:137], 0, s[66:67]
	s_mov_b32 m0, s22
	v_lshl_add_u64 v[138:139], s[80:81], 0, v[130:131]
	global_load_lds_dwordx4 v[144:145], off
	v_lshl_add_u64 v[144:145], v[138:139], 0, s[66:67]
	s_mov_b32 m0, s23
	s_nop 0
	global_load_lds_dwordx4 v[144:145], off
	s_waitcnt vmcnt(8) lgkmcnt(0)
	s_barrier
	v_mfma_f32_16x16x32_bf16 v[144:147], v[0:3], v[48:51], 0
	v_mfma_f32_16x16x32_bf16 v[154:157], v[0:3], v[56:59], 0
	v_mfma_f32_16x16x32_bf16 v[162:165], v[0:3], v[112:115], 0
	v_mfma_f32_16x16x32_bf16 v[0:3], v[0:3], v[120:123], 0
	v_mfma_f32_16x16x32_bf16 v[150:153], v[8:11], v[48:51], 0
	v_mfma_f32_16x16x32_bf16 v[158:161], v[8:11], v[56:59], 0
	v_mfma_f32_16x16x32_bf16 v[166:169], v[8:11], v[112:115], 0
	v_mfma_f32_16x16x32_bf16 v[170:173], v[4:7], v[124:127], v[0:3]
	v_mfma_f32_16x16x32_bf16 v[0:3], v[8:11], v[120:123], 0
	v_mfma_f32_16x16x32_bf16 v[146:149], v[4:7], v[52:55], v[144:147]
	v_mfma_f32_16x16x32_bf16 v[150:153], v[12:15], v[52:55], v[150:153]
	v_mfma_f32_16x16x32_bf16 v[154:157], v[4:7], v[60:63], v[154:157]
	v_mfma_f32_16x16x32_bf16 v[158:161], v[12:15], v[60:63], v[158:161]
	v_mfma_f32_16x16x32_bf16 v[162:165], v[4:7], v[116:119], v[162:165]
	v_mfma_f32_16x16x32_bf16 v[166:169], v[12:15], v[116:119], v[166:169]
	v_mfma_f32_16x16x32_bf16 v[174:177], v[12:15], v[124:127], v[0:3]
	v_mfma_f32_16x16x32_bf16 v[0:3], v[16:19], v[48:51], 0
	v_mfma_f32_16x16x32_bf16 v[178:181], v[20:23], v[52:55], v[0:3]
	v_mfma_f32_16x16x32_bf16 v[0:3], v[24:27], v[48:51], 0
	v_mfma_f32_16x16x32_bf16 v[182:185], v[28:31], v[52:55], v[0:3]
	v_mfma_f32_16x16x32_bf16 v[0:3], v[16:19], v[56:59], 0
	v_mfma_f32_16x16x32_bf16 v[186:189], v[20:23], v[60:63], v[0:3]
	v_mfma_f32_16x16x32_bf16 v[0:3], v[24:27], v[56:59], 0
	v_mfma_f32_16x16x32_bf16 v[190:193], v[28:31], v[60:63], v[0:3]
	v_mfma_f32_16x16x32_bf16 v[0:3], v[16:19], v[112:115], 0
	v_mfma_f32_16x16x32_bf16 v[194:197], v[20:23], v[116:119], v[0:3]
	v_mfma_f32_16x16x32_bf16 v[0:3], v[24:27], v[112:115], 0
	v_mfma_f32_16x16x32_bf16 v[198:201], v[28:31], v[116:119], v[0:3]
	v_mfma_f32_16x16x32_bf16 v[0:3], v[16:19], v[120:123], 0
	v_mfma_f32_16x16x32_bf16 v[202:205], v[20:23], v[124:127], v[0:3]
	v_mfma_f32_16x16x32_bf16 v[0:3], v[24:27], v[120:123], 0
	v_mfma_f32_16x16x32_bf16 v[206:209], v[28:31], v[124:127], v[0:3]
	s_barrier
	s_add_i32 s61, 0, 0x18000
	s_add_i32 s71, 0, 0x1c000
	v_add_u32_e32 v144, s61, v140
	v_add_u32_e32 v145, s71, v140
	ds_read_b128 v[112:115], v144
	ds_read_b128 v[116:119], v144 offset:1024
	ds_read_b128 v[120:123], v144 offset:2048
	ds_read_b128 v[124:127], v144 offset:3072
	ds_read_b128 v[210:213], v145
	ds_read_b128 v[214:217], v145 offset:1024
	ds_read_b128 v[218:221], v145 offset:2048
	ds_read_b128 v[222:225], v145 offset:3072
	s_add_u32 s58, s80, 0x80100
	s_addc_u32 s59, s81, 0
	s_mov_b32 m0, s36
	v_lshl_add_u64 v[0:1], s[58:59], 0, v[128:129]
	ds_read_b128 v[48:51], v143 offset:32768
	ds_read_b128 v[52:55], v143 offset:33792
	ds_read_b128 v[226:229], v143 offset:34816
	ds_read_b128 v[230:233], v143 offset:35840
	ds_read_b128 v[234:237], v143 offset:36864
	ds_read_b128 v[238:241], v143 offset:37888
	ds_read_b128 v[242:245], v143 offset:38912
	ds_read_b128 v[246:249], v143 offset:39936
	global_load_lds_dwordx4 v[0:1], off
	v_lshl_add_u64 v[0:1], s[58:59], 0, v[130:131]
	s_mov_b32 m0, s37
	s_nop 0
	global_load_lds_dwordx4 v[0:1], off
	s_waitcnt vmcnt(8) lgkmcnt(0)
	s_barrier
	v_mfma_f32_16x16x32_bf16 v[0:3], v[112:115], v[48:51], v[64:67]
	v_mfma_f32_16x16x32_bf16 v[24:27], v[116:119], v[52:55], v[0:3]
	v_mfma_f32_16x16x32_bf16 v[0:3], v[120:123], v[48:51], v[68:71]
	v_mfma_f32_16x16x32_bf16 v[28:31], v[124:127], v[52:55], v[0:3]
	v_mfma_f32_16x16x32_bf16 v[0:3], v[112:115], v[226:229], v[72:75]
	v_mfma_f32_16x16x32_bf16 v[16:19], v[116:119], v[230:233], v[0:3]
	v_mfma_f32_16x16x32_bf16 v[0:3], v[120:123], v[226:229], v[76:79]
	v_mfma_f32_16x16x32_bf16 v[20:23], v[124:127], v[230:233], v[0:3]
	v_mfma_f32_16x16x32_bf16 v[0:3], v[112:115], v[234:237], v[80:83]
	v_mfma_f32_16x16x32_bf16 v[8:11], v[116:119], v[238:241], v[0:3]
	v_mfma_f32_16x16x32_bf16 v[0:3], v[120:123], v[234:237], v[84:87]
	v_mfma_f32_16x16x32_bf16 v[12:15], v[124:127], v[238:241], v[0:3]
	v_mfma_f32_16x16x32_bf16 v[0:3], v[112:115], v[242:245], v[88:91]
	v_mfma_f32_16x16x32_bf16 v[4:7], v[120:123], v[242:245], v[92:95]
	v_mfma_f32_16x16x32_bf16 v[0:3], v[116:119], v[246:249], v[0:3]
	v_mfma_f32_16x16x32_bf16 v[4:7], v[124:127], v[246:249], v[4:7]
	v_mfma_f32_16x16x32_bf16 v[32:35], v[218:221], v[48:51], v[32:35]
	v_mfma_f32_16x16x32_bf16 v[60:63], v[222:225], v[52:55], v[32:35]
	v_mfma_f32_16x16x32_bf16 v[32:35], v[210:213], v[226:229], v[36:39]
	v_mfma_f32_16x16x32_bf16 v[56:59], v[210:213], v[48:51], v[96:99]
	v_mfma_f32_16x16x32_bf16 v[48:51], v[214:217], v[230:233], v[32:35]
	v_mfma_f32_16x16x32_bf16 v[32:35], v[218:221], v[226:229], v[40:43]
	v_mfma_f32_16x16x32_bf16 v[56:59], v[214:217], v[52:55], v[56:59]
	v_mfma_f32_16x16x32_bf16 v[52:55], v[222:225], v[230:233], v[32:35]
	v_mfma_f32_16x16x32_bf16 v[32:35], v[210:213], v[234:237], v[44:47]
	v_mfma_f32_16x16x32_bf16 v[40:43], v[214:217], v[238:241], v[32:35]
	v_mfma_f32_16x16x32_bf16 v[32:35], v[218:221], v[234:237], v[100:103]
	v_mfma_f32_16x16x32_bf16 v[44:47], v[222:225], v[238:241], v[32:35]
	v_mfma_f32_16x16x32_bf16 v[32:35], v[210:213], v[242:245], v[104:107]
	v_mfma_f32_16x16x32_bf16 v[36:39], v[218:221], v[242:245], v[108:111]
	v_mfma_f32_16x16x32_bf16 v[32:35], v[214:217], v[246:249], v[32:35]
	v_mfma_f32_16x16x32_bf16 v[36:39], v[222:225], v[246:249], v[36:39]
	s_barrier
; #define PG8_MMA(ai, bj, At, Bt) do { __builtin_amdgcn_s_setprio(1); _Pragma("unroll") for (int m = 0; m < 4; ++m) _Pragma("unroll") for (int n = 0; n < 2; ++n) _Pragma("unroll") for (int k = 0; k < 2; ++k) \
;         acc[ai][bj][m][n] = __builtin_amdgcn_mfma_f32_16x16x32_bf16(Bt[n][k], At[m][k], acc[ai][bj][m][n], 0, 0, 0); __builtin_amdgcn_s_setprio(0); } while (0)
; template <class Epi, class Sched, bool ALIGN_EPI = false, bool SP2 = false, bool A_TILED = false>
; __device__ __forceinline__ void gemm_phase(PG8_LAS unsigned char* lds, const Gemm g, const Sched& S, const Epi& E, const int wave_s) {
;     ...
;         for (int t = PEEL ? 2 : 0; t < nt; t += 2) {
;             const bool last = (t == nt - 2);
;             const char* a1 = cA + (size_t)(t + 1) * kstepA;
;             const char* a2 = last ? nA : cA + (size_t)(t + 2) * kstepA; const char* b2 = last ? nB : cB + (size_t)(t + 2) * kstep;
;             const char* a3 = a2 + kstepA; const char* b3 = b2 + kstep;
;             if (last && has_next) S.a_ready(nxt);
;             if constexpr (SP2) {
;             PG8_ITER(PG8_MMA)
	s_add_i32 s58, s61, s15
	s_add_i32 s59, s58, 0x2000
	v_lshl_add_u64 v[64:65], v[250:251], 0, s[68:69]
	s_mov_b32 m0, s58
	s_add_u32 s82, s78, 0x80180
	ds_read_b128 v[96:99], v143 offset:49152
	ds_read_b128 v[100:103], v143 offset:50176
	ds_read_b128 v[104:107], v143 offset:51200
	ds_read_b128 v[108:111], v143 offset:52224
	ds_read_b128 v[226:229], v143 offset:53248
	ds_read_b128 v[230:233], v143 offset:54272
	ds_read_b128 v[234:237], v143 offset:55296
	ds_read_b128 v[238:241], v143 offset:56320
	global_load_lds_dwordx4 v[64:65], off
	v_lshl_add_u64 v[64:65], v[252:253], 0, s[68:69]
	s_mov_b32 m0, s59
	s_addc_u32 s83, s79, 0
	s_add_i32 s61, s71, s15
	global_load_lds_dwordx4 v[64:65], off
	v_lshl_add_u64 v[64:65], s[82:83], 0, v[128:129]
	s_mov_b32 m0, s61
	s_add_i32 s71, s61, 0x2000
	global_load_lds_dwordx4 v[64:65], off
	v_lshl_add_u64 v[64:65], s[82:83], 0, v[130:131]
	s_mov_b32 m0, s71
	s_nop 0
	global_load_lds_dwordx4 v[64:65], off
	v_lshl_add_u64 v[64:65], v[136:137], 0, s[68:69]
	s_mov_b32 m0, s42
	s_nop 0
	global_load_lds_dwordx4 v[64:65], off
	v_lshl_add_u64 v[64:65], v[138:139], 0, s[68:69]
	s_mov_b32 m0, s43
	s_nop 0
	global_load_lds_dwordx4 v[64:65], off
	s_waitcnt vmcnt(8) lgkmcnt(0)
	s_barrier
	v_mfma_f32_16x16x32_bf16 v[64:67], v[112:115], v[96:99], v[146:149]
	v_mfma_f32_16x16x32_bf16 v[88:91], v[116:119], v[100:103], v[64:67]
	v_mfma_f32_16x16x32_bf16 v[64:67], v[120:123], v[96:99], v[150:153]
	v_mfma_f32_16x16x32_bf16 v[92:95], v[124:127], v[100:103], v[64:67]
	v_mfma_f32_16x16x32_bf16 v[64:67], v[112:115], v[104:107], v[154:157]
	v_mfma_f32_16x16x32_bf16 v[80:83], v[116:119], v[108:111], v[64:67]
	v_mfma_f32_16x16x32_bf16 v[64:67], v[120:123], v[104:107], v[158:161]
	v_mfma_f32_16x16x32_bf16 v[84:87], v[124:127], v[108:111], v[64:67]
	v_mfma_f32_16x16x32_bf16 v[64:67], v[112:115], v[226:229], v[162:165]
	v_mfma_f32_16x16x32_bf16 v[72:75], v[116:119], v[230:233], v[64:67]
	v_mfma_f32_16x16x32_bf16 v[64:67], v[120:123], v[226:229], v[166:169]
	v_mfma_f32_16x16x32_bf16 v[76:79], v[124:127], v[230:233], v[64:67]
	v_mfma_f32_16x16x32_bf16 v[64:67], v[112:115], v[234:237], v[170:173]
	v_mfma_f32_16x16x32_bf16 v[68:71], v[120:123], v[234:237], v[174:177]
	v_mfma_f32_16x16x32_bf16 v[64:67], v[116:119], v[238:241], v[64:67]
	v_mfma_f32_16x16x32_bf16 v[68:71], v[124:127], v[238:241], v[68:71]
	v_mfma_f32_16x16x32_bf16 v[112:115], v[210:213], v[96:99], v[178:181]
	v_mfma_f32_16x16x32_bf16 v[96:99], v[218:221], v[96:99], v[182:185]
	v_mfma_f32_16x16x32_bf16 v[124:127], v[222:225], v[100:103], v[96:99]
	v_mfma_f32_16x16x32_bf16 v[96:99], v[210:213], v[104:107], v[186:189]
	v_mfma_f32_16x16x32_bf16 v[120:123], v[214:217], v[100:103], v[112:115]
	v_mfma_f32_16x16x32_bf16 v[112:115], v[214:217], v[108:111], v[96:99]
	v_mfma_f32_16x16x32_bf16 v[96:99], v[218:221], v[104:107], v[190:193]
	v_mfma_f32_16x16x32_bf16 v[116:119], v[222:225], v[108:111], v[96:99]
	v_mfma_f32_16x16x32_bf16 v[96:99], v[210:213], v[226:229], v[194:197]
	v_mfma_f32_16x16x32_bf16 v[104:107], v[214:217], v[230:233], v[96:99]
	v_mfma_f32_16x16x32_bf16 v[96:99], v[218:221], v[226:229], v[198:201]
	v_mfma_f32_16x16x32_bf16 v[108:111], v[222:225], v[230:233], v[96:99]
	v_mfma_f32_16x16x32_bf16 v[96:99], v[210:213], v[234:237], v[202:205]
	v_mfma_f32_16x16x32_bf16 v[100:103], v[218:221], v[234:237], v[206:209]
	v_mfma_f32_16x16x32_bf16 v[96:99], v[214:217], v[238:241], v[96:99]
	v_mfma_f32_16x16x32_bf16 v[100:103], v[222:225], v[238:241], v[100:103]
	s_barrier
	s_add_u32 s73, s78, 0x200
	s_addc_u32 s85, s79, 0
	s_add_u32 s78, s80, 0x80180
	s_addc_u32 s79, s81, 0
	s_mov_b32 s88, 0
.LBB0_2417:
	ds_read_b128 v[146:149], v141
	ds_read_b128 v[150:153], v141 offset:1024
	ds_read_b128 v[154:157], v141 offset:2048
	ds_read_b128 v[158:161], v141 offset:3072
	ds_read_b128 v[162:165], v142
	ds_read_b128 v[166:169], v142 offset:1024
	ds_read_b128 v[170:173], v142 offset:2048
	ds_read_b128 v[174:177], v142 offset:3072
	s_add_u32 s80, s78, 0xfff80080
	s_addc_u32 s81, s79, -1
	s_cmp_eq_u32 s88, 28
	s_cselect_b32 s83, s50, s81
	s_cselect_b32 s82, s51, s80
	s_cselect_b32 s81, s52, s85
	s_cselect_b32 s80, s53, s73
	s_mov_b32 m0, s48
	v_lshl_add_u64 v[136:137], s[78:79], 0, v[134:135]
	ds_read_b128 v[178:181], v143
	ds_read_b128 v[182:185], v143 offset:1024
	ds_read_b128 v[186:189], v143 offset:2048
	ds_read_b128 v[190:193], v143 offset:3072
	ds_read_b128 v[194:197], v143 offset:4096
	ds_read_b128 v[198:201], v143 offset:5120
	ds_read_b128 v[202:205], v143 offset:6144
	ds_read_b128 v[206:209], v143 offset:7168
	global_load_lds_dwordx4 v[136:137], off
	v_lshl_add_u64 v[136:137], s[78:79], 0, v[132:133]
	s_mov_b32 m0, s49
	s_nop 0
	global_load_lds_dwordx4 v[136:137], off
	s_waitcnt vmcnt(8) lgkmcnt(0)
	s_barrier
	v_mfma_f32_16x16x32_bf16 v[24:27], v[146:149], v[178:181], v[24:27]
	v_mfma_f32_16x16x32_bf16 v[28:31], v[154:157], v[178:181], v[28:31]
	v_mfma_f32_16x16x32_bf16 v[16:19], v[146:149], v[186:189], v[16:19]
	v_mfma_f32_16x16x32_bf16 v[20:23], v[154:157], v[186:189], v[20:23]
	v_mfma_f32_16x16x32_bf16 v[8:11], v[146:149], v[194:197], v[8:11]
	v_mfma_f32_16x16x32_bf16 v[12:15], v[154:157], v[194:197], v[12:15]
	v_mfma_f32_16x16x32_bf16 v[0:3], v[146:149], v[202:205], v[0:3]
	v_mfma_f32_16x16x32_bf16 v[4:7], v[154:157], v[202:205], v[4:7]
	v_mfma_f32_16x16x32_bf16 v[24:27], v[150:153], v[182:185], v[24:27]
	v_mfma_f32_16x16x32_bf16 v[28:31], v[158:161], v[182:185], v[28:31]
	v_mfma_f32_16x16x32_bf16 v[16:19], v[150:153], v[190:193], v[16:19]
	v_mfma_f32_16x16x32_bf16 v[20:23], v[158:161], v[190:193], v[20:23]
	v_mfma_f32_16x16x32_bf16 v[8:11], v[150:153], v[198:201], v[8:11]
	v_mfma_f32_16x16x32_bf16 v[12:15], v[158:161], v[198:201], v[12:15]
	v_mfma_f32_16x16x32_bf16 v[0:3], v[150:153], v[206:209], v[0:3]
	v_mfma_f32_16x16x32_bf16 v[4:7], v[158:161], v[206:209], v[4:7]
	v_mfma_f32_16x16x32_bf16 v[56:59], v[162:165], v[178:181], v[56:59]
	v_mfma_f32_16x16x32_bf16 v[60:63], v[170:173], v[178:181], v[60:63]
	v_mfma_f32_16x16x32_bf16 v[48:51], v[162:165], v[186:189], v[48:51]
	v_mfma_f32_16x16x32_bf16 v[52:55], v[170:173], v[186:189], v[52:55]
	v_mfma_f32_16x16x32_bf16 v[40:43], v[162:165], v[194:197], v[40:43]
	v_mfma_f32_16x16x32_bf16 v[44:47], v[170:173], v[194:197], v[44:47]
	v_mfma_f32_16x16x32_bf16 v[32:35], v[162:165], v[202:205], v[32:35]
	v_mfma_f32_16x16x32_bf16 v[36:39], v[170:173], v[202:205], v[36:39]
	v_mfma_f32_16x16x32_bf16 v[56:59], v[166:169], v[182:185], v[56:59]
	v_mfma_f32_16x16x32_bf16 v[60:63], v[174:177], v[182:185], v[60:63]
	v_mfma_f32_16x16x32_bf16 v[48:51], v[166:169], v[190:193], v[48:51]
	v_mfma_f32_16x16x32_bf16 v[52:55], v[174:177], v[190:193], v[52:55]
	v_mfma_f32_16x16x32_bf16 v[40:43], v[166:169], v[198:201], v[40:43]
	v_mfma_f32_16x16x32_bf16 v[44:47], v[174:177], v[198:201], v[44:47]
	v_mfma_f32_16x16x32_bf16 v[32:35], v[166:169], v[206:209], v[32:35]
	v_mfma_f32_16x16x32_bf16 v[36:39], v[174:177], v[206:209], v[36:39]
	s_barrier
	s_mov_b32 m0, s54
	v_lshl_add_u64 v[136:137], s[80:81], 0, v[128:129]
	s_add_u32 s90, s80, 0x80000
	ds_read_b128 v[178:181], v143 offset:16384
	ds_read_b128 v[182:185], v143 offset:17408
	ds_read_b128 v[186:189], v143 offset:18432
	ds_read_b128 v[190:193], v143 offset:19456
	ds_read_b128 v[194:197], v143 offset:20480
	ds_read_b128 v[198:201], v143 offset:21504
	ds_read_b128 v[202:205], v143 offset:22528
	ds_read_b128 v[206:209], v143 offset:23552
	global_load_lds_dwordx4 v[136:137], off
	v_lshl_add_u64 v[138:139], s[80:81], 0, v[130:131]
	s_mov_b32 m0, s55
	s_addc_u32 s91, s81, 0
	global_load_lds_dwordx4 v[138:139], off
	v_lshl_add_u64 v[210:211], s[90:91], 0, v[128:129]
	s_mov_b32 m0, s56
	v_lshl_add_u64 v[212:213], s[82:83], 0, v[130:131]
	global_load_lds_dwordx4 v[210:211], off
	v_lshl_add_u64 v[210:211], s[90:91], 0, v[130:131]
	s_mov_b32 m0, s57
	s_nop 0
	global_load_lds_dwordx4 v[210:211], off
	v_lshl_add_u64 v[210:211], s[82:83], 0, v[128:129]
	s_mov_b32 m0, s22
	s_nop 0
	global_load_lds_dwordx4 v[210:211], off
	s_mov_b32 m0, s23
	s_nop 0
	global_load_lds_dwordx4 v[212:213], off
	s_waitcnt vmcnt(8) lgkmcnt(0)
	s_barrier
	v_mfma_f32_16x16x32_bf16 v[88:91], v[146:149], v[178:181], v[88:91]
	v_mfma_f32_16x16x32_bf16 v[92:95], v[154:157], v[178:181], v[92:95]
	v_mfma_f32_16x16x32_bf16 v[80:83], v[146:149], v[186:189], v[80:83]
	v_mfma_f32_16x16x32_bf16 v[84:87], v[154:157], v[186:189], v[84:87]
	v_mfma_f32_16x16x32_bf16 v[72:75], v[146:149], v[194:197], v[72:75]
	v_mfma_f32_16x16x32_bf16 v[76:79], v[154:157], v[194:197], v[76:79]
	v_mfma_f32_16x16x32_bf16 v[64:67], v[146:149], v[202:205], v[64:67]
	v_mfma_f32_16x16x32_bf16 v[68:71], v[154:157], v[202:205], v[68:71]
	v_mfma_f32_16x16x32_bf16 v[88:91], v[150:153], v[182:185], v[88:91]
	v_mfma_f32_16x16x32_bf16 v[92:95], v[158:161], v[182:185], v[92:95]
	v_mfma_f32_16x16x32_bf16 v[80:83], v[150:153], v[190:193], v[80:83]
	v_mfma_f32_16x16x32_bf16 v[84:87], v[158:161], v[190:193], v[84:87]
	v_mfma_f32_16x16x32_bf16 v[72:75], v[150:153], v[198:201], v[72:75]
	v_mfma_f32_16x16x32_bf16 v[76:79], v[158:161], v[198:201], v[76:79]
	v_mfma_f32_16x16x32_bf16 v[64:67], v[150:153], v[206:209], v[64:67]
	v_mfma_f32_16x16x32_bf16 v[68:71], v[158:161], v[206:209], v[68:71]
	v_mfma_f32_16x16x32_bf16 v[120:123], v[162:165], v[178:181], v[120:123]
	v_mfma_f32_16x16x32_bf16 v[124:127], v[170:173], v[178:181], v[124:127]
	v_mfma_f32_16x16x32_bf16 v[112:115], v[162:165], v[186:189], v[112:115]
	v_mfma_f32_16x16x32_bf16 v[116:119], v[170:173], v[186:189], v[116:119]
	v_mfma_f32_16x16x32_bf16 v[104:107], v[162:165], v[194:197], v[104:107]
	v_mfma_f32_16x16x32_bf16 v[108:111], v[170:173], v[194:197], v[108:111]
	v_mfma_f32_16x16x32_bf16 v[96:99], v[162:165], v[202:205], v[96:99]
	v_mfma_f32_16x16x32_bf16 v[100:103], v[170:173], v[202:205], v[100:103]
	v_mfma_f32_16x16x32_bf16 v[120:123], v[166:169], v[182:185], v[120:123]
	v_mfma_f32_16x16x32_bf16 v[124:127], v[174:177], v[182:185], v[124:127]
	v_mfma_f32_16x16x32_bf16 v[112:115], v[166:169], v[190:193], v[112:115]
	v_mfma_f32_16x16x32_bf16 v[116:119], v[174:177], v[190:193], v[116:119]
	v_mfma_f32_16x16x32_bf16 v[104:107], v[166:169], v[198:201], v[104:107]
	v_mfma_f32_16x16x32_bf16 v[108:111], v[174:177], v[198:201], v[108:111]
	v_mfma_f32_16x16x32_bf16 v[96:99], v[166:169], v[206:209], v[96:99]
	v_mfma_f32_16x16x32_bf16 v[100:103], v[174:177], v[206:209], v[100:103]
	s_barrier
	ds_read_b128 v[146:149], v144
	ds_read_b128 v[150:153], v144 offset:1024
	ds_read_b128 v[154:157], v144 offset:2048
	ds_read_b128 v[158:161], v144 offset:3072
	ds_read_b128 v[162:165], v145
	ds_read_b128 v[166:169], v145 offset:1024
	ds_read_b128 v[170:173], v145 offset:2048
	ds_read_b128 v[174:177], v145 offset:3072
	s_add_u32 s82, s82, 0x80000
	s_addc_u32 s83, s83, 0
	s_mov_b32 m0, s36
	v_lshl_add_u64 v[214:215], s[82:83], 0, v[128:129]
	ds_read_b128 v[178:181], v143 offset:32768
	ds_read_b128 v[182:185], v143 offset:33792
	ds_read_b128 v[186:189], v143 offset:34816
	ds_read_b128 v[190:193], v143 offset:35840
	ds_read_b128 v[194:197], v143 offset:36864
	ds_read_b128 v[198:201], v143 offset:37888
	ds_read_b128 v[202:205], v143 offset:38912
	ds_read_b128 v[206:209], v143 offset:39936
	global_load_lds_dwordx4 v[214:215], off
	v_lshl_add_u64 v[214:215], s[82:83], 0, v[130:131]
	s_mov_b32 m0, s37
	s_nop 0
	global_load_lds_dwordx4 v[214:215], off
	s_waitcnt vmcnt(8) lgkmcnt(0)
	s_barrier
	v_mfma_f32_16x16x32_bf16 v[24:27], v[146:149], v[178:181], v[24:27]
	v_mfma_f32_16x16x32_bf16 v[28:31], v[154:157], v[178:181], v[28:31]
	v_mfma_f32_16x16x32_bf16 v[16:19], v[146:149], v[186:189], v[16:19]
	v_mfma_f32_16x16x32_bf16 v[20:23], v[154:157], v[186:189], v[20:23]
	v_mfma_f32_16x16x32_bf16 v[8:11], v[146:149], v[194:197], v[8:11]
	v_mfma_f32_16x16x32_bf16 v[12:15], v[154:157], v[194:197], v[12:15]
	v_mfma_f32_16x16x32_bf16 v[0:3], v[146:149], v[202:205], v[0:3]
	v_mfma_f32_16x16x32_bf16 v[4:7], v[154:157], v[202:205], v[4:7]
	v_mfma_f32_16x16x32_bf16 v[24:27], v[150:153], v[182:185], v[24:27]
	v_mfma_f32_16x16x32_bf16 v[28:31], v[158:161], v[182:185], v[28:31]
	v_mfma_f32_16x16x32_bf16 v[16:19], v[150:153], v[190:193], v[16:19]
	v_mfma_f32_16x16x32_bf16 v[20:23], v[158:161], v[190:193], v[20:23]
	v_mfma_f32_16x16x32_bf16 v[8:11], v[150:153], v[198:201], v[8:11]
	v_mfma_f32_16x16x32_bf16 v[12:15], v[158:161], v[198:201], v[12:15]
	v_mfma_f32_16x16x32_bf16 v[0:3], v[150:153], v[206:209], v[0:3]
	v_mfma_f32_16x16x32_bf16 v[4:7], v[158:161], v[206:209], v[4:7]
	v_mfma_f32_16x16x32_bf16 v[56:59], v[162:165], v[178:181], v[56:59]
	v_mfma_f32_16x16x32_bf16 v[60:63], v[170:173], v[178:181], v[60:63]
	v_mfma_f32_16x16x32_bf16 v[48:51], v[162:165], v[186:189], v[48:51]
	v_mfma_f32_16x16x32_bf16 v[52:55], v[170:173], v[186:189], v[52:55]
	v_mfma_f32_16x16x32_bf16 v[40:43], v[162:165], v[194:197], v[40:43]
	v_mfma_f32_16x16x32_bf16 v[44:47], v[170:173], v[194:197], v[44:47]
	v_mfma_f32_16x16x32_bf16 v[32:35], v[162:165], v[202:205], v[32:35]
	v_mfma_f32_16x16x32_bf16 v[36:39], v[170:173], v[202:205], v[36:39]
	v_mfma_f32_16x16x32_bf16 v[56:59], v[166:169], v[182:185], v[56:59]
	v_mfma_f32_16x16x32_bf16 v[60:63], v[174:177], v[182:185], v[60:63]
	v_mfma_f32_16x16x32_bf16 v[48:51], v[166:169], v[190:193], v[48:51]
	v_mfma_f32_16x16x32_bf16 v[52:55], v[174:177], v[190:193], v[52:55]
	v_mfma_f32_16x16x32_bf16 v[40:43], v[166:169], v[198:201], v[40:43]
	v_mfma_f32_16x16x32_bf16 v[44:47], v[174:177], v[198:201], v[44:47]
	v_mfma_f32_16x16x32_bf16 v[32:35], v[166:169], v[206:209], v[32:35]
	v_mfma_f32_16x16x32_bf16 v[36:39], v[174:177], v[206:209], v[36:39]
	s_barrier
	s_mov_b32 m0, s58
	v_lshl_add_u64 v[136:137], v[136:137], 0, s[62:63]
	s_add_u32 s80, s80, 0x80080
	ds_read_b128 v[178:181], v143 offset:49152
	ds_read_b128 v[182:185], v143 offset:50176
	ds_read_b128 v[186:189], v143 offset:51200
	ds_read_b128 v[190:193], v143 offset:52224
	ds_read_b128 v[194:197], v143 offset:53248
	ds_read_b128 v[198:201], v143 offset:54272
	ds_read_b128 v[202:205], v143 offset:55296
	ds_read_b128 v[206:209], v143 offset:56320
	global_load_lds_dwordx4 v[136:137], off
	v_lshl_add_u64 v[136:137], v[138:139], 0, s[62:63]
	s_mov_b32 m0, s59
	s_addc_u32 s81, s81, 0
	global_load_lds_dwordx4 v[136:137], off
	v_lshl_add_u64 v[136:137], s[80:81], 0, v[128:129]
	s_mov_b32 m0, s61
	s_nop 0
	global_load_lds_dwordx4 v[136:137], off
	v_lshl_add_u64 v[136:137], s[80:81], 0, v[130:131]
	s_mov_b32 m0, s71
	s_nop 0
	global_load_lds_dwordx4 v[136:137], off
	v_lshl_add_u64 v[136:137], v[210:211], 0, s[62:63]
	s_mov_b32 m0, s42
	s_nop 0
	global_load_lds_dwordx4 v[136:137], off
	v_lshl_add_u64 v[136:137], v[212:213], 0, s[62:63]
	s_mov_b32 m0, s43
	s_nop 0
	global_load_lds_dwordx4 v[136:137], off
	s_waitcnt vmcnt(8) lgkmcnt(0)
	s_barrier
	v_mfma_f32_16x16x32_bf16 v[88:91], v[146:149], v[178:181], v[88:91]
	v_mfma_f32_16x16x32_bf16 v[92:95], v[154:157], v[178:181], v[92:95]
	v_mfma_f32_16x16x32_bf16 v[80:83], v[146:149], v[186:189], v[80:83]
	v_mfma_f32_16x16x32_bf16 v[84:87], v[154:157], v[186:189], v[84:87]
	v_mfma_f32_16x16x32_bf16 v[72:75], v[146:149], v[194:197], v[72:75]
	v_mfma_f32_16x16x32_bf16 v[76:79], v[154:157], v[194:197], v[76:79]
	v_mfma_f32_16x16x32_bf16 v[64:67], v[146:149], v[202:205], v[64:67]
	v_mfma_f32_16x16x32_bf16 v[68:71], v[154:157], v[202:205], v[68:71]
	v_mfma_f32_16x16x32_bf16 v[88:91], v[150:153], v[182:185], v[88:91]
	v_mfma_f32_16x16x32_bf16 v[92:95], v[158:161], v[182:185], v[92:95]
	v_mfma_f32_16x16x32_bf16 v[80:83], v[150:153], v[190:193], v[80:83]
	v_mfma_f32_16x16x32_bf16 v[84:87], v[158:161], v[190:193], v[84:87]
	v_mfma_f32_16x16x32_bf16 v[72:75], v[150:153], v[198:201], v[72:75]
	v_mfma_f32_16x16x32_bf16 v[76:79], v[158:161], v[198:201], v[76:79]
	v_mfma_f32_16x16x32_bf16 v[64:67], v[150:153], v[206:209], v[64:67]
	v_mfma_f32_16x16x32_bf16 v[68:71], v[158:161], v[206:209], v[68:71]
	v_mfma_f32_16x16x32_bf16 v[120:123], v[162:165], v[178:181], v[120:123]
	v_mfma_f32_16x16x32_bf16 v[124:127], v[170:173], v[178:181], v[124:127]
	v_mfma_f32_16x16x32_bf16 v[112:115], v[162:165], v[186:189], v[112:115]
	v_mfma_f32_16x16x32_bf16 v[116:119], v[170:173], v[186:189], v[116:119]
	v_mfma_f32_16x16x32_bf16 v[104:107], v[162:165], v[194:197], v[104:107]
	v_mfma_f32_16x16x32_bf16 v[108:111], v[170:173], v[194:197], v[108:111]
	v_mfma_f32_16x16x32_bf16 v[96:99], v[162:165], v[202:205], v[96:99]
	v_mfma_f32_16x16x32_bf16 v[100:103], v[170:173], v[202:205], v[100:103]
	v_mfma_f32_16x16x32_bf16 v[120:123], v[166:169], v[182:185], v[120:123]
	v_mfma_f32_16x16x32_bf16 v[124:127], v[174:177], v[182:185], v[124:127]
	v_mfma_f32_16x16x32_bf16 v[112:115], v[166:169], v[190:193], v[112:115]
	v_mfma_f32_16x16x32_bf16 v[116:119], v[174:177], v[190:193], v[116:119]
	v_mfma_f32_16x16x32_bf16 v[104:107], v[166:169], v[198:201], v[104:107]
	v_mfma_f32_16x16x32_bf16 v[108:111], v[174:177], v[198:201], v[108:111]
	v_mfma_f32_16x16x32_bf16 v[96:99], v[166:169], v[206:209], v[96:99]
	v_mfma_f32_16x16x32_bf16 v[100:103], v[174:177], v[206:209], v[100:103]
	s_barrier
	s_add_i32 s88, s88, 2
	s_add_u32 s73, s73, 0x100
	s_addc_u32 s85, s85, 0
	s_add_u32 s78, s78, 0x100
	s_addc_u32 s79, s79, 0
	s_cmp_gt_u32 s88, 29
	s_cbranch_scc0 .LBB0_2417
	s_and_b64 vcc, exec, s[64:65]
	s_cbranch_vccz .LBB0_2420
	s_barrier

; template <class Epi, class Sched, bool ALIGN_EPI = false, bool SP2 = false, bool A_TILED = false>
; __device__ __forceinline__ void gemm_phase(PG8_LAS unsigned char* lds, const Gemm g, const Sched& S, const Epi& E, const int wave_s) {
;     ...
;         const char* nA = has_next ? (const char*)g.A + (size_t)nxt.pm * tstepA : cA; const char* nB = has_next ? (const char*)g.Bt + (size_t)nxt.pn * tstep : cB;
;         constexpr bool PEEL = SP2 && !Epi::AFTER_DRAIN;
;         if constexpr (PEEL) {
;             const char* a1 = cA + kstepA; const char* a2 = cA + 2 * kstepA; const char* b2 = cB + 2 * kstep; const char* a3 = a2 + kstepA; const char* b3 = b2 + kstep;
;             PG8_ITER(PG8_MMAZ)
.LBB0_2545:
	s_ashr_i32 s73, s72, 31
	s_lshl_b64 s[58:59], s[72:73], 18
	s_add_u32 s74, s14, s58
	ds_read_b128 v[0:3], v149
	ds_read_b128 v[4:7], v149 offset:1024
	ds_read_b128 v[8:11], v149 offset:2048
	ds_read_b128 v[12:15], v149 offset:3072
	ds_read_b128 v[16:19], v150
	ds_read_b128 v[20:23], v150 offset:1024
	ds_read_b128 v[24:27], v150 offset:2048
	ds_read_b128 v[28:31], v150 offset:3072
	s_addc_u32 s75, s15, s59
	s_ashr_i32 s71, s70, 31
	s_lshl_b64 s[58:59], s[70:71], 18
	s_add_u32 s76, s23, s58
	s_addc_u32 s77, s36, s59
	s_and_b64 s[58:59], s[2:3], exec
	s_cselect_b32 s58, s75, s81
	s_cselect_b32 s59, s74, s80
	s_cselect_b32 s71, s77, s79
	s_cselect_b32 s73, s76, s78
	s_add_u32 s82, s80, 0x20080
	s_addc_u32 s83, s81, 0
	s_add_i32 s88, s38, 0xc000
	v_lshl_add_u64 v[64:65], s[82:83], 0, v[134:135]
	s_mov_b32 m0, s88
	s_add_i32 s89, s38, 0xe000
	ds_read_b128 v[32:35], v151
	ds_read_b128 v[36:39], v151 offset:1024
	ds_read_b128 v[40:43], v151 offset:2048
	ds_read_b128 v[44:47], v151 offset:3072
	ds_read_b128 v[48:51], v151 offset:4096
	ds_read_b128 v[52:55], v151 offset:5120
	ds_read_b128 v[56:59], v151 offset:6144
	ds_read_b128 v[60:63], v151 offset:7168
	global_load_lds_dwordx4 v[64:65], off
	v_lshl_add_u64 v[64:65], s[82:83], 0, v[132:133]
	s_mov_b32 m0, s89
	s_nop 0
	global_load_lds_dwordx4 v[64:65], off
	s_waitcnt vmcnt(8) lgkmcnt(0)
	s_barrier
	v_mfma_f32_16x16x32_bf16 v[88:91], v[0:3], v[56:59], 0
	v_mfma_f32_16x16x32_bf16 v[64:67], v[0:3], v[32:35], 0
	v_mfma_f32_16x16x32_bf16 v[68:71], v[8:11], v[32:35], 0
	v_mfma_f32_16x16x32_bf16 v[72:75], v[0:3], v[40:43], 0
	v_mfma_f32_16x16x32_bf16 v[76:79], v[8:11], v[40:43], 0
	v_mfma_f32_16x16x32_bf16 v[80:83], v[0:3], v[48:51], 0
	v_mfma_f32_16x16x32_bf16 v[84:87], v[8:11], v[48:51], 0
	v_mfma_f32_16x16x32_bf16 v[96:99], v[4:7], v[60:63], v[88:91]
	v_mfma_f32_16x16x32_bf16 v[88:91], v[8:11], v[56:59], 0
	v_mfma_f32_16x16x32_bf16 v[64:67], v[4:7], v[36:39], v[64:67]
	v_mfma_f32_16x16x32_bf16 v[68:71], v[12:15], v[36:39], v[68:71]
	v_mfma_f32_16x16x32_bf16 v[72:75], v[4:7], v[44:47], v[72:75]
	v_mfma_f32_16x16x32_bf16 v[76:79], v[12:15], v[44:47], v[76:79]
	v_mfma_f32_16x16x32_bf16 v[80:83], v[4:7], v[52:55], v[80:83]
	v_mfma_f32_16x16x32_bf16 v[84:87], v[12:15], v[52:55], v[84:87]
	v_mfma_f32_16x16x32_bf16 v[100:103], v[12:15], v[60:63], v[88:91]
	v_mfma_f32_16x16x32_bf16 v[88:91], v[16:19], v[32:35], 0
	v_mfma_f32_16x16x32_bf16 v[32:35], v[24:27], v[32:35], 0
	v_mfma_f32_16x16x32_bf16 v[112:115], v[20:23], v[36:39], v[88:91]
	v_mfma_f32_16x16x32_bf16 v[32:35], v[28:31], v[36:39], v[32:35]
	v_mfma_f32_16x16x32_bf16 v[36:39], v[16:19], v[40:43], 0
	v_mfma_f32_16x16x32_bf16 v[40:43], v[24:27], v[40:43], 0
	v_mfma_f32_16x16x32_bf16 v[36:39], v[20:23], v[44:47], v[36:39]
	v_mfma_f32_16x16x32_bf16 v[40:43], v[28:31], v[44:47], v[40:43]
	v_mfma_f32_16x16x32_bf16 v[44:47], v[16:19], v[48:51], 0
	v_mfma_f32_16x16x32_bf16 v[48:51], v[24:27], v[48:51], 0
	v_mfma_f32_16x16x32_bf16 v[44:47], v[20:23], v[52:55], v[44:47]
	v_mfma_f32_16x16x32_bf16 v[48:51], v[28:31], v[52:55], v[48:51]
	v_mfma_f32_16x16x32_bf16 v[52:55], v[16:19], v[56:59], 0
	v_mfma_f32_16x16x32_bf16 v[56:59], v[24:27], v[56:59], 0
	v_mfma_f32_16x16x32_bf16 v[52:55], v[20:23], v[60:63], v[52:55]
	v_mfma_f32_16x16x32_bf16 v[56:59], v[28:31], v[60:63], v[56:59]
	s_barrier
	s_add_i32 s90, s53, s37
	v_lshl_add_u64 v[250:251], s[78:79], 0, v[128:129]
	s_add_i32 s91, s90, 0x2000
	v_lshl_add_u64 v[144:145], v[250:251], 0, s[66:67]
	s_mov_b32 m0, s90
	v_lshl_add_u64 v[252:253], s[78:79], 0, v[130:131]
	s_add_u32 s82, s78, 0x20100
	ds_read_b128 v[60:63], v151 offset:16384
	ds_read_b128 v[88:91], v151 offset:17408
	ds_read_b128 v[92:95], v151 offset:18432
	ds_read_b128 v[104:107], v151 offset:19456
	ds_read_b128 v[108:111], v151 offset:20480
	ds_read_b128 v[116:119], v151 offset:21504
	ds_read_b128 v[120:123], v151 offset:22528
	ds_read_b128 v[124:127], v151 offset:23552
	global_load_lds_dwordx4 v[144:145], off
	v_lshl_add_u64 v[144:145], v[252:253], 0, s[66:67]
	s_mov_b32 m0, s91
	s_addc_u32 s83, s79, 0
	s_add_i32 s93, s54, s37
	global_load_lds_dwordx4 v[144:145], off
	v_lshl_add_u64 v[144:145], s[82:83], 0, v[128:129]
	s_mov_b32 m0, s93
	s_add_i32 s95, s93, 0x2000
	global_load_lds_dwordx4 v[144:145], off
	v_lshl_add_u64 v[144:145], s[82:83], 0, v[130:131]
	s_mov_b32 m0, s95
	v_lshl_add_u64 v[140:141], s[80:81], 0, v[134:135]
	global_load_lds_dwordx4 v[144:145], off
	v_lshl_add_u64 v[144:145], v[140:141], 0, s[66:67]
	s_mov_b32 m0, s38
	v_lshl_add_u64 v[142:143], s[80:81], 0, v[132:133]
	global_load_lds_dwordx4 v[144:145], off
	v_lshl_add_u64 v[144:145], v[142:143], 0, s[66:67]
	s_mov_b32 m0, s39
	s_nop 0
	global_load_lds_dwordx4 v[144:145], off
	s_waitcnt vmcnt(8) lgkmcnt(0)
	s_barrier
	v_mfma_f32_16x16x32_bf16 v[144:147], v[0:3], v[60:63], 0
	v_mfma_f32_16x16x32_bf16 v[154:157], v[4:7], v[88:91], v[144:147]
	v_mfma_f32_16x16x32_bf16 v[144:147], v[8:11], v[60:63], 0
	v_mfma_f32_16x16x32_bf16 v[158:161], v[12:15], v[88:91], v[144:147]
	v_mfma_f32_16x16x32_bf16 v[144:147], v[0:3], v[92:95], 0
	v_mfma_f32_16x16x32_bf16 v[162:165], v[4:7], v[104:107], v[144:147]
	v_mfma_f32_16x16x32_bf16 v[144:147], v[8:11], v[92:95], 0
	v_mfma_f32_16x16x32_bf16 v[166:169], v[12:15], v[104:107], v[144:147]
	v_mfma_f32_16x16x32_bf16 v[144:147], v[0:3], v[108:111], 0
	v_mfma_f32_16x16x32_bf16 v[0:3], v[0:3], v[120:123], 0
	v_mfma_f32_16x16x32_bf16 v[170:173], v[4:7], v[116:119], v[144:147]
	v_mfma_f32_16x16x32_bf16 v[0:3], v[4:7], v[124:127], v[0:3]
	v_mfma_f32_16x16x32_bf16 v[4:7], v[8:11], v[120:123], 0
	v_mfma_f32_16x16x32_bf16 v[144:147], v[8:11], v[108:111], 0
	v_mfma_f32_16x16x32_bf16 v[4:7], v[12:15], v[124:127], v[4:7]
	v_mfma_f32_16x16x32_bf16 v[174:177], v[12:15], v[116:119], v[144:147]
	v_mfma_f32_16x16x32_bf16 v[8:11], v[16:19], v[60:63], 0
	v_mfma_f32_16x16x32_bf16 v[178:181], v[20:23], v[88:91], v[8:11]
	v_mfma_f32_16x16x32_bf16 v[8:11], v[24:27], v[60:63], 0
	v_mfma_f32_16x16x32_bf16 v[182:185], v[28:31], v[88:91], v[8:11]
	v_mfma_f32_16x16x32_bf16 v[8:11], v[16:19], v[92:95], 0
	v_mfma_f32_16x16x32_bf16 v[186:189], v[20:23], v[104:107], v[8:11]
	v_mfma_f32_16x16x32_bf16 v[8:11], v[24:27], v[92:95], 0
	v_mfma_f32_16x16x32_bf16 v[190:193], v[28:31], v[104:107], v[8:11]
	v_mfma_f32_16x16x32_bf16 v[8:11], v[16:19], v[108:111], 0
	v_mfma_f32_16x16x32_bf16 v[194:197], v[20:23], v[116:119], v[8:11]
	v_mfma_f32_16x16x32_bf16 v[8:11], v[24:27], v[108:111], 0
	v_mfma_f32_16x16x32_bf16 v[198:201], v[28:31], v[116:119], v[8:11]
	v_mfma_f32_16x16x32_bf16 v[8:11], v[16:19], v[120:123], 0
	v_mfma_f32_16x16x32_bf16 v[202:205], v[20:23], v[124:127], v[8:11]
	v_mfma_f32_16x16x32_bf16 v[8:11], v[24:27], v[120:123], 0
	v_mfma_f32_16x16x32_bf16 v[206:209], v[28:31], v[124:127], v[8:11]
	s_barrier
	s_add_i32 s96, 0, 0x18000
	s_add_i32 vcc_lo, 0, 0x1c000
	v_add_u32_e32 v144, s96, v148
	v_add_u32_e32 v145, vcc_lo, v148
	s_nop 0
	ds_read_b128 v[8:11], v144
	ds_read_b128 v[12:15], v144 offset:1024
	ds_read_b128 v[16:19], v144 offset:2048
	ds_read_b128 v[20:23], v144 offset:3072
	ds_read_b128 v[210:213], v145
	ds_read_b128 v[214:217], v145 offset:1024
	ds_read_b128 v[218:221], v145 offset:2048
	ds_read_b128 v[222:225], v145 offset:3072
	s_add_u32 s82, s80, 0x20100
	s_addc_u32 s83, s81, 0
	s_mov_b32 m0, s40
	v_lshl_add_u64 v[88:89], s[82:83], 0, v[134:135]
	ds_read_b128 v[24:27], v151 offset:32768
	ds_read_b128 v[28:31], v151 offset:33792
	ds_read_b128 v[60:63], v151 offset:34816
	ds_read_b128 v[226:229], v151 offset:35840
	ds_read_b128 v[230:233], v151 offset:36864
	ds_read_b128 v[234:237], v151 offset:37888
	ds_read_b128 v[238:241], v151 offset:38912
	ds_read_b128 v[242:245], v151 offset:39936
	global_load_lds_dwordx4 v[88:89], off
	v_lshl_add_u64 v[88:89], s[82:83], 0, v[132:133]
	s_mov_b32 m0, s41
	s_nop 0
	global_load_lds_dwordx4 v[88:89], off
	s_waitcnt vmcnt(8) lgkmcnt(0)
	s_barrier
	v_mfma_f32_16x16x32_bf16 v[64:67], v[8:11], v[24:27], v[64:67]
	v_mfma_f32_16x16x32_bf16 v[124:127], v[12:15], v[28:31], v[64:67]
	v_mfma_f32_16x16x32_bf16 v[64:67], v[16:19], v[24:27], v[68:71]
	v_mfma_f32_16x16x32_bf16 v[120:123], v[20:23], v[28:31], v[64:67]
	v_mfma_f32_16x16x32_bf16 v[64:67], v[8:11], v[60:63], v[72:75]
	v_mfma_f32_16x16x32_bf16 v[108:111], v[12:15], v[226:229], v[64:67]
	v_mfma_f32_16x16x32_bf16 v[64:67], v[16:19], v[60:63], v[76:79]
	v_mfma_f32_16x16x32_bf16 v[104:107], v[20:23], v[226:229], v[64:67]
	v_mfma_f32_16x16x32_bf16 v[64:67], v[8:11], v[230:233], v[80:83]
	v_mfma_f32_16x16x32_bf16 v[92:95], v[12:15], v[234:237], v[64:67]
	v_mfma_f32_16x16x32_bf16 v[64:67], v[16:19], v[230:233], v[84:87]
	v_mfma_f32_16x16x32_bf16 v[88:91], v[20:23], v[234:237], v[64:67]
	v_mfma_f32_16x16x32_bf16 v[64:67], v[8:11], v[238:241], v[96:99]
	v_mfma_f32_16x16x32_bf16 v[76:79], v[12:15], v[242:245], v[64:67]
	v_mfma_f32_16x16x32_bf16 v[64:67], v[16:19], v[238:241], v[100:103]
	v_mfma_f32_16x16x32_bf16 v[72:75], v[20:23], v[242:245], v[64:67]
	v_mfma_f32_16x16x32_bf16 v[64:67], v[210:213], v[24:27], v[112:115]
	v_mfma_f32_16x16x32_bf16 v[24:27], v[218:221], v[24:27], v[32:35]
	v_mfma_f32_16x16x32_bf16 v[112:115], v[222:225], v[28:31], v[24:27]
	v_mfma_f32_16x16x32_bf16 v[24:27], v[210:213], v[60:63], v[36:39]
	v_mfma_f32_16x16x32_bf16 v[100:103], v[214:217], v[226:229], v[24:27]
	v_mfma_f32_16x16x32_bf16 v[24:27], v[218:221], v[60:63], v[40:43]
	v_mfma_f32_16x16x32_bf16 v[96:99], v[222:225], v[226:229], v[24:27]
	v_mfma_f32_16x16x32_bf16 v[24:27], v[210:213], v[230:233], v[44:47]
	v_mfma_f32_16x16x32_bf16 v[84:87], v[214:217], v[234:237], v[24:27]
	v_mfma_f32_16x16x32_bf16 v[24:27], v[218:221], v[230:233], v[48:51]
	v_mfma_f32_16x16x32_bf16 v[80:83], v[222:225], v[234:237], v[24:27]
	v_mfma_f32_16x16x32_bf16 v[24:27], v[210:213], v[238:241], v[52:55]
	v_mfma_f32_16x16x32_bf16 v[68:71], v[214:217], v[242:245], v[24:27]
	v_mfma_f32_16x16x32_bf16 v[24:27], v[218:221], v[238:241], v[56:59]
	v_mfma_f32_16x16x32_bf16 v[116:119], v[214:217], v[28:31], v[64:67]
	v_mfma_f32_16x16x32_bf16 v[64:67], v[222:225], v[242:245], v[24:27]
	s_barrier
; #define PG8_MMA(ai, bj, At, Bt) do { __builtin_amdgcn_s_setprio(1); _Pragma("unroll") for (int m = 0; m < 4; ++m) _Pragma("unroll") for (int n = 0; n < 2; ++n) _Pragma("unroll") for (int k = 0; k < 2; ++k) \
;         acc[ai][bj][m][n] = __builtin_amdgcn_mfma_f32_16x16x32_bf16(Bt[n][k], At[m][k], acc[ai][bj][m][n], 0, 0, 0); __builtin_amdgcn_s_setprio(0); } while (0)
; template <class Epi, class Sched, bool ALIGN_EPI = false, bool SP2 = false, bool A_TILED = false>
; __device__ __forceinline__ void gemm_phase(PG8_LAS unsigned char* lds, const Gemm g, const Sched& S, const Epi& E, const int wave_s) {
;     ...
;         for (int t = PEEL ? 2 : 0; t < nt; t += 2) {
;             const bool last = (t == nt - 2);
;             const char* a1 = cA + (size_t)(t + 1) * kstepA;
;             const char* a2 = last ? nA : cA + (size_t)(t + 2) * kstepA; const char* b2 = last ? nB : cB + (size_t)(t + 2) * kstep;
;             const char* a3 = a2 + kstepA; const char* b3 = b2 + kstep;
;             if (last && has_next) S.a_ready(nxt);
;             if constexpr (SP2) {
;             PG8_ITER(PG8_MMA)
	s_add_i32 s96, s96, s37
	s_add_i32 s97, s96, 0x2000
	s_nop 1
	v_lshl_add_u64 v[24:25], v[250:251], 0, s[68:69]
	s_mov_b32 m0, s96
	s_add_u32 s82, s78, 0x20180
	ds_read_b128 v[32:35], v151 offset:49152
	ds_read_b128 v[36:39], v151 offset:50176
	ds_read_b128 v[226:229], v151 offset:51200
	ds_read_b128 v[230:233], v151 offset:52224
	ds_read_b128 v[234:237], v151 offset:53248
	ds_read_b128 v[238:241], v151 offset:54272
	ds_read_b128 v[242:245], v151 offset:55296
	ds_read_b128 v[246:249], v151 offset:56320
	global_load_lds_dwordx4 v[24:25], off
	v_lshl_add_u64 v[24:25], v[252:253], 0, s[68:69]
	s_mov_b32 m0, s97
	s_addc_u32 s83, s79, 0
	s_add_i32 vcc_lo, vcc_lo, s37
	global_load_lds_dwordx4 v[24:25], off
	v_lshl_add_u64 v[24:25], s[82:83], 0, v[128:129]
	s_mov_b32 m0, vcc_lo
	s_add_i32 vcc_hi, vcc_lo, 0x2000
	global_load_lds_dwordx4 v[24:25], off
	v_lshl_add_u64 v[24:25], s[82:83], 0, v[130:131]
	s_mov_b32 m0, vcc_hi
	s_nop 0
	global_load_lds_dwordx4 v[24:25], off
	v_lshl_add_u64 v[24:25], v[140:141], 0, s[68:69]
	s_mov_b32 m0, s51
	s_nop 0
	global_load_lds_dwordx4 v[24:25], off
	v_lshl_add_u64 v[24:25], v[142:143], 0, s[68:69]
	s_mov_b32 m0, s52
	s_nop 0
	global_load_lds_dwordx4 v[24:25], off
	s_waitcnt vmcnt(8) lgkmcnt(0)
	s_barrier
	v_mfma_f32_16x16x32_bf16 v[24:27], v[8:11], v[32:35], v[154:157]
	v_mfma_f32_16x16x32_bf16 v[60:63], v[12:15], v[36:39], v[24:27]
	v_mfma_f32_16x16x32_bf16 v[24:27], v[16:19], v[32:35], v[158:161]
	v_mfma_f32_16x16x32_bf16 v[56:59], v[20:23], v[36:39], v[24:27]
	v_mfma_f32_16x16x32_bf16 v[24:27], v[8:11], v[226:229], v[162:165]
	v_mfma_f32_16x16x32_bf16 v[44:47], v[12:15], v[230:233], v[24:27]
	v_mfma_f32_16x16x32_bf16 v[24:27], v[16:19], v[226:229], v[166:169]
	v_mfma_f32_16x16x32_bf16 v[40:43], v[20:23], v[230:233], v[24:27]
	v_mfma_f32_16x16x32_bf16 v[24:27], v[8:11], v[234:237], v[170:173]
	v_mfma_f32_16x16x32_bf16 v[0:3], v[8:11], v[242:245], v[0:3]
	v_mfma_f32_16x16x32_bf16 v[28:31], v[12:15], v[238:241], v[24:27]
	v_mfma_f32_16x16x32_bf16 v[24:27], v[16:19], v[234:237], v[174:177]
	v_mfma_f32_16x16x32_bf16 v[12:15], v[12:15], v[246:249], v[0:3]
	v_mfma_f32_16x16x32_bf16 v[0:3], v[16:19], v[242:245], v[4:7]
	v_mfma_f32_16x16x32_bf16 v[24:27], v[20:23], v[238:241], v[24:27]
	v_mfma_f32_16x16x32_bf16 v[8:11], v[20:23], v[246:249], v[0:3]
	v_mfma_f32_16x16x32_bf16 v[0:3], v[210:213], v[32:35], v[178:181]
	v_mfma_f32_16x16x32_bf16 v[52:55], v[214:217], v[36:39], v[0:3]
	v_mfma_f32_16x16x32_bf16 v[0:3], v[218:221], v[32:35], v[182:185]
	v_mfma_f32_16x16x32_bf16 v[48:51], v[222:225], v[36:39], v[0:3]
	v_mfma_f32_16x16x32_bf16 v[0:3], v[210:213], v[226:229], v[186:189]
	v_mfma_f32_16x16x32_bf16 v[36:39], v[214:217], v[230:233], v[0:3]
	v_mfma_f32_16x16x32_bf16 v[0:3], v[218:221], v[226:229], v[190:193]
	v_mfma_f32_16x16x32_bf16 v[32:35], v[222:225], v[230:233], v[0:3]
	v_mfma_f32_16x16x32_bf16 v[0:3], v[210:213], v[234:237], v[194:197]
	v_mfma_f32_16x16x32_bf16 v[20:23], v[214:217], v[238:241], v[0:3]
	v_mfma_f32_16x16x32_bf16 v[0:3], v[218:221], v[234:237], v[198:201]
	v_mfma_f32_16x16x32_bf16 v[16:19], v[222:225], v[238:241], v[0:3]
	v_mfma_f32_16x16x32_bf16 v[0:3], v[210:213], v[242:245], v[202:205]
	v_mfma_f32_16x16x32_bf16 v[4:7], v[214:217], v[246:249], v[0:3]
	v_mfma_f32_16x16x32_bf16 v[0:3], v[218:221], v[242:245], v[206:209]
	v_mfma_f32_16x16x32_bf16 v[0:3], v[222:225], v[246:249], v[0:3]
	s_barrier
	s_add_u32 s85, s78, 0x200
	s_addc_u32 s8, s79, 0
	s_add_u32 s78, s80, 0x20180
	s_addc_u32 s79, s81, 0
	s_mov_b32 s94, 0
.LBB0_2546:
	ds_read_b128 v[154:157], v149
	ds_read_b128 v[158:161], v149 offset:1024
	ds_read_b128 v[162:165], v149 offset:2048
	ds_read_b128 v[166:169], v149 offset:3072
	ds_read_b128 v[170:173], v150
	ds_read_b128 v[174:177], v150 offset:1024
	ds_read_b128 v[178:181], v150 offset:2048
	ds_read_b128 v[182:185], v150 offset:3072
	s_add_u32 s44, s78, 0xfffe0080
	s_addc_u32 s45, s79, -1
	s_cmp_eq_u32 s94, 4
	s_cselect_b32 s83, s58, s45
	s_cselect_b32 s82, s59, s44
	s_cselect_b32 s81, s71, s8
	s_cselect_b32 s80, s73, s85
	s_mov_b32 m0, s88
	v_lshl_add_u64 v[140:141], s[78:79], 0, v[138:139]
	ds_read_b128 v[186:189], v151
	ds_read_b128 v[190:193], v151 offset:1024
	ds_read_b128 v[194:197], v151 offset:2048
	ds_read_b128 v[198:201], v151 offset:3072
	ds_read_b128 v[202:205], v151 offset:4096
	ds_read_b128 v[206:209], v151 offset:5120
	ds_read_b128 v[210:213], v151 offset:6144
	ds_read_b128 v[214:217], v151 offset:7168
	global_load_lds_dwordx4 v[140:141], off
	v_lshl_add_u64 v[140:141], s[78:79], 0, v[136:137]
	s_mov_b32 m0, s89
	s_nop 0
	global_load_lds_dwordx4 v[140:141], off
	s_waitcnt vmcnt(8) lgkmcnt(0)
	s_barrier
	v_mfma_f32_16x16x32_bf16 v[124:127], v[154:157], v[186:189], v[124:127]
	v_mfma_f32_16x16x32_bf16 v[120:123], v[162:165], v[186:189], v[120:123]
	v_mfma_f32_16x16x32_bf16 v[108:111], v[154:157], v[194:197], v[108:111]
	v_mfma_f32_16x16x32_bf16 v[104:107], v[162:165], v[194:197], v[104:107]
	v_mfma_f32_16x16x32_bf16 v[92:95], v[154:157], v[202:205], v[92:95]
	v_mfma_f32_16x16x32_bf16 v[88:91], v[162:165], v[202:205], v[88:91]
	v_mfma_f32_16x16x32_bf16 v[76:79], v[154:157], v[210:213], v[76:79]
	v_mfma_f32_16x16x32_bf16 v[72:75], v[162:165], v[210:213], v[72:75]
	v_mfma_f32_16x16x32_bf16 v[124:127], v[158:161], v[190:193], v[124:127]
	v_mfma_f32_16x16x32_bf16 v[120:123], v[166:169], v[190:193], v[120:123]
	v_mfma_f32_16x16x32_bf16 v[108:111], v[158:161], v[198:201], v[108:111]
	v_mfma_f32_16x16x32_bf16 v[104:107], v[166:169], v[198:201], v[104:107]
	v_mfma_f32_16x16x32_bf16 v[92:95], v[158:161], v[206:209], v[92:95]
	v_mfma_f32_16x16x32_bf16 v[88:91], v[166:169], v[206:209], v[88:91]
	v_mfma_f32_16x16x32_bf16 v[76:79], v[158:161], v[214:217], v[76:79]
	v_mfma_f32_16x16x32_bf16 v[72:75], v[166:169], v[214:217], v[72:75]
	v_mfma_f32_16x16x32_bf16 v[116:119], v[170:173], v[186:189], v[116:119]
	v_mfma_f32_16x16x32_bf16 v[112:115], v[178:181], v[186:189], v[112:115]
	v_mfma_f32_16x16x32_bf16 v[100:103], v[170:173], v[194:197], v[100:103]
	v_mfma_f32_16x16x32_bf16 v[96:99], v[178:181], v[194:197], v[96:99]
	v_mfma_f32_16x16x32_bf16 v[84:87], v[170:173], v[202:205], v[84:87]
	v_mfma_f32_16x16x32_bf16 v[80:83], v[178:181], v[202:205], v[80:83]
	v_mfma_f32_16x16x32_bf16 v[68:71], v[170:173], v[210:213], v[68:71]
	v_mfma_f32_16x16x32_bf16 v[64:67], v[178:181], v[210:213], v[64:67]
	v_mfma_f32_16x16x32_bf16 v[116:119], v[174:177], v[190:193], v[116:119]
	v_mfma_f32_16x16x32_bf16 v[112:115], v[182:185], v[190:193], v[112:115]
	v_mfma_f32_16x16x32_bf16 v[100:103], v[174:177], v[198:201], v[100:103]
	v_mfma_f32_16x16x32_bf16 v[96:99], v[182:185], v[198:201], v[96:99]
	v_mfma_f32_16x16x32_bf16 v[84:87], v[174:177], v[206:209], v[84:87]
	v_mfma_f32_16x16x32_bf16 v[80:83], v[182:185], v[206:209], v[80:83]
	v_mfma_f32_16x16x32_bf16 v[68:71], v[174:177], v[214:217], v[68:71]
	v_mfma_f32_16x16x32_bf16 v[64:67], v[182:185], v[214:217], v[64:67]
	s_barrier
	s_mov_b32 m0, s90
	v_lshl_add_u64 v[140:141], s[80:81], 0, v[128:129]
	s_add_u32 s44, s80, 0x20000
	ds_read_b128 v[186:189], v151 offset:16384
	ds_read_b128 v[190:193], v151 offset:17408
	ds_read_b128 v[194:197], v151 offset:18432
	ds_read_b128 v[198:201], v151 offset:19456
	ds_read_b128 v[202:205], v151 offset:20480
	ds_read_b128 v[206:209], v151 offset:21504
	ds_read_b128 v[210:213], v151 offset:22528
	ds_read_b128 v[214:217], v151 offset:23552
	global_load_lds_dwordx4 v[140:141], off
	v_lshl_add_u64 v[142:143], s[80:81], 0, v[130:131]
	s_mov_b32 m0, s91
	s_addc_u32 s45, s81, 0
	global_load_lds_dwordx4 v[142:143], off
	v_lshl_add_u64 v[146:147], s[44:45], 0, v[128:129]
	s_mov_b32 m0, s93
	v_lshl_add_u64 v[218:219], s[82:83], 0, v[132:133]
	global_load_lds_dwordx4 v[146:147], off
	v_lshl_add_u64 v[146:147], s[44:45], 0, v[130:131]
	s_mov_b32 m0, s95
	s_nop 0
	global_load_lds_dwordx4 v[146:147], off
	v_lshl_add_u64 v[146:147], s[82:83], 0, v[134:135]
	s_mov_b32 m0, s38
	s_nop 0
	global_load_lds_dwordx4 v[146:147], off
	s_mov_b32 m0, s39
	s_nop 0
	global_load_lds_dwordx4 v[218:219], off
	s_waitcnt vmcnt(8) lgkmcnt(0)
	s_barrier
	v_mfma_f32_16x16x32_bf16 v[60:63], v[154:157], v[186:189], v[60:63]
	v_mfma_f32_16x16x32_bf16 v[56:59], v[162:165], v[186:189], v[56:59]
	v_mfma_f32_16x16x32_bf16 v[44:47], v[154:157], v[194:197], v[44:47]
	v_mfma_f32_16x16x32_bf16 v[40:43], v[162:165], v[194:197], v[40:43]
	v_mfma_f32_16x16x32_bf16 v[28:31], v[154:157], v[202:205], v[28:31]
	v_mfma_f32_16x16x32_bf16 v[24:27], v[162:165], v[202:205], v[24:27]
	v_mfma_f32_16x16x32_bf16 v[12:15], v[154:157], v[210:213], v[12:15]
	v_mfma_f32_16x16x32_bf16 v[8:11], v[162:165], v[210:213], v[8:11]
	v_mfma_f32_16x16x32_bf16 v[60:63], v[158:161], v[190:193], v[60:63]
	v_mfma_f32_16x16x32_bf16 v[56:59], v[166:169], v[190:193], v[56:59]
	v_mfma_f32_16x16x32_bf16 v[44:47], v[158:161], v[198:201], v[44:47]
	v_mfma_f32_16x16x32_bf16 v[40:43], v[166:169], v[198:201], v[40:43]
	v_mfma_f32_16x16x32_bf16 v[28:31], v[158:161], v[206:209], v[28:31]
	v_mfma_f32_16x16x32_bf16 v[24:27], v[166:169], v[206:209], v[24:27]
	v_mfma_f32_16x16x32_bf16 v[12:15], v[158:161], v[214:217], v[12:15]
	v_mfma_f32_16x16x32_bf16 v[8:11], v[166:169], v[214:217], v[8:11]
	v_mfma_f32_16x16x32_bf16 v[52:55], v[170:173], v[186:189], v[52:55]
	v_mfma_f32_16x16x32_bf16 v[48:51], v[178:181], v[186:189], v[48:51]
	v_mfma_f32_16x16x32_bf16 v[36:39], v[170:173], v[194:197], v[36:39]
	v_mfma_f32_16x16x32_bf16 v[32:35], v[178:181], v[194:197], v[32:35]
	v_mfma_f32_16x16x32_bf16 v[20:23], v[170:173], v[202:205], v[20:23]
	v_mfma_f32_16x16x32_bf16 v[16:19], v[178:181], v[202:205], v[16:19]
	v_mfma_f32_16x16x32_bf16 v[4:7], v[170:173], v[210:213], v[4:7]
	v_mfma_f32_16x16x32_bf16 v[0:3], v[178:181], v[210:213], v[0:3]
	v_mfma_f32_16x16x32_bf16 v[52:55], v[174:177], v[190:193], v[52:55]
	v_mfma_f32_16x16x32_bf16 v[48:51], v[182:185], v[190:193], v[48:51]
	v_mfma_f32_16x16x32_bf16 v[36:39], v[174:177], v[198:201], v[36:39]
	v_mfma_f32_16x16x32_bf16 v[32:35], v[182:185], v[198:201], v[32:35]
	v_mfma_f32_16x16x32_bf16 v[20:23], v[174:177], v[206:209], v[20:23]
	v_mfma_f32_16x16x32_bf16 v[16:19], v[182:185], v[206:209], v[16:19]
	v_mfma_f32_16x16x32_bf16 v[4:7], v[174:177], v[214:217], v[4:7]
	v_mfma_f32_16x16x32_bf16 v[0:3], v[182:185], v[214:217], v[0:3]
	s_barrier
; #define PG8_MMA(ai, bj, At, Bt) do { __builtin_amdgcn_s_setprio(1); _Pragma("unroll") for (int m = 0; m < 4; ++m) _Pragma("unroll") for (int n = 0; n < 2; ++n) _Pragma("unroll") for (int k = 0; k < 2; ++k) \
;         acc[ai][bj][m][n] = __builtin_amdgcn_mfma_f32_16x16x32_bf16(Bt[n][k], At[m][k], acc[ai][bj][m][n], 0, 0, 0); __builtin_amdgcn_s_setprio(0); } while (0)
; template <class Epi, class Sched, bool ALIGN_EPI = false, bool SP2 = false, bool A_TILED = false>
; __device__ __forceinline__ void gemm_phase(PG8_LAS unsigned char* lds, const Gemm g, const Sched& S, const Epi& E, const int wave_s) {
;     ...
;         for (int t = PEEL ? 2 : 0; t < nt; t += 2) {
;             const bool last = (t == nt - 2);
;             const char* a1 = cA + (size_t)(t + 1) * kstepA;
;             const char* a2 = last ? nA : cA + (size_t)(t + 2) * kstepA; const char* b2 = last ? nB : cB + (size_t)(t + 2) * kstep;
;             const char* a3 = a2 + kstepA; const char* b3 = b2 + kstep;
;             if (last && has_next) S.a_ready(nxt);
;             if constexpr (SP2) {
;             PG8_ITER(PG8_MMA)
	ds_read_b128 v[154:157], v144
	ds_read_b128 v[158:161], v144 offset:1024
	ds_read_b128 v[162:165], v144 offset:2048
	ds_read_b128 v[166:169], v144 offset:3072
	ds_read_b128 v[170:173], v145
	ds_read_b128 v[174:177], v145 offset:1024
	ds_read_b128 v[178:181], v145 offset:2048
	ds_read_b128 v[182:185], v145 offset:3072
	s_add_u32 s44, s82, 0x20000
	s_addc_u32 s45, s83, 0
	s_mov_b32 m0, s40
	v_lshl_add_u64 v[220:221], s[44:45], 0, v[134:135]
	ds_read_b128 v[186:189], v151 offset:32768
	ds_read_b128 v[190:193], v151 offset:33792
	ds_read_b128 v[194:197], v151 offset:34816
	ds_read_b128 v[198:201], v151 offset:35840
	ds_read_b128 v[202:205], v151 offset:36864
	ds_read_b128 v[206:209], v151 offset:37888
	ds_read_b128 v[210:213], v151 offset:38912
	ds_read_b128 v[214:217], v151 offset:39936
	global_load_lds_dwordx4 v[220:221], off
	v_lshl_add_u64 v[220:221], s[44:45], 0, v[132:133]
	s_mov_b32 m0, s41
	s_nop 0
	global_load_lds_dwordx4 v[220:221], off
	s_waitcnt vmcnt(8) lgkmcnt(0)
	s_barrier
	v_mfma_f32_16x16x32_bf16 v[124:127], v[154:157], v[186:189], v[124:127]
	v_mfma_f32_16x16x32_bf16 v[120:123], v[162:165], v[186:189], v[120:123]
	v_mfma_f32_16x16x32_bf16 v[108:111], v[154:157], v[194:197], v[108:111]
	v_mfma_f32_16x16x32_bf16 v[104:107], v[162:165], v[194:197], v[104:107]
	v_mfma_f32_16x16x32_bf16 v[92:95], v[154:157], v[202:205], v[92:95]
	v_mfma_f32_16x16x32_bf16 v[88:91], v[162:165], v[202:205], v[88:91]
	v_mfma_f32_16x16x32_bf16 v[76:79], v[154:157], v[210:213], v[76:79]
	v_mfma_f32_16x16x32_bf16 v[72:75], v[162:165], v[210:213], v[72:75]
	v_mfma_f32_16x16x32_bf16 v[124:127], v[158:161], v[190:193], v[124:127]
	v_mfma_f32_16x16x32_bf16 v[120:123], v[166:169], v[190:193], v[120:123]
	v_mfma_f32_16x16x32_bf16 v[108:111], v[158:161], v[198:201], v[108:111]
	v_mfma_f32_16x16x32_bf16 v[104:107], v[166:169], v[198:201], v[104:107]
	v_mfma_f32_16x16x32_bf16 v[92:95], v[158:161], v[206:209], v[92:95]
	v_mfma_f32_16x16x32_bf16 v[88:91], v[166:169], v[206:209], v[88:91]
	v_mfma_f32_16x16x32_bf16 v[76:79], v[158:161], v[214:217], v[76:79]
	v_mfma_f32_16x16x32_bf16 v[72:75], v[166:169], v[214:217], v[72:75]
	v_mfma_f32_16x16x32_bf16 v[116:119], v[170:173], v[186:189], v[116:119]
	v_mfma_f32_16x16x32_bf16 v[112:115], v[178:181], v[186:189], v[112:115]
	v_mfma_f32_16x16x32_bf16 v[100:103], v[170:173], v[194:197], v[100:103]
	v_mfma_f32_16x16x32_bf16 v[96:99], v[178:181], v[194:197], v[96:99]
	v_mfma_f32_16x16x32_bf16 v[84:87], v[170:173], v[202:205], v[84:87]
	v_mfma_f32_16x16x32_bf16 v[80:83], v[178:181], v[202:205], v[80:83]
	v_mfma_f32_16x16x32_bf16 v[68:71], v[170:173], v[210:213], v[68:71]
	v_mfma_f32_16x16x32_bf16 v[64:67], v[178:181], v[210:213], v[64:67]
	v_mfma_f32_16x16x32_bf16 v[116:119], v[174:177], v[190:193], v[116:119]
	v_mfma_f32_16x16x32_bf16 v[112:115], v[182:185], v[190:193], v[112:115]
	v_mfma_f32_16x16x32_bf16 v[100:103], v[174:177], v[198:201], v[100:103]
	v_mfma_f32_16x16x32_bf16 v[96:99], v[182:185], v[198:201], v[96:99]
	v_mfma_f32_16x16x32_bf16 v[84:87], v[174:177], v[206:209], v[84:87]
	v_mfma_f32_16x16x32_bf16 v[80:83], v[182:185], v[206:209], v[80:83]
	v_mfma_f32_16x16x32_bf16 v[68:71], v[174:177], v[214:217], v[68:71]
	v_mfma_f32_16x16x32_bf16 v[64:67], v[182:185], v[214:217], v[64:67]
	s_barrier
	s_mov_b32 m0, s96
	v_lshl_add_u64 v[140:141], v[140:141], 0, s[62:63]
	s_add_u32 s44, s80, 0x20080
	ds_read_b128 v[186:189], v151 offset:49152
	ds_read_b128 v[190:193], v151 offset:50176
	ds_read_b128 v[194:197], v151 offset:51200
	ds_read_b128 v[198:201], v151 offset:52224
	ds_read_b128 v[202:205], v151 offset:53248
	ds_read_b128 v[206:209], v151 offset:54272
	ds_read_b128 v[210:213], v151 offset:55296
	ds_read_b128 v[214:217], v151 offset:56320
	global_load_lds_dwordx4 v[140:141], off
	v_lshl_add_u64 v[140:141], v[142:143], 0, s[62:63]
	s_mov_b32 m0, s97
	s_addc_u32 s45, s81, 0
	global_load_lds_dwordx4 v[140:141], off
	v_lshl_add_u64 v[140:141], s[44:45], 0, v[128:129]
	s_mov_b32 m0, vcc_lo
	s_nop 0
	global_load_lds_dwordx4 v[140:141], off
	v_lshl_add_u64 v[140:141], s[44:45], 0, v[130:131]
	s_mov_b32 m0, vcc_hi
	s_nop 0
	global_load_lds_dwordx4 v[140:141], off
	v_lshl_add_u64 v[140:141], v[146:147], 0, s[62:63]
	s_mov_b32 m0, s51
	s_nop 0
	global_load_lds_dwordx4 v[140:141], off
	v_lshl_add_u64 v[140:141], v[218:219], 0, s[62:63]
	s_mov_b32 m0, s52
	s_nop 0
	global_load_lds_dwordx4 v[140:141], off
	s_waitcnt vmcnt(8) lgkmcnt(0)
	s_barrier
	v_mfma_f32_16x16x32_bf16 v[60:63], v[154:157], v[186:189], v[60:63]
	v_mfma_f32_16x16x32_bf16 v[56:59], v[162:165], v[186:189], v[56:59]
	v_mfma_f32_16x16x32_bf16 v[44:47], v[154:157], v[194:197], v[44:47]
	v_mfma_f32_16x16x32_bf16 v[40:43], v[162:165], v[194:197], v[40:43]
	v_mfma_f32_16x16x32_bf16 v[28:31], v[154:157], v[202:205], v[28:31]
	v_mfma_f32_16x16x32_bf16 v[24:27], v[162:165], v[202:205], v[24:27]
	v_mfma_f32_16x16x32_bf16 v[12:15], v[154:157], v[210:213], v[12:15]
	v_mfma_f32_16x16x32_bf16 v[8:11], v[162:165], v[210:213], v[8:11]
	v_mfma_f32_16x16x32_bf16 v[60:63], v[158:161], v[190:193], v[60:63]
	v_mfma_f32_16x16x32_bf16 v[56:59], v[166:169], v[190:193], v[56:59]
	v_mfma_f32_16x16x32_bf16 v[44:47], v[158:161], v[198:201], v[44:47]
	v_mfma_f32_16x16x32_bf16 v[40:43], v[166:169], v[198:201], v[40:43]
	v_mfma_f32_16x16x32_bf16 v[28:31], v[158:161], v[206:209], v[28:31]
	v_mfma_f32_16x16x32_bf16 v[24:27], v[166:169], v[206:209], v[24:27]
	v_mfma_f32_16x16x32_bf16 v[12:15], v[158:161], v[214:217], v[12:15]
	v_mfma_f32_16x16x32_bf16 v[8:11], v[166:169], v[214:217], v[8:11]
	v_mfma_f32_16x16x32_bf16 v[52:55], v[170:173], v[186:189], v[52:55]
	v_mfma_f32_16x16x32_bf16 v[48:51], v[178:181], v[186:189], v[48:51]
	v_mfma_f32_16x16x32_bf16 v[36:39], v[170:173], v[194:197], v[36:39]
	v_mfma_f32_16x16x32_bf16 v[32:35], v[178:181], v[194:197], v[32:35]
	v_mfma_f32_16x16x32_bf16 v[20:23], v[170:173], v[202:205], v[20:23]
	v_mfma_f32_16x16x32_bf16 v[16:19], v[178:181], v[202:205], v[16:19]
	v_mfma_f32_16x16x32_bf16 v[4:7], v[170:173], v[210:213], v[4:7]
	v_mfma_f32_16x16x32_bf16 v[0:3], v[178:181], v[210:213], v[0:3]
	v_mfma_f32_16x16x32_bf16 v[52:55], v[174:177], v[190:193], v[52:55]
	v_mfma_f32_16x16x32_bf16 v[48:51], v[182:185], v[190:193], v[48:51]
	v_mfma_f32_16x16x32_bf16 v[36:39], v[174:177], v[198:201], v[36:39]
	v_mfma_f32_16x16x32_bf16 v[32:35], v[182:185], v[198:201], v[32:35]
	v_mfma_f32_16x16x32_bf16 v[20:23], v[174:177], v[206:209], v[20:23]
	v_mfma_f32_16x16x32_bf16 v[16:19], v[182:185], v[206:209], v[16:19]
	v_mfma_f32_16x16x32_bf16 v[4:7], v[174:177], v[214:217], v[4:7]
	v_mfma_f32_16x16x32_bf16 v[0:3], v[182:185], v[214:217], v[0:3]
	s_barrier
	s_add_i32 s94, s94, 2
	s_add_u32 s85, s85, 0x100
	s_addc_u32 s8, s8, 0
	s_add_u32 s78, s78, 0x100
	s_addc_u32 s79, s79, 0
	s_cmp_gt_u32 s94, 5
	s_cbranch_scc0 .LBB0_2546
	s_and_b64 vcc, exec, s[64:65]
	s_cbranch_vccz .LBB0_2549
	s_barrier

; template <class Epi, class Sched, bool ALIGN_EPI = false, bool SP2 = false, bool A_TILED = false>
; __device__ __forceinline__ void gemm_phase(PG8_LAS unsigned char* lds, const Gemm g, const Sched& S, const Epi& E, const int wave_s) {
;     ...
;         const char* nA = has_next ? (const char*)g.A + (size_t)nxt.pm * tstepA : cA; const char* nB = has_next ? (const char*)g.Bt + (size_t)nxt.pn * tstep : cB;
;         constexpr bool PEEL = SP2 && !Epi::AFTER_DRAIN;
;         if constexpr (PEEL) {
;             const char* a1 = cA + kstepA; const char* a2 = cA + 2 * kstepA; const char* b2 = cB + 2 * kstep; const char* a3 = a2 + kstepA; const char* b3 = b2 + kstep;
;             PG8_ITER(PG8_MMAZ)
.LBB0_2565:
	s_ashr_i32 s67, s66, 31
	ds_read_b128 v[0:3], v147
	ds_read_b128 v[4:7], v147 offset:1024
	ds_read_b128 v[8:11], v147 offset:2048
	ds_read_b128 v[12:15], v147 offset:3072
	ds_read_b128 v[16:19], v148
	ds_read_b128 v[20:23], v148 offset:1024
	ds_read_b128 v[24:27], v148 offset:2048
	ds_read_b128 v[28:31], v148 offset:3072
	s_lshl_b64 s[52:53], s[66:67], 18
	s_add_u32 s68, s8, s52
	s_addc_u32 s69, s14, s53
	s_and_b64 s[52:53], s[2:3], exec
	s_cselect_b32 s51, s69, s77
	s_cselect_b32 s52, s68, s76
	s_ashr_i32 s65, s64, 31
	s_lshl_b64 s[54:55], s[64:65], 18
	s_add_u32 s72, s15, s54
	s_addc_u32 s73, s23, s55
	s_and_b64 s[54:55], s[2:3], exec
	s_cselect_b32 s53, s73, s75
	s_cselect_b32 s54, s72, s74
	s_add_u32 s56, s76, 0x20080
	s_addc_u32 s57, s77, 0
	s_add_i32 s55, s0, 0xc000
	v_lshl_add_u64 v[64:65], s[56:57], 0, v[134:135]
	s_mov_b32 m0, s55
	ds_read_b128 v[32:35], v149
	ds_read_b128 v[36:39], v149 offset:1024
	ds_read_b128 v[40:43], v149 offset:2048
	ds_read_b128 v[44:47], v149 offset:3072
	ds_read_b128 v[48:51], v149 offset:4096
	ds_read_b128 v[52:55], v149 offset:5120
	ds_read_b128 v[56:59], v149 offset:6144
	ds_read_b128 v[60:63], v149 offset:7168
	global_load_lds_dwordx4 v[64:65], off
	v_lshl_add_u64 v[64:65], s[56:57], 0, v[132:133]
	s_add_i32 s56, s0, 0xe000
	s_mov_b32 m0, s56
	s_nop 0
	global_load_lds_dwordx4 v[64:65], off
	s_waitcnt vmcnt(8) lgkmcnt(0)
	s_barrier
	v_mfma_f32_16x16x32_bf16 v[88:91], v[0:3], v[56:59], 0
	v_mfma_f32_16x16x32_bf16 v[64:67], v[0:3], v[32:35], 0
	v_mfma_f32_16x16x32_bf16 v[68:71], v[8:11], v[32:35], 0
	v_mfma_f32_16x16x32_bf16 v[72:75], v[0:3], v[40:43], 0
	v_mfma_f32_16x16x32_bf16 v[76:79], v[8:11], v[40:43], 0
	v_mfma_f32_16x16x32_bf16 v[80:83], v[0:3], v[48:51], 0
	v_mfma_f32_16x16x32_bf16 v[84:87], v[8:11], v[48:51], 0
	v_mfma_f32_16x16x32_bf16 v[92:95], v[4:7], v[60:63], v[88:91]
	v_mfma_f32_16x16x32_bf16 v[88:91], v[8:11], v[56:59], 0
	v_mfma_f32_16x16x32_bf16 v[64:67], v[4:7], v[36:39], v[64:67]
	v_mfma_f32_16x16x32_bf16 v[68:71], v[12:15], v[36:39], v[68:71]
	v_mfma_f32_16x16x32_bf16 v[72:75], v[4:7], v[44:47], v[72:75]
	v_mfma_f32_16x16x32_bf16 v[76:79], v[12:15], v[44:47], v[76:79]
	v_mfma_f32_16x16x32_bf16 v[80:83], v[4:7], v[52:55], v[80:83]
	v_mfma_f32_16x16x32_bf16 v[84:87], v[12:15], v[52:55], v[84:87]
	v_mfma_f32_16x16x32_bf16 v[100:103], v[12:15], v[60:63], v[88:91]
	v_mfma_f32_16x16x32_bf16 v[88:91], v[16:19], v[32:35], 0
	v_mfma_f32_16x16x32_bf16 v[32:35], v[24:27], v[32:35], 0
	v_mfma_f32_16x16x32_bf16 v[108:111], v[20:23], v[36:39], v[88:91]
	v_mfma_f32_16x16x32_bf16 v[32:35], v[28:31], v[36:39], v[32:35]
	v_mfma_f32_16x16x32_bf16 v[36:39], v[16:19], v[40:43], 0
	v_mfma_f32_16x16x32_bf16 v[40:43], v[24:27], v[40:43], 0
	v_mfma_f32_16x16x32_bf16 v[36:39], v[20:23], v[44:47], v[36:39]
	v_mfma_f32_16x16x32_bf16 v[40:43], v[28:31], v[44:47], v[40:43]
	v_mfma_f32_16x16x32_bf16 v[44:47], v[16:19], v[48:51], 0
	v_mfma_f32_16x16x32_bf16 v[48:51], v[24:27], v[48:51], 0
	v_mfma_f32_16x16x32_bf16 v[44:47], v[20:23], v[52:55], v[44:47]
	v_mfma_f32_16x16x32_bf16 v[52:55], v[28:31], v[52:55], v[48:51]
	v_mfma_f32_16x16x32_bf16 v[48:51], v[16:19], v[56:59], 0
	v_mfma_f32_16x16x32_bf16 v[150:153], v[20:23], v[60:63], v[48:51]
	v_mfma_f32_16x16x32_bf16 v[48:51], v[24:27], v[56:59], 0
	v_mfma_f32_16x16x32_bf16 v[154:157], v[28:31], v[60:63], v[48:51]
	s_barrier
	s_add_i32 s57, s48, s36
	v_lshl_add_u64 v[250:251], s[74:75], 0, v[128:129]
	s_add_i32 s58, s57, 0x2000
	v_lshl_add_u64 v[120:121], v[250:251], 0, s[60:61]
	s_mov_b32 m0, s57
	v_lshl_add_u64 v[252:253], s[74:75], 0, v[130:131]
	s_add_u32 s78, s74, 0x20100
	ds_read_b128 v[48:51], v149 offset:16384
	ds_read_b128 v[56:59], v149 offset:17408
	ds_read_b128 v[60:63], v149 offset:18432
	ds_read_b128 v[88:91], v149 offset:19456
	ds_read_b128 v[96:99], v149 offset:20480
	ds_read_b128 v[104:107], v149 offset:21504
	ds_read_b128 v[112:115], v149 offset:22528
	ds_read_b128 v[116:119], v149 offset:23552
	global_load_lds_dwordx4 v[120:121], off
	v_lshl_add_u64 v[120:121], v[252:253], 0, s[60:61]
	s_mov_b32 m0, s58
	s_addc_u32 s79, s75, 0
	s_add_i32 s59, s49, s36
	global_load_lds_dwordx4 v[120:121], off
	v_lshl_add_u64 v[120:121], s[78:79], 0, v[128:129]
	s_mov_b32 m0, s59
	s_add_i32 s65, s59, 0x2000
	global_load_lds_dwordx4 v[120:121], off
	v_lshl_add_u64 v[120:121], s[78:79], 0, v[130:131]
	s_mov_b32 m0, s65
	v_lshl_add_u64 v[140:141], s[76:77], 0, v[134:135]
	global_load_lds_dwordx4 v[120:121], off
	v_lshl_add_u64 v[120:121], v[140:141], 0, s[60:61]
	s_mov_b32 m0, s0
	v_lshl_add_u64 v[142:143], s[76:77], 0, v[132:133]
	global_load_lds_dwordx4 v[120:121], off
	v_lshl_add_u64 v[120:121], v[142:143], 0, s[60:61]
	s_mov_b32 m0, s1
	s_nop 0
	global_load_lds_dwordx4 v[120:121], off
	s_waitcnt vmcnt(8) lgkmcnt(0)
	s_barrier
	v_mfma_f32_16x16x32_bf16 v[120:123], v[0:3], v[48:51], 0
	v_mfma_f32_16x16x32_bf16 v[158:161], v[4:7], v[56:59], v[120:123]
	v_mfma_f32_16x16x32_bf16 v[120:123], v[8:11], v[48:51], 0
	v_mfma_f32_16x16x32_bf16 v[162:165], v[12:15], v[56:59], v[120:123]
	v_mfma_f32_16x16x32_bf16 v[120:123], v[0:3], v[60:63], 0
	v_mfma_f32_16x16x32_bf16 v[166:169], v[4:7], v[88:91], v[120:123]
	v_mfma_f32_16x16x32_bf16 v[120:123], v[8:11], v[60:63], 0
	v_mfma_f32_16x16x32_bf16 v[170:173], v[12:15], v[88:91], v[120:123]
	v_mfma_f32_16x16x32_bf16 v[120:123], v[0:3], v[96:99], 0
	v_mfma_f32_16x16x32_bf16 v[0:3], v[0:3], v[112:115], 0
	v_mfma_f32_16x16x32_bf16 v[174:177], v[4:7], v[104:107], v[120:123]
	v_mfma_f32_16x16x32_bf16 v[0:3], v[4:7], v[116:119], v[0:3]
	v_mfma_f32_16x16x32_bf16 v[4:7], v[8:11], v[112:115], 0
	v_mfma_f32_16x16x32_bf16 v[120:123], v[8:11], v[96:99], 0
	v_mfma_f32_16x16x32_bf16 v[4:7], v[12:15], v[116:119], v[4:7]
	v_mfma_f32_16x16x32_bf16 v[178:181], v[12:15], v[104:107], v[120:123]
	v_mfma_f32_16x16x32_bf16 v[8:11], v[16:19], v[48:51], 0
	v_mfma_f32_16x16x32_bf16 v[182:185], v[20:23], v[56:59], v[8:11]
	v_mfma_f32_16x16x32_bf16 v[8:11], v[24:27], v[48:51], 0
	v_mfma_f32_16x16x32_bf16 v[186:189], v[28:31], v[56:59], v[8:11]
	v_mfma_f32_16x16x32_bf16 v[8:11], v[16:19], v[60:63], 0
	v_mfma_f32_16x16x32_bf16 v[190:193], v[20:23], v[88:91], v[8:11]
	v_mfma_f32_16x16x32_bf16 v[8:11], v[24:27], v[60:63], 0
	v_mfma_f32_16x16x32_bf16 v[194:197], v[28:31], v[88:91], v[8:11]
	v_mfma_f32_16x16x32_bf16 v[8:11], v[16:19], v[96:99], 0
	v_mfma_f32_16x16x32_bf16 v[198:201], v[20:23], v[104:107], v[8:11]
	v_mfma_f32_16x16x32_bf16 v[8:11], v[24:27], v[96:99], 0
	v_mfma_f32_16x16x32_bf16 v[202:205], v[28:31], v[104:107], v[8:11]
	v_mfma_f32_16x16x32_bf16 v[8:11], v[16:19], v[112:115], 0
	v_mfma_f32_16x16x32_bf16 v[206:209], v[20:23], v[116:119], v[8:11]
	v_mfma_f32_16x16x32_bf16 v[8:11], v[24:27], v[112:115], 0
	v_mfma_f32_16x16x32_bf16 v[210:213], v[28:31], v[116:119], v[8:11]
	s_barrier
	s_add_i32 s67, 0, 0x18000
	s_add_i32 s80, 0, 0x1c000
	v_add_u32_e32 v144, s67, v146
	v_add_u32_e32 v145, s80, v146
	s_nop 0
	ds_read_b128 v[8:11], v144
	ds_read_b128 v[12:15], v144 offset:1024
	ds_read_b128 v[16:19], v144 offset:2048
	ds_read_b128 v[20:23], v144 offset:3072
	ds_read_b128 v[214:217], v145
	ds_read_b128 v[218:221], v145 offset:1024
	ds_read_b128 v[222:225], v145 offset:2048
	ds_read_b128 v[226:229], v145 offset:3072
	s_add_u32 s78, s76, 0x20100
	s_addc_u32 s79, s77, 0
	s_mov_b32 m0, s37
	v_lshl_add_u64 v[48:49], s[78:79], 0, v[134:135]
	ds_read_b128 v[24:27], v149 offset:32768
	ds_read_b128 v[28:31], v149 offset:33792
	ds_read_b128 v[60:63], v149 offset:34816
	ds_read_b128 v[230:233], v149 offset:35840
	ds_read_b128 v[234:237], v149 offset:36864
	ds_read_b128 v[238:241], v149 offset:37888
	ds_read_b128 v[242:245], v149 offset:38912
	ds_read_b128 v[246:249], v149 offset:39936
	global_load_lds_dwordx4 v[48:49], off
	v_lshl_add_u64 v[48:49], s[78:79], 0, v[132:133]
	s_mov_b32 m0, s38
	s_nop 0
	global_load_lds_dwordx4 v[48:49], off
	s_waitcnt vmcnt(8) lgkmcnt(0)
	s_barrier
	v_mfma_f32_16x16x32_bf16 v[48:51], v[8:11], v[24:27], v[64:67]
	v_mfma_f32_16x16x32_bf16 v[120:123], v[12:15], v[28:31], v[48:51]
	v_mfma_f32_16x16x32_bf16 v[48:51], v[16:19], v[24:27], v[68:71]
	v_mfma_f32_16x16x32_bf16 v[112:115], v[20:23], v[28:31], v[48:51]
	v_mfma_f32_16x16x32_bf16 v[48:51], v[8:11], v[60:63], v[72:75]
	v_mfma_f32_16x16x32_bf16 v[104:107], v[12:15], v[230:233], v[48:51]
	v_mfma_f32_16x16x32_bf16 v[48:51], v[16:19], v[60:63], v[76:79]
	v_mfma_f32_16x16x32_bf16 v[96:99], v[20:23], v[230:233], v[48:51]
	v_mfma_f32_16x16x32_bf16 v[48:51], v[8:11], v[234:237], v[80:83]
	v_mfma_f32_16x16x32_bf16 v[88:91], v[12:15], v[238:241], v[48:51]
	v_mfma_f32_16x16x32_bf16 v[48:51], v[16:19], v[234:237], v[84:87]
	v_mfma_f32_16x16x32_bf16 v[80:83], v[20:23], v[238:241], v[48:51]
	v_mfma_f32_16x16x32_bf16 v[48:51], v[8:11], v[242:245], v[92:95]
	v_mfma_f32_16x16x32_bf16 v[56:59], v[12:15], v[246:249], v[48:51]
	v_mfma_f32_16x16x32_bf16 v[48:51], v[16:19], v[242:245], v[100:103]
	v_mfma_f32_16x16x32_bf16 v[48:51], v[20:23], v[246:249], v[48:51]
	v_mfma_f32_16x16x32_bf16 v[64:67], v[214:217], v[24:27], v[108:111]
	v_mfma_f32_16x16x32_bf16 v[24:27], v[222:225], v[24:27], v[32:35]
	v_mfma_f32_16x16x32_bf16 v[116:119], v[226:229], v[28:31], v[24:27]
	v_mfma_f32_16x16x32_bf16 v[24:27], v[214:217], v[60:63], v[36:39]
	v_mfma_f32_16x16x32_bf16 v[108:111], v[218:221], v[230:233], v[24:27]
	v_mfma_f32_16x16x32_bf16 v[24:27], v[222:225], v[60:63], v[40:43]
	v_mfma_f32_16x16x32_bf16 v[100:103], v[226:229], v[230:233], v[24:27]
	v_mfma_f32_16x16x32_bf16 v[24:27], v[214:217], v[234:237], v[44:47]
	v_mfma_f32_16x16x32_bf16 v[92:95], v[218:221], v[238:241], v[24:27]
	v_mfma_f32_16x16x32_bf16 v[24:27], v[222:225], v[234:237], v[52:55]
	v_mfma_f32_16x16x32_bf16 v[84:87], v[226:229], v[238:241], v[24:27]
	v_mfma_f32_16x16x32_bf16 v[24:27], v[214:217], v[242:245], v[150:153]
	v_mfma_f32_16x16x32_bf16 v[60:63], v[218:221], v[246:249], v[24:27]
	v_mfma_f32_16x16x32_bf16 v[24:27], v[222:225], v[242:245], v[154:157]
	v_mfma_f32_16x16x32_bf16 v[124:127], v[218:221], v[28:31], v[64:67]
	v_mfma_f32_16x16x32_bf16 v[52:55], v[226:229], v[246:249], v[24:27]
	s_barrier
; #define PG8_MMA(ai, bj, At, Bt) do { __builtin_amdgcn_s_setprio(1); _Pragma("unroll") for (int m = 0; m < 4; ++m) _Pragma("unroll") for (int n = 0; n < 2; ++n) _Pragma("unroll") for (int k = 0; k < 2; ++k) \
;         acc[ai][bj][m][n] = __builtin_amdgcn_mfma_f32_16x16x32_bf16(Bt[n][k], At[m][k], acc[ai][bj][m][n], 0, 0, 0); __builtin_amdgcn_s_setprio(0); } while (0)
; template <class Epi, class Sched, bool ALIGN_EPI = false, bool SP2 = false, bool A_TILED = false>
; __device__ __forceinline__ void gemm_phase(PG8_LAS unsigned char* lds, const Gemm g, const Sched& S, const Epi& E, const int wave_s) {
;     ...
;         for (int t = PEEL ? 2 : 0; t < nt; t += 2) {
;             const bool last = (t == nt - 2);
;             const char* a1 = cA + (size_t)(t + 1) * kstepA;
;             const char* a2 = last ? nA : cA + (size_t)(t + 2) * kstepA; const char* b2 = last ? nB : cB + (size_t)(t + 2) * kstep;
;             const char* a3 = a2 + kstepA; const char* b3 = b2 + kstep;
;             if (last && has_next) S.a_ready(nxt);
;             if constexpr (SP2) {
;             PG8_ITER(PG8_MMA)
	s_add_i32 s67, s67, s36
	s_add_i32 s71, s67, 0x2000
	s_nop 1
	v_lshl_add_u64 v[24:25], v[250:251], 0, s[62:63]
	s_mov_b32 m0, s67
	s_add_u32 s78, s74, 0x20180
	ds_read_b128 v[32:35], v149 offset:49152
	ds_read_b128 v[36:39], v149 offset:50176
	ds_read_b128 v[150:153], v149 offset:51200
	ds_read_b128 v[154:157], v149 offset:52224
	ds_read_b128 v[230:233], v149 offset:53248
	ds_read_b128 v[234:237], v149 offset:54272
	ds_read_b128 v[238:241], v149 offset:55296
	ds_read_b128 v[242:245], v149 offset:56320
	global_load_lds_dwordx4 v[24:25], off
	v_lshl_add_u64 v[24:25], v[252:253], 0, s[62:63]
	s_mov_b32 m0, s71
	s_addc_u32 s79, s75, 0
	s_add_i32 s80, s80, s36
	global_load_lds_dwordx4 v[24:25], off
	v_lshl_add_u64 v[24:25], s[78:79], 0, v[128:129]
	s_mov_b32 m0, s80
	s_add_i32 s81, s80, 0x2000
	global_load_lds_dwordx4 v[24:25], off
	v_lshl_add_u64 v[24:25], s[78:79], 0, v[130:131]
	s_mov_b32 m0, s81
	s_nop 0
	global_load_lds_dwordx4 v[24:25], off
	v_lshl_add_u64 v[24:25], v[140:141], 0, s[62:63]
	s_mov_b32 m0, s42
	s_nop 0
	global_load_lds_dwordx4 v[24:25], off
	v_lshl_add_u64 v[24:25], v[142:143], 0, s[62:63]
	s_mov_b32 m0, s43
	s_nop 0
	global_load_lds_dwordx4 v[24:25], off
	s_waitcnt vmcnt(8) lgkmcnt(0)
	s_barrier
	v_mfma_f32_16x16x32_bf16 v[24:27], v[8:11], v[32:35], v[158:161]
	v_mfma_f32_16x16x32_bf16 v[76:79], v[12:15], v[36:39], v[24:27]
	v_mfma_f32_16x16x32_bf16 v[24:27], v[16:19], v[32:35], v[162:165]
	v_mfma_f32_16x16x32_bf16 v[72:75], v[20:23], v[36:39], v[24:27]
	v_mfma_f32_16x16x32_bf16 v[24:27], v[8:11], v[150:153], v[166:169]
	v_mfma_f32_16x16x32_bf16 v[44:47], v[12:15], v[154:157], v[24:27]
	v_mfma_f32_16x16x32_bf16 v[24:27], v[16:19], v[150:153], v[170:173]
	v_mfma_f32_16x16x32_bf16 v[40:43], v[20:23], v[154:157], v[24:27]
	v_mfma_f32_16x16x32_bf16 v[24:27], v[8:11], v[230:233], v[174:177]
	v_mfma_f32_16x16x32_bf16 v[0:3], v[8:11], v[238:241], v[0:3]
	v_mfma_f32_16x16x32_bf16 v[28:31], v[12:15], v[234:237], v[24:27]
	v_mfma_f32_16x16x32_bf16 v[24:27], v[16:19], v[230:233], v[178:181]
	v_mfma_f32_16x16x32_bf16 v[12:15], v[12:15], v[242:245], v[0:3]
	v_mfma_f32_16x16x32_bf16 v[0:3], v[16:19], v[238:241], v[4:7]
	v_mfma_f32_16x16x32_bf16 v[24:27], v[20:23], v[234:237], v[24:27]
	v_mfma_f32_16x16x32_bf16 v[8:11], v[20:23], v[242:245], v[0:3]
	v_mfma_f32_16x16x32_bf16 v[0:3], v[214:217], v[32:35], v[182:185]
	v_mfma_f32_16x16x32_bf16 v[68:71], v[218:221], v[36:39], v[0:3]
	v_mfma_f32_16x16x32_bf16 v[0:3], v[222:225], v[32:35], v[186:189]
	v_mfma_f32_16x16x32_bf16 v[64:67], v[226:229], v[36:39], v[0:3]
	v_mfma_f32_16x16x32_bf16 v[0:3], v[214:217], v[150:153], v[190:193]
	v_mfma_f32_16x16x32_bf16 v[36:39], v[218:221], v[154:157], v[0:3]
	v_mfma_f32_16x16x32_bf16 v[0:3], v[222:225], v[150:153], v[194:197]
	v_mfma_f32_16x16x32_bf16 v[32:35], v[226:229], v[154:157], v[0:3]
	v_mfma_f32_16x16x32_bf16 v[0:3], v[214:217], v[230:233], v[198:201]
	v_mfma_f32_16x16x32_bf16 v[20:23], v[218:221], v[234:237], v[0:3]
	v_mfma_f32_16x16x32_bf16 v[0:3], v[222:225], v[230:233], v[202:205]
	v_mfma_f32_16x16x32_bf16 v[16:19], v[226:229], v[234:237], v[0:3]
	v_mfma_f32_16x16x32_bf16 v[0:3], v[214:217], v[238:241], v[206:209]
	v_mfma_f32_16x16x32_bf16 v[4:7], v[218:221], v[242:245], v[0:3]
	v_mfma_f32_16x16x32_bf16 v[0:3], v[222:225], v[238:241], v[210:213]
	v_mfma_f32_16x16x32_bf16 v[0:3], v[226:229], v[242:245], v[0:3]
	s_barrier
	s_add_u32 s82, s74, 0x200
	s_addc_u32 s83, s75, 0
	s_add_u32 s74, s76, 0x20180
	s_addc_u32 s75, s77, 0
	s_mov_b32 s85, 0
.LBB0_2566:
	ds_read_b128 v[150:153], v147
	ds_read_b128 v[154:157], v147 offset:1024
	ds_read_b128 v[158:161], v147 offset:2048
	ds_read_b128 v[162:165], v147 offset:3072
	ds_read_b128 v[166:169], v148
	ds_read_b128 v[170:173], v148 offset:1024
	ds_read_b128 v[174:177], v148 offset:2048
	ds_read_b128 v[178:181], v148 offset:3072
	s_add_u32 s76, s74, 0xfffe0080
	s_addc_u32 s77, s75, -1
	s_cmp_eq_u32 s85, 4
	s_cselect_b32 s79, s51, s77
	s_cselect_b32 s78, s52, s76
	s_cselect_b32 s77, s53, s83
	s_cselect_b32 s76, s54, s82
	s_mov_b32 m0, s55
	v_lshl_add_u64 v[140:141], s[74:75], 0, v[138:139]
	ds_read_b128 v[182:185], v149
	ds_read_b128 v[186:189], v149 offset:1024
	ds_read_b128 v[190:193], v149 offset:2048
	ds_read_b128 v[194:197], v149 offset:3072
	ds_read_b128 v[198:201], v149 offset:4096
	ds_read_b128 v[202:205], v149 offset:5120
	ds_read_b128 v[206:209], v149 offset:6144
	ds_read_b128 v[210:213], v149 offset:7168
	global_load_lds_dwordx4 v[140:141], off
	v_lshl_add_u64 v[140:141], s[74:75], 0, v[136:137]
	s_mov_b32 m0, s56
	s_nop 0
	global_load_lds_dwordx4 v[140:141], off
	s_waitcnt vmcnt(8) lgkmcnt(0)
	s_barrier
	v_mfma_f32_16x16x32_bf16 v[120:123], v[150:153], v[182:185], v[120:123]
	v_mfma_f32_16x16x32_bf16 v[112:115], v[158:161], v[182:185], v[112:115]
	v_mfma_f32_16x16x32_bf16 v[104:107], v[150:153], v[190:193], v[104:107]
	v_mfma_f32_16x16x32_bf16 v[96:99], v[158:161], v[190:193], v[96:99]
	v_mfma_f32_16x16x32_bf16 v[88:91], v[150:153], v[198:201], v[88:91]
	v_mfma_f32_16x16x32_bf16 v[80:83], v[158:161], v[198:201], v[80:83]
	v_mfma_f32_16x16x32_bf16 v[56:59], v[150:153], v[206:209], v[56:59]
	v_mfma_f32_16x16x32_bf16 v[48:51], v[158:161], v[206:209], v[48:51]
	v_mfma_f32_16x16x32_bf16 v[120:123], v[154:157], v[186:189], v[120:123]
	v_mfma_f32_16x16x32_bf16 v[112:115], v[162:165], v[186:189], v[112:115]
	v_mfma_f32_16x16x32_bf16 v[104:107], v[154:157], v[194:197], v[104:107]
	v_mfma_f32_16x16x32_bf16 v[96:99], v[162:165], v[194:197], v[96:99]
	v_mfma_f32_16x16x32_bf16 v[88:91], v[154:157], v[202:205], v[88:91]
	v_mfma_f32_16x16x32_bf16 v[80:83], v[162:165], v[202:205], v[80:83]
	v_mfma_f32_16x16x32_bf16 v[56:59], v[154:157], v[210:213], v[56:59]
	v_mfma_f32_16x16x32_bf16 v[48:51], v[162:165], v[210:213], v[48:51]
	v_mfma_f32_16x16x32_bf16 v[124:127], v[166:169], v[182:185], v[124:127]
	v_mfma_f32_16x16x32_bf16 v[116:119], v[174:177], v[182:185], v[116:119]
	v_mfma_f32_16x16x32_bf16 v[108:111], v[166:169], v[190:193], v[108:111]
	v_mfma_f32_16x16x32_bf16 v[100:103], v[174:177], v[190:193], v[100:103]
	v_mfma_f32_16x16x32_bf16 v[92:95], v[166:169], v[198:201], v[92:95]
	v_mfma_f32_16x16x32_bf16 v[84:87], v[174:177], v[198:201], v[84:87]
	v_mfma_f32_16x16x32_bf16 v[60:63], v[166:169], v[206:209], v[60:63]
	v_mfma_f32_16x16x32_bf16 v[52:55], v[174:177], v[206:209], v[52:55]
	v_mfma_f32_16x16x32_bf16 v[124:127], v[170:173], v[186:189], v[124:127]
	v_mfma_f32_16x16x32_bf16 v[116:119], v[178:181], v[186:189], v[116:119]
	v_mfma_f32_16x16x32_bf16 v[108:111], v[170:173], v[194:197], v[108:111]
	v_mfma_f32_16x16x32_bf16 v[100:103], v[178:181], v[194:197], v[100:103]
	v_mfma_f32_16x16x32_bf16 v[92:95], v[170:173], v[202:205], v[92:95]
	v_mfma_f32_16x16x32_bf16 v[84:87], v[178:181], v[202:205], v[84:87]
	v_mfma_f32_16x16x32_bf16 v[60:63], v[170:173], v[210:213], v[60:63]
	v_mfma_f32_16x16x32_bf16 v[52:55], v[178:181], v[210:213], v[52:55]
	s_barrier
	s_mov_b32 m0, s57
	v_lshl_add_u64 v[140:141], s[76:77], 0, v[128:129]
	s_add_u32 s88, s76, 0x20000
	ds_read_b128 v[182:185], v149 offset:16384
	ds_read_b128 v[186:189], v149 offset:17408
	ds_read_b128 v[190:193], v149 offset:18432
	ds_read_b128 v[194:197], v149 offset:19456
	ds_read_b128 v[198:201], v149 offset:20480
	ds_read_b128 v[202:205], v149 offset:21504
	ds_read_b128 v[206:209], v149 offset:22528
	ds_read_b128 v[210:213], v149 offset:23552
	global_load_lds_dwordx4 v[140:141], off
	v_lshl_add_u64 v[142:143], s[76:77], 0, v[130:131]
	s_mov_b32 m0, s58
	s_addc_u32 s89, s77, 0
	global_load_lds_dwordx4 v[142:143], off
	v_lshl_add_u64 v[214:215], s[88:89], 0, v[128:129]
	s_mov_b32 m0, s59
	v_lshl_add_u64 v[216:217], s[78:79], 0, v[132:133]
	global_load_lds_dwordx4 v[214:215], off
	v_lshl_add_u64 v[214:215], s[88:89], 0, v[130:131]
	s_mov_b32 m0, s65
	s_nop 0
	global_load_lds_dwordx4 v[214:215], off
	v_lshl_add_u64 v[214:215], s[78:79], 0, v[134:135]
	s_mov_b32 m0, s0
	s_nop 0
	global_load_lds_dwordx4 v[214:215], off
	s_mov_b32 m0, s1
	s_nop 0
	global_load_lds_dwordx4 v[216:217], off
	s_waitcnt vmcnt(8) lgkmcnt(0)
	s_barrier
	v_mfma_f32_16x16x32_bf16 v[76:79], v[150:153], v[182:185], v[76:79]
	v_mfma_f32_16x16x32_bf16 v[72:75], v[158:161], v[182:185], v[72:75]
	v_mfma_f32_16x16x32_bf16 v[44:47], v[150:153], v[190:193], v[44:47]
	v_mfma_f32_16x16x32_bf16 v[40:43], v[158:161], v[190:193], v[40:43]
	v_mfma_f32_16x16x32_bf16 v[28:31], v[150:153], v[198:201], v[28:31]
	v_mfma_f32_16x16x32_bf16 v[24:27], v[158:161], v[198:201], v[24:27]
	v_mfma_f32_16x16x32_bf16 v[12:15], v[150:153], v[206:209], v[12:15]
	v_mfma_f32_16x16x32_bf16 v[8:11], v[158:161], v[206:209], v[8:11]
	v_mfma_f32_16x16x32_bf16 v[76:79], v[154:157], v[186:189], v[76:79]
	v_mfma_f32_16x16x32_bf16 v[72:75], v[162:165], v[186:189], v[72:75]
	v_mfma_f32_16x16x32_bf16 v[44:47], v[154:157], v[194:197], v[44:47]
	v_mfma_f32_16x16x32_bf16 v[40:43], v[162:165], v[194:197], v[40:43]
	v_mfma_f32_16x16x32_bf16 v[28:31], v[154:157], v[202:205], v[28:31]
	v_mfma_f32_16x16x32_bf16 v[24:27], v[162:165], v[202:205], v[24:27]
	v_mfma_f32_16x16x32_bf16 v[12:15], v[154:157], v[210:213], v[12:15]
	v_mfma_f32_16x16x32_bf16 v[8:11], v[162:165], v[210:213], v[8:11]
	v_mfma_f32_16x16x32_bf16 v[68:71], v[166:169], v[182:185], v[68:71]
	v_mfma_f32_16x16x32_bf16 v[64:67], v[174:177], v[182:185], v[64:67]
	v_mfma_f32_16x16x32_bf16 v[36:39], v[166:169], v[190:193], v[36:39]
	v_mfma_f32_16x16x32_bf16 v[32:35], v[174:177], v[190:193], v[32:35]
	v_mfma_f32_16x16x32_bf16 v[20:23], v[166:169], v[198:201], v[20:23]
	v_mfma_f32_16x16x32_bf16 v[16:19], v[174:177], v[198:201], v[16:19]
	v_mfma_f32_16x16x32_bf16 v[4:7], v[166:169], v[206:209], v[4:7]
	v_mfma_f32_16x16x32_bf16 v[0:3], v[174:177], v[206:209], v[0:3]
	v_mfma_f32_16x16x32_bf16 v[68:71], v[170:173], v[186:189], v[68:71]
	v_mfma_f32_16x16x32_bf16 v[64:67], v[178:181], v[186:189], v[64:67]
	v_mfma_f32_16x16x32_bf16 v[36:39], v[170:173], v[194:197], v[36:39]
	v_mfma_f32_16x16x32_bf16 v[32:35], v[178:181], v[194:197], v[32:35]
	v_mfma_f32_16x16x32_bf16 v[20:23], v[170:173], v[202:205], v[20:23]
	v_mfma_f32_16x16x32_bf16 v[16:19], v[178:181], v[202:205], v[16:19]
	v_mfma_f32_16x16x32_bf16 v[4:7], v[170:173], v[210:213], v[4:7]
	v_mfma_f32_16x16x32_bf16 v[0:3], v[178:181], v[210:213], v[0:3]
	s_barrier
; #define PG8_MMA(ai, bj, At, Bt) do { __builtin_amdgcn_s_setprio(1); _Pragma("unroll") for (int m = 0; m < 4; ++m) _Pragma("unroll") for (int n = 0; n < 2; ++n) _Pragma("unroll") for (int k = 0; k < 2; ++k) \
;         acc[ai][bj][m][n] = __builtin_amdgcn_mfma_f32_16x16x32_bf16(Bt[n][k], At[m][k], acc[ai][bj][m][n], 0, 0, 0); __builtin_amdgcn_s_setprio(0); } while (0)
; template <class Epi, class Sched, bool ALIGN_EPI = false, bool SP2 = false, bool A_TILED = false>
; __device__ __forceinline__ void gemm_phase(PG8_LAS unsigned char* lds, const Gemm g, const Sched& S, const Epi& E, const int wave_s) {
;     ...
;         for (int t = PEEL ? 2 : 0; t < nt; t += 2) {
;             const bool last = (t == nt - 2);
;             const char* a1 = cA + (size_t)(t + 1) * kstepA;
;             const char* a2 = last ? nA : cA + (size_t)(t + 2) * kstepA; const char* b2 = last ? nB : cB + (size_t)(t + 2) * kstep;
;             const char* a3 = a2 + kstepA; const char* b3 = b2 + kstep;
;             if (last && has_next) S.a_ready(nxt);
;             if constexpr (SP2) {
;             PG8_ITER(PG8_MMA)
	ds_read_b128 v[150:153], v144
	ds_read_b128 v[154:157], v144 offset:1024
	ds_read_b128 v[158:161], v144 offset:2048
	ds_read_b128 v[162:165], v144 offset:3072
	ds_read_b128 v[166:169], v145
	ds_read_b128 v[170:173], v145 offset:1024
	ds_read_b128 v[174:177], v145 offset:2048
	ds_read_b128 v[178:181], v145 offset:3072
	s_add_u32 s78, s78, 0x20000
	s_addc_u32 s79, s79, 0
	s_mov_b32 m0, s37
	v_lshl_add_u64 v[218:219], s[78:79], 0, v[134:135]
	ds_read_b128 v[182:185], v149 offset:32768
	ds_read_b128 v[186:189], v149 offset:33792
	ds_read_b128 v[190:193], v149 offset:34816
	ds_read_b128 v[194:197], v149 offset:35840
	ds_read_b128 v[198:201], v149 offset:36864
	ds_read_b128 v[202:205], v149 offset:37888
	ds_read_b128 v[206:209], v149 offset:38912
	ds_read_b128 v[210:213], v149 offset:39936
	global_load_lds_dwordx4 v[218:219], off
	v_lshl_add_u64 v[218:219], s[78:79], 0, v[132:133]
	s_mov_b32 m0, s38
	s_nop 0
	global_load_lds_dwordx4 v[218:219], off
	s_waitcnt vmcnt(8) lgkmcnt(0)
	s_barrier
	v_mfma_f32_16x16x32_bf16 v[120:123], v[150:153], v[182:185], v[120:123]
	v_mfma_f32_16x16x32_bf16 v[112:115], v[158:161], v[182:185], v[112:115]
	v_mfma_f32_16x16x32_bf16 v[104:107], v[150:153], v[190:193], v[104:107]
	v_mfma_f32_16x16x32_bf16 v[96:99], v[158:161], v[190:193], v[96:99]
	v_mfma_f32_16x16x32_bf16 v[88:91], v[150:153], v[198:201], v[88:91]
	v_mfma_f32_16x16x32_bf16 v[80:83], v[158:161], v[198:201], v[80:83]
	v_mfma_f32_16x16x32_bf16 v[56:59], v[150:153], v[206:209], v[56:59]
	v_mfma_f32_16x16x32_bf16 v[48:51], v[158:161], v[206:209], v[48:51]
	v_mfma_f32_16x16x32_bf16 v[120:123], v[154:157], v[186:189], v[120:123]
	v_mfma_f32_16x16x32_bf16 v[112:115], v[162:165], v[186:189], v[112:115]
	v_mfma_f32_16x16x32_bf16 v[104:107], v[154:157], v[194:197], v[104:107]
	v_mfma_f32_16x16x32_bf16 v[96:99], v[162:165], v[194:197], v[96:99]
	v_mfma_f32_16x16x32_bf16 v[88:91], v[154:157], v[202:205], v[88:91]
	v_mfma_f32_16x16x32_bf16 v[80:83], v[162:165], v[202:205], v[80:83]
	v_mfma_f32_16x16x32_bf16 v[56:59], v[154:157], v[210:213], v[56:59]
	v_mfma_f32_16x16x32_bf16 v[48:51], v[162:165], v[210:213], v[48:51]
	v_mfma_f32_16x16x32_bf16 v[124:127], v[166:169], v[182:185], v[124:127]
	v_mfma_f32_16x16x32_bf16 v[116:119], v[174:177], v[182:185], v[116:119]
	v_mfma_f32_16x16x32_bf16 v[108:111], v[166:169], v[190:193], v[108:111]
	v_mfma_f32_16x16x32_bf16 v[100:103], v[174:177], v[190:193], v[100:103]
	v_mfma_f32_16x16x32_bf16 v[92:95], v[166:169], v[198:201], v[92:95]
	v_mfma_f32_16x16x32_bf16 v[84:87], v[174:177], v[198:201], v[84:87]
	v_mfma_f32_16x16x32_bf16 v[60:63], v[166:169], v[206:209], v[60:63]
	v_mfma_f32_16x16x32_bf16 v[52:55], v[174:177], v[206:209], v[52:55]
	v_mfma_f32_16x16x32_bf16 v[124:127], v[170:173], v[186:189], v[124:127]
	v_mfma_f32_16x16x32_bf16 v[116:119], v[178:181], v[186:189], v[116:119]
	v_mfma_f32_16x16x32_bf16 v[108:111], v[170:173], v[194:197], v[108:111]
	v_mfma_f32_16x16x32_bf16 v[100:103], v[178:181], v[194:197], v[100:103]
	v_mfma_f32_16x16x32_bf16 v[92:95], v[170:173], v[202:205], v[92:95]
	v_mfma_f32_16x16x32_bf16 v[84:87], v[178:181], v[202:205], v[84:87]
	v_mfma_f32_16x16x32_bf16 v[60:63], v[170:173], v[210:213], v[60:63]
	v_mfma_f32_16x16x32_bf16 v[52:55], v[178:181], v[210:213], v[52:55]
	s_barrier
	s_mov_b32 m0, s67
	v_lshl_add_u64 v[140:141], v[140:141], 0, s[44:45]
	s_add_u32 s76, s76, 0x20080
	ds_read_b128 v[182:185], v149 offset:49152
	ds_read_b128 v[186:189], v149 offset:50176
	ds_read_b128 v[190:193], v149 offset:51200
	ds_read_b128 v[194:197], v149 offset:52224
	ds_read_b128 v[198:201], v149 offset:53248
	ds_read_b128 v[202:205], v149 offset:54272
	ds_read_b128 v[206:209], v149 offset:55296
	ds_read_b128 v[210:213], v149 offset:56320
	global_load_lds_dwordx4 v[140:141], off
	v_lshl_add_u64 v[140:141], v[142:143], 0, s[44:45]
	s_mov_b32 m0, s71
	s_addc_u32 s77, s77, 0
	global_load_lds_dwordx4 v[140:141], off
	v_lshl_add_u64 v[140:141], s[76:77], 0, v[128:129]
	s_mov_b32 m0, s80
	s_nop 0
	global_load_lds_dwordx4 v[140:141], off
	v_lshl_add_u64 v[140:141], s[76:77], 0, v[130:131]
	s_mov_b32 m0, s81
	s_nop 0
	global_load_lds_dwordx4 v[140:141], off
	v_lshl_add_u64 v[140:141], v[214:215], 0, s[44:45]
	s_mov_b32 m0, s42
	s_nop 0
	global_load_lds_dwordx4 v[140:141], off
	v_lshl_add_u64 v[140:141], v[216:217], 0, s[44:45]
	s_mov_b32 m0, s43
	s_nop 0
	global_load_lds_dwordx4 v[140:141], off
	s_waitcnt vmcnt(8) lgkmcnt(0)
	s_barrier
	v_mfma_f32_16x16x32_bf16 v[76:79], v[150:153], v[182:185], v[76:79]
	v_mfma_f32_16x16x32_bf16 v[72:75], v[158:161], v[182:185], v[72:75]
	v_mfma_f32_16x16x32_bf16 v[44:47], v[150:153], v[190:193], v[44:47]
	v_mfma_f32_16x16x32_bf16 v[40:43], v[158:161], v[190:193], v[40:43]
	v_mfma_f32_16x16x32_bf16 v[28:31], v[150:153], v[198:201], v[28:31]
	v_mfma_f32_16x16x32_bf16 v[24:27], v[158:161], v[198:201], v[24:27]
	v_mfma_f32_16x16x32_bf16 v[12:15], v[150:153], v[206:209], v[12:15]
	v_mfma_f32_16x16x32_bf16 v[8:11], v[158:161], v[206:209], v[8:11]
	v_mfma_f32_16x16x32_bf16 v[76:79], v[154:157], v[186:189], v[76:79]
	v_mfma_f32_16x16x32_bf16 v[72:75], v[162:165], v[186:189], v[72:75]
	v_mfma_f32_16x16x32_bf16 v[44:47], v[154:157], v[194:197], v[44:47]
	v_mfma_f32_16x16x32_bf16 v[40:43], v[162:165], v[194:197], v[40:43]
	v_mfma_f32_16x16x32_bf16 v[28:31], v[154:157], v[202:205], v[28:31]
	v_mfma_f32_16x16x32_bf16 v[24:27], v[162:165], v[202:205], v[24:27]
	v_mfma_f32_16x16x32_bf16 v[12:15], v[154:157], v[210:213], v[12:15]
	v_mfma_f32_16x16x32_bf16 v[8:11], v[162:165], v[210:213], v[8:11]
	v_mfma_f32_16x16x32_bf16 v[68:71], v[166:169], v[182:185], v[68:71]
	v_mfma_f32_16x16x32_bf16 v[64:67], v[174:177], v[182:185], v[64:67]
	v_mfma_f32_16x16x32_bf16 v[36:39], v[166:169], v[190:193], v[36:39]
	v_mfma_f32_16x16x32_bf16 v[32:35], v[174:177], v[190:193], v[32:35]
	v_mfma_f32_16x16x32_bf16 v[20:23], v[166:169], v[198:201], v[20:23]
	v_mfma_f32_16x16x32_bf16 v[16:19], v[174:177], v[198:201], v[16:19]
	v_mfma_f32_16x16x32_bf16 v[4:7], v[166:169], v[206:209], v[4:7]
	v_mfma_f32_16x16x32_bf16 v[0:3], v[174:177], v[206:209], v[0:3]
	v_mfma_f32_16x16x32_bf16 v[68:71], v[170:173], v[186:189], v[68:71]
	v_mfma_f32_16x16x32_bf16 v[64:67], v[178:181], v[186:189], v[64:67]
	v_mfma_f32_16x16x32_bf16 v[36:39], v[170:173], v[194:197], v[36:39]
	v_mfma_f32_16x16x32_bf16 v[32:35], v[178:181], v[194:197], v[32:35]
	v_mfma_f32_16x16x32_bf16 v[20:23], v[170:173], v[202:205], v[20:23]
	v_mfma_f32_16x16x32_bf16 v[16:19], v[178:181], v[202:205], v[16:19]
	v_mfma_f32_16x16x32_bf16 v[4:7], v[170:173], v[210:213], v[4:7]
	v_mfma_f32_16x16x32_bf16 v[0:3], v[178:181], v[210:213], v[0:3]
	s_barrier
	s_add_i32 s85, s85, 2
	s_add_u32 s82, s82, 0x100
	s_addc_u32 s83, s83, 0
	s_add_u32 s74, s74, 0x100
	s_addc_u32 s75, s75, 0
	s_cmp_gt_u32 s85, 5
	s_cbranch_scc0 .LBB0_2566
	s_and_b64 vcc, exec, s[46:47]
	s_cbranch_vccz .LBB0_2569
	s_barrier

; #define PG8_MMA(ai, bj, At, Bt) do { __builtin_amdgcn_s_setprio(1); _Pragma("unroll") for (int m = 0; m < 4; ++m) _Pragma("unroll") for (int n = 0; n < 2; ++n) _Pragma("unroll") for (int k = 0; k < 2; ++k) \
;         acc[ai][bj][m][n] = __builtin_amdgcn_mfma_f32_16x16x32_bf16(Bt[n][k], At[m][k], acc[ai][bj][m][n], 0, 0, 0); __builtin_amdgcn_s_setprio(0); } while (0)
; template <class Epi, class Sched, bool ALIGN_EPI = false, bool SP2 = false, bool A_TILED = false>
; __device__ __forceinline__ void gemm_phase(PG8_LAS unsigned char* lds, const Gemm g, const Sched& S, const Epi& E, const int wave_s) {
;     ...
;         for (int t = PEEL ? 2 : 0; t < nt; t += 2) {
;             const bool last = (t == nt - 2);
;             const char* a1 = cA + (size_t)(t + 1) * kstepA;
;             const char* a2 = last ? nA : cA + (size_t)(t + 2) * kstepA; const char* b2 = last ? nB : cB + (size_t)(t + 2) * kstep;
;             const char* a3 = a2 + kstepA; const char* b3 = b2 + kstep;
;             if (last && has_next) S.a_ready(nxt);
;             if constexpr (SP2) {
;             PG8_ITER(PG8_MMA)
.LBB0_2729:
	ds_read_b128 v[146:149], v140
	ds_read_b128 v[150:153], v140 offset:1024
	ds_read_b128 v[154:157], v140 offset:2048
	ds_read_b128 v[158:161], v140 offset:3072
	ds_read_b128 v[162:165], v141
	ds_read_b128 v[166:169], v141 offset:1024
	ds_read_b128 v[170:173], v141 offset:2048
	ds_read_b128 v[174:177], v141 offset:3072
	s_add_u32 s55, s44, s39
	s_addc_u32 s56, s45, s40
	s_add_u32 s57, s44, s37
	s_addc_u32 s58, s45, s38
	s_cmp_eq_u32 s41, 28
	s_cselect_b32 s67, s7, s56
	s_cselect_b32 s66, s6, s55
	s_cselect_b32 s65, s3, s58
	s_cselect_b32 s64, s2, s57
	s_mov_b32 m0, s42
	v_lshl_add_u64 v[210:211], s[44:45], 0, v[138:139]
	ds_read_b128 v[178:181], v142
	ds_read_b128 v[182:185], v142 offset:1024
	ds_read_b128 v[186:189], v142 offset:2048
	ds_read_b128 v[190:193], v142 offset:3072
	ds_read_b128 v[194:197], v142 offset:4096
	ds_read_b128 v[198:201], v142 offset:5120
	ds_read_b128 v[202:205], v142 offset:6144
	ds_read_b128 v[206:209], v142 offset:7168
	global_load_lds_dwordx4 v[210:211], off
	v_lshl_add_u64 v[210:211], s[44:45], 0, v[136:137]
	s_mov_b32 m0, s43
	s_nop 0
	global_load_lds_dwordx4 v[210:211], off
	s_waitcnt vmcnt(8) lgkmcnt(0)
	s_barrier
	v_mfma_f32_16x16x32_bf16 v[8:11], v[146:149], v[178:181], v[8:11]
	v_mfma_f32_16x16x32_bf16 v[12:15], v[154:157], v[178:181], v[12:15]
	v_mfma_f32_16x16x32_bf16 v[60:63], v[146:149], v[186:189], v[60:63]
	v_mfma_f32_16x16x32_bf16 v[20:23], v[154:157], v[186:189], v[20:23]
	v_mfma_f32_16x16x32_bf16 v[76:79], v[146:149], v[194:197], v[76:79]
	v_mfma_f32_16x16x32_bf16 v[52:55], v[154:157], v[194:197], v[52:55]
	v_mfma_f32_16x16x32_bf16 v[128:131], v[146:149], v[202:205], v[128:131]
	v_mfma_f32_16x16x32_bf16 v[68:71], v[154:157], v[202:205], v[68:71]
	v_mfma_f32_16x16x32_bf16 v[8:11], v[150:153], v[182:185], v[8:11]
	v_mfma_f32_16x16x32_bf16 v[12:15], v[158:161], v[182:185], v[12:15]
	v_mfma_f32_16x16x32_bf16 v[60:63], v[150:153], v[190:193], v[60:63]
	v_mfma_f32_16x16x32_bf16 v[20:23], v[158:161], v[190:193], v[20:23]
	v_mfma_f32_16x16x32_bf16 v[76:79], v[150:153], v[198:201], v[76:79]
	v_mfma_f32_16x16x32_bf16 v[52:55], v[158:161], v[198:201], v[52:55]
	v_mfma_f32_16x16x32_bf16 v[128:131], v[150:153], v[206:209], v[128:131]
	v_mfma_f32_16x16x32_bf16 v[68:71], v[158:161], v[206:209], v[68:71]
	v_mfma_f32_16x16x32_bf16 v[24:27], v[162:165], v[178:181], v[24:27]
	v_mfma_f32_16x16x32_bf16 v[16:19], v[170:173], v[178:181], v[16:19]
	v_mfma_f32_16x16x32_bf16 v[56:59], v[162:165], v[186:189], v[56:59]
	v_mfma_f32_16x16x32_bf16 v[48:51], v[170:173], v[186:189], v[48:51]
	v_mfma_f32_16x16x32_bf16 v[72:75], v[162:165], v[194:197], v[72:75]
	v_mfma_f32_16x16x32_bf16 v[64:67], v[170:173], v[194:197], v[64:67]
	v_mfma_f32_16x16x32_bf16 v[108:111], v[162:165], v[202:205], v[108:111]
	v_mfma_f32_16x16x32_bf16 v[96:99], v[170:173], v[202:205], v[96:99]
	v_mfma_f32_16x16x32_bf16 v[24:27], v[166:169], v[182:185], v[24:27]
	v_mfma_f32_16x16x32_bf16 v[16:19], v[174:177], v[182:185], v[16:19]
	v_mfma_f32_16x16x32_bf16 v[56:59], v[166:169], v[190:193], v[56:59]
	v_mfma_f32_16x16x32_bf16 v[48:51], v[174:177], v[190:193], v[48:51]
	v_mfma_f32_16x16x32_bf16 v[72:75], v[166:169], v[198:201], v[72:75]
	v_mfma_f32_16x16x32_bf16 v[64:67], v[174:177], v[198:201], v[64:67]
	v_mfma_f32_16x16x32_bf16 v[108:111], v[166:169], v[206:209], v[108:111]
	v_mfma_f32_16x16x32_bf16 v[96:99], v[174:177], v[206:209], v[96:99]
	s_barrier
	s_mov_b32 m0, s47
	v_lshl_add_u64 v[210:211], s[64:65], 0, v[34:35]
	s_add_u32 s56, s64, 0x80000
	ds_read_b128 v[178:181], v142 offset:16384
	ds_read_b128 v[182:185], v142 offset:17408
	ds_read_b128 v[186:189], v142 offset:18432
	ds_read_b128 v[190:193], v142 offset:19456
	ds_read_b128 v[194:197], v142 offset:20480
	ds_read_b128 v[198:201], v142 offset:21504
	ds_read_b128 v[202:205], v142 offset:22528
	ds_read_b128 v[206:209], v142 offset:23552
	global_load_lds_dwordx4 v[210:211], off
	v_lshl_add_u64 v[212:213], s[64:65], 0, v[134:135]
	s_mov_b32 m0, s48
	s_addc_u32 s57, s65, 0
	global_load_lds_dwordx4 v[212:213], off
	v_lshl_add_u64 v[214:215], s[56:57], 0, v[34:35]
	s_mov_b32 m0, s49
	v_lshl_add_u64 v[216:217], s[66:67], 0, v[132:133]
	global_load_lds_dwordx4 v[214:215], off
	v_lshl_add_u64 v[214:215], s[56:57], 0, v[134:135]
	s_mov_b32 m0, s50
	s_nop 0
	global_load_lds_dwordx4 v[214:215], off
	v_lshl_add_u64 v[214:215], s[66:67], 0, v[32:33]
	s_mov_b32 m0, s14
	s_nop 0
	global_load_lds_dwordx4 v[214:215], off
	s_mov_b32 m0, s15
	s_nop 0
	global_load_lds_dwordx4 v[216:217], off
	s_waitcnt vmcnt(8) lgkmcnt(0)
	s_barrier
	v_mfma_f32_16x16x32_bf16 v[100:103], v[146:149], v[178:181], v[100:103]
	v_mfma_f32_16x16x32_bf16 v[104:107], v[154:157], v[178:181], v[104:107]
	v_mfma_f32_16x16x32_bf16 v[116:119], v[146:149], v[186:189], v[116:119]
	v_mfma_f32_16x16x32_bf16 v[120:123], v[154:157], v[186:189], v[120:123]
	v_mfma_f32_16x16x32_bf16 v[84:87], v[146:149], v[194:197], v[84:87]
	v_mfma_f32_16x16x32_bf16 v[80:83], v[154:157], v[194:197], v[80:83]
	v_mfma_f32_16x16x32_bf16 v[36:39], v[146:149], v[202:205], v[36:39]
	v_mfma_f32_16x16x32_bf16 v[28:31], v[154:157], v[202:205], v[28:31]
	v_mfma_f32_16x16x32_bf16 v[100:103], v[150:153], v[182:185], v[100:103]
	v_mfma_f32_16x16x32_bf16 v[104:107], v[158:161], v[182:185], v[104:107]
	v_mfma_f32_16x16x32_bf16 v[116:119], v[150:153], v[190:193], v[116:119]
	v_mfma_f32_16x16x32_bf16 v[120:123], v[158:161], v[190:193], v[120:123]
	v_mfma_f32_16x16x32_bf16 v[84:87], v[150:153], v[198:201], v[84:87]
	v_mfma_f32_16x16x32_bf16 v[80:83], v[158:161], v[198:201], v[80:83]
	v_mfma_f32_16x16x32_bf16 v[36:39], v[150:153], v[206:209], v[36:39]
	v_mfma_f32_16x16x32_bf16 v[28:31], v[158:161], v[206:209], v[28:31]
	v_mfma_f32_16x16x32_bf16 v[124:127], v[162:165], v[178:181], v[124:127]
	v_mfma_f32_16x16x32_bf16 v[112:115], v[170:173], v[178:181], v[112:115]
	v_mfma_f32_16x16x32_bf16 v[92:95], v[162:165], v[186:189], v[92:95]
	v_mfma_f32_16x16x32_bf16 v[88:91], v[170:173], v[186:189], v[88:91]
	v_mfma_f32_16x16x32_bf16 v[44:47], v[162:165], v[194:197], v[44:47]
	v_mfma_f32_16x16x32_bf16 v[40:43], v[170:173], v[194:197], v[40:43]
	v_mfma_f32_16x16x32_bf16 v[4:7], v[162:165], v[202:205], v[4:7]
	v_mfma_f32_16x16x32_bf16 v[0:3], v[170:173], v[202:205], v[0:3]
	v_mfma_f32_16x16x32_bf16 v[124:127], v[166:169], v[182:185], v[124:127]
	v_mfma_f32_16x16x32_bf16 v[112:115], v[174:177], v[182:185], v[112:115]
	v_mfma_f32_16x16x32_bf16 v[92:95], v[166:169], v[190:193], v[92:95]
	v_mfma_f32_16x16x32_bf16 v[88:91], v[174:177], v[190:193], v[88:91]
	v_mfma_f32_16x16x32_bf16 v[44:47], v[166:169], v[198:201], v[44:47]
	v_mfma_f32_16x16x32_bf16 v[40:43], v[174:177], v[198:201], v[40:43]
	v_mfma_f32_16x16x32_bf16 v[4:7], v[166:169], v[206:209], v[4:7]
	v_mfma_f32_16x16x32_bf16 v[0:3], v[174:177], v[206:209], v[0:3]
	s_barrier
	ds_read_b128 v[146:149], v143
	ds_read_b128 v[150:153], v143 offset:1024
	ds_read_b128 v[154:157], v143 offset:2048
	ds_read_b128 v[158:161], v143 offset:3072
	ds_read_b128 v[162:165], v144
	ds_read_b128 v[166:169], v144 offset:1024
	ds_read_b128 v[170:173], v144 offset:2048
	ds_read_b128 v[174:177], v144 offset:3072
	s_add_u32 s56, s66, 0x80000
	s_addc_u32 s57, s67, 0
	s_mov_b32 m0, s21
	v_lshl_add_u64 v[218:219], s[56:57], 0, v[32:33]
	ds_read_b128 v[178:181], v142 offset:32768
	ds_read_b128 v[182:185], v142 offset:33792
	ds_read_b128 v[186:189], v142 offset:34816
	ds_read_b128 v[190:193], v142 offset:35840
	ds_read_b128 v[194:197], v142 offset:36864
	ds_read_b128 v[198:201], v142 offset:37888
	ds_read_b128 v[202:205], v142 offset:38912
	ds_read_b128 v[206:209], v142 offset:39936
	global_load_lds_dwordx4 v[218:219], off
	v_lshl_add_u64 v[218:219], s[56:57], 0, v[132:133]
	s_mov_b32 m0, s22
	s_nop 0
	global_load_lds_dwordx4 v[218:219], off
	s_waitcnt vmcnt(8) lgkmcnt(0)
	s_barrier
	v_mfma_f32_16x16x32_bf16 v[8:11], v[146:149], v[178:181], v[8:11]
	v_mfma_f32_16x16x32_bf16 v[12:15], v[154:157], v[178:181], v[12:15]
	v_mfma_f32_16x16x32_bf16 v[60:63], v[146:149], v[186:189], v[60:63]
	v_mfma_f32_16x16x32_bf16 v[20:23], v[154:157], v[186:189], v[20:23]
	v_mfma_f32_16x16x32_bf16 v[76:79], v[146:149], v[194:197], v[76:79]
	v_mfma_f32_16x16x32_bf16 v[52:55], v[154:157], v[194:197], v[52:55]
	v_mfma_f32_16x16x32_bf16 v[128:131], v[146:149], v[202:205], v[128:131]
	v_mfma_f32_16x16x32_bf16 v[68:71], v[154:157], v[202:205], v[68:71]
	v_mfma_f32_16x16x32_bf16 v[8:11], v[150:153], v[182:185], v[8:11]
	v_mfma_f32_16x16x32_bf16 v[12:15], v[158:161], v[182:185], v[12:15]
	v_mfma_f32_16x16x32_bf16 v[60:63], v[150:153], v[190:193], v[60:63]
	v_mfma_f32_16x16x32_bf16 v[20:23], v[158:161], v[190:193], v[20:23]
	v_mfma_f32_16x16x32_bf16 v[76:79], v[150:153], v[198:201], v[76:79]
	v_mfma_f32_16x16x32_bf16 v[52:55], v[158:161], v[198:201], v[52:55]
	v_mfma_f32_16x16x32_bf16 v[128:131], v[150:153], v[206:209], v[128:131]
	v_mfma_f32_16x16x32_bf16 v[68:71], v[158:161], v[206:209], v[68:71]
	v_mfma_f32_16x16x32_bf16 v[24:27], v[162:165], v[178:181], v[24:27]
	v_mfma_f32_16x16x32_bf16 v[16:19], v[170:173], v[178:181], v[16:19]
	v_mfma_f32_16x16x32_bf16 v[56:59], v[162:165], v[186:189], v[56:59]
	v_mfma_f32_16x16x32_bf16 v[48:51], v[170:173], v[186:189], v[48:51]
	v_mfma_f32_16x16x32_bf16 v[72:75], v[162:165], v[194:197], v[72:75]
	v_mfma_f32_16x16x32_bf16 v[64:67], v[170:173], v[194:197], v[64:67]
	v_mfma_f32_16x16x32_bf16 v[108:111], v[162:165], v[202:205], v[108:111]
	v_mfma_f32_16x16x32_bf16 v[96:99], v[170:173], v[202:205], v[96:99]
	v_mfma_f32_16x16x32_bf16 v[24:27], v[166:169], v[182:185], v[24:27]
	v_mfma_f32_16x16x32_bf16 v[16:19], v[174:177], v[182:185], v[16:19]
	v_mfma_f32_16x16x32_bf16 v[56:59], v[166:169], v[190:193], v[56:59]
	v_mfma_f32_16x16x32_bf16 v[48:51], v[174:177], v[190:193], v[48:51]
	v_mfma_f32_16x16x32_bf16 v[72:75], v[166:169], v[198:201], v[72:75]
	v_mfma_f32_16x16x32_bf16 v[64:67], v[174:177], v[198:201], v[64:67]
	v_mfma_f32_16x16x32_bf16 v[108:111], v[166:169], v[206:209], v[108:111]
	v_mfma_f32_16x16x32_bf16 v[96:99], v[174:177], v[206:209], v[96:99]
	s_barrier
; template <class Epi, class Sched, bool ALIGN_EPI = false, bool SP2 = false, bool A_TILED = false>
; __device__ __forceinline__ void gemm_phase(PG8_LAS unsigned char* lds, const Gemm g, const Sched& S, const Epi& E, const int wave_s) {
;     ...
;         for (int t = PEEL ? 2 : 0; t < nt; t += 2) {
;             const bool last = (t == nt - 2);
;             const char* a1 = cA + (size_t)(t + 1) * kstepA;
;             const char* a2 = last ? nA : cA + (size_t)(t + 2) * kstepA; const char* b2 = last ? nB : cB + (size_t)(t + 2) * kstep;
;             const char* a3 = a2 + kstepA; const char* b3 = b2 + kstep;
;             if (last && has_next) S.a_ready(nxt);
;             if constexpr (SP2) {
;             PG8_ITER(PG8_MMA)
;             } else {
;             PG8_LDB(B0, 0, 0); PG8_SCHED; PG8_LDA(At, 0, 0); PG8_STAGE(PG8_SA(1, 1), a1 + hstepA, voffA);
;             PG8_WAIT_L(8); PG8_BAR; PG8_WAIT_L(0); PG8_MMA(0, 0, At, B0); PG8_BAR; PG8_SCHED;
;             PG8_LDB(B1, 0, 1); PG8_STAGE(PG8_SB(0, 0), b2, voffB);
;             PG8_BAR; PG8_WAIT_L(0); PG8_MMA(0, 1, At, B1); PG8_BAR;
;             PG8_LDA(At, 0, 1); PG8_STAGE(PG8_SA(0, 0), a2, voffA);
;             PG8_BAR; PG8_WAIT_L(0); PG8_MMA(1, 0, At, B0); PG8_BAR; PG8_SCHED;
;             PG8_STAGE(PG8_SB(0, 1), b2 + hstep, voffB);
;             PG8_WAIT_V(6); PG8_BAR; PG8_MMA(1, 1, At, B1); PG8_BAR;
;             PG8_LDB(B0, 1, 0); PG8_SCHED; PG8_LDA(At, 1, 0); PG8_STAGE(PG8_SA(0, 1), a2 + hstepA, voffA);
;             PG8_WAIT_L(8); PG8_BAR; PG8_WAIT_L(0); PG8_MMA(0, 0, At, B0); PG8_BAR; PG8_SCHED;
;             PG8_LDB(B1, 1, 1); PG8_STAGE(PG8_SB(1, 0), b3, voffB);
;             PG8_BAR; PG8_WAIT_L(0); PG8_MMA(0, 1, At, B1); PG8_BAR;
;             PG8_LDA(At, 1, 1); PG8_STAGE(PG8_SA(1, 0), a3, voffA);
;             PG8_BAR; PG8_WAIT_L(0); PG8_MMA(1, 0, At, B0); PG8_BAR; PG8_SCHED;
;             PG8_STAGE(PG8_SB(1, 1), b3 + hstep, voffB);
;             PG8_WAIT_V(6); PG8_BAR; PG8_MMA(1, 1, At, B1); PG8_BAR;
;             }
;         }
;         if constexpr (ALIGN_EPI) { if (wr == 0) PG8_BAR; }
;         if constexpr (!Epi::AFTER_DRAIN) { int te = tid_now(wave_s); asm volatile("" : "+v"(te));
;             E(acc, cur, wr, wc, te & 15, (te & 63) >> 4); S.done(cur); }
;         if (!has_next) break;
;         cur = nxt; cA = nA; cB = nB; ++ui;
;         if constexpr (ALIGN_EPI) { if (wr == 1) PG8_BAR; }
	s_mov_b32 m0, s51
	v_lshl_add_u64 v[210:211], v[210:211], 0, s[60:61]
	s_add_u32 s56, s64, 0x80080
	ds_read_b128 v[178:181], v142 offset:49152
	ds_read_b128 v[182:185], v142 offset:50176
	ds_read_b128 v[186:189], v142 offset:51200
	ds_read_b128 v[190:193], v142 offset:52224
	ds_read_b128 v[194:197], v142 offset:53248
	ds_read_b128 v[198:201], v142 offset:54272
	ds_read_b128 v[202:205], v142 offset:55296
	ds_read_b128 v[206:209], v142 offset:56320
	global_load_lds_dwordx4 v[210:211], off
	v_lshl_add_u64 v[210:211], v[212:213], 0, s[60:61]
	s_mov_b32 m0, s52
	s_addc_u32 s57, s65, 0
	global_load_lds_dwordx4 v[210:211], off
	v_lshl_add_u64 v[210:211], s[56:57], 0, v[34:35]
	s_mov_b32 m0, s53
	s_nop 0
	global_load_lds_dwordx4 v[210:211], off
	v_lshl_add_u64 v[210:211], s[56:57], 0, v[134:135]
	s_mov_b32 m0, s54
	s_nop 0
	global_load_lds_dwordx4 v[210:211], off
	v_lshl_add_u64 v[210:211], v[214:215], 0, s[60:61]
	s_mov_b32 m0, s23
	s_nop 0
	global_load_lds_dwordx4 v[210:211], off
	v_lshl_add_u64 v[210:211], v[216:217], 0, s[60:61]
	s_mov_b32 m0, s36
	s_nop 0
	global_load_lds_dwordx4 v[210:211], off
	s_waitcnt vmcnt(8) lgkmcnt(0)
	s_barrier
	v_mfma_f32_16x16x32_bf16 v[100:103], v[146:149], v[178:181], v[100:103]
	v_mfma_f32_16x16x32_bf16 v[104:107], v[154:157], v[178:181], v[104:107]
	v_mfma_f32_16x16x32_bf16 v[116:119], v[146:149], v[186:189], v[116:119]
	v_mfma_f32_16x16x32_bf16 v[120:123], v[154:157], v[186:189], v[120:123]
	v_mfma_f32_16x16x32_bf16 v[84:87], v[146:149], v[194:197], v[84:87]
	v_mfma_f32_16x16x32_bf16 v[80:83], v[154:157], v[194:197], v[80:83]
	v_mfma_f32_16x16x32_bf16 v[36:39], v[146:149], v[202:205], v[36:39]
	v_mfma_f32_16x16x32_bf16 v[28:31], v[154:157], v[202:205], v[28:31]
	v_mfma_f32_16x16x32_bf16 v[100:103], v[150:153], v[182:185], v[100:103]
	v_mfma_f32_16x16x32_bf16 v[104:107], v[158:161], v[182:185], v[104:107]
	v_mfma_f32_16x16x32_bf16 v[116:119], v[150:153], v[190:193], v[116:119]
	v_mfma_f32_16x16x32_bf16 v[120:123], v[158:161], v[190:193], v[120:123]
	v_mfma_f32_16x16x32_bf16 v[84:87], v[150:153], v[198:201], v[84:87]
	v_mfma_f32_16x16x32_bf16 v[80:83], v[158:161], v[198:201], v[80:83]
	v_mfma_f32_16x16x32_bf16 v[36:39], v[150:153], v[206:209], v[36:39]
	v_mfma_f32_16x16x32_bf16 v[28:31], v[158:161], v[206:209], v[28:31]
	v_mfma_f32_16x16x32_bf16 v[124:127], v[162:165], v[178:181], v[124:127]
	v_mfma_f32_16x16x32_bf16 v[112:115], v[170:173], v[178:181], v[112:115]
	v_mfma_f32_16x16x32_bf16 v[92:95], v[162:165], v[186:189], v[92:95]
	v_mfma_f32_16x16x32_bf16 v[88:91], v[170:173], v[186:189], v[88:91]
	v_mfma_f32_16x16x32_bf16 v[44:47], v[162:165], v[194:197], v[44:47]
	v_mfma_f32_16x16x32_bf16 v[40:43], v[170:173], v[194:197], v[40:43]
	v_mfma_f32_16x16x32_bf16 v[4:7], v[162:165], v[202:205], v[4:7]
	v_mfma_f32_16x16x32_bf16 v[0:3], v[170:173], v[202:205], v[0:3]
	v_mfma_f32_16x16x32_bf16 v[124:127], v[166:169], v[182:185], v[124:127]
	v_mfma_f32_16x16x32_bf16 v[112:115], v[174:177], v[182:185], v[112:115]
	v_mfma_f32_16x16x32_bf16 v[92:95], v[166:169], v[190:193], v[92:95]
	v_mfma_f32_16x16x32_bf16 v[88:91], v[174:177], v[190:193], v[88:91]
	v_mfma_f32_16x16x32_bf16 v[44:47], v[166:169], v[198:201], v[44:47]
	v_mfma_f32_16x16x32_bf16 v[40:43], v[174:177], v[198:201], v[40:43]
	v_mfma_f32_16x16x32_bf16 v[4:7], v[166:169], v[206:209], v[4:7]
	v_mfma_f32_16x16x32_bf16 v[0:3], v[174:177], v[206:209], v[0:3]
	s_barrier
	s_add_i32 s41, s41, 2
	s_add_u32 s37, s37, 0x100
	s_addc_u32 s38, s38, 0
	s_add_u32 s39, s39, 0x100
	s_addc_u32 s40, s40, 0
	v_lshl_add_u64 v[136:137], v[136:137], 0, s[62:63]
	s_cmp_gt_u32 s41, 29
	v_lshl_add_u64 v[138:139], v[138:139], 0, s[62:63]
	s_cbranch_scc0 .LBB0_2729
	s_waitcnt vmcnt(0)
	s_cmpk_lt_u32 s0, 0x100
	s_cbranch_scc0 .LBB0_2732
	s_barrier

; template <class Epi, class Sched, bool ALIGN_EPI = false, bool SP2 = false, bool A_TILED = false>
; __device__ __forceinline__ void gemm_phase(PG8_LAS unsigned char* lds, const Gemm g, const Sched& S, const Epi& E, const int wave_s) {
;     ...
;         const char* nA = has_next ? (const char*)g.A + (size_t)nxt.pm * tstepA : cA; const char* nB = has_next ? (const char*)g.Bt + (size_t)nxt.pn * tstep : cB;
;         constexpr bool PEEL = SP2 && !Epi::AFTER_DRAIN;
;         if constexpr (PEEL) {
;             const char* a1 = cA + kstepA; const char* a2 = cA + 2 * kstepA; const char* b2 = cB + 2 * kstep; const char* a3 = a2 + kstepA; const char* b3 = b2 + kstep;
;             PG8_ITER(PG8_MMAZ)
.LBB0_2840:
	s_ashr_i32 s65, s64, 31
	s_lshl_b64 s[54:55], s[64:65], 20
	s_add_u32 s66, s1, s54
	ds_read_b128 v[0:3], v145
	ds_read_b128 v[4:7], v145 offset:1024
	ds_read_b128 v[8:11], v145 offset:2048
	ds_read_b128 v[12:15], v145 offset:3072
	ds_read_b128 v[16:19], v146
	ds_read_b128 v[20:23], v146 offset:1024
	ds_read_b128 v[24:27], v146 offset:2048
	ds_read_b128 v[28:31], v146 offset:3072
	s_addc_u32 s67, s8, s55
	s_ashr_i32 s63, s62, 31
	s_lshl_b64 s[54:55], s[62:63], 20
	s_add_u32 s68, s9, s54
	s_addc_u32 s69, s14, s55
	s_and_b64 s[54:55], s[2:3], exec
	s_cselect_b32 s54, s67, s75
	s_cselect_b32 s55, s66, s74
	s_cselect_b32 s56, s69, s73
	s_cselect_b32 s57, s68, s72
	s_add_u32 s76, s74, 0x80080
	s_addc_u32 s77, s75, 0
	s_add_i32 s58, s22, 0xc000
	v_lshl_add_u64 v[64:65], s[76:77], 0, v[134:135]
	s_mov_b32 m0, s58
	s_add_i32 s59, s22, 0xe000
	ds_read_b128 v[32:35], v147
	ds_read_b128 v[36:39], v147 offset:1024
	ds_read_b128 v[40:43], v147 offset:2048
	ds_read_b128 v[44:47], v147 offset:3072
	ds_read_b128 v[48:51], v147 offset:4096
	ds_read_b128 v[52:55], v147 offset:5120
	ds_read_b128 v[56:59], v147 offset:6144
	ds_read_b128 v[60:63], v147 offset:7168
	global_load_lds_dwordx4 v[64:65], off
	v_lshl_add_u64 v[64:65], s[76:77], 0, v[132:133]
	s_mov_b32 m0, s59
	s_nop 0
	global_load_lds_dwordx4 v[64:65], off
	s_waitcnt vmcnt(8) lgkmcnt(0)
	s_barrier
	v_mfma_f32_16x16x32_bf16 v[88:91], v[0:3], v[56:59], 0
	v_mfma_f32_16x16x32_bf16 v[64:67], v[0:3], v[32:35], 0
	v_mfma_f32_16x16x32_bf16 v[68:71], v[8:11], v[32:35], 0
	v_mfma_f32_16x16x32_bf16 v[72:75], v[0:3], v[40:43], 0
	v_mfma_f32_16x16x32_bf16 v[76:79], v[8:11], v[40:43], 0
	v_mfma_f32_16x16x32_bf16 v[80:83], v[0:3], v[48:51], 0
	v_mfma_f32_16x16x32_bf16 v[84:87], v[8:11], v[48:51], 0
	v_mfma_f32_16x16x32_bf16 v[96:99], v[4:7], v[60:63], v[88:91]
	v_mfma_f32_16x16x32_bf16 v[88:91], v[8:11], v[56:59], 0
	v_mfma_f32_16x16x32_bf16 v[64:67], v[4:7], v[36:39], v[64:67]
	v_mfma_f32_16x16x32_bf16 v[68:71], v[12:15], v[36:39], v[68:71]
	v_mfma_f32_16x16x32_bf16 v[72:75], v[4:7], v[44:47], v[72:75]
	v_mfma_f32_16x16x32_bf16 v[76:79], v[12:15], v[44:47], v[76:79]
	v_mfma_f32_16x16x32_bf16 v[80:83], v[4:7], v[52:55], v[80:83]
	v_mfma_f32_16x16x32_bf16 v[84:87], v[12:15], v[52:55], v[84:87]
	v_mfma_f32_16x16x32_bf16 v[100:103], v[12:15], v[60:63], v[88:91]
	v_mfma_f32_16x16x32_bf16 v[88:91], v[16:19], v[32:35], 0
	v_mfma_f32_16x16x32_bf16 v[32:35], v[24:27], v[32:35], 0
	v_mfma_f32_16x16x32_bf16 v[112:115], v[20:23], v[36:39], v[88:91]
	v_mfma_f32_16x16x32_bf16 v[32:35], v[28:31], v[36:39], v[32:35]
	v_mfma_f32_16x16x32_bf16 v[36:39], v[16:19], v[40:43], 0
	v_mfma_f32_16x16x32_bf16 v[40:43], v[24:27], v[40:43], 0
	v_mfma_f32_16x16x32_bf16 v[36:39], v[20:23], v[44:47], v[36:39]
	v_mfma_f32_16x16x32_bf16 v[40:43], v[28:31], v[44:47], v[40:43]
	v_mfma_f32_16x16x32_bf16 v[44:47], v[16:19], v[48:51], 0
	v_mfma_f32_16x16x32_bf16 v[48:51], v[24:27], v[48:51], 0
	v_mfma_f32_16x16x32_bf16 v[44:47], v[20:23], v[52:55], v[44:47]
	v_mfma_f32_16x16x32_bf16 v[48:51], v[28:31], v[52:55], v[48:51]
	v_mfma_f32_16x16x32_bf16 v[52:55], v[16:19], v[56:59], 0
	v_mfma_f32_16x16x32_bf16 v[56:59], v[24:27], v[56:59], 0
	v_mfma_f32_16x16x32_bf16 v[52:55], v[20:23], v[60:63], v[52:55]
	v_mfma_f32_16x16x32_bf16 v[56:59], v[28:31], v[60:63], v[56:59]
	s_barrier
	s_add_i32 s63, s51, s15
	v_lshl_add_u64 v[242:243], s[72:73], 0, v[128:129]
	s_add_i32 s65, s63, 0x2000
	v_lshl_add_u64 v[148:149], v[242:243], 0, s[46:47]
	s_mov_b32 m0, s63
	v_lshl_add_u64 v[244:245], s[72:73], 0, v[130:131]
	s_add_u32 s76, s72, 0x80100
	ds_read_b128 v[60:63], v147 offset:16384
	ds_read_b128 v[88:91], v147 offset:17408
	ds_read_b128 v[92:95], v147 offset:18432
	ds_read_b128 v[104:107], v147 offset:19456
	ds_read_b128 v[108:111], v147 offset:20480
	ds_read_b128 v[116:119], v147 offset:21504
	ds_read_b128 v[120:123], v147 offset:22528
	ds_read_b128 v[124:127], v147 offset:23552
	global_load_lds_dwordx4 v[148:149], off
	v_lshl_add_u64 v[148:149], v[244:245], 0, s[46:47]
	s_mov_b32 m0, s65
	s_addc_u32 s77, s73, 0
	s_add_i32 s71, s52, s15
	global_load_lds_dwordx4 v[148:149], off
	v_lshl_add_u64 v[148:149], s[76:77], 0, v[128:129]
	s_mov_b32 m0, s71
	s_add_i32 s78, s71, 0x2000
	global_load_lds_dwordx4 v[148:149], off
	v_lshl_add_u64 v[148:149], s[76:77], 0, v[130:131]
	s_mov_b32 m0, s78
	v_lshl_add_u64 v[246:247], s[74:75], 0, v[134:135]
	global_load_lds_dwordx4 v[148:149], off
	v_lshl_add_u64 v[148:149], v[246:247], 0, s[46:47]
	s_mov_b32 m0, s22
	v_lshl_add_u64 v[248:249], s[74:75], 0, v[132:133]
	global_load_lds_dwordx4 v[148:149], off
	v_lshl_add_u64 v[148:149], v[248:249], 0, s[46:47]
	s_mov_b32 m0, s23
	s_nop 0
	global_load_lds_dwordx4 v[148:149], off
	s_waitcnt vmcnt(8) lgkmcnt(0)
	s_barrier
	v_mfma_f32_16x16x32_bf16 v[148:151], v[0:3], v[60:63], 0
	v_mfma_f32_16x16x32_bf16 v[158:161], v[0:3], v[92:95], 0
	v_mfma_f32_16x16x32_bf16 v[166:169], v[0:3], v[108:111], 0
	v_mfma_f32_16x16x32_bf16 v[0:3], v[0:3], v[120:123], 0
	v_mfma_f32_16x16x32_bf16 v[150:153], v[4:7], v[88:91], v[148:151]
	v_mfma_f32_16x16x32_bf16 v[158:161], v[4:7], v[104:107], v[158:161]
	v_mfma_f32_16x16x32_bf16 v[166:169], v[4:7], v[116:119], v[166:169]
	v_mfma_f32_16x16x32_bf16 v[0:3], v[4:7], v[124:127], v[0:3]
	v_mfma_f32_16x16x32_bf16 v[4:7], v[8:11], v[120:123], 0
	v_mfma_f32_16x16x32_bf16 v[154:157], v[8:11], v[60:63], 0
	v_mfma_f32_16x16x32_bf16 v[162:165], v[8:11], v[92:95], 0
	v_mfma_f32_16x16x32_bf16 v[170:173], v[8:11], v[108:111], 0
	v_mfma_f32_16x16x32_bf16 v[4:7], v[12:15], v[124:127], v[4:7]
	v_mfma_f32_16x16x32_bf16 v[154:157], v[12:15], v[88:91], v[154:157]
	v_mfma_f32_16x16x32_bf16 v[162:165], v[12:15], v[104:107], v[162:165]
	v_mfma_f32_16x16x32_bf16 v[170:173], v[12:15], v[116:119], v[170:173]
	v_mfma_f32_16x16x32_bf16 v[8:11], v[16:19], v[60:63], 0
	v_mfma_f32_16x16x32_bf16 v[174:177], v[20:23], v[88:91], v[8:11]
	v_mfma_f32_16x16x32_bf16 v[8:11], v[24:27], v[60:63], 0
	v_mfma_f32_16x16x32_bf16 v[60:63], v[28:31], v[88:91], v[8:11]
	v_mfma_f32_16x16x32_bf16 v[8:11], v[16:19], v[92:95], 0
	v_mfma_f32_16x16x32_bf16 v[178:181], v[20:23], v[104:107], v[8:11]
	v_mfma_f32_16x16x32_bf16 v[8:11], v[24:27], v[92:95], 0
	v_mfma_f32_16x16x32_bf16 v[182:185], v[28:31], v[104:107], v[8:11]
	v_mfma_f32_16x16x32_bf16 v[8:11], v[16:19], v[108:111], 0
	v_mfma_f32_16x16x32_bf16 v[186:189], v[20:23], v[116:119], v[8:11]
	v_mfma_f32_16x16x32_bf16 v[8:11], v[24:27], v[108:111], 0
	v_mfma_f32_16x16x32_bf16 v[190:193], v[28:31], v[116:119], v[8:11]
	v_mfma_f32_16x16x32_bf16 v[8:11], v[16:19], v[120:123], 0
	v_mfma_f32_16x16x32_bf16 v[194:197], v[20:23], v[124:127], v[8:11]
	v_mfma_f32_16x16x32_bf16 v[8:11], v[24:27], v[120:123], 0
	v_mfma_f32_16x16x32_bf16 v[198:201], v[28:31], v[124:127], v[8:11]
	s_barrier
	s_add_i32 s79, 0, 0x18000
	s_add_i32 s81, 0, 0x1c000
	v_add_u32_e32 v148, s79, v144
	v_add_u32_e32 v149, s81, v144
	s_nop 0
	ds_read_b128 v[8:11], v148
	ds_read_b128 v[12:15], v148 offset:1024
	ds_read_b128 v[16:19], v148 offset:2048
	ds_read_b128 v[20:23], v148 offset:3072
	ds_read_b128 v[202:205], v149
	ds_read_b128 v[206:209], v149 offset:1024
	ds_read_b128 v[210:213], v149 offset:2048
	ds_read_b128 v[214:217], v149 offset:3072
	s_add_u32 s76, s74, 0x80100
	s_addc_u32 s77, s75, 0
	s_mov_b32 m0, s36
	v_lshl_add_u64 v[88:89], s[76:77], 0, v[134:135]
	ds_read_b128 v[24:27], v147 offset:32768
	ds_read_b128 v[28:31], v147 offset:33792
	ds_read_b128 v[218:221], v147 offset:34816
	ds_read_b128 v[222:225], v147 offset:35840
	ds_read_b128 v[226:229], v147 offset:36864
	ds_read_b128 v[230:233], v147 offset:37888
	ds_read_b128 v[234:237], v147 offset:38912
	ds_read_b128 v[238:241], v147 offset:39936
	global_load_lds_dwordx4 v[88:89], off
	v_lshl_add_u64 v[88:89], s[76:77], 0, v[132:133]
	s_mov_b32 m0, s37
	s_nop 0
	global_load_lds_dwordx4 v[88:89], off
	s_waitcnt vmcnt(8) lgkmcnt(0)
	s_barrier
	v_mfma_f32_16x16x32_bf16 v[64:67], v[8:11], v[24:27], v[64:67]
	v_mfma_f32_16x16x32_bf16 v[120:123], v[12:15], v[28:31], v[64:67]
	v_mfma_f32_16x16x32_bf16 v[64:67], v[16:19], v[24:27], v[68:71]
	v_mfma_f32_16x16x32_bf16 v[124:127], v[20:23], v[28:31], v[64:67]
	v_mfma_f32_16x16x32_bf16 v[64:67], v[8:11], v[218:221], v[72:75]
	v_mfma_f32_16x16x32_bf16 v[104:107], v[12:15], v[222:225], v[64:67]
	v_mfma_f32_16x16x32_bf16 v[64:67], v[16:19], v[218:221], v[76:79]
	v_mfma_f32_16x16x32_bf16 v[108:111], v[20:23], v[222:225], v[64:67]
	v_mfma_f32_16x16x32_bf16 v[64:67], v[8:11], v[226:229], v[80:83]
	v_mfma_f32_16x16x32_bf16 v[88:91], v[12:15], v[230:233], v[64:67]
	v_mfma_f32_16x16x32_bf16 v[64:67], v[16:19], v[226:229], v[84:87]
	v_mfma_f32_16x16x32_bf16 v[92:95], v[20:23], v[230:233], v[64:67]
	v_mfma_f32_16x16x32_bf16 v[64:67], v[8:11], v[234:237], v[96:99]
	v_mfma_f32_16x16x32_bf16 v[68:71], v[16:19], v[234:237], v[100:103]
	v_mfma_f32_16x16x32_bf16 v[64:67], v[12:15], v[238:241], v[64:67]
	v_mfma_f32_16x16x32_bf16 v[68:71], v[20:23], v[238:241], v[68:71]
	v_mfma_f32_16x16x32_bf16 v[72:75], v[202:205], v[24:27], v[112:115]
	v_mfma_f32_16x16x32_bf16 v[24:27], v[210:213], v[24:27], v[32:35]
	v_mfma_f32_16x16x32_bf16 v[116:119], v[214:217], v[28:31], v[24:27]
	v_mfma_f32_16x16x32_bf16 v[24:27], v[202:205], v[218:221], v[36:39]
	v_mfma_f32_16x16x32_bf16 v[96:99], v[206:209], v[222:225], v[24:27]
	v_mfma_f32_16x16x32_bf16 v[24:27], v[210:213], v[218:221], v[40:43]
	v_mfma_f32_16x16x32_bf16 v[100:103], v[214:217], v[222:225], v[24:27]
	v_mfma_f32_16x16x32_bf16 v[24:27], v[202:205], v[226:229], v[44:47]
	v_mfma_f32_16x16x32_bf16 v[80:83], v[206:209], v[230:233], v[24:27]
	v_mfma_f32_16x16x32_bf16 v[24:27], v[210:213], v[226:229], v[48:51]
	v_mfma_f32_16x16x32_bf16 v[84:87], v[214:217], v[230:233], v[24:27]
	v_mfma_f32_16x16x32_bf16 v[24:27], v[202:205], v[234:237], v[52:55]
	v_mfma_f32_16x16x32_bf16 v[48:51], v[206:209], v[238:241], v[24:27]
	v_mfma_f32_16x16x32_bf16 v[24:27], v[210:213], v[234:237], v[56:59]
	v_mfma_f32_16x16x32_bf16 v[112:115], v[206:209], v[28:31], v[72:75]
	v_mfma_f32_16x16x32_bf16 v[52:55], v[214:217], v[238:241], v[24:27]
	s_barrier
; #define PG8_MMA(ai, bj, At, Bt) do { __builtin_amdgcn_s_setprio(1); _Pragma("unroll") for (int m = 0; m < 4; ++m) _Pragma("unroll") for (int n = 0; n < 2; ++n) _Pragma("unroll") for (int k = 0; k < 2; ++k) \
;         acc[ai][bj][m][n] = __builtin_amdgcn_mfma_f32_16x16x32_bf16(Bt[n][k], At[m][k], acc[ai][bj][m][n], 0, 0, 0); __builtin_amdgcn_s_setprio(0); } while (0)
; template <class Epi, class Sched, bool ALIGN_EPI = false, bool SP2 = false, bool A_TILED = false>
; __device__ __forceinline__ void gemm_phase(PG8_LAS unsigned char* lds, const Gemm g, const Sched& S, const Epi& E, const int wave_s) {
;     ...
;         for (int t = PEEL ? 2 : 0; t < nt; t += 2) {
;             const bool last = (t == nt - 2);
;             const char* a1 = cA + (size_t)(t + 1) * kstepA;
;             const char* a2 = last ? nA : cA + (size_t)(t + 2) * kstepA; const char* b2 = last ? nB : cB + (size_t)(t + 2) * kstep;
;             const char* a3 = a2 + kstepA; const char* b3 = b2 + kstep;
;             if (last && has_next) S.a_ready(nxt);
;             if constexpr (SP2) {
;             PG8_ITER(PG8_MMA)
	s_add_i32 s79, s79, s15
	s_add_i32 s80, s79, 0x2000
	s_nop 1
	v_lshl_add_u64 v[24:25], v[242:243], 0, s[60:61]
	s_mov_b32 m0, s79
	s_add_u32 s76, s72, 0x80180
	ds_read_b128 v[32:35], v147 offset:49152
	ds_read_b128 v[36:39], v147 offset:50176
	ds_read_b128 v[218:221], v147 offset:51200
	ds_read_b128 v[222:225], v147 offset:52224
	ds_read_b128 v[226:229], v147 offset:53248
	ds_read_b128 v[230:233], v147 offset:54272
	ds_read_b128 v[234:237], v147 offset:55296
	ds_read_b128 v[238:241], v147 offset:56320
	global_load_lds_dwordx4 v[24:25], off
	v_lshl_add_u64 v[24:25], v[244:245], 0, s[60:61]
	s_mov_b32 m0, s80
	s_addc_u32 s77, s73, 0
	s_add_i32 s81, s81, s15
	global_load_lds_dwordx4 v[24:25], off
	v_lshl_add_u64 v[24:25], s[76:77], 0, v[128:129]
	s_mov_b32 m0, s81
	s_add_i32 s82, s81, 0x2000
	global_load_lds_dwordx4 v[24:25], off
	v_lshl_add_u64 v[24:25], s[76:77], 0, v[130:131]
	s_mov_b32 m0, s82
	s_nop 0
	global_load_lds_dwordx4 v[24:25], off
	v_lshl_add_u64 v[24:25], v[246:247], 0, s[60:61]
	s_mov_b32 m0, s43
	s_nop 0
	global_load_lds_dwordx4 v[24:25], off
	v_lshl_add_u64 v[24:25], v[248:249], 0, s[60:61]
	s_mov_b32 m0, s48
	s_nop 0
	global_load_lds_dwordx4 v[24:25], off
	s_waitcnt vmcnt(8) lgkmcnt(0)
	s_barrier
	v_mfma_f32_16x16x32_bf16 v[24:27], v[8:11], v[32:35], v[150:153]
	v_mfma_f32_16x16x32_bf16 v[72:75], v[12:15], v[36:39], v[24:27]
	v_mfma_f32_16x16x32_bf16 v[24:27], v[16:19], v[32:35], v[154:157]
	v_mfma_f32_16x16x32_bf16 v[76:79], v[20:23], v[36:39], v[24:27]
	v_mfma_f32_16x16x32_bf16 v[24:27], v[8:11], v[218:221], v[158:161]
	v_mfma_f32_16x16x32_bf16 v[40:43], v[12:15], v[222:225], v[24:27]
	v_mfma_f32_16x16x32_bf16 v[24:27], v[16:19], v[218:221], v[162:165]
	v_mfma_f32_16x16x32_bf16 v[0:3], v[8:11], v[234:237], v[0:3]
	v_mfma_f32_16x16x32_bf16 v[44:47], v[20:23], v[222:225], v[24:27]
	v_mfma_f32_16x16x32_bf16 v[24:27], v[8:11], v[226:229], v[166:169]
	v_mfma_f32_16x16x32_bf16 v[28:31], v[16:19], v[226:229], v[170:173]
	v_mfma_f32_16x16x32_bf16 v[8:11], v[12:15], v[238:241], v[0:3]
	v_mfma_f32_16x16x32_bf16 v[0:3], v[16:19], v[234:237], v[4:7]
	v_mfma_f32_16x16x32_bf16 v[24:27], v[12:15], v[230:233], v[24:27]
	v_mfma_f32_16x16x32_bf16 v[28:31], v[20:23], v[230:233], v[28:31]
	v_mfma_f32_16x16x32_bf16 v[12:15], v[20:23], v[238:241], v[0:3]
	v_mfma_f32_16x16x32_bf16 v[0:3], v[202:205], v[32:35], v[174:177]
	v_mfma_f32_16x16x32_bf16 v[56:59], v[206:209], v[36:39], v[0:3]
	v_mfma_f32_16x16x32_bf16 v[0:3], v[210:213], v[32:35], v[60:63]
	v_mfma_f32_16x16x32_bf16 v[60:63], v[214:217], v[36:39], v[0:3]
	v_mfma_f32_16x16x32_bf16 v[0:3], v[202:205], v[218:221], v[178:181]
	v_mfma_f32_16x16x32_bf16 v[32:35], v[206:209], v[222:225], v[0:3]
	v_mfma_f32_16x16x32_bf16 v[0:3], v[210:213], v[218:221], v[182:185]
	v_mfma_f32_16x16x32_bf16 v[36:39], v[214:217], v[222:225], v[0:3]
	v_mfma_f32_16x16x32_bf16 v[0:3], v[202:205], v[226:229], v[186:189]
	v_mfma_f32_16x16x32_bf16 v[16:19], v[206:209], v[230:233], v[0:3]
	v_mfma_f32_16x16x32_bf16 v[0:3], v[210:213], v[226:229], v[190:193]
	v_mfma_f32_16x16x32_bf16 v[20:23], v[214:217], v[230:233], v[0:3]
	v_mfma_f32_16x16x32_bf16 v[0:3], v[202:205], v[234:237], v[194:197]
	v_mfma_f32_16x16x32_bf16 v[4:7], v[210:213], v[234:237], v[198:201]
	v_mfma_f32_16x16x32_bf16 v[0:3], v[206:209], v[238:241], v[0:3]
	v_mfma_f32_16x16x32_bf16 v[4:7], v[214:217], v[238:241], v[4:7]
	s_barrier
	s_add_u32 s83, s72, 0x200
	s_addc_u32 s85, s73, 0
	s_add_u32 s72, s74, 0x80180
	s_addc_u32 s73, s75, 0
	s_mov_b32 s88, 0
.LBB0_2841:
	ds_read_b128 v[150:153], v145
	ds_read_b128 v[154:157], v145 offset:1024
	ds_read_b128 v[158:161], v145 offset:2048
	ds_read_b128 v[162:165], v145 offset:3072
	ds_read_b128 v[166:169], v146
	ds_read_b128 v[170:173], v146 offset:1024
	ds_read_b128 v[174:177], v146 offset:2048
	ds_read_b128 v[178:181], v146 offset:3072
	s_add_u32 s74, s72, 0xfff80080
	s_addc_u32 s75, s73, -1
	s_cmp_eq_u32 s88, 28
	s_cselect_b32 s77, s54, s75
	s_cselect_b32 s76, s55, s74
	s_cselect_b32 s75, s56, s85
	s_cselect_b32 s74, s57, s83
	s_mov_b32 m0, s58
	v_lshl_add_u64 v[214:215], s[72:73], 0, v[138:139]
	ds_read_b128 v[182:185], v147
	ds_read_b128 v[186:189], v147 offset:1024
	ds_read_b128 v[190:193], v147 offset:2048
	ds_read_b128 v[194:197], v147 offset:3072
	ds_read_b128 v[198:201], v147 offset:4096
	ds_read_b128 v[202:205], v147 offset:5120
	ds_read_b128 v[206:209], v147 offset:6144
	ds_read_b128 v[210:213], v147 offset:7168
	global_load_lds_dwordx4 v[214:215], off
	v_lshl_add_u64 v[214:215], s[72:73], 0, v[136:137]
	s_mov_b32 m0, s59
	s_nop 0
	global_load_lds_dwordx4 v[214:215], off
	s_waitcnt vmcnt(8) lgkmcnt(0)
	s_barrier
	v_mfma_f32_16x16x32_bf16 v[120:123], v[150:153], v[182:185], v[120:123]
	v_mfma_f32_16x16x32_bf16 v[124:127], v[158:161], v[182:185], v[124:127]
	v_mfma_f32_16x16x32_bf16 v[104:107], v[150:153], v[190:193], v[104:107]
	v_mfma_f32_16x16x32_bf16 v[108:111], v[158:161], v[190:193], v[108:111]
	v_mfma_f32_16x16x32_bf16 v[88:91], v[150:153], v[198:201], v[88:91]
	v_mfma_f32_16x16x32_bf16 v[92:95], v[158:161], v[198:201], v[92:95]
	v_mfma_f32_16x16x32_bf16 v[64:67], v[150:153], v[206:209], v[64:67]
	v_mfma_f32_16x16x32_bf16 v[68:71], v[158:161], v[206:209], v[68:71]
	v_mfma_f32_16x16x32_bf16 v[120:123], v[154:157], v[186:189], v[120:123]
	v_mfma_f32_16x16x32_bf16 v[124:127], v[162:165], v[186:189], v[124:127]
	v_mfma_f32_16x16x32_bf16 v[104:107], v[154:157], v[194:197], v[104:107]
	v_mfma_f32_16x16x32_bf16 v[108:111], v[162:165], v[194:197], v[108:111]
	v_mfma_f32_16x16x32_bf16 v[88:91], v[154:157], v[202:205], v[88:91]
	v_mfma_f32_16x16x32_bf16 v[92:95], v[162:165], v[202:205], v[92:95]
	v_mfma_f32_16x16x32_bf16 v[64:67], v[154:157], v[210:213], v[64:67]
	v_mfma_f32_16x16x32_bf16 v[68:71], v[162:165], v[210:213], v[68:71]
	v_mfma_f32_16x16x32_bf16 v[112:115], v[166:169], v[182:185], v[112:115]
	v_mfma_f32_16x16x32_bf16 v[116:119], v[174:177], v[182:185], v[116:119]
	v_mfma_f32_16x16x32_bf16 v[96:99], v[166:169], v[190:193], v[96:99]
	v_mfma_f32_16x16x32_bf16 v[100:103], v[174:177], v[190:193], v[100:103]
	v_mfma_f32_16x16x32_bf16 v[80:83], v[166:169], v[198:201], v[80:83]
	v_mfma_f32_16x16x32_bf16 v[84:87], v[174:177], v[198:201], v[84:87]
	v_mfma_f32_16x16x32_bf16 v[48:51], v[166:169], v[206:209], v[48:51]
	v_mfma_f32_16x16x32_bf16 v[52:55], v[174:177], v[206:209], v[52:55]
	v_mfma_f32_16x16x32_bf16 v[112:115], v[170:173], v[186:189], v[112:115]
	v_mfma_f32_16x16x32_bf16 v[116:119], v[178:181], v[186:189], v[116:119]
	v_mfma_f32_16x16x32_bf16 v[96:99], v[170:173], v[194:197], v[96:99]
	v_mfma_f32_16x16x32_bf16 v[100:103], v[178:181], v[194:197], v[100:103]
	v_mfma_f32_16x16x32_bf16 v[80:83], v[170:173], v[202:205], v[80:83]
	v_mfma_f32_16x16x32_bf16 v[84:87], v[178:181], v[202:205], v[84:87]
	v_mfma_f32_16x16x32_bf16 v[48:51], v[170:173], v[210:213], v[48:51]
	v_mfma_f32_16x16x32_bf16 v[52:55], v[178:181], v[210:213], v[52:55]
	s_barrier
	s_mov_b32 m0, s63
	v_lshl_add_u64 v[214:215], s[74:75], 0, v[128:129]
	s_add_u32 s90, s74, 0x80000
	ds_read_b128 v[182:185], v147 offset:16384
	ds_read_b128 v[186:189], v147 offset:17408
	ds_read_b128 v[190:193], v147 offset:18432
	ds_read_b128 v[194:197], v147 offset:19456
	ds_read_b128 v[198:201], v147 offset:20480
	ds_read_b128 v[202:205], v147 offset:21504
	ds_read_b128 v[206:209], v147 offset:22528
	ds_read_b128 v[210:213], v147 offset:23552
	global_load_lds_dwordx4 v[214:215], off
	v_lshl_add_u64 v[216:217], s[74:75], 0, v[130:131]
	s_mov_b32 m0, s65
	s_addc_u32 s91, s75, 0
	global_load_lds_dwordx4 v[216:217], off
	v_lshl_add_u64 v[218:219], s[90:91], 0, v[128:129]
	s_mov_b32 m0, s71
	v_lshl_add_u64 v[220:221], s[76:77], 0, v[132:133]
	global_load_lds_dwordx4 v[218:219], off
	v_lshl_add_u64 v[218:219], s[90:91], 0, v[130:131]
	s_mov_b32 m0, s78
	s_nop 0
	global_load_lds_dwordx4 v[218:219], off
	v_lshl_add_u64 v[218:219], s[76:77], 0, v[134:135]
	s_mov_b32 m0, s22
	s_nop 0
	global_load_lds_dwordx4 v[218:219], off
	s_mov_b32 m0, s23
	s_nop 0
	global_load_lds_dwordx4 v[220:221], off
	s_waitcnt vmcnt(8) lgkmcnt(0)
	s_barrier
	v_mfma_f32_16x16x32_bf16 v[72:75], v[150:153], v[182:185], v[72:75]
	v_mfma_f32_16x16x32_bf16 v[76:79], v[158:161], v[182:185], v[76:79]
	v_mfma_f32_16x16x32_bf16 v[40:43], v[150:153], v[190:193], v[40:43]
	v_mfma_f32_16x16x32_bf16 v[44:47], v[158:161], v[190:193], v[44:47]
	v_mfma_f32_16x16x32_bf16 v[24:27], v[150:153], v[198:201], v[24:27]
	v_mfma_f32_16x16x32_bf16 v[28:31], v[158:161], v[198:201], v[28:31]
	v_mfma_f32_16x16x32_bf16 v[8:11], v[150:153], v[206:209], v[8:11]
	v_mfma_f32_16x16x32_bf16 v[12:15], v[158:161], v[206:209], v[12:15]
	v_mfma_f32_16x16x32_bf16 v[72:75], v[154:157], v[186:189], v[72:75]
	v_mfma_f32_16x16x32_bf16 v[76:79], v[162:165], v[186:189], v[76:79]
	v_mfma_f32_16x16x32_bf16 v[40:43], v[154:157], v[194:197], v[40:43]
	v_mfma_f32_16x16x32_bf16 v[44:47], v[162:165], v[194:197], v[44:47]
	v_mfma_f32_16x16x32_bf16 v[24:27], v[154:157], v[202:205], v[24:27]
	v_mfma_f32_16x16x32_bf16 v[28:31], v[162:165], v[202:205], v[28:31]
	v_mfma_f32_16x16x32_bf16 v[8:11], v[154:157], v[210:213], v[8:11]
	v_mfma_f32_16x16x32_bf16 v[12:15], v[162:165], v[210:213], v[12:15]
	v_mfma_f32_16x16x32_bf16 v[56:59], v[166:169], v[182:185], v[56:59]
	v_mfma_f32_16x16x32_bf16 v[60:63], v[174:177], v[182:185], v[60:63]
	v_mfma_f32_16x16x32_bf16 v[32:35], v[166:169], v[190:193], v[32:35]
	v_mfma_f32_16x16x32_bf16 v[36:39], v[174:177], v[190:193], v[36:39]
	v_mfma_f32_16x16x32_bf16 v[16:19], v[166:169], v[198:201], v[16:19]
	v_mfma_f32_16x16x32_bf16 v[20:23], v[174:177], v[198:201], v[20:23]
	v_mfma_f32_16x16x32_bf16 v[0:3], v[166:169], v[206:209], v[0:3]
	v_mfma_f32_16x16x32_bf16 v[4:7], v[174:177], v[206:209], v[4:7]
	v_mfma_f32_16x16x32_bf16 v[56:59], v[170:173], v[186:189], v[56:59]
	v_mfma_f32_16x16x32_bf16 v[60:63], v[178:181], v[186:189], v[60:63]
	v_mfma_f32_16x16x32_bf16 v[32:35], v[170:173], v[194:197], v[32:35]
	v_mfma_f32_16x16x32_bf16 v[36:39], v[178:181], v[194:197], v[36:39]
	v_mfma_f32_16x16x32_bf16 v[16:19], v[170:173], v[202:205], v[16:19]
	v_mfma_f32_16x16x32_bf16 v[20:23], v[178:181], v[202:205], v[20:23]
	v_mfma_f32_16x16x32_bf16 v[0:3], v[170:173], v[210:213], v[0:3]
	v_mfma_f32_16x16x32_bf16 v[4:7], v[178:181], v[210:213], v[4:7]
	s_barrier
; #define PG8_MMA(ai, bj, At, Bt) do { __builtin_amdgcn_s_setprio(1); _Pragma("unroll") for (int m = 0; m < 4; ++m) _Pragma("unroll") for (int n = 0; n < 2; ++n) _Pragma("unroll") for (int k = 0; k < 2; ++k) \
;         acc[ai][bj][m][n] = __builtin_amdgcn_mfma_f32_16x16x32_bf16(Bt[n][k], At[m][k], acc[ai][bj][m][n], 0, 0, 0); __builtin_amdgcn_s_setprio(0); } while (0)
; template <class Epi, class Sched, bool ALIGN_EPI = false, bool SP2 = false, bool A_TILED = false>
; __device__ __forceinline__ void gemm_phase(PG8_LAS unsigned char* lds, const Gemm g, const Sched& S, const Epi& E, const int wave_s) {
;     ...
;         for (int t = PEEL ? 2 : 0; t < nt; t += 2) {
;             const bool last = (t == nt - 2);
;             const char* a1 = cA + (size_t)(t + 1) * kstepA;
;             const char* a2 = last ? nA : cA + (size_t)(t + 2) * kstepA; const char* b2 = last ? nB : cB + (size_t)(t + 2) * kstep;
;             const char* a3 = a2 + kstepA; const char* b3 = b2 + kstep;
;             if (last && has_next) S.a_ready(nxt);
;             if constexpr (SP2) {
;             PG8_ITER(PG8_MMA)
	ds_read_b128 v[150:153], v148
	ds_read_b128 v[154:157], v148 offset:1024
	ds_read_b128 v[158:161], v148 offset:2048
	ds_read_b128 v[162:165], v148 offset:3072
	ds_read_b128 v[166:169], v149
	ds_read_b128 v[170:173], v149 offset:1024
	ds_read_b128 v[174:177], v149 offset:2048
	ds_read_b128 v[178:181], v149 offset:3072
	s_add_u32 s76, s76, 0x80000
	s_addc_u32 s77, s77, 0
	s_mov_b32 m0, s36
	v_lshl_add_u64 v[222:223], s[76:77], 0, v[134:135]
	ds_read_b128 v[182:185], v147 offset:32768
	ds_read_b128 v[186:189], v147 offset:33792
	ds_read_b128 v[190:193], v147 offset:34816
	ds_read_b128 v[194:197], v147 offset:35840
	ds_read_b128 v[198:201], v147 offset:36864
	ds_read_b128 v[202:205], v147 offset:37888
	ds_read_b128 v[206:209], v147 offset:38912
	ds_read_b128 v[210:213], v147 offset:39936
	global_load_lds_dwordx4 v[222:223], off
	v_lshl_add_u64 v[222:223], s[76:77], 0, v[132:133]
	s_mov_b32 m0, s37
	s_nop 0
	global_load_lds_dwordx4 v[222:223], off
	s_waitcnt vmcnt(8) lgkmcnt(0)
	s_barrier
	v_mfma_f32_16x16x32_bf16 v[120:123], v[150:153], v[182:185], v[120:123]
	v_mfma_f32_16x16x32_bf16 v[124:127], v[158:161], v[182:185], v[124:127]
	v_mfma_f32_16x16x32_bf16 v[104:107], v[150:153], v[190:193], v[104:107]
	v_mfma_f32_16x16x32_bf16 v[108:111], v[158:161], v[190:193], v[108:111]
	v_mfma_f32_16x16x32_bf16 v[88:91], v[150:153], v[198:201], v[88:91]
	v_mfma_f32_16x16x32_bf16 v[92:95], v[158:161], v[198:201], v[92:95]
	v_mfma_f32_16x16x32_bf16 v[64:67], v[150:153], v[206:209], v[64:67]
	v_mfma_f32_16x16x32_bf16 v[68:71], v[158:161], v[206:209], v[68:71]
	v_mfma_f32_16x16x32_bf16 v[120:123], v[154:157], v[186:189], v[120:123]
	v_mfma_f32_16x16x32_bf16 v[124:127], v[162:165], v[186:189], v[124:127]
	v_mfma_f32_16x16x32_bf16 v[104:107], v[154:157], v[194:197], v[104:107]
	v_mfma_f32_16x16x32_bf16 v[108:111], v[162:165], v[194:197], v[108:111]
	v_mfma_f32_16x16x32_bf16 v[88:91], v[154:157], v[202:205], v[88:91]
	v_mfma_f32_16x16x32_bf16 v[92:95], v[162:165], v[202:205], v[92:95]
	v_mfma_f32_16x16x32_bf16 v[64:67], v[154:157], v[210:213], v[64:67]
	v_mfma_f32_16x16x32_bf16 v[68:71], v[162:165], v[210:213], v[68:71]
	v_mfma_f32_16x16x32_bf16 v[112:115], v[166:169], v[182:185], v[112:115]
	v_mfma_f32_16x16x32_bf16 v[116:119], v[174:177], v[182:185], v[116:119]
	v_mfma_f32_16x16x32_bf16 v[96:99], v[166:169], v[190:193], v[96:99]
	v_mfma_f32_16x16x32_bf16 v[100:103], v[174:177], v[190:193], v[100:103]
	v_mfma_f32_16x16x32_bf16 v[80:83], v[166:169], v[198:201], v[80:83]
	v_mfma_f32_16x16x32_bf16 v[84:87], v[174:177], v[198:201], v[84:87]
	v_mfma_f32_16x16x32_bf16 v[48:51], v[166:169], v[206:209], v[48:51]
	v_mfma_f32_16x16x32_bf16 v[52:55], v[174:177], v[206:209], v[52:55]
	v_mfma_f32_16x16x32_bf16 v[112:115], v[170:173], v[186:189], v[112:115]
	v_mfma_f32_16x16x32_bf16 v[116:119], v[178:181], v[186:189], v[116:119]
	v_mfma_f32_16x16x32_bf16 v[96:99], v[170:173], v[194:197], v[96:99]
	v_mfma_f32_16x16x32_bf16 v[100:103], v[178:181], v[194:197], v[100:103]
	v_mfma_f32_16x16x32_bf16 v[80:83], v[170:173], v[202:205], v[80:83]
	v_mfma_f32_16x16x32_bf16 v[84:87], v[178:181], v[202:205], v[84:87]
	v_mfma_f32_16x16x32_bf16 v[48:51], v[170:173], v[210:213], v[48:51]
	v_mfma_f32_16x16x32_bf16 v[52:55], v[178:181], v[210:213], v[52:55]
	s_barrier
	s_mov_b32 m0, s79
	v_lshl_add_u64 v[214:215], v[214:215], 0, s[12:13]
	s_add_u32 s74, s74, 0x80080
	ds_read_b128 v[182:185], v147 offset:49152
	ds_read_b128 v[186:189], v147 offset:50176
	ds_read_b128 v[190:193], v147 offset:51200
	ds_read_b128 v[194:197], v147 offset:52224
	ds_read_b128 v[198:201], v147 offset:53248
	ds_read_b128 v[202:205], v147 offset:54272
	ds_read_b128 v[206:209], v147 offset:55296
	ds_read_b128 v[210:213], v147 offset:56320
	global_load_lds_dwordx4 v[214:215], off
	v_lshl_add_u64 v[214:215], v[216:217], 0, s[12:13]
	s_mov_b32 m0, s80
	s_addc_u32 s75, s75, 0
	global_load_lds_dwordx4 v[214:215], off
	v_lshl_add_u64 v[214:215], s[74:75], 0, v[128:129]
	s_mov_b32 m0, s81
	s_nop 0
	global_load_lds_dwordx4 v[214:215], off
	v_lshl_add_u64 v[214:215], s[74:75], 0, v[130:131]
	s_mov_b32 m0, s82
	s_nop 0
	global_load_lds_dwordx4 v[214:215], off
	v_lshl_add_u64 v[214:215], v[218:219], 0, s[12:13]
	s_mov_b32 m0, s43
	s_nop 0
	global_load_lds_dwordx4 v[214:215], off
	v_lshl_add_u64 v[214:215], v[220:221], 0, s[12:13]
	s_mov_b32 m0, s48
	s_nop 0
	global_load_lds_dwordx4 v[214:215], off
	s_waitcnt vmcnt(8) lgkmcnt(0)
	s_barrier
	v_mfma_f32_16x16x32_bf16 v[72:75], v[150:153], v[182:185], v[72:75]
	v_mfma_f32_16x16x32_bf16 v[76:79], v[158:161], v[182:185], v[76:79]
	v_mfma_f32_16x16x32_bf16 v[40:43], v[150:153], v[190:193], v[40:43]
	v_mfma_f32_16x16x32_bf16 v[44:47], v[158:161], v[190:193], v[44:47]
	v_mfma_f32_16x16x32_bf16 v[24:27], v[150:153], v[198:201], v[24:27]
	v_mfma_f32_16x16x32_bf16 v[28:31], v[158:161], v[198:201], v[28:31]
	v_mfma_f32_16x16x32_bf16 v[8:11], v[150:153], v[206:209], v[8:11]
	v_mfma_f32_16x16x32_bf16 v[12:15], v[158:161], v[206:209], v[12:15]
	v_mfma_f32_16x16x32_bf16 v[72:75], v[154:157], v[186:189], v[72:75]
	v_mfma_f32_16x16x32_bf16 v[76:79], v[162:165], v[186:189], v[76:79]
	v_mfma_f32_16x16x32_bf16 v[40:43], v[154:157], v[194:197], v[40:43]
	v_mfma_f32_16x16x32_bf16 v[44:47], v[162:165], v[194:197], v[44:47]
	v_mfma_f32_16x16x32_bf16 v[24:27], v[154:157], v[202:205], v[24:27]
	v_mfma_f32_16x16x32_bf16 v[28:31], v[162:165], v[202:205], v[28:31]
	v_mfma_f32_16x16x32_bf16 v[8:11], v[154:157], v[210:213], v[8:11]
	v_mfma_f32_16x16x32_bf16 v[12:15], v[162:165], v[210:213], v[12:15]
	v_mfma_f32_16x16x32_bf16 v[56:59], v[166:169], v[182:185], v[56:59]
	v_mfma_f32_16x16x32_bf16 v[60:63], v[174:177], v[182:185], v[60:63]
	v_mfma_f32_16x16x32_bf16 v[32:35], v[166:169], v[190:193], v[32:35]
	v_mfma_f32_16x16x32_bf16 v[36:39], v[174:177], v[190:193], v[36:39]
	v_mfma_f32_16x16x32_bf16 v[16:19], v[166:169], v[198:201], v[16:19]
	v_mfma_f32_16x16x32_bf16 v[20:23], v[174:177], v[198:201], v[20:23]
	v_mfma_f32_16x16x32_bf16 v[0:3], v[166:169], v[206:209], v[0:3]
	v_mfma_f32_16x16x32_bf16 v[4:7], v[174:177], v[206:209], v[4:7]
	v_mfma_f32_16x16x32_bf16 v[56:59], v[170:173], v[186:189], v[56:59]
	v_mfma_f32_16x16x32_bf16 v[60:63], v[178:181], v[186:189], v[60:63]
	v_mfma_f32_16x16x32_bf16 v[32:35], v[170:173], v[194:197], v[32:35]
	v_mfma_f32_16x16x32_bf16 v[36:39], v[178:181], v[194:197], v[36:39]
	v_mfma_f32_16x16x32_bf16 v[16:19], v[170:173], v[202:205], v[16:19]
	v_mfma_f32_16x16x32_bf16 v[20:23], v[178:181], v[202:205], v[20:23]
	v_mfma_f32_16x16x32_bf16 v[0:3], v[170:173], v[210:213], v[0:3]
	v_mfma_f32_16x16x32_bf16 v[4:7], v[178:181], v[210:213], v[4:7]
	s_barrier
	s_add_i32 s88, s88, 2
	s_add_u32 s83, s83, 0x100
	s_addc_u32 s85, s85, 0
	s_add_u32 s72, s72, 0x100
	s_addc_u32 s73, s73, 0
	s_cmp_gt_u32 s88, 29
	s_cbranch_scc0 .LBB0_2841
	s_and_b64 vcc, exec, s[44:45]
	s_cbranch_vccz .LBB0_2844
	s_barrier

; #define PG8_MMA(ai, bj, At, Bt) do { __builtin_amdgcn_s_setprio(1); _Pragma("unroll") for (int m = 0; m < 4; ++m) _Pragma("unroll") for (int n = 0; n < 2; ++n) _Pragma("unroll") for (int k = 0; k < 2; ++k) \
;         acc[ai][bj][m][n] = __builtin_amdgcn_mfma_f32_16x16x32_bf16(Bt[n][k], At[m][k], acc[ai][bj][m][n], 0, 0, 0); __builtin_amdgcn_s_setprio(0); } while (0)
; template <class Epi, class Sched, bool ALIGN_EPI = false, bool SP2 = false, bool A_TILED = false>
; __device__ __forceinline__ void gemm_phase(PG8_LAS unsigned char* lds, const Gemm g, const Sched& S, const Epi& E, const int wave_s) {
;     ...
;         for (int t = PEEL ? 2 : 0; t < nt; t += 2) {
;             const bool last = (t == nt - 2);
;             const char* a1 = cA + (size_t)(t + 1) * kstepA;
;             const char* a2 = last ? nA : cA + (size_t)(t + 2) * kstepA; const char* b2 = last ? nB : cB + (size_t)(t + 2) * kstep;
;             const char* a3 = a2 + kstepA; const char* b3 = b2 + kstep;
;             if (last && has_next) S.a_ready(nxt);
;             if constexpr (SP2) {
;             PG8_ITER(PG8_MMA)
.LBB0_2914:
	ds_read_b128 v[146:149], v140
	ds_read_b128 v[150:153], v140 offset:1024
	ds_read_b128 v[154:157], v140 offset:2048
	ds_read_b128 v[158:161], v140 offset:3072
	ds_read_b128 v[162:165], v141
	ds_read_b128 v[166:169], v141 offset:1024
	ds_read_b128 v[170:173], v141 offset:2048
	ds_read_b128 v[174:177], v141 offset:3072
	s_add_u32 s55, s44, s39
	s_addc_u32 s56, s45, s40
	s_add_u32 s57, s44, s37
	s_addc_u32 s58, s45, s38
	s_cmpk_eq_i32 s41, 0x7c
	s_cselect_b32 s68, s6, s55
	s_cselect_b32 s69, s7, s56
	s_cselect_b32 s66, s2, s57
	s_cselect_b32 s67, s3, s58
	s_add_u32 s64, s68, 0x8000
	s_addc_u32 s65, s69, 0
	s_mov_b32 m0, s42
	v_lshl_add_u64 v[210:211], s[44:45], 0, v[138:139]
	ds_read_b128 v[178:181], v142
	ds_read_b128 v[182:185], v142 offset:1024
	ds_read_b128 v[186:189], v142 offset:2048
	ds_read_b128 v[190:193], v142 offset:3072
	ds_read_b128 v[194:197], v142 offset:4096
	ds_read_b128 v[198:201], v142 offset:5120
	ds_read_b128 v[202:205], v142 offset:6144
	ds_read_b128 v[206:209], v142 offset:7168
	global_load_lds_dwordx4 v[210:211], off
	v_lshl_add_u64 v[210:211], s[44:45], 0, v[136:137]
	s_mov_b32 m0, s43
	s_nop 0
	global_load_lds_dwordx4 v[210:211], off
	s_waitcnt vmcnt(8) lgkmcnt(0)
	s_barrier
	v_mfma_f32_16x16x32_bf16 v[8:11], v[146:149], v[178:181], v[8:11]
	v_mfma_f32_16x16x32_bf16 v[12:15], v[154:157], v[178:181], v[12:15]
	v_mfma_f32_16x16x32_bf16 v[60:63], v[146:149], v[186:189], v[60:63]
	v_mfma_f32_16x16x32_bf16 v[20:23], v[154:157], v[186:189], v[20:23]
	v_mfma_f32_16x16x32_bf16 v[76:79], v[146:149], v[194:197], v[76:79]
	v_mfma_f32_16x16x32_bf16 v[52:55], v[154:157], v[194:197], v[52:55]
	v_mfma_f32_16x16x32_bf16 v[128:131], v[146:149], v[202:205], v[128:131]
	v_mfma_f32_16x16x32_bf16 v[68:71], v[154:157], v[202:205], v[68:71]
	v_mfma_f32_16x16x32_bf16 v[8:11], v[150:153], v[182:185], v[8:11]
	v_mfma_f32_16x16x32_bf16 v[12:15], v[158:161], v[182:185], v[12:15]
	v_mfma_f32_16x16x32_bf16 v[60:63], v[150:153], v[190:193], v[60:63]
	v_mfma_f32_16x16x32_bf16 v[20:23], v[158:161], v[190:193], v[20:23]
	v_mfma_f32_16x16x32_bf16 v[76:79], v[150:153], v[198:201], v[76:79]
	v_mfma_f32_16x16x32_bf16 v[52:55], v[158:161], v[198:201], v[52:55]
	v_mfma_f32_16x16x32_bf16 v[128:131], v[150:153], v[206:209], v[128:131]
	v_mfma_f32_16x16x32_bf16 v[68:71], v[158:161], v[206:209], v[68:71]
	v_mfma_f32_16x16x32_bf16 v[28:31], v[162:165], v[178:181], v[28:31]
	v_mfma_f32_16x16x32_bf16 v[16:19], v[170:173], v[178:181], v[16:19]
	v_mfma_f32_16x16x32_bf16 v[56:59], v[162:165], v[186:189], v[56:59]
	v_mfma_f32_16x16x32_bf16 v[48:51], v[170:173], v[186:189], v[48:51]
	v_mfma_f32_16x16x32_bf16 v[72:75], v[162:165], v[194:197], v[72:75]
	v_mfma_f32_16x16x32_bf16 v[64:67], v[170:173], v[194:197], v[64:67]
	v_mfma_f32_16x16x32_bf16 v[108:111], v[162:165], v[202:205], v[108:111]
	v_mfma_f32_16x16x32_bf16 v[96:99], v[170:173], v[202:205], v[96:99]
	v_mfma_f32_16x16x32_bf16 v[28:31], v[166:169], v[182:185], v[28:31]
	v_mfma_f32_16x16x32_bf16 v[16:19], v[174:177], v[182:185], v[16:19]
	v_mfma_f32_16x16x32_bf16 v[56:59], v[166:169], v[190:193], v[56:59]
	v_mfma_f32_16x16x32_bf16 v[48:51], v[174:177], v[190:193], v[48:51]
	v_mfma_f32_16x16x32_bf16 v[72:75], v[166:169], v[198:201], v[72:75]
	v_mfma_f32_16x16x32_bf16 v[64:67], v[174:177], v[198:201], v[64:67]
	v_mfma_f32_16x16x32_bf16 v[108:111], v[166:169], v[206:209], v[108:111]
	v_mfma_f32_16x16x32_bf16 v[96:99], v[174:177], v[206:209], v[96:99]
	s_barrier
	s_mov_b32 m0, s47
	v_lshl_add_u64 v[210:211], s[66:67], 0, v[34:35]
	s_add_u32 s56, s66, 0x200000
	ds_read_b128 v[178:181], v142 offset:16384
	ds_read_b128 v[182:185], v142 offset:17408
	ds_read_b128 v[186:189], v142 offset:18432
	ds_read_b128 v[190:193], v142 offset:19456
	ds_read_b128 v[194:197], v142 offset:20480
	ds_read_b128 v[198:201], v142 offset:21504
	ds_read_b128 v[202:205], v142 offset:22528
	ds_read_b128 v[206:209], v142 offset:23552
	global_load_lds_dwordx4 v[210:211], off
	v_lshl_add_u64 v[212:213], s[66:67], 0, v[134:135]
	s_mov_b32 m0, s48
	s_addc_u32 s57, s67, 0
	global_load_lds_dwordx4 v[212:213], off
	v_lshl_add_u64 v[214:215], s[56:57], 0, v[34:35]
	s_mov_b32 m0, s49
	s_nop 0
	global_load_lds_dwordx4 v[214:215], off
	v_lshl_add_u64 v[214:215], s[56:57], 0, v[134:135]
	s_mov_b32 m0, s50
	s_nop 0
	global_load_lds_dwordx4 v[214:215], off
	v_lshl_add_u64 v[214:215], s[68:69], 0, v[32:33]
	s_mov_b32 m0, s14
	s_nop 0
	global_load_lds_dwordx4 v[214:215], off
	v_lshl_add_u64 v[214:215], s[68:69], 0, v[132:133]
	s_mov_b32 m0, s15
	s_nop 0
	global_load_lds_dwordx4 v[214:215], off
	s_waitcnt vmcnt(8) lgkmcnt(0)
	s_barrier
	v_mfma_f32_16x16x32_bf16 v[100:103], v[146:149], v[178:181], v[100:103]
	v_mfma_f32_16x16x32_bf16 v[104:107], v[154:157], v[178:181], v[104:107]
	v_mfma_f32_16x16x32_bf16 v[116:119], v[146:149], v[186:189], v[116:119]
	v_mfma_f32_16x16x32_bf16 v[120:123], v[154:157], v[186:189], v[120:123]
	v_mfma_f32_16x16x32_bf16 v[84:87], v[146:149], v[194:197], v[84:87]
	v_mfma_f32_16x16x32_bf16 v[80:83], v[154:157], v[194:197], v[80:83]
	v_mfma_f32_16x16x32_bf16 v[36:39], v[146:149], v[202:205], v[36:39]
	v_mfma_f32_16x16x32_bf16 v[24:27], v[154:157], v[202:205], v[24:27]
	v_mfma_f32_16x16x32_bf16 v[100:103], v[150:153], v[182:185], v[100:103]
	v_mfma_f32_16x16x32_bf16 v[104:107], v[158:161], v[182:185], v[104:107]
	v_mfma_f32_16x16x32_bf16 v[116:119], v[150:153], v[190:193], v[116:119]
	v_mfma_f32_16x16x32_bf16 v[120:123], v[158:161], v[190:193], v[120:123]
	v_mfma_f32_16x16x32_bf16 v[84:87], v[150:153], v[198:201], v[84:87]
	v_mfma_f32_16x16x32_bf16 v[80:83], v[158:161], v[198:201], v[80:83]
	v_mfma_f32_16x16x32_bf16 v[36:39], v[150:153], v[206:209], v[36:39]
	v_mfma_f32_16x16x32_bf16 v[24:27], v[158:161], v[206:209], v[24:27]
	v_mfma_f32_16x16x32_bf16 v[124:127], v[162:165], v[178:181], v[124:127]
	v_mfma_f32_16x16x32_bf16 v[112:115], v[170:173], v[178:181], v[112:115]
	v_mfma_f32_16x16x32_bf16 v[92:95], v[162:165], v[186:189], v[92:95]
	v_mfma_f32_16x16x32_bf16 v[88:91], v[170:173], v[186:189], v[88:91]
	v_mfma_f32_16x16x32_bf16 v[44:47], v[162:165], v[194:197], v[44:47]
	v_mfma_f32_16x16x32_bf16 v[40:43], v[170:173], v[194:197], v[40:43]
	v_mfma_f32_16x16x32_bf16 v[4:7], v[162:165], v[202:205], v[4:7]
	v_mfma_f32_16x16x32_bf16 v[0:3], v[170:173], v[202:205], v[0:3]
	v_mfma_f32_16x16x32_bf16 v[124:127], v[166:169], v[182:185], v[124:127]
	v_mfma_f32_16x16x32_bf16 v[112:115], v[174:177], v[182:185], v[112:115]
	v_mfma_f32_16x16x32_bf16 v[92:95], v[166:169], v[190:193], v[92:95]
	v_mfma_f32_16x16x32_bf16 v[88:91], v[174:177], v[190:193], v[88:91]
	v_mfma_f32_16x16x32_bf16 v[44:47], v[166:169], v[198:201], v[44:47]
	v_mfma_f32_16x16x32_bf16 v[40:43], v[174:177], v[198:201], v[40:43]
	v_mfma_f32_16x16x32_bf16 v[4:7], v[166:169], v[206:209], v[4:7]
	v_mfma_f32_16x16x32_bf16 v[0:3], v[174:177], v[206:209], v[0:3]
	s_barrier
	ds_read_b128 v[146:149], v143
	ds_read_b128 v[150:153], v143 offset:1024
	ds_read_b128 v[154:157], v143 offset:2048
	ds_read_b128 v[158:161], v143 offset:3072
	ds_read_b128 v[162:165], v144
	ds_read_b128 v[166:169], v144 offset:1024
	ds_read_b128 v[170:173], v144 offset:2048
	ds_read_b128 v[174:177], v144 offset:3072
	s_add_u32 s56, s68, 0x4000
	s_addc_u32 s57, s69, 0
	s_mov_b32 m0, s21
	v_lshl_add_u64 v[214:215], s[56:57], 0, v[32:33]
	ds_read_b128 v[178:181], v142 offset:32768
	ds_read_b128 v[182:185], v142 offset:33792
	ds_read_b128 v[186:189], v142 offset:34816
	ds_read_b128 v[190:193], v142 offset:35840
	ds_read_b128 v[194:197], v142 offset:36864
	ds_read_b128 v[198:201], v142 offset:37888
	ds_read_b128 v[202:205], v142 offset:38912
	ds_read_b128 v[206:209], v142 offset:39936
	global_load_lds_dwordx4 v[214:215], off
	v_lshl_add_u64 v[214:215], s[56:57], 0, v[132:133]
	s_mov_b32 m0, s22
	s_nop 0
	global_load_lds_dwordx4 v[214:215], off
	s_waitcnt vmcnt(8) lgkmcnt(0)
	s_barrier
	v_mfma_f32_16x16x32_bf16 v[8:11], v[146:149], v[178:181], v[8:11]
	v_mfma_f32_16x16x32_bf16 v[12:15], v[154:157], v[178:181], v[12:15]
	v_mfma_f32_16x16x32_bf16 v[60:63], v[146:149], v[186:189], v[60:63]
	v_mfma_f32_16x16x32_bf16 v[20:23], v[154:157], v[186:189], v[20:23]
	v_mfma_f32_16x16x32_bf16 v[76:79], v[146:149], v[194:197], v[76:79]
	v_mfma_f32_16x16x32_bf16 v[52:55], v[154:157], v[194:197], v[52:55]
	v_mfma_f32_16x16x32_bf16 v[128:131], v[146:149], v[202:205], v[128:131]
	v_mfma_f32_16x16x32_bf16 v[68:71], v[154:157], v[202:205], v[68:71]
	v_mfma_f32_16x16x32_bf16 v[8:11], v[150:153], v[182:185], v[8:11]
	v_mfma_f32_16x16x32_bf16 v[12:15], v[158:161], v[182:185], v[12:15]
	v_mfma_f32_16x16x32_bf16 v[60:63], v[150:153], v[190:193], v[60:63]
	v_mfma_f32_16x16x32_bf16 v[20:23], v[158:161], v[190:193], v[20:23]
	v_mfma_f32_16x16x32_bf16 v[76:79], v[150:153], v[198:201], v[76:79]
	v_mfma_f32_16x16x32_bf16 v[52:55], v[158:161], v[198:201], v[52:55]
	v_mfma_f32_16x16x32_bf16 v[128:131], v[150:153], v[206:209], v[128:131]
	v_mfma_f32_16x16x32_bf16 v[68:71], v[158:161], v[206:209], v[68:71]
	v_mfma_f32_16x16x32_bf16 v[28:31], v[162:165], v[178:181], v[28:31]
	v_mfma_f32_16x16x32_bf16 v[16:19], v[170:173], v[178:181], v[16:19]
	v_mfma_f32_16x16x32_bf16 v[56:59], v[162:165], v[186:189], v[56:59]
	v_mfma_f32_16x16x32_bf16 v[48:51], v[170:173], v[186:189], v[48:51]
	v_mfma_f32_16x16x32_bf16 v[72:75], v[162:165], v[194:197], v[72:75]
	v_mfma_f32_16x16x32_bf16 v[64:67], v[170:173], v[194:197], v[64:67]
	v_mfma_f32_16x16x32_bf16 v[108:111], v[162:165], v[202:205], v[108:111]
	v_mfma_f32_16x16x32_bf16 v[96:99], v[170:173], v[202:205], v[96:99]
	v_mfma_f32_16x16x32_bf16 v[28:31], v[166:169], v[182:185], v[28:31]
	v_mfma_f32_16x16x32_bf16 v[16:19], v[174:177], v[182:185], v[16:19]
	v_mfma_f32_16x16x32_bf16 v[56:59], v[166:169], v[190:193], v[56:59]
	v_mfma_f32_16x16x32_bf16 v[48:51], v[174:177], v[190:193], v[48:51]
	v_mfma_f32_16x16x32_bf16 v[72:75], v[166:169], v[198:201], v[72:75]
	v_mfma_f32_16x16x32_bf16 v[64:67], v[174:177], v[198:201], v[64:67]
	v_mfma_f32_16x16x32_bf16 v[108:111], v[166:169], v[206:209], v[108:111]
	v_mfma_f32_16x16x32_bf16 v[96:99], v[174:177], v[206:209], v[96:99]
	s_barrier
; template <class Epi, class Sched, bool ALIGN_EPI = false, bool SP2 = false, bool A_TILED = false>
; __device__ __forceinline__ void gemm_phase(PG8_LAS unsigned char* lds, const Gemm g, const Sched& S, const Epi& E, const int wave_s) {
;     ...
;         for (int t = PEEL ? 2 : 0; t < nt; t += 2) {
;             const bool last = (t == nt - 2);
;             const char* a1 = cA + (size_t)(t + 1) * kstepA;
;             const char* a2 = last ? nA : cA + (size_t)(t + 2) * kstepA; const char* b2 = last ? nB : cB + (size_t)(t + 2) * kstep;
;             const char* a3 = a2 + kstepA; const char* b3 = b2 + kstep;
;             if (last && has_next) S.a_ready(nxt);
;             if constexpr (SP2) {
;             PG8_ITER(PG8_MMA)
;             } else {
;             PG8_LDB(B0, 0, 0); PG8_SCHED; PG8_LDA(At, 0, 0); PG8_STAGE(PG8_SA(1, 1), a1 + hstepA, voffA);
;             PG8_WAIT_L(8); PG8_BAR; PG8_WAIT_L(0); PG8_MMA(0, 0, At, B0); PG8_BAR; PG8_SCHED;
;             PG8_LDB(B1, 0, 1); PG8_STAGE(PG8_SB(0, 0), b2, voffB);
;             PG8_BAR; PG8_WAIT_L(0); PG8_MMA(0, 1, At, B1); PG8_BAR;
;             PG8_LDA(At, 0, 1); PG8_STAGE(PG8_SA(0, 0), a2, voffA);
;             PG8_BAR; PG8_WAIT_L(0); PG8_MMA(1, 0, At, B0); PG8_BAR; PG8_SCHED;
;             PG8_STAGE(PG8_SB(0, 1), b2 + hstep, voffB);
;             PG8_WAIT_V(6); PG8_BAR; PG8_MMA(1, 1, At, B1); PG8_BAR;
;             PG8_LDB(B0, 1, 0); PG8_SCHED; PG8_LDA(At, 1, 0); PG8_STAGE(PG8_SA(0, 1), a2 + hstepA, voffA);
;             PG8_WAIT_L(8); PG8_BAR; PG8_WAIT_L(0); PG8_MMA(0, 0, At, B0); PG8_BAR; PG8_SCHED;
;             PG8_LDB(B1, 1, 1); PG8_STAGE(PG8_SB(1, 0), b3, voffB);
;             PG8_BAR; PG8_WAIT_L(0); PG8_MMA(0, 1, At, B1); PG8_BAR;
;             PG8_LDA(At, 1, 1); PG8_STAGE(PG8_SA(1, 0), a3, voffA);
;             PG8_BAR; PG8_WAIT_L(0); PG8_MMA(1, 0, At, B0); PG8_BAR; PG8_SCHED;
;             PG8_STAGE(PG8_SB(1, 1), b3 + hstep, voffB);
;             PG8_WAIT_V(6); PG8_BAR; PG8_MMA(1, 1, At, B1); PG8_BAR;
;             }
;         }
;         if constexpr (ALIGN_EPI) { if (wr == 0) PG8_BAR; }
;         if constexpr (!Epi::AFTER_DRAIN) { int te = tid_now(wave_s); asm volatile("" : "+v"(te));
;             E(acc, cur, wr, wc, te & 15, (te & 63) >> 4); S.done(cur); }
;         if (!has_next) break;
;         cur = nxt; cA = nA; cB = nB; ++ui;
;         if constexpr (ALIGN_EPI) { if (wr == 1) PG8_BAR; }
	s_mov_b32 m0, s51
	v_lshl_add_u64 v[210:211], v[210:211], 0, s[60:61]
	s_add_u32 s56, s66, 0x200080
	ds_read_b128 v[178:181], v142 offset:49152
	ds_read_b128 v[182:185], v142 offset:50176
	ds_read_b128 v[186:189], v142 offset:51200
	ds_read_b128 v[190:193], v142 offset:52224
	ds_read_b128 v[194:197], v142 offset:53248
	ds_read_b128 v[198:201], v142 offset:54272
	ds_read_b128 v[202:205], v142 offset:55296
	ds_read_b128 v[206:209], v142 offset:56320
	global_load_lds_dwordx4 v[210:211], off
	v_lshl_add_u64 v[210:211], v[212:213], 0, s[60:61]
	s_mov_b32 m0, s52
	s_addc_u32 s57, s67, 0
	global_load_lds_dwordx4 v[210:211], off
	v_lshl_add_u64 v[210:211], s[56:57], 0, v[34:35]
	s_mov_b32 m0, s53
	s_nop 0
	global_load_lds_dwordx4 v[210:211], off
	v_lshl_add_u64 v[210:211], s[56:57], 0, v[134:135]
	s_mov_b32 m0, s54
	s_nop 0
	global_load_lds_dwordx4 v[210:211], off
	v_lshl_add_u64 v[210:211], s[64:65], 0, v[32:33]
	s_mov_b32 m0, s23
	s_nop 0
	global_load_lds_dwordx4 v[210:211], off
	v_lshl_add_u64 v[210:211], s[64:65], 0, v[132:133]
	s_mov_b32 m0, s36
	s_nop 0
	global_load_lds_dwordx4 v[210:211], off
	s_waitcnt vmcnt(8) lgkmcnt(0)
	s_barrier
	v_mfma_f32_16x16x32_bf16 v[100:103], v[146:149], v[178:181], v[100:103]
	v_mfma_f32_16x16x32_bf16 v[104:107], v[154:157], v[178:181], v[104:107]
	v_mfma_f32_16x16x32_bf16 v[116:119], v[146:149], v[186:189], v[116:119]
	v_mfma_f32_16x16x32_bf16 v[120:123], v[154:157], v[186:189], v[120:123]
	v_mfma_f32_16x16x32_bf16 v[84:87], v[146:149], v[194:197], v[84:87]
	v_mfma_f32_16x16x32_bf16 v[80:83], v[154:157], v[194:197], v[80:83]
	v_mfma_f32_16x16x32_bf16 v[36:39], v[146:149], v[202:205], v[36:39]
	v_mfma_f32_16x16x32_bf16 v[24:27], v[154:157], v[202:205], v[24:27]
	v_mfma_f32_16x16x32_bf16 v[100:103], v[150:153], v[182:185], v[100:103]
	v_mfma_f32_16x16x32_bf16 v[104:107], v[158:161], v[182:185], v[104:107]
	v_mfma_f32_16x16x32_bf16 v[116:119], v[150:153], v[190:193], v[116:119]
	v_mfma_f32_16x16x32_bf16 v[120:123], v[158:161], v[190:193], v[120:123]
	v_mfma_f32_16x16x32_bf16 v[84:87], v[150:153], v[198:201], v[84:87]
	v_mfma_f32_16x16x32_bf16 v[80:83], v[158:161], v[198:201], v[80:83]
	v_mfma_f32_16x16x32_bf16 v[36:39], v[150:153], v[206:209], v[36:39]
	v_mfma_f32_16x16x32_bf16 v[24:27], v[158:161], v[206:209], v[24:27]
	v_mfma_f32_16x16x32_bf16 v[124:127], v[162:165], v[178:181], v[124:127]
	v_mfma_f32_16x16x32_bf16 v[112:115], v[170:173], v[178:181], v[112:115]
	v_mfma_f32_16x16x32_bf16 v[92:95], v[162:165], v[186:189], v[92:95]
	v_mfma_f32_16x16x32_bf16 v[88:91], v[170:173], v[186:189], v[88:91]
	v_mfma_f32_16x16x32_bf16 v[44:47], v[162:165], v[194:197], v[44:47]
	v_mfma_f32_16x16x32_bf16 v[40:43], v[170:173], v[194:197], v[40:43]
	v_mfma_f32_16x16x32_bf16 v[4:7], v[162:165], v[202:205], v[4:7]
	v_mfma_f32_16x16x32_bf16 v[0:3], v[170:173], v[202:205], v[0:3]
	v_mfma_f32_16x16x32_bf16 v[124:127], v[166:169], v[182:185], v[124:127]
	v_mfma_f32_16x16x32_bf16 v[112:115], v[174:177], v[182:185], v[112:115]
	v_mfma_f32_16x16x32_bf16 v[92:95], v[166:169], v[190:193], v[92:95]
	v_mfma_f32_16x16x32_bf16 v[88:91], v[174:177], v[190:193], v[88:91]
	v_mfma_f32_16x16x32_bf16 v[44:47], v[166:169], v[198:201], v[44:47]
	v_mfma_f32_16x16x32_bf16 v[40:43], v[174:177], v[198:201], v[40:43]
	v_mfma_f32_16x16x32_bf16 v[4:7], v[166:169], v[206:209], v[4:7]
	v_mfma_f32_16x16x32_bf16 v[0:3], v[174:177], v[206:209], v[0:3]
	s_barrier
	s_add_i32 s41, s41, 2
	s_add_u32 s37, s37, 0x100
	s_addc_u32 s38, s38, 0
	s_add_u32 s39, s39, 0x10000
	s_addc_u32 s40, s40, 0
	v_lshl_add_u64 v[136:137], v[136:137], 0, s[62:63]
	s_cmpk_gt_u32 s41, 0x7d
	v_lshl_add_u64 v[138:139], v[138:139], 0, s[62:63]
	s_cbranch_scc0 .LBB0_2914
	s_waitcnt vmcnt(0)
	s_cmpk_lt_u32 s0, 0x100
	s_cbranch_scc0 .LBB0_2917
	s_barrier

; template <class Epi, class Sched, bool ALIGN_EPI = false, bool SP2 = false, bool A_TILED = false>
; __device__ __forceinline__ void gemm_phase(PG8_LAS unsigned char* lds, const Gemm g, const Sched& S, const Epi& E, const int wave_s) {
;     ...
;         const char* nA = has_next ? (const char*)g.A + (size_t)nxt.pm * tstepA : cA; const char* nB = has_next ? (const char*)g.Bt + (size_t)nxt.pn * tstep : cB;
;         constexpr bool PEEL = SP2 && !Epi::AFTER_DRAIN;
;         if constexpr (PEEL) {
;             const char* a1 = cA + kstepA; const char* a2 = cA + 2 * kstepA; const char* b2 = cB + 2 * kstep; const char* a3 = a2 + kstepA; const char* b3 = b2 + kstep;
;             PG8_ITER(PG8_MMAZ)
.LBB0_3341:
	s_ashr_i32 s25, s24, 31
	ds_read_b128 v[0:3], v149
	ds_read_b128 v[4:7], v149 offset:1024
	ds_read_b128 v[8:11], v149 offset:2048
	ds_read_b128 v[12:15], v149 offset:3072
	ds_read_b128 v[16:19], v150
	ds_read_b128 v[20:23], v150 offset:1024
	ds_read_b128 v[24:27], v150 offset:2048
	ds_read_b128 v[28:31], v150 offset:3072
	s_lshl_b64 s[26:27], s[24:25], 20
	s_add_u32 s26, s9, s26
	s_addc_u32 s27, s36, s27
	s_and_b64 s[38:39], s[0:1], exec
	s_cselect_b32 s25, s27, s45
	s_cselect_b32 s67, s26, s44
	s_ashr_i32 s23, s22, 31
	s_lshl_b64 s[38:39], s[22:23], 20
	s_add_u32 s38, s37, s38
	s_addc_u32 s39, s48, s39
	s_and_b64 s[46:47], s[0:1], exec
	s_cselect_b32 s23, s39, s43
	s_cselect_b32 s68, s38, s42
	s_add_u32 s46, s44, 0x80080
	s_addc_u32 s47, s45, 0
	s_mov_b32 m0, s64
	v_lshl_add_u64 v[64:65], s[46:47], 0, v[134:135]
	ds_read_b128 v[32:35], v151
	ds_read_b128 v[36:39], v151 offset:1024
	ds_read_b128 v[40:43], v151 offset:2048
	ds_read_b128 v[44:47], v151 offset:3072
	ds_read_b128 v[48:51], v151 offset:4096
	ds_read_b128 v[52:55], v151 offset:5120
	ds_read_b128 v[56:59], v151 offset:6144
	ds_read_b128 v[60:63], v151 offset:7168
	global_load_lds_dwordx4 v[64:65], off
	v_lshl_add_u64 v[64:65], s[46:47], 0, v[132:133]
	s_mov_b32 m0, s65
	s_nop 0
	global_load_lds_dwordx4 v[64:65], off
	s_waitcnt vmcnt(8) lgkmcnt(0)
	s_barrier
	v_mfma_f32_16x16x32_bf16 v[88:91], v[0:3], v[56:59], 0
	v_mfma_f32_16x16x32_bf16 v[64:67], v[0:3], v[32:35], 0
	v_mfma_f32_16x16x32_bf16 v[68:71], v[8:11], v[32:35], 0
	v_mfma_f32_16x16x32_bf16 v[72:75], v[0:3], v[40:43], 0
	v_mfma_f32_16x16x32_bf16 v[76:79], v[8:11], v[40:43], 0
	v_mfma_f32_16x16x32_bf16 v[80:83], v[0:3], v[48:51], 0
	v_mfma_f32_16x16x32_bf16 v[84:87], v[8:11], v[48:51], 0
	v_mfma_f32_16x16x32_bf16 v[92:95], v[4:7], v[60:63], v[88:91]
	v_mfma_f32_16x16x32_bf16 v[88:91], v[8:11], v[56:59], 0
	v_mfma_f32_16x16x32_bf16 v[64:67], v[4:7], v[36:39], v[64:67]
	v_mfma_f32_16x16x32_bf16 v[68:71], v[12:15], v[36:39], v[68:71]
	v_mfma_f32_16x16x32_bf16 v[72:75], v[4:7], v[44:47], v[72:75]
	v_mfma_f32_16x16x32_bf16 v[76:79], v[12:15], v[44:47], v[76:79]
	v_mfma_f32_16x16x32_bf16 v[80:83], v[4:7], v[52:55], v[80:83]
	v_mfma_f32_16x16x32_bf16 v[84:87], v[12:15], v[52:55], v[84:87]
	v_mfma_f32_16x16x32_bf16 v[100:103], v[12:15], v[60:63], v[88:91]
	v_mfma_f32_16x16x32_bf16 v[88:91], v[16:19], v[32:35], 0
	v_mfma_f32_16x16x32_bf16 v[32:35], v[24:27], v[32:35], 0
	v_mfma_f32_16x16x32_bf16 v[108:111], v[20:23], v[36:39], v[88:91]
	v_mfma_f32_16x16x32_bf16 v[32:35], v[28:31], v[36:39], v[32:35]
	v_mfma_f32_16x16x32_bf16 v[36:39], v[16:19], v[40:43], 0
	v_mfma_f32_16x16x32_bf16 v[40:43], v[24:27], v[40:43], 0
	v_mfma_f32_16x16x32_bf16 v[36:39], v[20:23], v[44:47], v[36:39]
	v_mfma_f32_16x16x32_bf16 v[40:43], v[28:31], v[44:47], v[40:43]
	v_mfma_f32_16x16x32_bf16 v[44:47], v[16:19], v[48:51], 0
	v_mfma_f32_16x16x32_bf16 v[48:51], v[24:27], v[48:51], 0
	v_mfma_f32_16x16x32_bf16 v[44:47], v[20:23], v[52:55], v[44:47]
	v_mfma_f32_16x16x32_bf16 v[52:55], v[28:31], v[52:55], v[48:51]
	v_mfma_f32_16x16x32_bf16 v[48:51], v[16:19], v[56:59], 0
	v_mfma_f32_16x16x32_bf16 v[152:155], v[20:23], v[60:63], v[48:51]
	v_mfma_f32_16x16x32_bf16 v[48:51], v[24:27], v[56:59], 0
	v_mfma_f32_16x16x32_bf16 v[156:159], v[28:31], v[60:63], v[48:51]
	s_barrier
	s_add_i32 s69, s61, s49
	v_lshl_add_u64 v[146:147], s[42:43], 0, v[128:129]
	s_add_i32 s70, s69, 0x2000
	v_lshl_add_u64 v[120:121], v[146:147], 0, s[20:21]
	s_mov_b32 m0, s69
	v_lshl_add_u64 v[252:253], s[42:43], 0, v[130:131]
	s_add_u32 s46, s42, 0x80100
	ds_read_b128 v[48:51], v151 offset:16384
	ds_read_b128 v[56:59], v151 offset:17408
	ds_read_b128 v[60:63], v151 offset:18432
	ds_read_b128 v[88:91], v151 offset:19456
	ds_read_b128 v[96:99], v151 offset:20480
	ds_read_b128 v[104:107], v151 offset:21504
	ds_read_b128 v[112:115], v151 offset:22528
	ds_read_b128 v[116:119], v151 offset:23552
	global_load_lds_dwordx4 v[120:121], off
	v_lshl_add_u64 v[120:121], v[252:253], 0, s[20:21]
	s_mov_b32 m0, s70
	s_addc_u32 s47, s43, 0
	s_add_i32 s71, s62, s49
	global_load_lds_dwordx4 v[120:121], off
	v_lshl_add_u64 v[120:121], s[46:47], 0, v[128:129]
	s_mov_b32 m0, s71
	s_add_i32 s72, s71, 0x2000
	global_load_lds_dwordx4 v[120:121], off
	v_lshl_add_u64 v[120:121], s[46:47], 0, v[130:131]
	s_mov_b32 m0, s72
	v_lshl_add_u64 v[140:141], s[44:45], 0, v[134:135]
	global_load_lds_dwordx4 v[120:121], off
	v_lshl_add_u64 v[120:121], v[140:141], 0, s[20:21]
	s_mov_b32 m0, s41
	v_lshl_add_u64 v[142:143], s[44:45], 0, v[132:133]
	global_load_lds_dwordx4 v[120:121], off
	v_lshl_add_u64 v[120:121], v[142:143], 0, s[20:21]
	s_mov_b32 m0, s52
	s_nop 0
	global_load_lds_dwordx4 v[120:121], off
	s_waitcnt vmcnt(8) lgkmcnt(0)
	s_barrier
	v_mfma_f32_16x16x32_bf16 v[120:123], v[0:3], v[48:51], 0
	v_mfma_f32_16x16x32_bf16 v[160:163], v[4:7], v[56:59], v[120:123]
	v_mfma_f32_16x16x32_bf16 v[120:123], v[8:11], v[48:51], 0
	v_mfma_f32_16x16x32_bf16 v[164:167], v[12:15], v[56:59], v[120:123]
	v_mfma_f32_16x16x32_bf16 v[120:123], v[0:3], v[60:63], 0
	v_mfma_f32_16x16x32_bf16 v[168:171], v[4:7], v[88:91], v[120:123]
	v_mfma_f32_16x16x32_bf16 v[120:123], v[8:11], v[60:63], 0
	v_mfma_f32_16x16x32_bf16 v[172:175], v[12:15], v[88:91], v[120:123]
	v_mfma_f32_16x16x32_bf16 v[120:123], v[0:3], v[96:99], 0
	v_mfma_f32_16x16x32_bf16 v[0:3], v[0:3], v[112:115], 0
	v_mfma_f32_16x16x32_bf16 v[176:179], v[4:7], v[104:107], v[120:123]
	v_mfma_f32_16x16x32_bf16 v[0:3], v[4:7], v[116:119], v[0:3]
	v_mfma_f32_16x16x32_bf16 v[4:7], v[8:11], v[112:115], 0
	v_mfma_f32_16x16x32_bf16 v[120:123], v[8:11], v[96:99], 0
	v_mfma_f32_16x16x32_bf16 v[4:7], v[12:15], v[116:119], v[4:7]
	v_mfma_f32_16x16x32_bf16 v[180:183], v[12:15], v[104:107], v[120:123]
	v_mfma_f32_16x16x32_bf16 v[8:11], v[16:19], v[48:51], 0
	v_mfma_f32_16x16x32_bf16 v[12:15], v[20:23], v[56:59], v[8:11]
	v_mfma_f32_16x16x32_bf16 v[8:11], v[24:27], v[48:51], 0
	v_mfma_f32_16x16x32_bf16 v[184:187], v[28:31], v[56:59], v[8:11]
	v_mfma_f32_16x16x32_bf16 v[8:11], v[16:19], v[60:63], 0
	v_mfma_f32_16x16x32_bf16 v[188:191], v[20:23], v[88:91], v[8:11]
	v_mfma_f32_16x16x32_bf16 v[8:11], v[24:27], v[60:63], 0
	v_mfma_f32_16x16x32_bf16 v[192:195], v[28:31], v[88:91], v[8:11]
	v_mfma_f32_16x16x32_bf16 v[8:11], v[16:19], v[96:99], 0
	v_mfma_f32_16x16x32_bf16 v[196:199], v[20:23], v[104:107], v[8:11]
	v_mfma_f32_16x16x32_bf16 v[8:11], v[24:27], v[96:99], 0
	v_mfma_f32_16x16x32_bf16 v[200:203], v[28:31], v[104:107], v[8:11]
	v_mfma_f32_16x16x32_bf16 v[8:11], v[16:19], v[112:115], 0
	v_mfma_f32_16x16x32_bf16 v[204:207], v[20:23], v[116:119], v[8:11]
	v_mfma_f32_16x16x32_bf16 v[8:11], v[24:27], v[112:115], 0
	v_mfma_f32_16x16x32_bf16 v[208:211], v[28:31], v[116:119], v[8:11]
	s_barrier
	s_add_i32 s73, 0, 0x18000
	s_add_i32 s75, 0, 0x1c000
	v_add_u32_e32 v144, s73, v148
	v_add_u32_e32 v145, s75, v148
	s_nop 0
	ds_read_b128 v[8:11], v144
	ds_read_b128 v[20:23], v144 offset:1024
	ds_read_b128 v[28:31], v144 offset:2048
	ds_read_b128 v[212:215], v144 offset:3072
	ds_read_b128 v[216:219], v145
	ds_read_b128 v[220:223], v145 offset:1024
	ds_read_b128 v[224:227], v145 offset:2048
	ds_read_b128 v[228:231], v145 offset:3072
	s_add_u32 s46, s44, 0x80100
	s_addc_u32 s47, s45, 0
	s_mov_b32 m0, s53
	v_lshl_add_u64 v[48:49], s[46:47], 0, v[134:135]
	ds_read_b128 v[16:19], v151 offset:32768
	ds_read_b128 v[24:27], v151 offset:33792
	ds_read_b128 v[60:63], v151 offset:34816
	ds_read_b128 v[232:235], v151 offset:35840
	ds_read_b128 v[236:239], v151 offset:36864
	ds_read_b128 v[240:243], v151 offset:37888
	ds_read_b128 v[244:247], v151 offset:38912
	ds_read_b128 v[248:251], v151 offset:39936
	global_load_lds_dwordx4 v[48:49], off
	v_lshl_add_u64 v[48:49], s[46:47], 0, v[132:133]
	s_mov_b32 m0, s54
	s_nop 0
	global_load_lds_dwordx4 v[48:49], off
	s_waitcnt vmcnt(8) lgkmcnt(0)
	s_barrier
	v_mfma_f32_16x16x32_bf16 v[48:51], v[8:11], v[16:19], v[64:67]
	v_mfma_f32_16x16x32_bf16 v[120:123], v[20:23], v[24:27], v[48:51]
	v_mfma_f32_16x16x32_bf16 v[48:51], v[28:31], v[16:19], v[68:71]
	v_mfma_f32_16x16x32_bf16 v[112:115], v[212:215], v[24:27], v[48:51]
	v_mfma_f32_16x16x32_bf16 v[48:51], v[8:11], v[60:63], v[72:75]
	v_mfma_f32_16x16x32_bf16 v[104:107], v[20:23], v[232:235], v[48:51]
	v_mfma_f32_16x16x32_bf16 v[48:51], v[28:31], v[60:63], v[76:79]
	v_mfma_f32_16x16x32_bf16 v[96:99], v[212:215], v[232:235], v[48:51]
	v_mfma_f32_16x16x32_bf16 v[48:51], v[8:11], v[236:239], v[80:83]
	v_mfma_f32_16x16x32_bf16 v[88:91], v[20:23], v[240:243], v[48:51]
	v_mfma_f32_16x16x32_bf16 v[48:51], v[28:31], v[236:239], v[84:87]
	v_mfma_f32_16x16x32_bf16 v[80:83], v[212:215], v[240:243], v[48:51]
	v_mfma_f32_16x16x32_bf16 v[48:51], v[8:11], v[244:247], v[92:95]
	v_mfma_f32_16x16x32_bf16 v[56:59], v[20:23], v[248:251], v[48:51]
	v_mfma_f32_16x16x32_bf16 v[48:51], v[28:31], v[244:247], v[100:103]
	v_mfma_f32_16x16x32_bf16 v[48:51], v[212:215], v[248:251], v[48:51]
	v_mfma_f32_16x16x32_bf16 v[64:67], v[216:219], v[16:19], v[108:111]
	v_mfma_f32_16x16x32_bf16 v[16:19], v[224:227], v[16:19], v[32:35]
	v_mfma_f32_16x16x32_bf16 v[116:119], v[228:231], v[24:27], v[16:19]
	v_mfma_f32_16x16x32_bf16 v[16:19], v[216:219], v[60:63], v[36:39]
	v_mfma_f32_16x16x32_bf16 v[108:111], v[220:223], v[232:235], v[16:19]
	v_mfma_f32_16x16x32_bf16 v[16:19], v[224:227], v[60:63], v[40:43]
	v_mfma_f32_16x16x32_bf16 v[100:103], v[228:231], v[232:235], v[16:19]
	v_mfma_f32_16x16x32_bf16 v[16:19], v[216:219], v[236:239], v[44:47]
	v_mfma_f32_16x16x32_bf16 v[92:95], v[220:223], v[240:243], v[16:19]
	v_mfma_f32_16x16x32_bf16 v[16:19], v[224:227], v[236:239], v[52:55]
	v_mfma_f32_16x16x32_bf16 v[84:87], v[228:231], v[240:243], v[16:19]
	v_mfma_f32_16x16x32_bf16 v[16:19], v[216:219], v[244:247], v[152:155]
	v_mfma_f32_16x16x32_bf16 v[60:63], v[220:223], v[248:251], v[16:19]
	v_mfma_f32_16x16x32_bf16 v[16:19], v[224:227], v[244:247], v[156:159]
	v_mfma_f32_16x16x32_bf16 v[124:127], v[220:223], v[24:27], v[64:67]
	v_mfma_f32_16x16x32_bf16 v[52:55], v[228:231], v[248:251], v[16:19]
	s_barrier
; template <class Epi, class Sched, bool ALIGN_EPI = false, bool SP2 = false, bool A_TILED = false>
; __device__ __forceinline__ void gemm_phase(PG8_LAS unsigned char* lds, const Gemm g, const Sched& S, const Epi& E, const int wave_s) {
;     ...
;         for (int t = PEEL ? 2 : 0; t < nt; t += 2) {
;             const bool last = (t == nt - 2);
;             const char* a1 = cA + (size_t)(t + 1) * kstepA;
;             const char* a2 = last ? nA : cA + (size_t)(t + 2) * kstepA; const char* b2 = last ? nB : cB + (size_t)(t + 2) * kstep;
;             const char* a3 = a2 + kstepA; const char* b3 = b2 + kstep;
	s_add_i32 s73, s73, s49
	s_add_i32 s74, s73, 0x2000
	s_nop 1
	v_lshl_add_u64 v[16:17], v[146:147], 0, s[16:17]
	s_mov_b32 m0, s73
	s_add_u32 s46, s42, 0x80180
	ds_read_b128 v[36:39], v151 offset:49152
	ds_read_b128 v[44:47], v151 offset:50176
	ds_read_b128 v[152:155], v151 offset:51200
	ds_read_b128 v[156:159], v151 offset:52224
	ds_read_b128 v[232:235], v151 offset:53248
	ds_read_b128 v[236:239], v151 offset:54272
	ds_read_b128 v[240:243], v151 offset:55296
	ds_read_b128 v[244:247], v151 offset:56320
	global_load_lds_dwordx4 v[16:17], off
	v_lshl_add_u64 v[16:17], v[252:253], 0, s[16:17]
	s_mov_b32 m0, s74
	s_addc_u32 s47, s43, 0
	s_add_i32 s75, s75, s49
	global_load_lds_dwordx4 v[16:17], off
	v_lshl_add_u64 v[16:17], s[46:47], 0, v[128:129]
	s_mov_b32 m0, s75
	s_add_i32 s76, s75, 0x2000
	global_load_lds_dwordx4 v[16:17], off
	v_lshl_add_u64 v[16:17], s[46:47], 0, v[130:131]
	s_mov_b32 m0, s76
	s_nop 0
	global_load_lds_dwordx4 v[16:17], off
	v_lshl_add_u64 v[16:17], v[140:141], 0, s[16:17]
	s_mov_b32 m0, s59
	s_nop 0
	global_load_lds_dwordx4 v[16:17], off
	v_lshl_add_u64 v[16:17], v[142:143], 0, s[16:17]
	s_mov_b32 m0, s60
	s_nop 0
	global_load_lds_dwordx4 v[16:17], off
	s_waitcnt vmcnt(8) lgkmcnt(0)
	s_barrier
	v_mfma_f32_16x16x32_bf16 v[16:19], v[8:11], v[36:39], v[160:163]
	v_mfma_f32_16x16x32_bf16 v[72:75], v[20:23], v[44:47], v[16:19]
	v_mfma_f32_16x16x32_bf16 v[16:19], v[28:31], v[36:39], v[164:167]
	v_mfma_f32_16x16x32_bf16 v[64:67], v[212:215], v[44:47], v[16:19]
	v_mfma_f32_16x16x32_bf16 v[16:19], v[8:11], v[152:155], v[168:171]
	v_mfma_f32_16x16x32_bf16 v[40:43], v[20:23], v[156:159], v[16:19]
	v_mfma_f32_16x16x32_bf16 v[16:19], v[28:31], v[152:155], v[172:175]
	v_mfma_f32_16x16x32_bf16 v[32:35], v[212:215], v[156:159], v[16:19]
	v_mfma_f32_16x16x32_bf16 v[16:19], v[8:11], v[232:235], v[176:179]
	v_mfma_f32_16x16x32_bf16 v[0:3], v[8:11], v[240:243], v[0:3]
	v_mfma_f32_16x16x32_bf16 v[24:27], v[20:23], v[236:239], v[16:19]
	v_mfma_f32_16x16x32_bf16 v[16:19], v[28:31], v[232:235], v[180:183]
	v_mfma_f32_16x16x32_bf16 v[8:11], v[20:23], v[244:247], v[0:3]
	v_mfma_f32_16x16x32_bf16 v[0:3], v[28:31], v[240:243], v[4:7]
	v_mfma_f32_16x16x32_bf16 v[16:19], v[212:215], v[236:239], v[16:19]
	v_mfma_f32_16x16x32_bf16 v[0:3], v[212:215], v[244:247], v[0:3]
	v_mfma_f32_16x16x32_bf16 v[4:7], v[216:219], v[36:39], v[12:15]
	v_mfma_f32_16x16x32_bf16 v[76:79], v[220:223], v[44:47], v[4:7]
	v_mfma_f32_16x16x32_bf16 v[4:7], v[224:227], v[36:39], v[184:187]
	v_mfma_f32_16x16x32_bf16 v[68:71], v[228:231], v[44:47], v[4:7]
	v_mfma_f32_16x16x32_bf16 v[4:7], v[216:219], v[152:155], v[188:191]
	v_mfma_f32_16x16x32_bf16 v[44:47], v[220:223], v[156:159], v[4:7]
	v_mfma_f32_16x16x32_bf16 v[4:7], v[224:227], v[152:155], v[192:195]
	v_mfma_f32_16x16x32_bf16 v[36:39], v[228:231], v[156:159], v[4:7]
	v_mfma_f32_16x16x32_bf16 v[4:7], v[216:219], v[232:235], v[196:199]
	v_mfma_f32_16x16x32_bf16 v[28:31], v[220:223], v[236:239], v[4:7]
	v_mfma_f32_16x16x32_bf16 v[4:7], v[224:227], v[232:235], v[200:203]
	v_mfma_f32_16x16x32_bf16 v[20:23], v[228:231], v[236:239], v[4:7]
	v_mfma_f32_16x16x32_bf16 v[4:7], v[216:219], v[240:243], v[204:207]
	v_mfma_f32_16x16x32_bf16 v[12:15], v[220:223], v[244:247], v[4:7]
	v_mfma_f32_16x16x32_bf16 v[4:7], v[224:227], v[240:243], v[208:211]
	v_mfma_f32_16x16x32_bf16 v[4:7], v[228:231], v[244:247], v[4:7]
	s_barrier
	s_add_u32 s77, s42, 0x200
	s_addc_u32 s78, s43, 0
	s_add_u32 s42, s44, 0x80180
	s_addc_u32 s43, s45, 0
	s_mov_b32 s79, 0
.LBB0_3342:
	ds_read_b128 v[152:155], v149
	ds_read_b128 v[156:159], v149 offset:1024
	ds_read_b128 v[160:163], v149 offset:2048
	ds_read_b128 v[164:167], v149 offset:3072
	ds_read_b128 v[168:171], v150
	ds_read_b128 v[172:175], v150 offset:1024
	ds_read_b128 v[176:179], v150 offset:2048
	ds_read_b128 v[180:183], v150 offset:3072
	s_add_u32 s44, s42, 0xfff80080
	s_addc_u32 s45, s43, -1
	s_cmp_eq_u32 s79, 28
	s_cselect_b32 s47, s25, s45
	s_cselect_b32 s46, s67, s44
	s_cselect_b32 s45, s23, s78
	s_cselect_b32 s44, s68, s77
	s_mov_b32 m0, s64
	v_lshl_add_u64 v[140:141], s[42:43], 0, v[138:139]
	ds_read_b128 v[184:187], v151
	ds_read_b128 v[188:191], v151 offset:1024
	ds_read_b128 v[192:195], v151 offset:2048
	ds_read_b128 v[196:199], v151 offset:3072
	ds_read_b128 v[200:203], v151 offset:4096
	ds_read_b128 v[204:207], v151 offset:5120
	ds_read_b128 v[208:211], v151 offset:6144
	ds_read_b128 v[212:215], v151 offset:7168
	global_load_lds_dwordx4 v[140:141], off
	v_lshl_add_u64 v[140:141], s[42:43], 0, v[136:137]
	s_mov_b32 m0, s65
	s_nop 0
	global_load_lds_dwordx4 v[140:141], off
	s_waitcnt vmcnt(8) lgkmcnt(0)
	s_barrier
	v_mfma_f32_16x16x32_bf16 v[120:123], v[152:155], v[184:187], v[120:123]
	v_mfma_f32_16x16x32_bf16 v[112:115], v[160:163], v[184:187], v[112:115]
	v_mfma_f32_16x16x32_bf16 v[104:107], v[152:155], v[192:195], v[104:107]
	v_mfma_f32_16x16x32_bf16 v[96:99], v[160:163], v[192:195], v[96:99]
	v_mfma_f32_16x16x32_bf16 v[88:91], v[152:155], v[200:203], v[88:91]
	v_mfma_f32_16x16x32_bf16 v[80:83], v[160:163], v[200:203], v[80:83]
	v_mfma_f32_16x16x32_bf16 v[56:59], v[152:155], v[208:211], v[56:59]
	v_mfma_f32_16x16x32_bf16 v[48:51], v[160:163], v[208:211], v[48:51]
	v_mfma_f32_16x16x32_bf16 v[120:123], v[156:159], v[188:191], v[120:123]
	v_mfma_f32_16x16x32_bf16 v[112:115], v[164:167], v[188:191], v[112:115]
	v_mfma_f32_16x16x32_bf16 v[104:107], v[156:159], v[196:199], v[104:107]
	v_mfma_f32_16x16x32_bf16 v[96:99], v[164:167], v[196:199], v[96:99]
	v_mfma_f32_16x16x32_bf16 v[88:91], v[156:159], v[204:207], v[88:91]
	v_mfma_f32_16x16x32_bf16 v[80:83], v[164:167], v[204:207], v[80:83]
	v_mfma_f32_16x16x32_bf16 v[56:59], v[156:159], v[212:215], v[56:59]
	v_mfma_f32_16x16x32_bf16 v[48:51], v[164:167], v[212:215], v[48:51]
	v_mfma_f32_16x16x32_bf16 v[124:127], v[168:171], v[184:187], v[124:127]
	v_mfma_f32_16x16x32_bf16 v[116:119], v[176:179], v[184:187], v[116:119]
	v_mfma_f32_16x16x32_bf16 v[108:111], v[168:171], v[192:195], v[108:111]
	v_mfma_f32_16x16x32_bf16 v[100:103], v[176:179], v[192:195], v[100:103]
	v_mfma_f32_16x16x32_bf16 v[92:95], v[168:171], v[200:203], v[92:95]
	v_mfma_f32_16x16x32_bf16 v[84:87], v[176:179], v[200:203], v[84:87]
	v_mfma_f32_16x16x32_bf16 v[60:63], v[168:171], v[208:211], v[60:63]
	v_mfma_f32_16x16x32_bf16 v[52:55], v[176:179], v[208:211], v[52:55]
	v_mfma_f32_16x16x32_bf16 v[124:127], v[172:175], v[188:191], v[124:127]
	v_mfma_f32_16x16x32_bf16 v[116:119], v[180:183], v[188:191], v[116:119]
	v_mfma_f32_16x16x32_bf16 v[108:111], v[172:175], v[196:199], v[108:111]
	v_mfma_f32_16x16x32_bf16 v[100:103], v[180:183], v[196:199], v[100:103]
	v_mfma_f32_16x16x32_bf16 v[92:95], v[172:175], v[204:207], v[92:95]
	v_mfma_f32_16x16x32_bf16 v[84:87], v[180:183], v[204:207], v[84:87]
	v_mfma_f32_16x16x32_bf16 v[60:63], v[172:175], v[212:215], v[60:63]
	v_mfma_f32_16x16x32_bf16 v[52:55], v[180:183], v[212:215], v[52:55]
	s_barrier
	s_mov_b32 m0, s69
	v_lshl_add_u64 v[140:141], s[44:45], 0, v[128:129]
	s_add_u32 s80, s44, 0x80000
	ds_read_b128 v[184:187], v151 offset:16384
	ds_read_b128 v[188:191], v151 offset:17408
	ds_read_b128 v[192:195], v151 offset:18432
	ds_read_b128 v[196:199], v151 offset:19456
	ds_read_b128 v[200:203], v151 offset:20480
	ds_read_b128 v[204:207], v151 offset:21504
	ds_read_b128 v[208:211], v151 offset:22528
	ds_read_b128 v[212:215], v151 offset:23552
	global_load_lds_dwordx4 v[140:141], off
	v_lshl_add_u64 v[142:143], s[44:45], 0, v[130:131]
	s_mov_b32 m0, s70
	s_addc_u32 s81, s45, 0
	global_load_lds_dwordx4 v[142:143], off
	v_lshl_add_u64 v[146:147], s[80:81], 0, v[128:129]
	s_mov_b32 m0, s71
	v_lshl_add_u64 v[216:217], s[46:47], 0, v[132:133]
	global_load_lds_dwordx4 v[146:147], off
	v_lshl_add_u64 v[146:147], s[80:81], 0, v[130:131]
	s_mov_b32 m0, s72
	s_nop 0
	global_load_lds_dwordx4 v[146:147], off
	v_lshl_add_u64 v[146:147], s[46:47], 0, v[134:135]
	s_mov_b32 m0, s41
	s_nop 0
	global_load_lds_dwordx4 v[146:147], off
	s_mov_b32 m0, s52
	s_nop 0
	global_load_lds_dwordx4 v[216:217], off
	s_waitcnt vmcnt(8) lgkmcnt(0)
	s_barrier
	v_mfma_f32_16x16x32_bf16 v[72:75], v[152:155], v[184:187], v[72:75]
	v_mfma_f32_16x16x32_bf16 v[64:67], v[160:163], v[184:187], v[64:67]
	v_mfma_f32_16x16x32_bf16 v[40:43], v[152:155], v[192:195], v[40:43]
	v_mfma_f32_16x16x32_bf16 v[32:35], v[160:163], v[192:195], v[32:35]
	v_mfma_f32_16x16x32_bf16 v[24:27], v[152:155], v[200:203], v[24:27]
	v_mfma_f32_16x16x32_bf16 v[16:19], v[160:163], v[200:203], v[16:19]
	v_mfma_f32_16x16x32_bf16 v[8:11], v[152:155], v[208:211], v[8:11]
	v_mfma_f32_16x16x32_bf16 v[0:3], v[160:163], v[208:211], v[0:3]
	v_mfma_f32_16x16x32_bf16 v[72:75], v[156:159], v[188:191], v[72:75]
	v_mfma_f32_16x16x32_bf16 v[64:67], v[164:167], v[188:191], v[64:67]
	v_mfma_f32_16x16x32_bf16 v[40:43], v[156:159], v[196:199], v[40:43]
	v_mfma_f32_16x16x32_bf16 v[32:35], v[164:167], v[196:199], v[32:35]
	v_mfma_f32_16x16x32_bf16 v[24:27], v[156:159], v[204:207], v[24:27]
	v_mfma_f32_16x16x32_bf16 v[16:19], v[164:167], v[204:207], v[16:19]
	v_mfma_f32_16x16x32_bf16 v[8:11], v[156:159], v[212:215], v[8:11]
	v_mfma_f32_16x16x32_bf16 v[0:3], v[164:167], v[212:215], v[0:3]
	v_mfma_f32_16x16x32_bf16 v[76:79], v[168:171], v[184:187], v[76:79]
	v_mfma_f32_16x16x32_bf16 v[68:71], v[176:179], v[184:187], v[68:71]
	v_mfma_f32_16x16x32_bf16 v[44:47], v[168:171], v[192:195], v[44:47]
	v_mfma_f32_16x16x32_bf16 v[36:39], v[176:179], v[192:195], v[36:39]
	v_mfma_f32_16x16x32_bf16 v[28:31], v[168:171], v[200:203], v[28:31]
	v_mfma_f32_16x16x32_bf16 v[20:23], v[176:179], v[200:203], v[20:23]
	v_mfma_f32_16x16x32_bf16 v[12:15], v[168:171], v[208:211], v[12:15]
	v_mfma_f32_16x16x32_bf16 v[4:7], v[176:179], v[208:211], v[4:7]
	v_mfma_f32_16x16x32_bf16 v[76:79], v[172:175], v[188:191], v[76:79]
	v_mfma_f32_16x16x32_bf16 v[68:71], v[180:183], v[188:191], v[68:71]
	v_mfma_f32_16x16x32_bf16 v[44:47], v[172:175], v[196:199], v[44:47]
	v_mfma_f32_16x16x32_bf16 v[36:39], v[180:183], v[196:199], v[36:39]
	v_mfma_f32_16x16x32_bf16 v[28:31], v[172:175], v[204:207], v[28:31]
	v_mfma_f32_16x16x32_bf16 v[20:23], v[180:183], v[204:207], v[20:23]
	v_mfma_f32_16x16x32_bf16 v[12:15], v[172:175], v[212:215], v[12:15]
	v_mfma_f32_16x16x32_bf16 v[4:7], v[180:183], v[212:215], v[4:7]
	s_barrier
; template <class Epi, class Sched, bool ALIGN_EPI = false, bool SP2 = false, bool A_TILED = false>
; __device__ __forceinline__ void gemm_phase(PG8_LAS unsigned char* lds, const Gemm g, const Sched& S, const Epi& E, const int wave_s) {
;     ...
;         for (int t = PEEL ? 2 : 0; t < nt; t += 2) {
;             const bool last = (t == nt - 2);
;             const char* a1 = cA + (size_t)(t + 1) * kstepA;
;             const char* a2 = last ? nA : cA + (size_t)(t + 2) * kstepA; const char* b2 = last ? nB : cB + (size_t)(t + 2) * kstep;
;             const char* a3 = a2 + kstepA; const char* b3 = b2 + kstep;
	ds_read_b128 v[152:155], v144
	ds_read_b128 v[156:159], v144 offset:1024
	ds_read_b128 v[160:163], v144 offset:2048
	ds_read_b128 v[164:167], v144 offset:3072
	ds_read_b128 v[168:171], v145
	ds_read_b128 v[172:175], v145 offset:1024
	ds_read_b128 v[176:179], v145 offset:2048
	ds_read_b128 v[180:183], v145 offset:3072
	s_add_u32 s46, s46, 0x80000
	s_addc_u32 s47, s47, 0
	s_mov_b32 m0, s53
	v_lshl_add_u64 v[218:219], s[46:47], 0, v[134:135]
	ds_read_b128 v[184:187], v151 offset:32768
	ds_read_b128 v[188:191], v151 offset:33792
	ds_read_b128 v[192:195], v151 offset:34816
	ds_read_b128 v[196:199], v151 offset:35840
	ds_read_b128 v[200:203], v151 offset:36864
	ds_read_b128 v[204:207], v151 offset:37888
	ds_read_b128 v[208:211], v151 offset:38912
	ds_read_b128 v[212:215], v151 offset:39936
	global_load_lds_dwordx4 v[218:219], off
	v_lshl_add_u64 v[218:219], s[46:47], 0, v[132:133]
	s_mov_b32 m0, s54
	s_nop 0
	global_load_lds_dwordx4 v[218:219], off
	s_waitcnt vmcnt(8) lgkmcnt(0)
	s_barrier
	v_mfma_f32_16x16x32_bf16 v[120:123], v[152:155], v[184:187], v[120:123]
	v_mfma_f32_16x16x32_bf16 v[112:115], v[160:163], v[184:187], v[112:115]
	v_mfma_f32_16x16x32_bf16 v[104:107], v[152:155], v[192:195], v[104:107]
	v_mfma_f32_16x16x32_bf16 v[96:99], v[160:163], v[192:195], v[96:99]
	v_mfma_f32_16x16x32_bf16 v[88:91], v[152:155], v[200:203], v[88:91]
	v_mfma_f32_16x16x32_bf16 v[80:83], v[160:163], v[200:203], v[80:83]
	v_mfma_f32_16x16x32_bf16 v[56:59], v[152:155], v[208:211], v[56:59]
	v_mfma_f32_16x16x32_bf16 v[48:51], v[160:163], v[208:211], v[48:51]
	v_mfma_f32_16x16x32_bf16 v[120:123], v[156:159], v[188:191], v[120:123]
	v_mfma_f32_16x16x32_bf16 v[112:115], v[164:167], v[188:191], v[112:115]
	v_mfma_f32_16x16x32_bf16 v[104:107], v[156:159], v[196:199], v[104:107]
	v_mfma_f32_16x16x32_bf16 v[96:99], v[164:167], v[196:199], v[96:99]
	v_mfma_f32_16x16x32_bf16 v[88:91], v[156:159], v[204:207], v[88:91]
	v_mfma_f32_16x16x32_bf16 v[80:83], v[164:167], v[204:207], v[80:83]
	v_mfma_f32_16x16x32_bf16 v[56:59], v[156:159], v[212:215], v[56:59]
	v_mfma_f32_16x16x32_bf16 v[48:51], v[164:167], v[212:215], v[48:51]
	v_mfma_f32_16x16x32_bf16 v[124:127], v[168:171], v[184:187], v[124:127]
	v_mfma_f32_16x16x32_bf16 v[116:119], v[176:179], v[184:187], v[116:119]
	v_mfma_f32_16x16x32_bf16 v[108:111], v[168:171], v[192:195], v[108:111]
	v_mfma_f32_16x16x32_bf16 v[100:103], v[176:179], v[192:195], v[100:103]
	v_mfma_f32_16x16x32_bf16 v[92:95], v[168:171], v[200:203], v[92:95]
	v_mfma_f32_16x16x32_bf16 v[84:87], v[176:179], v[200:203], v[84:87]
	v_mfma_f32_16x16x32_bf16 v[60:63], v[168:171], v[208:211], v[60:63]
	v_mfma_f32_16x16x32_bf16 v[52:55], v[176:179], v[208:211], v[52:55]
	v_mfma_f32_16x16x32_bf16 v[124:127], v[172:175], v[188:191], v[124:127]
	v_mfma_f32_16x16x32_bf16 v[116:119], v[180:183], v[188:191], v[116:119]
	v_mfma_f32_16x16x32_bf16 v[108:111], v[172:175], v[196:199], v[108:111]
	v_mfma_f32_16x16x32_bf16 v[100:103], v[180:183], v[196:199], v[100:103]
	v_mfma_f32_16x16x32_bf16 v[92:95], v[172:175], v[204:207], v[92:95]
	v_mfma_f32_16x16x32_bf16 v[84:87], v[180:183], v[204:207], v[84:87]
	v_mfma_f32_16x16x32_bf16 v[60:63], v[172:175], v[212:215], v[60:63]
	v_mfma_f32_16x16x32_bf16 v[52:55], v[180:183], v[212:215], v[52:55]
	s_barrier
	s_mov_b32 m0, s73
	v_lshl_add_u64 v[140:141], v[140:141], 0, s[12:13]
	s_add_u32 s44, s44, 0x80080
	ds_read_b128 v[184:187], v151 offset:49152
	ds_read_b128 v[188:191], v151 offset:50176
	ds_read_b128 v[192:195], v151 offset:51200
	ds_read_b128 v[196:199], v151 offset:52224
	ds_read_b128 v[200:203], v151 offset:53248
	ds_read_b128 v[204:207], v151 offset:54272
	ds_read_b128 v[208:211], v151 offset:55296
	ds_read_b128 v[212:215], v151 offset:56320
	global_load_lds_dwordx4 v[140:141], off
	v_lshl_add_u64 v[140:141], v[142:143], 0, s[12:13]
	s_mov_b32 m0, s74
	s_addc_u32 s45, s45, 0
	global_load_lds_dwordx4 v[140:141], off
	v_lshl_add_u64 v[140:141], s[44:45], 0, v[128:129]
	s_mov_b32 m0, s75
	s_nop 0
	global_load_lds_dwordx4 v[140:141], off
	v_lshl_add_u64 v[140:141], s[44:45], 0, v[130:131]
	s_mov_b32 m0, s76
	s_nop 0
	global_load_lds_dwordx4 v[140:141], off
	v_lshl_add_u64 v[140:141], v[146:147], 0, s[12:13]
	s_mov_b32 m0, s59
	s_nop 0
	global_load_lds_dwordx4 v[140:141], off
	v_lshl_add_u64 v[140:141], v[216:217], 0, s[12:13]
	s_mov_b32 m0, s60
	s_nop 0
	global_load_lds_dwordx4 v[140:141], off
	s_waitcnt vmcnt(8) lgkmcnt(0)
	s_barrier
	v_mfma_f32_16x16x32_bf16 v[72:75], v[152:155], v[184:187], v[72:75]
	v_mfma_f32_16x16x32_bf16 v[64:67], v[160:163], v[184:187], v[64:67]
	v_mfma_f32_16x16x32_bf16 v[40:43], v[152:155], v[192:195], v[40:43]
	v_mfma_f32_16x16x32_bf16 v[32:35], v[160:163], v[192:195], v[32:35]
	v_mfma_f32_16x16x32_bf16 v[24:27], v[152:155], v[200:203], v[24:27]
	v_mfma_f32_16x16x32_bf16 v[16:19], v[160:163], v[200:203], v[16:19]
	v_mfma_f32_16x16x32_bf16 v[8:11], v[152:155], v[208:211], v[8:11]
	v_mfma_f32_16x16x32_bf16 v[0:3], v[160:163], v[208:211], v[0:3]
	v_mfma_f32_16x16x32_bf16 v[72:75], v[156:159], v[188:191], v[72:75]
	v_mfma_f32_16x16x32_bf16 v[64:67], v[164:167], v[188:191], v[64:67]
	v_mfma_f32_16x16x32_bf16 v[40:43], v[156:159], v[196:199], v[40:43]
	v_mfma_f32_16x16x32_bf16 v[32:35], v[164:167], v[196:199], v[32:35]
	v_mfma_f32_16x16x32_bf16 v[24:27], v[156:159], v[204:207], v[24:27]
	v_mfma_f32_16x16x32_bf16 v[16:19], v[164:167], v[204:207], v[16:19]
	v_mfma_f32_16x16x32_bf16 v[8:11], v[156:159], v[212:215], v[8:11]
	v_mfma_f32_16x16x32_bf16 v[0:3], v[164:167], v[212:215], v[0:3]
	v_mfma_f32_16x16x32_bf16 v[76:79], v[168:171], v[184:187], v[76:79]
	v_mfma_f32_16x16x32_bf16 v[68:71], v[176:179], v[184:187], v[68:71]
	v_mfma_f32_16x16x32_bf16 v[44:47], v[168:171], v[192:195], v[44:47]
	v_mfma_f32_16x16x32_bf16 v[36:39], v[176:179], v[192:195], v[36:39]
	v_mfma_f32_16x16x32_bf16 v[28:31], v[168:171], v[200:203], v[28:31]
	v_mfma_f32_16x16x32_bf16 v[20:23], v[176:179], v[200:203], v[20:23]
	v_mfma_f32_16x16x32_bf16 v[12:15], v[168:171], v[208:211], v[12:15]
	v_mfma_f32_16x16x32_bf16 v[4:7], v[176:179], v[208:211], v[4:7]
	v_mfma_f32_16x16x32_bf16 v[76:79], v[172:175], v[188:191], v[76:79]
	v_mfma_f32_16x16x32_bf16 v[68:71], v[180:183], v[188:191], v[68:71]
	v_mfma_f32_16x16x32_bf16 v[44:47], v[172:175], v[196:199], v[44:47]
	v_mfma_f32_16x16x32_bf16 v[36:39], v[180:183], v[196:199], v[36:39]
	v_mfma_f32_16x16x32_bf16 v[28:31], v[172:175], v[204:207], v[28:31]
	v_mfma_f32_16x16x32_bf16 v[20:23], v[180:183], v[204:207], v[20:23]
	v_mfma_f32_16x16x32_bf16 v[12:15], v[172:175], v[212:215], v[12:15]
	v_mfma_f32_16x16x32_bf16 v[4:7], v[180:183], v[212:215], v[4:7]
	s_barrier
	s_add_i32 s79, s79, 2
	s_add_u32 s77, s77, 0x100
	s_addc_u32 s78, s78, 0
	s_add_u32 s42, s42, 0x100
	s_addc_u32 s43, s43, 0
	s_cmp_gt_u32 s79, 29
	s_cbranch_scc0 .LBB0_3342
	s_and_b64 vcc, exec, s[14:15]
	s_cbranch_vccz .LBB0_3345
	s_barrier

; #define PG8_MMA(ai, bj, At, Bt) do { __builtin_amdgcn_s_setprio(1); _Pragma("unroll") for (int m = 0; m < 4; ++m) _Pragma("unroll") for (int n = 0; n < 2; ++n) _Pragma("unroll") for (int k = 0; k < 2; ++k) \
;         acc[ai][bj][m][n] = __builtin_amdgcn_mfma_f32_16x16x32_bf16(Bt[n][k], At[m][k], acc[ai][bj][m][n], 0, 0, 0); __builtin_amdgcn_s_setprio(0); } while (0)
; template <class Epi, class Sched, bool ALIGN_EPI = false, bool SP2 = false, bool A_TILED = false>
; __device__ __forceinline__ void gemm_phase(PG8_LAS unsigned char* lds, const Gemm g, const Sched& S, const Epi& E, const int wave_s) {
;     ...
;         for (int t = PEEL ? 2 : 0; t < nt; t += 2) {
;             const bool last = (t == nt - 2);
;             const char* a1 = cA + (size_t)(t + 1) * kstepA;
;             const char* a2 = last ? nA : cA + (size_t)(t + 2) * kstepA; const char* b2 = last ? nB : cB + (size_t)(t + 2) * kstep;
;             const char* a3 = a2 + kstepA; const char* b3 = b2 + kstep;
;             if (last && has_next) S.a_ready(nxt);
;             if constexpr (SP2) {
;             PG8_ITER(PG8_MMA)
.LBB0_3608:
	ds_read_b128 v[146:149], v140
	ds_read_b128 v[150:153], v140 offset:1024
	ds_read_b128 v[154:157], v140 offset:2048
	ds_read_b128 v[158:161], v140 offset:3072
	ds_read_b128 v[162:165], v141
	ds_read_b128 v[166:169], v141 offset:1024
	ds_read_b128 v[170:173], v141 offset:2048
	ds_read_b128 v[174:177], v141 offset:3072
	s_add_u32 s20, s8, s43
	s_addc_u32 s21, s9, s44
	s_add_u32 s56, s8, s41
	s_addc_u32 s57, s9, s42
	s_cmp_eq_u32 s45, 28
	s_cselect_b32 s23, s5, s21
	s_cselect_b32 s22, s4, s20
	s_cselect_b32 s21, s1, s57
	s_cselect_b32 s20, s0, s56
	s_mov_b32 m0, s46
	v_lshl_add_u64 v[210:211], s[8:9], 0, v[138:139]
	ds_read_b128 v[178:181], v142
	ds_read_b128 v[182:185], v142 offset:1024
	ds_read_b128 v[186:189], v142 offset:2048
	ds_read_b128 v[190:193], v142 offset:3072
	ds_read_b128 v[194:197], v142 offset:4096
	ds_read_b128 v[198:201], v142 offset:5120
	ds_read_b128 v[202:205], v142 offset:6144
	ds_read_b128 v[206:209], v142 offset:7168
	global_load_lds_dwordx4 v[210:211], off
	v_lshl_add_u64 v[210:211], s[8:9], 0, v[136:137]
	s_mov_b32 m0, s47
	s_nop 0
	global_load_lds_dwordx4 v[210:211], off
	s_waitcnt vmcnt(8) lgkmcnt(0)
	s_barrier
	v_mfma_f32_16x16x32_bf16 v[8:11], v[146:149], v[178:181], v[8:11]
	v_mfma_f32_16x16x32_bf16 v[12:15], v[154:157], v[178:181], v[12:15]
	v_mfma_f32_16x16x32_bf16 v[60:63], v[146:149], v[186:189], v[60:63]
	v_mfma_f32_16x16x32_bf16 v[20:23], v[154:157], v[186:189], v[20:23]
	v_mfma_f32_16x16x32_bf16 v[76:79], v[146:149], v[194:197], v[76:79]
	v_mfma_f32_16x16x32_bf16 v[52:55], v[154:157], v[194:197], v[52:55]
	v_mfma_f32_16x16x32_bf16 v[128:131], v[146:149], v[202:205], v[128:131]
	v_mfma_f32_16x16x32_bf16 v[68:71], v[154:157], v[202:205], v[68:71]
	v_mfma_f32_16x16x32_bf16 v[8:11], v[150:153], v[182:185], v[8:11]
	v_mfma_f32_16x16x32_bf16 v[12:15], v[158:161], v[182:185], v[12:15]
	v_mfma_f32_16x16x32_bf16 v[60:63], v[150:153], v[190:193], v[60:63]
	v_mfma_f32_16x16x32_bf16 v[20:23], v[158:161], v[190:193], v[20:23]
	v_mfma_f32_16x16x32_bf16 v[76:79], v[150:153], v[198:201], v[76:79]
	v_mfma_f32_16x16x32_bf16 v[52:55], v[158:161], v[198:201], v[52:55]
	v_mfma_f32_16x16x32_bf16 v[128:131], v[150:153], v[206:209], v[128:131]
	v_mfma_f32_16x16x32_bf16 v[68:71], v[158:161], v[206:209], v[68:71]
	v_mfma_f32_16x16x32_bf16 v[24:27], v[162:165], v[178:181], v[24:27]
	v_mfma_f32_16x16x32_bf16 v[16:19], v[170:173], v[178:181], v[16:19]
	v_mfma_f32_16x16x32_bf16 v[56:59], v[162:165], v[186:189], v[56:59]
	v_mfma_f32_16x16x32_bf16 v[48:51], v[170:173], v[186:189], v[48:51]
	v_mfma_f32_16x16x32_bf16 v[72:75], v[162:165], v[194:197], v[72:75]
	v_mfma_f32_16x16x32_bf16 v[64:67], v[170:173], v[194:197], v[64:67]
	v_mfma_f32_16x16x32_bf16 v[108:111], v[162:165], v[202:205], v[108:111]
	v_mfma_f32_16x16x32_bf16 v[96:99], v[170:173], v[202:205], v[96:99]
	v_mfma_f32_16x16x32_bf16 v[24:27], v[166:169], v[182:185], v[24:27]
	v_mfma_f32_16x16x32_bf16 v[16:19], v[174:177], v[182:185], v[16:19]
	v_mfma_f32_16x16x32_bf16 v[56:59], v[166:169], v[190:193], v[56:59]
	v_mfma_f32_16x16x32_bf16 v[48:51], v[174:177], v[190:193], v[48:51]
	v_mfma_f32_16x16x32_bf16 v[72:75], v[166:169], v[198:201], v[72:75]
	v_mfma_f32_16x16x32_bf16 v[64:67], v[174:177], v[198:201], v[64:67]
	v_mfma_f32_16x16x32_bf16 v[108:111], v[166:169], v[206:209], v[108:111]
	v_mfma_f32_16x16x32_bf16 v[96:99], v[174:177], v[206:209], v[96:99]
	s_barrier
	s_mov_b32 m0, s48
	v_lshl_add_u64 v[210:211], s[20:21], 0, v[34:35]
	s_add_u32 s56, s20, 0x80000
	ds_read_b128 v[178:181], v142 offset:16384
	ds_read_b128 v[182:185], v142 offset:17408
	ds_read_b128 v[186:189], v142 offset:18432
	ds_read_b128 v[190:193], v142 offset:19456
	ds_read_b128 v[194:197], v142 offset:20480
	ds_read_b128 v[198:201], v142 offset:21504
	ds_read_b128 v[202:205], v142 offset:22528
	ds_read_b128 v[206:209], v142 offset:23552
	global_load_lds_dwordx4 v[210:211], off
	v_lshl_add_u64 v[212:213], s[20:21], 0, v[134:135]
	s_mov_b32 m0, s49
	s_addc_u32 s57, s21, 0
	global_load_lds_dwordx4 v[212:213], off
	v_lshl_add_u64 v[214:215], s[56:57], 0, v[34:35]
	s_mov_b32 m0, s50
	v_lshl_add_u64 v[216:217], s[22:23], 0, v[132:133]
	global_load_lds_dwordx4 v[214:215], off
	v_lshl_add_u64 v[214:215], s[56:57], 0, v[134:135]
	s_mov_b32 m0, s51
	s_nop 0
	global_load_lds_dwordx4 v[214:215], off
	v_lshl_add_u64 v[214:215], s[22:23], 0, v[32:33]
	s_mov_b32 m0, s27
	s_nop 0
	global_load_lds_dwordx4 v[214:215], off
	s_mov_b32 m0, s36
	s_nop 0
	global_load_lds_dwordx4 v[216:217], off
	s_waitcnt vmcnt(8) lgkmcnt(0)
	s_barrier
	v_mfma_f32_16x16x32_bf16 v[100:103], v[146:149], v[178:181], v[100:103]
	v_mfma_f32_16x16x32_bf16 v[104:107], v[154:157], v[178:181], v[104:107]
	v_mfma_f32_16x16x32_bf16 v[116:119], v[146:149], v[186:189], v[116:119]
	v_mfma_f32_16x16x32_bf16 v[120:123], v[154:157], v[186:189], v[120:123]
	v_mfma_f32_16x16x32_bf16 v[84:87], v[146:149], v[194:197], v[84:87]
	v_mfma_f32_16x16x32_bf16 v[80:83], v[154:157], v[194:197], v[80:83]
	v_mfma_f32_16x16x32_bf16 v[36:39], v[146:149], v[202:205], v[36:39]
	v_mfma_f32_16x16x32_bf16 v[28:31], v[154:157], v[202:205], v[28:31]
	v_mfma_f32_16x16x32_bf16 v[100:103], v[150:153], v[182:185], v[100:103]
	v_mfma_f32_16x16x32_bf16 v[104:107], v[158:161], v[182:185], v[104:107]
	v_mfma_f32_16x16x32_bf16 v[116:119], v[150:153], v[190:193], v[116:119]
	v_mfma_f32_16x16x32_bf16 v[120:123], v[158:161], v[190:193], v[120:123]
	v_mfma_f32_16x16x32_bf16 v[84:87], v[150:153], v[198:201], v[84:87]
	v_mfma_f32_16x16x32_bf16 v[80:83], v[158:161], v[198:201], v[80:83]
	v_mfma_f32_16x16x32_bf16 v[36:39], v[150:153], v[206:209], v[36:39]
	v_mfma_f32_16x16x32_bf16 v[28:31], v[158:161], v[206:209], v[28:31]
	v_mfma_f32_16x16x32_bf16 v[124:127], v[162:165], v[178:181], v[124:127]
	v_mfma_f32_16x16x32_bf16 v[112:115], v[170:173], v[178:181], v[112:115]
	v_mfma_f32_16x16x32_bf16 v[92:95], v[162:165], v[186:189], v[92:95]
	v_mfma_f32_16x16x32_bf16 v[88:91], v[170:173], v[186:189], v[88:91]
	v_mfma_f32_16x16x32_bf16 v[44:47], v[162:165], v[194:197], v[44:47]
	v_mfma_f32_16x16x32_bf16 v[40:43], v[170:173], v[194:197], v[40:43]
	v_mfma_f32_16x16x32_bf16 v[4:7], v[162:165], v[202:205], v[4:7]
	v_mfma_f32_16x16x32_bf16 v[0:3], v[170:173], v[202:205], v[0:3]
	v_mfma_f32_16x16x32_bf16 v[124:127], v[166:169], v[182:185], v[124:127]
	v_mfma_f32_16x16x32_bf16 v[112:115], v[174:177], v[182:185], v[112:115]
	v_mfma_f32_16x16x32_bf16 v[92:95], v[166:169], v[190:193], v[92:95]
	v_mfma_f32_16x16x32_bf16 v[88:91], v[174:177], v[190:193], v[88:91]
	v_mfma_f32_16x16x32_bf16 v[44:47], v[166:169], v[198:201], v[44:47]
	v_mfma_f32_16x16x32_bf16 v[40:43], v[174:177], v[198:201], v[40:43]
	v_mfma_f32_16x16x32_bf16 v[4:7], v[166:169], v[206:209], v[4:7]
	v_mfma_f32_16x16x32_bf16 v[0:3], v[174:177], v[206:209], v[0:3]
	s_barrier
	ds_read_b128 v[146:149], v143
	ds_read_b128 v[150:153], v143 offset:1024
	ds_read_b128 v[154:157], v143 offset:2048
	ds_read_b128 v[158:161], v143 offset:3072
	ds_read_b128 v[162:165], v144
	ds_read_b128 v[166:169], v144 offset:1024
	ds_read_b128 v[170:173], v144 offset:2048
	ds_read_b128 v[174:177], v144 offset:3072
	s_add_u32 s22, s22, 0x80000
	s_addc_u32 s23, s23, 0
	s_mov_b32 m0, s37
	v_lshl_add_u64 v[218:219], s[22:23], 0, v[32:33]
	ds_read_b128 v[178:181], v142 offset:32768
	ds_read_b128 v[182:185], v142 offset:33792
	ds_read_b128 v[186:189], v142 offset:34816
	ds_read_b128 v[190:193], v142 offset:35840
	ds_read_b128 v[194:197], v142 offset:36864
	ds_read_b128 v[198:201], v142 offset:37888
	ds_read_b128 v[202:205], v142 offset:38912
	ds_read_b128 v[206:209], v142 offset:39936
	global_load_lds_dwordx4 v[218:219], off
	v_lshl_add_u64 v[218:219], s[22:23], 0, v[132:133]
	s_mov_b32 m0, s38
	s_nop 0
	global_load_lds_dwordx4 v[218:219], off
	s_waitcnt vmcnt(8) lgkmcnt(0)
	s_barrier
	v_mfma_f32_16x16x32_bf16 v[8:11], v[146:149], v[178:181], v[8:11]
	v_mfma_f32_16x16x32_bf16 v[12:15], v[154:157], v[178:181], v[12:15]
	v_mfma_f32_16x16x32_bf16 v[60:63], v[146:149], v[186:189], v[60:63]
	v_mfma_f32_16x16x32_bf16 v[20:23], v[154:157], v[186:189], v[20:23]
	v_mfma_f32_16x16x32_bf16 v[76:79], v[146:149], v[194:197], v[76:79]
	v_mfma_f32_16x16x32_bf16 v[52:55], v[154:157], v[194:197], v[52:55]
	v_mfma_f32_16x16x32_bf16 v[128:131], v[146:149], v[202:205], v[128:131]
	v_mfma_f32_16x16x32_bf16 v[68:71], v[154:157], v[202:205], v[68:71]
	v_mfma_f32_16x16x32_bf16 v[8:11], v[150:153], v[182:185], v[8:11]
	v_mfma_f32_16x16x32_bf16 v[12:15], v[158:161], v[182:185], v[12:15]
	v_mfma_f32_16x16x32_bf16 v[60:63], v[150:153], v[190:193], v[60:63]
	v_mfma_f32_16x16x32_bf16 v[20:23], v[158:161], v[190:193], v[20:23]
	v_mfma_f32_16x16x32_bf16 v[76:79], v[150:153], v[198:201], v[76:79]
	v_mfma_f32_16x16x32_bf16 v[52:55], v[158:161], v[198:201], v[52:55]
	v_mfma_f32_16x16x32_bf16 v[128:131], v[150:153], v[206:209], v[128:131]
	v_mfma_f32_16x16x32_bf16 v[68:71], v[158:161], v[206:209], v[68:71]
	v_mfma_f32_16x16x32_bf16 v[24:27], v[162:165], v[178:181], v[24:27]
	v_mfma_f32_16x16x32_bf16 v[16:19], v[170:173], v[178:181], v[16:19]
	v_mfma_f32_16x16x32_bf16 v[56:59], v[162:165], v[186:189], v[56:59]
	v_mfma_f32_16x16x32_bf16 v[48:51], v[170:173], v[186:189], v[48:51]
	v_mfma_f32_16x16x32_bf16 v[72:75], v[162:165], v[194:197], v[72:75]
	v_mfma_f32_16x16x32_bf16 v[64:67], v[170:173], v[194:197], v[64:67]
	v_mfma_f32_16x16x32_bf16 v[108:111], v[162:165], v[202:205], v[108:111]
	v_mfma_f32_16x16x32_bf16 v[96:99], v[170:173], v[202:205], v[96:99]
	v_mfma_f32_16x16x32_bf16 v[24:27], v[166:169], v[182:185], v[24:27]
	v_mfma_f32_16x16x32_bf16 v[16:19], v[174:177], v[182:185], v[16:19]
	v_mfma_f32_16x16x32_bf16 v[56:59], v[166:169], v[190:193], v[56:59]
	v_mfma_f32_16x16x32_bf16 v[48:51], v[174:177], v[190:193], v[48:51]
	v_mfma_f32_16x16x32_bf16 v[72:75], v[166:169], v[198:201], v[72:75]
	v_mfma_f32_16x16x32_bf16 v[64:67], v[174:177], v[198:201], v[64:67]
	v_mfma_f32_16x16x32_bf16 v[108:111], v[166:169], v[206:209], v[108:111]
	v_mfma_f32_16x16x32_bf16 v[96:99], v[174:177], v[206:209], v[96:99]
	s_barrier
; #define PG8_MMA(ai, bj, At, Bt) do { __builtin_amdgcn_s_setprio(1); _Pragma("unroll") for (int m = 0; m < 4; ++m) _Pragma("unroll") for (int n = 0; n < 2; ++n) _Pragma("unroll") for (int k = 0; k < 2; ++k) \
;         acc[ai][bj][m][n] = __builtin_amdgcn_mfma_f32_16x16x32_bf16(Bt[n][k], At[m][k], acc[ai][bj][m][n], 0, 0, 0); __builtin_amdgcn_s_setprio(0); } while (0)
; #define PG8_WAIT_V(n) asm volatile("s_waitcnt vmcnt(" #n ")" ::: "memory")
; #define PG8_BAR __builtin_amdgcn_s_barrier()
; template <class Epi, class Sched, bool ALIGN_EPI = false, bool SP2 = false, bool A_TILED = false>
; __device__ __forceinline__ void gemm_phase(PG8_LAS unsigned char* lds, const Gemm g, const Sched& S, const Epi& E, const int wave_s) {
;     ...
;         for (int t = PEEL ? 2 : 0; t < nt; t += 2) {
;             const bool last = (t == nt - 2);
;             const char* a1 = cA + (size_t)(t + 1) * kstepA;
;             const char* a2 = last ? nA : cA + (size_t)(t + 2) * kstepA; const char* b2 = last ? nB : cB + (size_t)(t + 2) * kstep;
;             const char* a3 = a2 + kstepA; const char* b3 = b2 + kstep;
;             if (last && has_next) S.a_ready(nxt);
;             if constexpr (SP2) {
;             PG8_ITER(PG8_MMA)
;     ...
;     PG8_WAIT_V(0);
;     if constexpr (!ALIGN_EPI) { if (wr == 0) PG8_BAR; }
;     PG8_BAR;
	s_mov_b32 m0, s52
	v_lshl_add_u64 v[210:211], v[210:211], 0, s[14:15]
	s_add_u32 s20, s20, 0x80080
	ds_read_b128 v[178:181], v142 offset:49152
	ds_read_b128 v[182:185], v142 offset:50176
	ds_read_b128 v[186:189], v142 offset:51200
	ds_read_b128 v[190:193], v142 offset:52224
	ds_read_b128 v[194:197], v142 offset:53248
	ds_read_b128 v[198:201], v142 offset:54272
	ds_read_b128 v[202:205], v142 offset:55296
	ds_read_b128 v[206:209], v142 offset:56320
	global_load_lds_dwordx4 v[210:211], off
	v_lshl_add_u64 v[210:211], v[212:213], 0, s[14:15]
	s_mov_b32 m0, s53
	s_addc_u32 s21, s21, 0
	global_load_lds_dwordx4 v[210:211], off
	v_lshl_add_u64 v[210:211], s[20:21], 0, v[34:35]
	s_mov_b32 m0, s54
	s_nop 0
	global_load_lds_dwordx4 v[210:211], off
	v_lshl_add_u64 v[210:211], s[20:21], 0, v[134:135]
	s_mov_b32 m0, s55
	s_nop 0
	global_load_lds_dwordx4 v[210:211], off
	v_lshl_add_u64 v[210:211], v[214:215], 0, s[14:15]
	s_mov_b32 m0, s39
	s_nop 0
	global_load_lds_dwordx4 v[210:211], off
	v_lshl_add_u64 v[210:211], v[216:217], 0, s[14:15]
	s_mov_b32 m0, s40
	s_nop 0
	global_load_lds_dwordx4 v[210:211], off
	s_waitcnt vmcnt(8) lgkmcnt(0)
	s_barrier
	v_mfma_f32_16x16x32_bf16 v[100:103], v[146:149], v[178:181], v[100:103]
	v_mfma_f32_16x16x32_bf16 v[104:107], v[154:157], v[178:181], v[104:107]
	v_mfma_f32_16x16x32_bf16 v[116:119], v[146:149], v[186:189], v[116:119]
	v_mfma_f32_16x16x32_bf16 v[120:123], v[154:157], v[186:189], v[120:123]
	v_mfma_f32_16x16x32_bf16 v[84:87], v[146:149], v[194:197], v[84:87]
	v_mfma_f32_16x16x32_bf16 v[80:83], v[154:157], v[194:197], v[80:83]
	v_mfma_f32_16x16x32_bf16 v[36:39], v[146:149], v[202:205], v[36:39]
	v_mfma_f32_16x16x32_bf16 v[28:31], v[154:157], v[202:205], v[28:31]
	v_mfma_f32_16x16x32_bf16 v[100:103], v[150:153], v[182:185], v[100:103]
	v_mfma_f32_16x16x32_bf16 v[104:107], v[158:161], v[182:185], v[104:107]
	v_mfma_f32_16x16x32_bf16 v[116:119], v[150:153], v[190:193], v[116:119]
	v_mfma_f32_16x16x32_bf16 v[120:123], v[158:161], v[190:193], v[120:123]
	v_mfma_f32_16x16x32_bf16 v[84:87], v[150:153], v[198:201], v[84:87]
	v_mfma_f32_16x16x32_bf16 v[80:83], v[158:161], v[198:201], v[80:83]
	v_mfma_f32_16x16x32_bf16 v[36:39], v[150:153], v[206:209], v[36:39]
	v_mfma_f32_16x16x32_bf16 v[28:31], v[158:161], v[206:209], v[28:31]
	v_mfma_f32_16x16x32_bf16 v[124:127], v[162:165], v[178:181], v[124:127]
	v_mfma_f32_16x16x32_bf16 v[112:115], v[170:173], v[178:181], v[112:115]
	v_mfma_f32_16x16x32_bf16 v[92:95], v[162:165], v[186:189], v[92:95]
	v_mfma_f32_16x16x32_bf16 v[88:91], v[170:173], v[186:189], v[88:91]
	v_mfma_f32_16x16x32_bf16 v[44:47], v[162:165], v[194:197], v[44:47]
	v_mfma_f32_16x16x32_bf16 v[40:43], v[170:173], v[194:197], v[40:43]
	v_mfma_f32_16x16x32_bf16 v[4:7], v[162:165], v[202:205], v[4:7]
	v_mfma_f32_16x16x32_bf16 v[0:3], v[170:173], v[202:205], v[0:3]
	v_mfma_f32_16x16x32_bf16 v[124:127], v[166:169], v[182:185], v[124:127]
	v_mfma_f32_16x16x32_bf16 v[112:115], v[174:177], v[182:185], v[112:115]
	v_mfma_f32_16x16x32_bf16 v[92:95], v[166:169], v[190:193], v[92:95]
	v_mfma_f32_16x16x32_bf16 v[88:91], v[174:177], v[190:193], v[88:91]
	v_mfma_f32_16x16x32_bf16 v[44:47], v[166:169], v[198:201], v[44:47]
	v_mfma_f32_16x16x32_bf16 v[40:43], v[174:177], v[198:201], v[40:43]
	v_mfma_f32_16x16x32_bf16 v[4:7], v[166:169], v[206:209], v[4:7]
	v_mfma_f32_16x16x32_bf16 v[0:3], v[174:177], v[206:209], v[0:3]
	s_barrier
	s_add_i32 s45, s45, 2
	s_add_u32 s41, s41, 0x100
	s_addc_u32 s42, s42, 0
	s_add_u32 s43, s43, 0x100
	s_addc_u32 s44, s44, 0
	v_lshl_add_u64 v[136:137], v[136:137], 0, s[16:17]
	s_cmp_gt_u32 s45, 29
	v_lshl_add_u64 v[138:139], v[138:139], 0, s[16:17]
	s_cbranch_scc0 .LBB0_3608
	s_waitcnt vmcnt(0)
	s_cmpk_lt_u32 s24, 0x100
	s_cbranch_scc0 .LBB0_3611
	s_barrier

; #define PG8_STAGE(bufoff, gbase, voff) do { _Pragma("unroll") for (int _i = 0; _i < 2; ++_i) \
;         __builtin_amdgcn_global_load_lds((const unsigned*)((const char*)(gbase) + (voff)[_i]), (PG8_LAS unsigned*)(lds + (bufoff) + ldsw + _i * 8192), 16, 0, 0); } while (0)
; #define PG8_WAIT_V(n) asm volatile("s_waitcnt vmcnt(" #n ")" ::: "memory")
; #define PG8_BAR __builtin_amdgcn_s_barrier()
; template <class Epi, class Sched, bool ALIGN_EPI = false, bool SP2 = false, bool A_TILED = false>
; __device__ __forceinline__ void gemm_phase(PG8_LAS unsigned char* lds, const Gemm g, const Sched& S, const Epi& E, const int wave_s) {
;     ...
;     Unit cur, nxt; int ui = 0;
;     if (!S.next(0, cur)) return;
;     f32x4 acc[2][2][4][2];
;     bf16x8 At[4][2], B0[2][2], B1[2][2];
;     const char* cA = (const char*)g.A + (size_t)cur.pm * tstepA; const char* cB = (const char*)g.Bt + (size_t)cur.pn * tstep;
;     S.a_ready(cur);
;     if constexpr (SP2) {
;         PG8_STAGE(PG8_SB(0, 0), cB, voffB); PG8_STAGE(PG8_SB(0, 1), cB + hstep, voffB); PG8_STAGE(PG8_SA(0, 0), cA, voffA); PG8_STAGE(PG8_SA(0, 1), cA + hstepA, voffA);
;         if (wr == 1) PG8_BAR;
;         PG8_WAIT_V(2); PG8_BAR;
;         PG8_STAGE(PG8_SB(1, 0), cB + kstep, voffB); PG8_STAGE(PG8_SA(1, 0), cA + kstepA, voffA); PG8_STAGE(PG8_SB(1, 1), cB + hstep + kstep, voffB);
;         PG8_WAIT_V(6); PG8_BAR;
;     } else {
;         PG8_STAGE(PG8_SB(0, 0), cB, voffB); PG8_STAGE(PG8_SA(0, 0), cA, voffA); PG8_STAGE(PG8_SB(0, 1), cB + hstep, voffB); PG8_STAGE(PG8_SA(0, 1), cA + hstepA, voffA);
;         if (wr == 1) PG8_BAR;
;         PG8_WAIT_V(4); PG8_BAR;
;         PG8_STAGE(PG8_SB(1, 0), cB + kstep, voffB); PG8_STAGE(PG8_SA(1, 0), cA + kstepA, voffA); PG8_STAGE(PG8_SB(1, 1), cB + hstep + kstep, voffB);
;         PG8_WAIT_V(6); PG8_BAR;
;     }
;     for (;;) {
;         const bool has_next = Epi::AFTER_DRAIN ? false : S.next(ui + 1, nxt);
;         const char* nA = has_next ? (const char*)g.A + (size_t)nxt.pm * tstepA : cA; const char* nB = has_next ? (const char*)g.Bt + (size_t)nxt.pn * tstep : cB;
;         constexpr bool PEEL = SP2 && !Epi::AFTER_DRAIN;
;         if constexpr (PEEL) {
;             const char* a1 = cA + kstepA; const char* a2 = cA + 2 * kstepA; const char* b2 = cB + 2 * kstep; const char* a3 = a2 + kstepA; const char* b3 = b2 + kstep;
;             PG8_ITER(PG8_MMAZ)
.LBB0_3719:
	s_ashr_i32 s19, s18, 31
	s_lshl_b64 s[20:21], s[18:19], 20
	s_add_u32 s20, s41, s20
	ds_read_b128 v[0:3], v145
	ds_read_b128 v[4:7], v145 offset:1024
	ds_read_b128 v[8:11], v145 offset:2048
	ds_read_b128 v[12:15], v145 offset:3072
	ds_read_b128 v[16:19], v146
	ds_read_b128 v[20:23], v146 offset:1024
	ds_read_b128 v[24:27], v146 offset:2048
	ds_read_b128 v[28:31], v146 offset:3072
	s_addc_u32 s21, s42, s21
	s_ashr_i32 s17, s16, 31
	s_lshl_b64 s[22:23], s[16:17], 20
	s_add_u32 s22, s43, s22
	s_addc_u32 s23, s44, s23
	s_and_b64 s[38:39], s[0:1], exec
	s_cselect_b32 s17, s21, s37
	s_cselect_b32 s19, s20, s36
	s_cselect_b32 s62, s23, s27
	s_cselect_b32 s63, s22, s26
	s_add_u32 s38, s36, 0x80080
	s_addc_u32 s39, s37, 0
	s_add_i32 s64, s47, 0xc000
	v_lshl_add_u64 v[64:65], s[38:39], 0, v[134:135]
	s_mov_b32 m0, s64
	s_add_i32 s65, s47, 0xe000
	ds_read_b128 v[32:35], v147
	ds_read_b128 v[36:39], v147 offset:1024
	ds_read_b128 v[40:43], v147 offset:2048
	ds_read_b128 v[44:47], v147 offset:3072
	ds_read_b128 v[48:51], v147 offset:4096
	ds_read_b128 v[52:55], v147 offset:5120
	ds_read_b128 v[56:59], v147 offset:6144
	ds_read_b128 v[60:63], v147 offset:7168
	global_load_lds_dwordx4 v[64:65], off
	v_lshl_add_u64 v[64:65], s[38:39], 0, v[132:133]
	s_mov_b32 m0, s65
	s_nop 0
	global_load_lds_dwordx4 v[64:65], off
	s_waitcnt vmcnt(8) lgkmcnt(0)
	s_barrier
	v_mfma_f32_16x16x32_bf16 v[88:91], v[0:3], v[56:59], 0
	v_mfma_f32_16x16x32_bf16 v[64:67], v[0:3], v[32:35], 0
	v_mfma_f32_16x16x32_bf16 v[68:71], v[8:11], v[32:35], 0
	v_mfma_f32_16x16x32_bf16 v[72:75], v[0:3], v[40:43], 0
	v_mfma_f32_16x16x32_bf16 v[76:79], v[8:11], v[40:43], 0
	v_mfma_f32_16x16x32_bf16 v[80:83], v[0:3], v[48:51], 0
	v_mfma_f32_16x16x32_bf16 v[84:87], v[8:11], v[48:51], 0
	v_mfma_f32_16x16x32_bf16 v[96:99], v[4:7], v[60:63], v[88:91]
	v_mfma_f32_16x16x32_bf16 v[88:91], v[8:11], v[56:59], 0
	v_mfma_f32_16x16x32_bf16 v[64:67], v[4:7], v[36:39], v[64:67]
	v_mfma_f32_16x16x32_bf16 v[68:71], v[12:15], v[36:39], v[68:71]
	v_mfma_f32_16x16x32_bf16 v[72:75], v[4:7], v[44:47], v[72:75]
	v_mfma_f32_16x16x32_bf16 v[76:79], v[12:15], v[44:47], v[76:79]
	v_mfma_f32_16x16x32_bf16 v[80:83], v[4:7], v[52:55], v[80:83]
	v_mfma_f32_16x16x32_bf16 v[84:87], v[12:15], v[52:55], v[84:87]
	v_mfma_f32_16x16x32_bf16 v[100:103], v[12:15], v[60:63], v[88:91]
	v_mfma_f32_16x16x32_bf16 v[88:91], v[16:19], v[32:35], 0
	v_mfma_f32_16x16x32_bf16 v[32:35], v[24:27], v[32:35], 0
	v_mfma_f32_16x16x32_bf16 v[112:115], v[20:23], v[36:39], v[88:91]
	v_mfma_f32_16x16x32_bf16 v[32:35], v[28:31], v[36:39], v[32:35]
	v_mfma_f32_16x16x32_bf16 v[36:39], v[16:19], v[40:43], 0
	v_mfma_f32_16x16x32_bf16 v[40:43], v[24:27], v[40:43], 0
	v_mfma_f32_16x16x32_bf16 v[36:39], v[20:23], v[44:47], v[36:39]
	v_mfma_f32_16x16x32_bf16 v[40:43], v[28:31], v[44:47], v[40:43]
	v_mfma_f32_16x16x32_bf16 v[44:47], v[16:19], v[48:51], 0
	v_mfma_f32_16x16x32_bf16 v[48:51], v[24:27], v[48:51], 0
	v_mfma_f32_16x16x32_bf16 v[44:47], v[20:23], v[52:55], v[44:47]
	v_mfma_f32_16x16x32_bf16 v[48:51], v[28:31], v[52:55], v[48:51]
	v_mfma_f32_16x16x32_bf16 v[52:55], v[16:19], v[56:59], 0
	v_mfma_f32_16x16x32_bf16 v[56:59], v[24:27], v[56:59], 0
	v_mfma_f32_16x16x32_bf16 v[52:55], v[20:23], v[60:63], v[52:55]
	v_mfma_f32_16x16x32_bf16 v[56:59], v[28:31], v[60:63], v[56:59]
	s_barrier
	s_add_i32 s66, s60, s45
	v_lshl_add_u64 v[242:243], s[26:27], 0, v[128:129]
	s_add_i32 s67, s66, 0x2000
	v_lshl_add_u64 v[148:149], v[242:243], 0, s[12:13]
	s_mov_b32 m0, s66
	v_lshl_add_u64 v[244:245], s[26:27], 0, v[130:131]
	s_add_u32 s38, s26, 0x80100
	ds_read_b128 v[60:63], v147 offset:16384
	ds_read_b128 v[88:91], v147 offset:17408
	ds_read_b128 v[92:95], v147 offset:18432
	ds_read_b128 v[104:107], v147 offset:19456
	ds_read_b128 v[108:111], v147 offset:20480
	ds_read_b128 v[116:119], v147 offset:21504
	ds_read_b128 v[120:123], v147 offset:22528
	ds_read_b128 v[124:127], v147 offset:23552
	global_load_lds_dwordx4 v[148:149], off
	v_lshl_add_u64 v[148:149], v[244:245], 0, s[12:13]
	s_mov_b32 m0, s67
	s_addc_u32 s39, s27, 0
	s_add_i32 s68, s61, s45
	global_load_lds_dwordx4 v[148:149], off
	v_lshl_add_u64 v[148:149], s[38:39], 0, v[128:129]
	s_mov_b32 m0, s68
	s_add_i32 s69, s68, 0x2000
	global_load_lds_dwordx4 v[148:149], off
	v_lshl_add_u64 v[148:149], s[38:39], 0, v[130:131]
	s_mov_b32 m0, s69
	v_lshl_add_u64 v[246:247], s[36:37], 0, v[134:135]
	global_load_lds_dwordx4 v[148:149], off
	v_lshl_add_u64 v[148:149], v[246:247], 0, s[12:13]
	s_mov_b32 m0, s47
	v_lshl_add_u64 v[248:249], s[36:37], 0, v[132:133]
	global_load_lds_dwordx4 v[148:149], off
	v_lshl_add_u64 v[148:149], v[248:249], 0, s[12:13]
	s_mov_b32 m0, s48
	s_nop 0
	global_load_lds_dwordx4 v[148:149], off
	s_waitcnt vmcnt(8) lgkmcnt(0)
	s_barrier
	v_mfma_f32_16x16x32_bf16 v[148:151], v[0:3], v[60:63], 0
	v_mfma_f32_16x16x32_bf16 v[158:161], v[0:3], v[92:95], 0
	v_mfma_f32_16x16x32_bf16 v[166:169], v[0:3], v[108:111], 0
	v_mfma_f32_16x16x32_bf16 v[0:3], v[0:3], v[120:123], 0
	v_mfma_f32_16x16x32_bf16 v[150:153], v[4:7], v[88:91], v[148:151]
	v_mfma_f32_16x16x32_bf16 v[158:161], v[4:7], v[104:107], v[158:161]
	v_mfma_f32_16x16x32_bf16 v[166:169], v[4:7], v[116:119], v[166:169]
	v_mfma_f32_16x16x32_bf16 v[0:3], v[4:7], v[124:127], v[0:3]
	v_mfma_f32_16x16x32_bf16 v[4:7], v[8:11], v[120:123], 0
	v_mfma_f32_16x16x32_bf16 v[154:157], v[8:11], v[60:63], 0
	v_mfma_f32_16x16x32_bf16 v[162:165], v[8:11], v[92:95], 0
	v_mfma_f32_16x16x32_bf16 v[170:173], v[8:11], v[108:111], 0
	v_mfma_f32_16x16x32_bf16 v[4:7], v[12:15], v[124:127], v[4:7]
	v_mfma_f32_16x16x32_bf16 v[154:157], v[12:15], v[88:91], v[154:157]
	v_mfma_f32_16x16x32_bf16 v[162:165], v[12:15], v[104:107], v[162:165]
	v_mfma_f32_16x16x32_bf16 v[170:173], v[12:15], v[116:119], v[170:173]
	v_mfma_f32_16x16x32_bf16 v[8:11], v[16:19], v[60:63], 0
	v_mfma_f32_16x16x32_bf16 v[174:177], v[20:23], v[88:91], v[8:11]
	v_mfma_f32_16x16x32_bf16 v[8:11], v[24:27], v[60:63], 0
	v_mfma_f32_16x16x32_bf16 v[60:63], v[28:31], v[88:91], v[8:11]
	v_mfma_f32_16x16x32_bf16 v[8:11], v[16:19], v[92:95], 0
	v_mfma_f32_16x16x32_bf16 v[178:181], v[20:23], v[104:107], v[8:11]
	v_mfma_f32_16x16x32_bf16 v[8:11], v[24:27], v[92:95], 0
	v_mfma_f32_16x16x32_bf16 v[182:185], v[28:31], v[104:107], v[8:11]
	v_mfma_f32_16x16x32_bf16 v[8:11], v[16:19], v[108:111], 0
	v_mfma_f32_16x16x32_bf16 v[186:189], v[20:23], v[116:119], v[8:11]
	v_mfma_f32_16x16x32_bf16 v[8:11], v[24:27], v[108:111], 0
	v_mfma_f32_16x16x32_bf16 v[190:193], v[28:31], v[116:119], v[8:11]
	v_mfma_f32_16x16x32_bf16 v[8:11], v[16:19], v[120:123], 0
	v_mfma_f32_16x16x32_bf16 v[194:197], v[20:23], v[124:127], v[8:11]
	v_mfma_f32_16x16x32_bf16 v[8:11], v[24:27], v[120:123], 0
	v_mfma_f32_16x16x32_bf16 v[198:201], v[28:31], v[124:127], v[8:11]
	s_barrier
	s_add_i32 s70, 0, 0x18000
	s_add_i32 s72, 0, 0x1c000
	v_add_u32_e32 v148, s70, v144
	v_add_u32_e32 v149, s72, v144
	s_nop 0
	ds_read_b128 v[8:11], v148
	ds_read_b128 v[12:15], v148 offset:1024
	ds_read_b128 v[16:19], v148 offset:2048
	ds_read_b128 v[20:23], v148 offset:3072
	ds_read_b128 v[202:205], v149
	ds_read_b128 v[206:209], v149 offset:1024
	ds_read_b128 v[210:213], v149 offset:2048
	ds_read_b128 v[214:217], v149 offset:3072
	s_add_u32 s38, s36, 0x80100
	s_addc_u32 s39, s37, 0
	s_mov_b32 m0, s49
	v_lshl_add_u64 v[88:89], s[38:39], 0, v[134:135]
	ds_read_b128 v[24:27], v147 offset:32768
	ds_read_b128 v[28:31], v147 offset:33792
	ds_read_b128 v[218:221], v147 offset:34816
	ds_read_b128 v[222:225], v147 offset:35840
	ds_read_b128 v[226:229], v147 offset:36864
	ds_read_b128 v[230:233], v147 offset:37888
	ds_read_b128 v[234:237], v147 offset:38912
	ds_read_b128 v[238:241], v147 offset:39936
	global_load_lds_dwordx4 v[88:89], off
	v_lshl_add_u64 v[88:89], s[38:39], 0, v[132:133]
	s_mov_b32 m0, s50
	s_nop 0
	global_load_lds_dwordx4 v[88:89], off
	s_waitcnt vmcnt(8) lgkmcnt(0)
	s_barrier
	v_mfma_f32_16x16x32_bf16 v[64:67], v[8:11], v[24:27], v[64:67]
	v_mfma_f32_16x16x32_bf16 v[120:123], v[12:15], v[28:31], v[64:67]
	v_mfma_f32_16x16x32_bf16 v[64:67], v[16:19], v[24:27], v[68:71]
	v_mfma_f32_16x16x32_bf16 v[124:127], v[20:23], v[28:31], v[64:67]
	v_mfma_f32_16x16x32_bf16 v[64:67], v[8:11], v[218:221], v[72:75]
	v_mfma_f32_16x16x32_bf16 v[104:107], v[12:15], v[222:225], v[64:67]
	v_mfma_f32_16x16x32_bf16 v[64:67], v[16:19], v[218:221], v[76:79]
	v_mfma_f32_16x16x32_bf16 v[108:111], v[20:23], v[222:225], v[64:67]
	v_mfma_f32_16x16x32_bf16 v[64:67], v[8:11], v[226:229], v[80:83]
	v_mfma_f32_16x16x32_bf16 v[88:91], v[12:15], v[230:233], v[64:67]
	v_mfma_f32_16x16x32_bf16 v[64:67], v[16:19], v[226:229], v[84:87]
	v_mfma_f32_16x16x32_bf16 v[92:95], v[20:23], v[230:233], v[64:67]
	v_mfma_f32_16x16x32_bf16 v[64:67], v[8:11], v[234:237], v[96:99]
	v_mfma_f32_16x16x32_bf16 v[68:71], v[16:19], v[234:237], v[100:103]
	v_mfma_f32_16x16x32_bf16 v[64:67], v[12:15], v[238:241], v[64:67]
	v_mfma_f32_16x16x32_bf16 v[68:71], v[20:23], v[238:241], v[68:71]
	v_mfma_f32_16x16x32_bf16 v[72:75], v[202:205], v[24:27], v[112:115]
	v_mfma_f32_16x16x32_bf16 v[24:27], v[210:213], v[24:27], v[32:35]
	v_mfma_f32_16x16x32_bf16 v[116:119], v[214:217], v[28:31], v[24:27]
	v_mfma_f32_16x16x32_bf16 v[24:27], v[202:205], v[218:221], v[36:39]
	v_mfma_f32_16x16x32_bf16 v[96:99], v[206:209], v[222:225], v[24:27]
	v_mfma_f32_16x16x32_bf16 v[24:27], v[210:213], v[218:221], v[40:43]
	v_mfma_f32_16x16x32_bf16 v[100:103], v[214:217], v[222:225], v[24:27]
	v_mfma_f32_16x16x32_bf16 v[24:27], v[202:205], v[226:229], v[44:47]
	v_mfma_f32_16x16x32_bf16 v[80:83], v[206:209], v[230:233], v[24:27]
	v_mfma_f32_16x16x32_bf16 v[24:27], v[210:213], v[226:229], v[48:51]
	v_mfma_f32_16x16x32_bf16 v[84:87], v[214:217], v[230:233], v[24:27]
	v_mfma_f32_16x16x32_bf16 v[24:27], v[202:205], v[234:237], v[52:55]
	v_mfma_f32_16x16x32_bf16 v[48:51], v[206:209], v[238:241], v[24:27]
	v_mfma_f32_16x16x32_bf16 v[24:27], v[210:213], v[234:237], v[56:59]
	v_mfma_f32_16x16x32_bf16 v[112:115], v[206:209], v[28:31], v[72:75]
	v_mfma_f32_16x16x32_bf16 v[52:55], v[214:217], v[238:241], v[24:27]
	s_barrier
; template <class Epi, class Sched, bool ALIGN_EPI = false, bool SP2 = false, bool A_TILED = false>
; __device__ __forceinline__ void gemm_phase(PG8_LAS unsigned char* lds, const Gemm g, const Sched& S, const Epi& E, const int wave_s) {
;     ...
;         for (int t = PEEL ? 2 : 0; t < nt; t += 2) {
;             const bool last = (t == nt - 2);
;             const char* a1 = cA + (size_t)(t + 1) * kstepA;
;             const char* a2 = last ? nA : cA + (size_t)(t + 2) * kstepA; const char* b2 = last ? nB : cB + (size_t)(t + 2) * kstep;
;             const char* a3 = a2 + kstepA; const char* b3 = b2 + kstep;
	s_add_i32 s70, s70, s45
	s_add_i32 s71, s70, 0x2000
	s_nop 1
	v_lshl_add_u64 v[24:25], v[242:243], 0, s[14:15]
	s_mov_b32 m0, s70
	s_add_u32 s38, s26, 0x80180
	ds_read_b128 v[32:35], v147 offset:49152
	ds_read_b128 v[36:39], v147 offset:50176
	ds_read_b128 v[218:221], v147 offset:51200
	ds_read_b128 v[222:225], v147 offset:52224
	ds_read_b128 v[226:229], v147 offset:53248
	ds_read_b128 v[230:233], v147 offset:54272
	ds_read_b128 v[234:237], v147 offset:55296
	ds_read_b128 v[238:241], v147 offset:56320
	global_load_lds_dwordx4 v[24:25], off
	v_lshl_add_u64 v[24:25], v[244:245], 0, s[14:15]
	s_mov_b32 m0, s71
	s_addc_u32 s39, s27, 0
	s_add_i32 s72, s72, s45
	global_load_lds_dwordx4 v[24:25], off
	v_lshl_add_u64 v[24:25], s[38:39], 0, v[128:129]
	s_mov_b32 m0, s72
	s_add_i32 s73, s72, 0x2000
	global_load_lds_dwordx4 v[24:25], off
	v_lshl_add_u64 v[24:25], s[38:39], 0, v[130:131]
	s_mov_b32 m0, s73
	s_nop 0
	global_load_lds_dwordx4 v[24:25], off
	v_lshl_add_u64 v[24:25], v[246:247], 0, s[14:15]
	s_mov_b32 m0, s56
	s_nop 0
	global_load_lds_dwordx4 v[24:25], off
	v_lshl_add_u64 v[24:25], v[248:249], 0, s[14:15]
	s_mov_b32 m0, s57
	s_nop 0
	global_load_lds_dwordx4 v[24:25], off
	s_waitcnt vmcnt(8) lgkmcnt(0)
	s_barrier
	v_mfma_f32_16x16x32_bf16 v[24:27], v[8:11], v[32:35], v[150:153]
	v_mfma_f32_16x16x32_bf16 v[72:75], v[12:15], v[36:39], v[24:27]
	v_mfma_f32_16x16x32_bf16 v[24:27], v[16:19], v[32:35], v[154:157]
	v_mfma_f32_16x16x32_bf16 v[76:79], v[20:23], v[36:39], v[24:27]
	v_mfma_f32_16x16x32_bf16 v[24:27], v[8:11], v[218:221], v[158:161]
	v_mfma_f32_16x16x32_bf16 v[40:43], v[12:15], v[222:225], v[24:27]
	v_mfma_f32_16x16x32_bf16 v[24:27], v[16:19], v[218:221], v[162:165]
	v_mfma_f32_16x16x32_bf16 v[0:3], v[8:11], v[234:237], v[0:3]
	v_mfma_f32_16x16x32_bf16 v[44:47], v[20:23], v[222:225], v[24:27]
	v_mfma_f32_16x16x32_bf16 v[24:27], v[8:11], v[226:229], v[166:169]
	v_mfma_f32_16x16x32_bf16 v[28:31], v[16:19], v[226:229], v[170:173]
	v_mfma_f32_16x16x32_bf16 v[8:11], v[12:15], v[238:241], v[0:3]
	v_mfma_f32_16x16x32_bf16 v[0:3], v[16:19], v[234:237], v[4:7]
	v_mfma_f32_16x16x32_bf16 v[24:27], v[12:15], v[230:233], v[24:27]
	v_mfma_f32_16x16x32_bf16 v[28:31], v[20:23], v[230:233], v[28:31]
	v_mfma_f32_16x16x32_bf16 v[12:15], v[20:23], v[238:241], v[0:3]
	v_mfma_f32_16x16x32_bf16 v[0:3], v[202:205], v[32:35], v[174:177]
	v_mfma_f32_16x16x32_bf16 v[56:59], v[206:209], v[36:39], v[0:3]
	v_mfma_f32_16x16x32_bf16 v[0:3], v[210:213], v[32:35], v[60:63]
	v_mfma_f32_16x16x32_bf16 v[60:63], v[214:217], v[36:39], v[0:3]
	v_mfma_f32_16x16x32_bf16 v[0:3], v[202:205], v[218:221], v[178:181]
	v_mfma_f32_16x16x32_bf16 v[32:35], v[206:209], v[222:225], v[0:3]
	v_mfma_f32_16x16x32_bf16 v[0:3], v[210:213], v[218:221], v[182:185]
	v_mfma_f32_16x16x32_bf16 v[36:39], v[214:217], v[222:225], v[0:3]
	v_mfma_f32_16x16x32_bf16 v[0:3], v[202:205], v[226:229], v[186:189]
	v_mfma_f32_16x16x32_bf16 v[16:19], v[206:209], v[230:233], v[0:3]
	v_mfma_f32_16x16x32_bf16 v[0:3], v[210:213], v[226:229], v[190:193]
	v_mfma_f32_16x16x32_bf16 v[20:23], v[214:217], v[230:233], v[0:3]
	v_mfma_f32_16x16x32_bf16 v[0:3], v[202:205], v[234:237], v[194:197]
	v_mfma_f32_16x16x32_bf16 v[4:7], v[210:213], v[234:237], v[198:201]
	v_mfma_f32_16x16x32_bf16 v[0:3], v[206:209], v[238:241], v[0:3]
	v_mfma_f32_16x16x32_bf16 v[4:7], v[214:217], v[238:241], v[4:7]
	s_barrier
	s_add_u32 s74, s26, 0x200
	s_addc_u32 s75, s27, 0
	s_add_u32 s26, s36, 0x80180
	s_addc_u32 s27, s37, 0
	s_mov_b32 s76, 0
.LBB0_3720:
	ds_read_b128 v[150:153], v145
	ds_read_b128 v[154:157], v145 offset:1024
	ds_read_b128 v[158:161], v145 offset:2048
	ds_read_b128 v[162:165], v145 offset:3072
	ds_read_b128 v[166:169], v146
	ds_read_b128 v[170:173], v146 offset:1024
	ds_read_b128 v[174:177], v146 offset:2048
	ds_read_b128 v[178:181], v146 offset:3072
	s_add_u32 s36, s26, 0xfff80080
	s_addc_u32 s37, s27, -1
	s_cmp_eq_u32 s76, 28
	s_cselect_b32 s39, s17, s37
	s_cselect_b32 s38, s19, s36
	s_cselect_b32 s37, s62, s75
	s_cselect_b32 s36, s63, s74
	s_mov_b32 m0, s64
	v_lshl_add_u64 v[214:215], s[26:27], 0, v[138:139]
	ds_read_b128 v[182:185], v147
	ds_read_b128 v[186:189], v147 offset:1024
	ds_read_b128 v[190:193], v147 offset:2048
	ds_read_b128 v[194:197], v147 offset:3072
	ds_read_b128 v[198:201], v147 offset:4096
	ds_read_b128 v[202:205], v147 offset:5120
	ds_read_b128 v[206:209], v147 offset:6144
	ds_read_b128 v[210:213], v147 offset:7168
	global_load_lds_dwordx4 v[214:215], off
	v_lshl_add_u64 v[214:215], s[26:27], 0, v[136:137]
	s_mov_b32 m0, s65
	s_nop 0
	global_load_lds_dwordx4 v[214:215], off
	s_waitcnt vmcnt(8) lgkmcnt(0)
	s_barrier
	v_mfma_f32_16x16x32_bf16 v[120:123], v[150:153], v[182:185], v[120:123]
	v_mfma_f32_16x16x32_bf16 v[124:127], v[158:161], v[182:185], v[124:127]
	v_mfma_f32_16x16x32_bf16 v[104:107], v[150:153], v[190:193], v[104:107]
	v_mfma_f32_16x16x32_bf16 v[108:111], v[158:161], v[190:193], v[108:111]
	v_mfma_f32_16x16x32_bf16 v[88:91], v[150:153], v[198:201], v[88:91]
	v_mfma_f32_16x16x32_bf16 v[92:95], v[158:161], v[198:201], v[92:95]
	v_mfma_f32_16x16x32_bf16 v[64:67], v[150:153], v[206:209], v[64:67]
	v_mfma_f32_16x16x32_bf16 v[68:71], v[158:161], v[206:209], v[68:71]
	v_mfma_f32_16x16x32_bf16 v[120:123], v[154:157], v[186:189], v[120:123]
	v_mfma_f32_16x16x32_bf16 v[124:127], v[162:165], v[186:189], v[124:127]
	v_mfma_f32_16x16x32_bf16 v[104:107], v[154:157], v[194:197], v[104:107]
	v_mfma_f32_16x16x32_bf16 v[108:111], v[162:165], v[194:197], v[108:111]
	v_mfma_f32_16x16x32_bf16 v[88:91], v[154:157], v[202:205], v[88:91]
	v_mfma_f32_16x16x32_bf16 v[92:95], v[162:165], v[202:205], v[92:95]
	v_mfma_f32_16x16x32_bf16 v[64:67], v[154:157], v[210:213], v[64:67]
	v_mfma_f32_16x16x32_bf16 v[68:71], v[162:165], v[210:213], v[68:71]
	v_mfma_f32_16x16x32_bf16 v[112:115], v[166:169], v[182:185], v[112:115]
	v_mfma_f32_16x16x32_bf16 v[116:119], v[174:177], v[182:185], v[116:119]
	v_mfma_f32_16x16x32_bf16 v[96:99], v[166:169], v[190:193], v[96:99]
	v_mfma_f32_16x16x32_bf16 v[100:103], v[174:177], v[190:193], v[100:103]
	v_mfma_f32_16x16x32_bf16 v[80:83], v[166:169], v[198:201], v[80:83]
	v_mfma_f32_16x16x32_bf16 v[84:87], v[174:177], v[198:201], v[84:87]
	v_mfma_f32_16x16x32_bf16 v[48:51], v[166:169], v[206:209], v[48:51]
	v_mfma_f32_16x16x32_bf16 v[52:55], v[174:177], v[206:209], v[52:55]
	v_mfma_f32_16x16x32_bf16 v[112:115], v[170:173], v[186:189], v[112:115]
	v_mfma_f32_16x16x32_bf16 v[116:119], v[178:181], v[186:189], v[116:119]
	v_mfma_f32_16x16x32_bf16 v[96:99], v[170:173], v[194:197], v[96:99]
	v_mfma_f32_16x16x32_bf16 v[100:103], v[178:181], v[194:197], v[100:103]
	v_mfma_f32_16x16x32_bf16 v[80:83], v[170:173], v[202:205], v[80:83]
	v_mfma_f32_16x16x32_bf16 v[84:87], v[178:181], v[202:205], v[84:87]
	v_mfma_f32_16x16x32_bf16 v[48:51], v[170:173], v[210:213], v[48:51]
	v_mfma_f32_16x16x32_bf16 v[52:55], v[178:181], v[210:213], v[52:55]
	s_barrier
	s_mov_b32 m0, s66
	v_lshl_add_u64 v[214:215], s[36:37], 0, v[128:129]
	s_add_u32 s78, s36, 0x80000
	ds_read_b128 v[182:185], v147 offset:16384
	ds_read_b128 v[186:189], v147 offset:17408
	ds_read_b128 v[190:193], v147 offset:18432
	ds_read_b128 v[194:197], v147 offset:19456
	ds_read_b128 v[198:201], v147 offset:20480
	ds_read_b128 v[202:205], v147 offset:21504
	ds_read_b128 v[206:209], v147 offset:22528
	ds_read_b128 v[210:213], v147 offset:23552
	global_load_lds_dwordx4 v[214:215], off
	v_lshl_add_u64 v[216:217], s[36:37], 0, v[130:131]
	s_mov_b32 m0, s67
	s_addc_u32 s79, s37, 0
	global_load_lds_dwordx4 v[216:217], off
	v_lshl_add_u64 v[218:219], s[78:79], 0, v[128:129]
	s_mov_b32 m0, s68
	v_lshl_add_u64 v[220:221], s[38:39], 0, v[132:133]
	global_load_lds_dwordx4 v[218:219], off
	v_lshl_add_u64 v[218:219], s[78:79], 0, v[130:131]
	s_mov_b32 m0, s69
	s_nop 0
	global_load_lds_dwordx4 v[218:219], off
	v_lshl_add_u64 v[218:219], s[38:39], 0, v[134:135]
	s_mov_b32 m0, s47
	s_nop 0
	global_load_lds_dwordx4 v[218:219], off
	s_mov_b32 m0, s48
	s_nop 0
	global_load_lds_dwordx4 v[220:221], off
	s_waitcnt vmcnt(8) lgkmcnt(0)
	s_barrier
	v_mfma_f32_16x16x32_bf16 v[72:75], v[150:153], v[182:185], v[72:75]
	v_mfma_f32_16x16x32_bf16 v[76:79], v[158:161], v[182:185], v[76:79]
	v_mfma_f32_16x16x32_bf16 v[40:43], v[150:153], v[190:193], v[40:43]
	v_mfma_f32_16x16x32_bf16 v[44:47], v[158:161], v[190:193], v[44:47]
	v_mfma_f32_16x16x32_bf16 v[24:27], v[150:153], v[198:201], v[24:27]
	v_mfma_f32_16x16x32_bf16 v[28:31], v[158:161], v[198:201], v[28:31]
	v_mfma_f32_16x16x32_bf16 v[8:11], v[150:153], v[206:209], v[8:11]
	v_mfma_f32_16x16x32_bf16 v[12:15], v[158:161], v[206:209], v[12:15]
	v_mfma_f32_16x16x32_bf16 v[72:75], v[154:157], v[186:189], v[72:75]
	v_mfma_f32_16x16x32_bf16 v[76:79], v[162:165], v[186:189], v[76:79]
	v_mfma_f32_16x16x32_bf16 v[40:43], v[154:157], v[194:197], v[40:43]
	v_mfma_f32_16x16x32_bf16 v[44:47], v[162:165], v[194:197], v[44:47]
	v_mfma_f32_16x16x32_bf16 v[24:27], v[154:157], v[202:205], v[24:27]
	v_mfma_f32_16x16x32_bf16 v[28:31], v[162:165], v[202:205], v[28:31]
	v_mfma_f32_16x16x32_bf16 v[8:11], v[154:157], v[210:213], v[8:11]
	v_mfma_f32_16x16x32_bf16 v[12:15], v[162:165], v[210:213], v[12:15]
	v_mfma_f32_16x16x32_bf16 v[56:59], v[166:169], v[182:185], v[56:59]
	v_mfma_f32_16x16x32_bf16 v[60:63], v[174:177], v[182:185], v[60:63]
	v_mfma_f32_16x16x32_bf16 v[32:35], v[166:169], v[190:193], v[32:35]
	v_mfma_f32_16x16x32_bf16 v[36:39], v[174:177], v[190:193], v[36:39]
	v_mfma_f32_16x16x32_bf16 v[16:19], v[166:169], v[198:201], v[16:19]
	v_mfma_f32_16x16x32_bf16 v[20:23], v[174:177], v[198:201], v[20:23]
	v_mfma_f32_16x16x32_bf16 v[0:3], v[166:169], v[206:209], v[0:3]
	v_mfma_f32_16x16x32_bf16 v[4:7], v[174:177], v[206:209], v[4:7]
	v_mfma_f32_16x16x32_bf16 v[56:59], v[170:173], v[186:189], v[56:59]
	v_mfma_f32_16x16x32_bf16 v[60:63], v[178:181], v[186:189], v[60:63]
	v_mfma_f32_16x16x32_bf16 v[32:35], v[170:173], v[194:197], v[32:35]
	v_mfma_f32_16x16x32_bf16 v[36:39], v[178:181], v[194:197], v[36:39]
	v_mfma_f32_16x16x32_bf16 v[16:19], v[170:173], v[202:205], v[16:19]
	v_mfma_f32_16x16x32_bf16 v[20:23], v[178:181], v[202:205], v[20:23]
	v_mfma_f32_16x16x32_bf16 v[0:3], v[170:173], v[210:213], v[0:3]
	v_mfma_f32_16x16x32_bf16 v[4:7], v[178:181], v[210:213], v[4:7]
	s_barrier
; template <class Epi, class Sched, bool ALIGN_EPI = false, bool SP2 = false, bool A_TILED = false>
; __device__ __forceinline__ void gemm_phase(PG8_LAS unsigned char* lds, const Gemm g, const Sched& S, const Epi& E, const int wave_s) {
;     ...
;         for (int t = PEEL ? 2 : 0; t < nt; t += 2) {
;             const bool last = (t == nt - 2);
;             const char* a1 = cA + (size_t)(t + 1) * kstepA;
;             const char* a2 = last ? nA : cA + (size_t)(t + 2) * kstepA; const char* b2 = last ? nB : cB + (size_t)(t + 2) * kstep;
;             const char* a3 = a2 + kstepA; const char* b3 = b2 + kstep;
	ds_read_b128 v[150:153], v148
	ds_read_b128 v[154:157], v148 offset:1024
	ds_read_b128 v[158:161], v148 offset:2048
	ds_read_b128 v[162:165], v148 offset:3072
	ds_read_b128 v[166:169], v149
	ds_read_b128 v[170:173], v149 offset:1024
	ds_read_b128 v[174:177], v149 offset:2048
	ds_read_b128 v[178:181], v149 offset:3072
	s_add_u32 s38, s38, 0x80000
	s_addc_u32 s39, s39, 0
	s_mov_b32 m0, s49
	v_lshl_add_u64 v[222:223], s[38:39], 0, v[134:135]
	ds_read_b128 v[182:185], v147 offset:32768
	ds_read_b128 v[186:189], v147 offset:33792
	ds_read_b128 v[190:193], v147 offset:34816
	ds_read_b128 v[194:197], v147 offset:35840
	ds_read_b128 v[198:201], v147 offset:36864
	ds_read_b128 v[202:205], v147 offset:37888
	ds_read_b128 v[206:209], v147 offset:38912
	ds_read_b128 v[210:213], v147 offset:39936
	global_load_lds_dwordx4 v[222:223], off
	v_lshl_add_u64 v[222:223], s[38:39], 0, v[132:133]
	s_mov_b32 m0, s50
	s_nop 0
	global_load_lds_dwordx4 v[222:223], off
	s_waitcnt vmcnt(8) lgkmcnt(0)
	s_barrier
	v_mfma_f32_16x16x32_bf16 v[120:123], v[150:153], v[182:185], v[120:123]
	v_mfma_f32_16x16x32_bf16 v[124:127], v[158:161], v[182:185], v[124:127]
	v_mfma_f32_16x16x32_bf16 v[104:107], v[150:153], v[190:193], v[104:107]
	v_mfma_f32_16x16x32_bf16 v[108:111], v[158:161], v[190:193], v[108:111]
	v_mfma_f32_16x16x32_bf16 v[88:91], v[150:153], v[198:201], v[88:91]
	v_mfma_f32_16x16x32_bf16 v[92:95], v[158:161], v[198:201], v[92:95]
	v_mfma_f32_16x16x32_bf16 v[64:67], v[150:153], v[206:209], v[64:67]
	v_mfma_f32_16x16x32_bf16 v[68:71], v[158:161], v[206:209], v[68:71]
	v_mfma_f32_16x16x32_bf16 v[120:123], v[154:157], v[186:189], v[120:123]
	v_mfma_f32_16x16x32_bf16 v[124:127], v[162:165], v[186:189], v[124:127]
	v_mfma_f32_16x16x32_bf16 v[104:107], v[154:157], v[194:197], v[104:107]
	v_mfma_f32_16x16x32_bf16 v[108:111], v[162:165], v[194:197], v[108:111]
	v_mfma_f32_16x16x32_bf16 v[88:91], v[154:157], v[202:205], v[88:91]
	v_mfma_f32_16x16x32_bf16 v[92:95], v[162:165], v[202:205], v[92:95]
	v_mfma_f32_16x16x32_bf16 v[64:67], v[154:157], v[210:213], v[64:67]
	v_mfma_f32_16x16x32_bf16 v[68:71], v[162:165], v[210:213], v[68:71]
	v_mfma_f32_16x16x32_bf16 v[112:115], v[166:169], v[182:185], v[112:115]
	v_mfma_f32_16x16x32_bf16 v[116:119], v[174:177], v[182:185], v[116:119]
	v_mfma_f32_16x16x32_bf16 v[96:99], v[166:169], v[190:193], v[96:99]
	v_mfma_f32_16x16x32_bf16 v[100:103], v[174:177], v[190:193], v[100:103]
	v_mfma_f32_16x16x32_bf16 v[80:83], v[166:169], v[198:201], v[80:83]
	v_mfma_f32_16x16x32_bf16 v[84:87], v[174:177], v[198:201], v[84:87]
	v_mfma_f32_16x16x32_bf16 v[48:51], v[166:169], v[206:209], v[48:51]
	v_mfma_f32_16x16x32_bf16 v[52:55], v[174:177], v[206:209], v[52:55]
	v_mfma_f32_16x16x32_bf16 v[112:115], v[170:173], v[186:189], v[112:115]
	v_mfma_f32_16x16x32_bf16 v[116:119], v[178:181], v[186:189], v[116:119]
	v_mfma_f32_16x16x32_bf16 v[96:99], v[170:173], v[194:197], v[96:99]
	v_mfma_f32_16x16x32_bf16 v[100:103], v[178:181], v[194:197], v[100:103]
	v_mfma_f32_16x16x32_bf16 v[80:83], v[170:173], v[202:205], v[80:83]
	v_mfma_f32_16x16x32_bf16 v[84:87], v[178:181], v[202:205], v[84:87]
	v_mfma_f32_16x16x32_bf16 v[48:51], v[170:173], v[210:213], v[48:51]
	v_mfma_f32_16x16x32_bf16 v[52:55], v[178:181], v[210:213], v[52:55]
	s_barrier
	s_mov_b32 m0, s70
	v_lshl_add_u64 v[214:215], v[214:215], 0, s[6:7]
	s_add_u32 s36, s36, 0x80080
	ds_read_b128 v[182:185], v147 offset:49152
	ds_read_b128 v[186:189], v147 offset:50176
	ds_read_b128 v[190:193], v147 offset:51200
	ds_read_b128 v[194:197], v147 offset:52224
	ds_read_b128 v[198:201], v147 offset:53248
	ds_read_b128 v[202:205], v147 offset:54272
	ds_read_b128 v[206:209], v147 offset:55296
	ds_read_b128 v[210:213], v147 offset:56320
	global_load_lds_dwordx4 v[214:215], off
	v_lshl_add_u64 v[214:215], v[216:217], 0, s[6:7]
	s_mov_b32 m0, s71
	s_addc_u32 s37, s37, 0
	global_load_lds_dwordx4 v[214:215], off
	v_lshl_add_u64 v[214:215], s[36:37], 0, v[128:129]
	s_mov_b32 m0, s72
	s_nop 0
	global_load_lds_dwordx4 v[214:215], off
	v_lshl_add_u64 v[214:215], s[36:37], 0, v[130:131]
	s_mov_b32 m0, s73
	s_nop 0
	global_load_lds_dwordx4 v[214:215], off
	v_lshl_add_u64 v[214:215], v[218:219], 0, s[6:7]
	s_mov_b32 m0, s56
	s_nop 0
	global_load_lds_dwordx4 v[214:215], off
	v_lshl_add_u64 v[214:215], v[220:221], 0, s[6:7]
	s_mov_b32 m0, s57
	s_nop 0
	global_load_lds_dwordx4 v[214:215], off
	s_waitcnt vmcnt(8) lgkmcnt(0)
	s_barrier
	v_mfma_f32_16x16x32_bf16 v[72:75], v[150:153], v[182:185], v[72:75]
	v_mfma_f32_16x16x32_bf16 v[76:79], v[158:161], v[182:185], v[76:79]
	v_mfma_f32_16x16x32_bf16 v[40:43], v[150:153], v[190:193], v[40:43]
	v_mfma_f32_16x16x32_bf16 v[44:47], v[158:161], v[190:193], v[44:47]
	v_mfma_f32_16x16x32_bf16 v[24:27], v[150:153], v[198:201], v[24:27]
	v_mfma_f32_16x16x32_bf16 v[28:31], v[158:161], v[198:201], v[28:31]
	v_mfma_f32_16x16x32_bf16 v[8:11], v[150:153], v[206:209], v[8:11]
	v_mfma_f32_16x16x32_bf16 v[12:15], v[158:161], v[206:209], v[12:15]
	v_mfma_f32_16x16x32_bf16 v[72:75], v[154:157], v[186:189], v[72:75]
	v_mfma_f32_16x16x32_bf16 v[76:79], v[162:165], v[186:189], v[76:79]
	v_mfma_f32_16x16x32_bf16 v[40:43], v[154:157], v[194:197], v[40:43]
	v_mfma_f32_16x16x32_bf16 v[44:47], v[162:165], v[194:197], v[44:47]
	v_mfma_f32_16x16x32_bf16 v[24:27], v[154:157], v[202:205], v[24:27]
	v_mfma_f32_16x16x32_bf16 v[28:31], v[162:165], v[202:205], v[28:31]
	v_mfma_f32_16x16x32_bf16 v[8:11], v[154:157], v[210:213], v[8:11]
	v_mfma_f32_16x16x32_bf16 v[12:15], v[162:165], v[210:213], v[12:15]
	v_mfma_f32_16x16x32_bf16 v[56:59], v[166:169], v[182:185], v[56:59]
	v_mfma_f32_16x16x32_bf16 v[60:63], v[174:177], v[182:185], v[60:63]
	v_mfma_f32_16x16x32_bf16 v[32:35], v[166:169], v[190:193], v[32:35]
	v_mfma_f32_16x16x32_bf16 v[36:39], v[174:177], v[190:193], v[36:39]
	v_mfma_f32_16x16x32_bf16 v[16:19], v[166:169], v[198:201], v[16:19]
	v_mfma_f32_16x16x32_bf16 v[20:23], v[174:177], v[198:201], v[20:23]
	v_mfma_f32_16x16x32_bf16 v[0:3], v[166:169], v[206:209], v[0:3]
	v_mfma_f32_16x16x32_bf16 v[4:7], v[174:177], v[206:209], v[4:7]
	v_mfma_f32_16x16x32_bf16 v[56:59], v[170:173], v[186:189], v[56:59]
	v_mfma_f32_16x16x32_bf16 v[60:63], v[178:181], v[186:189], v[60:63]
	v_mfma_f32_16x16x32_bf16 v[32:35], v[170:173], v[194:197], v[32:35]
	v_mfma_f32_16x16x32_bf16 v[36:39], v[178:181], v[194:197], v[36:39]
	v_mfma_f32_16x16x32_bf16 v[16:19], v[170:173], v[202:205], v[16:19]
	v_mfma_f32_16x16x32_bf16 v[20:23], v[178:181], v[202:205], v[20:23]
	v_mfma_f32_16x16x32_bf16 v[0:3], v[170:173], v[210:213], v[0:3]
	v_mfma_f32_16x16x32_bf16 v[4:7], v[178:181], v[210:213], v[4:7]
	s_barrier
	s_add_i32 s76, s76, 2
	s_add_u32 s74, s74, 0x100
	s_addc_u32 s75, s75, 0
	s_add_u32 s26, s26, 0x100
	s_addc_u32 s27, s27, 0
	s_cmp_gt_u32 s76, 29
	s_cbranch_scc0 .LBB0_3720
	s_and_b64 vcc, exec, s[8:9]
	s_cbranch_vccz .LBB0_3723
	s_barrier

; #define PG8_MMA(ai, bj, At, Bt) do { __builtin_amdgcn_s_setprio(1); _Pragma("unroll") for (int m = 0; m < 4; ++m) _Pragma("unroll") for (int n = 0; n < 2; ++n) _Pragma("unroll") for (int k = 0; k < 2; ++k) \
;         acc[ai][bj][m][n] = __builtin_amdgcn_mfma_f32_16x16x32_bf16(Bt[n][k], At[m][k], acc[ai][bj][m][n], 0, 0, 0); __builtin_amdgcn_s_setprio(0); } while (0)
; template <class Epi, class Sched, bool ALIGN_EPI = false, bool SP2 = false, bool A_TILED = false>
; __device__ __forceinline__ void gemm_phase(PG8_LAS unsigned char* lds, const Gemm g, const Sched& S, const Epi& E, const int wave_s) {
;     ...
;         for (int t = PEEL ? 2 : 0; t < nt; t += 2) {
;             const bool last = (t == nt - 2);
;             const char* a1 = cA + (size_t)(t + 1) * kstepA;
;             const char* a2 = last ? nA : cA + (size_t)(t + 2) * kstepA; const char* b2 = last ? nB : cB + (size_t)(t + 2) * kstep;
;             const char* a3 = a2 + kstepA; const char* b3 = b2 + kstep;
;             if (last && has_next) S.a_ready(nxt);
;             if constexpr (SP2) {
;             PG8_ITER(PG8_MMA)
.LBB0_3793:
	ds_read_b128 v[146:149], v140
	ds_read_b128 v[150:153], v140 offset:1024
	ds_read_b128 v[154:157], v140 offset:2048
	ds_read_b128 v[158:161], v140 offset:3072
	ds_read_b128 v[162:165], v141
	ds_read_b128 v[166:169], v141 offset:1024
	ds_read_b128 v[170:173], v141 offset:2048
	ds_read_b128 v[174:177], v141 offset:3072
	s_add_u32 s16, s58, s40
	s_addc_u32 s17, s59, s41
	s_add_u32 s18, s58, s38
	s_addc_u32 s19, s59, s39
	s_cmpk_eq_i32 s42, 0x7c
	s_cselect_b32 s20, s4, s16
	s_cselect_b32 s21, s5, s17
	s_cselect_b32 s18, s0, s18
	s_cselect_b32 s19, s1, s19
	s_add_u32 s16, s20, 0x8000
	s_addc_u32 s17, s21, 0
	s_mov_b32 m0, s43
	v_lshl_add_u64 v[210:211], s[58:59], 0, v[138:139]
	ds_read_b128 v[178:181], v142
	ds_read_b128 v[182:185], v142 offset:1024
	ds_read_b128 v[186:189], v142 offset:2048
	ds_read_b128 v[190:193], v142 offset:3072
	ds_read_b128 v[194:197], v142 offset:4096
	ds_read_b128 v[198:201], v142 offset:5120
	ds_read_b128 v[202:205], v142 offset:6144
	ds_read_b128 v[206:209], v142 offset:7168
	global_load_lds_dwordx4 v[210:211], off
	v_lshl_add_u64 v[210:211], s[58:59], 0, v[136:137]
	s_mov_b32 m0, s44
	s_nop 0
	global_load_lds_dwordx4 v[210:211], off
	s_waitcnt vmcnt(8) lgkmcnt(0)
	s_barrier
	v_mfma_f32_16x16x32_bf16 v[32:35], v[146:149], v[178:181], v[32:35]
	v_mfma_f32_16x16x32_bf16 v[36:39], v[154:157], v[178:181], v[36:39]
	v_mfma_f32_16x16x32_bf16 v[76:79], v[146:149], v[186:189], v[76:79]
	v_mfma_f32_16x16x32_bf16 v[80:83], v[154:157], v[186:189], v[80:83]
	v_mfma_f32_16x16x32_bf16 v[92:95], v[146:149], v[194:197], v[92:95]
	v_mfma_f32_16x16x32_bf16 v[84:87], v[154:157], v[194:197], v[84:87]
	v_mfma_f32_16x16x32_bf16 v[108:111], v[146:149], v[202:205], v[108:111]
	v_mfma_f32_16x16x32_bf16 v[104:107], v[154:157], v[202:205], v[104:107]
	v_mfma_f32_16x16x32_bf16 v[32:35], v[150:153], v[182:185], v[32:35]
	v_mfma_f32_16x16x32_bf16 v[36:39], v[158:161], v[182:185], v[36:39]
	v_mfma_f32_16x16x32_bf16 v[76:79], v[150:153], v[190:193], v[76:79]
	v_mfma_f32_16x16x32_bf16 v[80:83], v[158:161], v[190:193], v[80:83]
	v_mfma_f32_16x16x32_bf16 v[92:95], v[150:153], v[198:201], v[92:95]
	v_mfma_f32_16x16x32_bf16 v[84:87], v[158:161], v[198:201], v[84:87]
	v_mfma_f32_16x16x32_bf16 v[108:111], v[150:153], v[206:209], v[108:111]
	v_mfma_f32_16x16x32_bf16 v[104:107], v[158:161], v[206:209], v[104:107]
	v_mfma_f32_16x16x32_bf16 v[40:43], v[162:165], v[178:181], v[40:43]
	v_mfma_f32_16x16x32_bf16 v[44:47], v[170:173], v[178:181], v[44:47]
	v_mfma_f32_16x16x32_bf16 v[68:71], v[162:165], v[186:189], v[68:71]
	v_mfma_f32_16x16x32_bf16 v[64:67], v[170:173], v[186:189], v[64:67]
	v_mfma_f32_16x16x32_bf16 v[60:63], v[162:165], v[194:197], v[60:63]
	v_mfma_f32_16x16x32_bf16 v[56:59], v[170:173], v[194:197], v[56:59]
	v_mfma_f32_16x16x32_bf16 v[100:103], v[162:165], v[202:205], v[100:103]
	v_mfma_f32_16x16x32_bf16 v[96:99], v[170:173], v[202:205], v[96:99]
	v_mfma_f32_16x16x32_bf16 v[40:43], v[166:169], v[182:185], v[40:43]
	v_mfma_f32_16x16x32_bf16 v[44:47], v[174:177], v[182:185], v[44:47]
	v_mfma_f32_16x16x32_bf16 v[68:71], v[166:169], v[190:193], v[68:71]
	v_mfma_f32_16x16x32_bf16 v[64:67], v[174:177], v[190:193], v[64:67]
	v_mfma_f32_16x16x32_bf16 v[60:63], v[166:169], v[198:201], v[60:63]
	v_mfma_f32_16x16x32_bf16 v[56:59], v[174:177], v[198:201], v[56:59]
	v_mfma_f32_16x16x32_bf16 v[100:103], v[166:169], v[206:209], v[100:103]
	v_mfma_f32_16x16x32_bf16 v[96:99], v[174:177], v[206:209], v[96:99]
	s_barrier
	s_mov_b32 m0, s45
	v_lshl_add_u64 v[210:211], s[18:19], 0, v[130:131]
	s_add_u32 s54, s18, 0x200000
	ds_read_b128 v[178:181], v142 offset:16384
	ds_read_b128 v[182:185], v142 offset:17408
	ds_read_b128 v[186:189], v142 offset:18432
	ds_read_b128 v[190:193], v142 offset:19456
	ds_read_b128 v[194:197], v142 offset:20480
	ds_read_b128 v[198:201], v142 offset:21504
	ds_read_b128 v[202:205], v142 offset:22528
	ds_read_b128 v[206:209], v142 offset:23552
	global_load_lds_dwordx4 v[210:211], off
	v_lshl_add_u64 v[212:213], s[18:19], 0, v[134:135]
	s_mov_b32 m0, s46
	s_addc_u32 s55, s19, 0
	global_load_lds_dwordx4 v[212:213], off
	v_lshl_add_u64 v[214:215], s[54:55], 0, v[130:131]
	s_mov_b32 m0, s47
	s_nop 0
	global_load_lds_dwordx4 v[214:215], off
	v_lshl_add_u64 v[214:215], s[54:55], 0, v[134:135]
	s_mov_b32 m0, s48
	s_nop 0
	global_load_lds_dwordx4 v[214:215], off
	v_lshl_add_u64 v[214:215], s[20:21], 0, v[128:129]
	s_mov_b32 m0, s25
	s_nop 0
	global_load_lds_dwordx4 v[214:215], off
	v_lshl_add_u64 v[214:215], s[20:21], 0, v[132:133]
	s_mov_b32 m0, s26
	s_nop 0
	global_load_lds_dwordx4 v[214:215], off
	s_waitcnt vmcnt(8) lgkmcnt(0)
	s_barrier
	v_mfma_f32_16x16x32_bf16 v[124:127], v[146:149], v[178:181], v[124:127]
	v_mfma_f32_16x16x32_bf16 v[120:123], v[154:157], v[178:181], v[120:123]
	v_mfma_f32_16x16x32_bf16 v[88:91], v[146:149], v[186:189], v[88:91]
	v_mfma_f32_16x16x32_bf16 v[72:75], v[154:157], v[186:189], v[72:75]
	v_mfma_f32_16x16x32_bf16 v[28:31], v[146:149], v[194:197], v[28:31]
	v_mfma_f32_16x16x32_bf16 v[24:27], v[154:157], v[194:197], v[24:27]
	v_mfma_f32_16x16x32_bf16 v[12:15], v[146:149], v[202:205], v[12:15]
	v_mfma_f32_16x16x32_bf16 v[8:11], v[154:157], v[202:205], v[8:11]
	v_mfma_f32_16x16x32_bf16 v[124:127], v[150:153], v[182:185], v[124:127]
	v_mfma_f32_16x16x32_bf16 v[120:123], v[158:161], v[182:185], v[120:123]
	v_mfma_f32_16x16x32_bf16 v[88:91], v[150:153], v[190:193], v[88:91]
	v_mfma_f32_16x16x32_bf16 v[72:75], v[158:161], v[190:193], v[72:75]
	v_mfma_f32_16x16x32_bf16 v[28:31], v[150:153], v[198:201], v[28:31]
	v_mfma_f32_16x16x32_bf16 v[24:27], v[158:161], v[198:201], v[24:27]
	v_mfma_f32_16x16x32_bf16 v[12:15], v[150:153], v[206:209], v[12:15]
	v_mfma_f32_16x16x32_bf16 v[8:11], v[158:161], v[206:209], v[8:11]
	v_mfma_f32_16x16x32_bf16 v[116:119], v[162:165], v[178:181], v[116:119]
	v_mfma_f32_16x16x32_bf16 v[112:115], v[170:173], v[178:181], v[112:115]
	v_mfma_f32_16x16x32_bf16 v[52:55], v[162:165], v[186:189], v[52:55]
	v_mfma_f32_16x16x32_bf16 v[48:51], v[170:173], v[186:189], v[48:51]
	v_mfma_f32_16x16x32_bf16 v[20:23], v[162:165], v[194:197], v[20:23]
	v_mfma_f32_16x16x32_bf16 v[16:19], v[170:173], v[194:197], v[16:19]
	v_mfma_f32_16x16x32_bf16 v[4:7], v[162:165], v[202:205], v[4:7]
	v_mfma_f32_16x16x32_bf16 v[0:3], v[170:173], v[202:205], v[0:3]
	v_mfma_f32_16x16x32_bf16 v[116:119], v[166:169], v[182:185], v[116:119]
	v_mfma_f32_16x16x32_bf16 v[112:115], v[174:177], v[182:185], v[112:115]
	v_mfma_f32_16x16x32_bf16 v[52:55], v[166:169], v[190:193], v[52:55]
	v_mfma_f32_16x16x32_bf16 v[48:51], v[174:177], v[190:193], v[48:51]
	v_mfma_f32_16x16x32_bf16 v[20:23], v[166:169], v[198:201], v[20:23]
	v_mfma_f32_16x16x32_bf16 v[16:19], v[174:177], v[198:201], v[16:19]
	v_mfma_f32_16x16x32_bf16 v[4:7], v[166:169], v[206:209], v[4:7]
	v_mfma_f32_16x16x32_bf16 v[0:3], v[174:177], v[206:209], v[0:3]
	s_barrier
	ds_read_b128 v[146:149], v143
	ds_read_b128 v[150:153], v143 offset:1024
	ds_read_b128 v[154:157], v143 offset:2048
	ds_read_b128 v[158:161], v143 offset:3072
	ds_read_b128 v[162:165], v144
	ds_read_b128 v[166:169], v144 offset:1024
	ds_read_b128 v[170:173], v144 offset:2048
	ds_read_b128 v[174:177], v144 offset:3072
	s_add_u32 s20, s20, 0x4000
	s_addc_u32 s21, s21, 0
	s_mov_b32 m0, s27
	v_lshl_add_u64 v[214:215], s[20:21], 0, v[128:129]
	ds_read_b128 v[178:181], v142 offset:32768
	ds_read_b128 v[182:185], v142 offset:33792
	ds_read_b128 v[186:189], v142 offset:34816
	ds_read_b128 v[190:193], v142 offset:35840
	ds_read_b128 v[194:197], v142 offset:36864
	ds_read_b128 v[198:201], v142 offset:37888
	ds_read_b128 v[202:205], v142 offset:38912
	ds_read_b128 v[206:209], v142 offset:39936
	global_load_lds_dwordx4 v[214:215], off
	v_lshl_add_u64 v[214:215], s[20:21], 0, v[132:133]
	s_mov_b32 m0, s34
	s_nop 0
	global_load_lds_dwordx4 v[214:215], off
	s_waitcnt vmcnt(8) lgkmcnt(0)
	s_barrier
	v_mfma_f32_16x16x32_bf16 v[32:35], v[146:149], v[178:181], v[32:35]
	v_mfma_f32_16x16x32_bf16 v[36:39], v[154:157], v[178:181], v[36:39]
	v_mfma_f32_16x16x32_bf16 v[76:79], v[146:149], v[186:189], v[76:79]
	v_mfma_f32_16x16x32_bf16 v[80:83], v[154:157], v[186:189], v[80:83]
	v_mfma_f32_16x16x32_bf16 v[92:95], v[146:149], v[194:197], v[92:95]
	v_mfma_f32_16x16x32_bf16 v[84:87], v[154:157], v[194:197], v[84:87]
	v_mfma_f32_16x16x32_bf16 v[108:111], v[146:149], v[202:205], v[108:111]
	v_mfma_f32_16x16x32_bf16 v[104:107], v[154:157], v[202:205], v[104:107]
	v_mfma_f32_16x16x32_bf16 v[32:35], v[150:153], v[182:185], v[32:35]
	v_mfma_f32_16x16x32_bf16 v[36:39], v[158:161], v[182:185], v[36:39]
	v_mfma_f32_16x16x32_bf16 v[76:79], v[150:153], v[190:193], v[76:79]
	v_mfma_f32_16x16x32_bf16 v[80:83], v[158:161], v[190:193], v[80:83]
	v_mfma_f32_16x16x32_bf16 v[92:95], v[150:153], v[198:201], v[92:95]
	v_mfma_f32_16x16x32_bf16 v[84:87], v[158:161], v[198:201], v[84:87]
	v_mfma_f32_16x16x32_bf16 v[108:111], v[150:153], v[206:209], v[108:111]
	v_mfma_f32_16x16x32_bf16 v[104:107], v[158:161], v[206:209], v[104:107]
	v_mfma_f32_16x16x32_bf16 v[40:43], v[162:165], v[178:181], v[40:43]
	v_mfma_f32_16x16x32_bf16 v[44:47], v[170:173], v[178:181], v[44:47]
	v_mfma_f32_16x16x32_bf16 v[68:71], v[162:165], v[186:189], v[68:71]
	v_mfma_f32_16x16x32_bf16 v[64:67], v[170:173], v[186:189], v[64:67]
	v_mfma_f32_16x16x32_bf16 v[60:63], v[162:165], v[194:197], v[60:63]
	v_mfma_f32_16x16x32_bf16 v[56:59], v[170:173], v[194:197], v[56:59]
	v_mfma_f32_16x16x32_bf16 v[100:103], v[162:165], v[202:205], v[100:103]
	v_mfma_f32_16x16x32_bf16 v[96:99], v[170:173], v[202:205], v[96:99]
	v_mfma_f32_16x16x32_bf16 v[40:43], v[166:169], v[182:185], v[40:43]
	v_mfma_f32_16x16x32_bf16 v[44:47], v[174:177], v[182:185], v[44:47]
	v_mfma_f32_16x16x32_bf16 v[68:71], v[166:169], v[190:193], v[68:71]
	v_mfma_f32_16x16x32_bf16 v[64:67], v[174:177], v[190:193], v[64:67]
	v_mfma_f32_16x16x32_bf16 v[60:63], v[166:169], v[198:201], v[60:63]
	v_mfma_f32_16x16x32_bf16 v[56:59], v[174:177], v[198:201], v[56:59]
	v_mfma_f32_16x16x32_bf16 v[100:103], v[166:169], v[206:209], v[100:103]
	v_mfma_f32_16x16x32_bf16 v[96:99], v[174:177], v[206:209], v[96:99]
	s_barrier
; #define PG8_MMA(ai, bj, At, Bt) do { __builtin_amdgcn_s_setprio(1); _Pragma("unroll") for (int m = 0; m < 4; ++m) _Pragma("unroll") for (int n = 0; n < 2; ++n) _Pragma("unroll") for (int k = 0; k < 2; ++k) \
;         acc[ai][bj][m][n] = __builtin_amdgcn_mfma_f32_16x16x32_bf16(Bt[n][k], At[m][k], acc[ai][bj][m][n], 0, 0, 0); __builtin_amdgcn_s_setprio(0); } while (0)
; #define PG8_WAIT_V(n) asm volatile("s_waitcnt vmcnt(" #n ")" ::: "memory")
; #define PG8_BAR __builtin_amdgcn_s_barrier()
; template <class Epi, class Sched, bool ALIGN_EPI = false, bool SP2 = false, bool A_TILED = false>
; __device__ __forceinline__ void gemm_phase(PG8_LAS unsigned char* lds, const Gemm g, const Sched& S, const Epi& E, const int wave_s) {
;     ...
;         for (int t = PEEL ? 2 : 0; t < nt; t += 2) {
;             const bool last = (t == nt - 2);
;             const char* a1 = cA + (size_t)(t + 1) * kstepA;
;             const char* a2 = last ? nA : cA + (size_t)(t + 2) * kstepA; const char* b2 = last ? nB : cB + (size_t)(t + 2) * kstep;
;             const char* a3 = a2 + kstepA; const char* b3 = b2 + kstep;
;             if (last && has_next) S.a_ready(nxt);
;             if constexpr (SP2) {
;             PG8_ITER(PG8_MMA)
;     ...
;     PG8_WAIT_V(0);
;     if constexpr (!ALIGN_EPI) { if (wr == 0) PG8_BAR; }
;     PG8_BAR;
	s_mov_b32 m0, s49
	v_lshl_add_u64 v[210:211], v[210:211], 0, s[12:13]
	s_add_u32 s18, s18, 0x200080
	ds_read_b128 v[178:181], v142 offset:49152
	ds_read_b128 v[182:185], v142 offset:50176
	ds_read_b128 v[186:189], v142 offset:51200
	ds_read_b128 v[190:193], v142 offset:52224
	ds_read_b128 v[194:197], v142 offset:53248
	ds_read_b128 v[198:201], v142 offset:54272
	ds_read_b128 v[202:205], v142 offset:55296
	ds_read_b128 v[206:209], v142 offset:56320
	global_load_lds_dwordx4 v[210:211], off
	v_lshl_add_u64 v[210:211], v[212:213], 0, s[12:13]
	s_mov_b32 m0, s50
	s_addc_u32 s19, s19, 0
	global_load_lds_dwordx4 v[210:211], off
	v_lshl_add_u64 v[210:211], s[18:19], 0, v[130:131]
	s_mov_b32 m0, s51
	s_nop 0
	global_load_lds_dwordx4 v[210:211], off
	v_lshl_add_u64 v[210:211], s[18:19], 0, v[134:135]
	s_mov_b32 m0, s52
	s_nop 0
	global_load_lds_dwordx4 v[210:211], off
	v_lshl_add_u64 v[210:211], s[16:17], 0, v[128:129]
	s_mov_b32 m0, s36
	s_nop 0
	global_load_lds_dwordx4 v[210:211], off
	v_lshl_add_u64 v[210:211], s[16:17], 0, v[132:133]
	s_mov_b32 m0, s37
	s_nop 0
	global_load_lds_dwordx4 v[210:211], off
	s_waitcnt vmcnt(8) lgkmcnt(0)
	s_barrier
	v_mfma_f32_16x16x32_bf16 v[124:127], v[146:149], v[178:181], v[124:127]
	v_mfma_f32_16x16x32_bf16 v[120:123], v[154:157], v[178:181], v[120:123]
	v_mfma_f32_16x16x32_bf16 v[88:91], v[146:149], v[186:189], v[88:91]
	v_mfma_f32_16x16x32_bf16 v[72:75], v[154:157], v[186:189], v[72:75]
	v_mfma_f32_16x16x32_bf16 v[28:31], v[146:149], v[194:197], v[28:31]
	v_mfma_f32_16x16x32_bf16 v[24:27], v[154:157], v[194:197], v[24:27]
	v_mfma_f32_16x16x32_bf16 v[12:15], v[146:149], v[202:205], v[12:15]
	v_mfma_f32_16x16x32_bf16 v[8:11], v[154:157], v[202:205], v[8:11]
	v_mfma_f32_16x16x32_bf16 v[124:127], v[150:153], v[182:185], v[124:127]
	v_mfma_f32_16x16x32_bf16 v[120:123], v[158:161], v[182:185], v[120:123]
	v_mfma_f32_16x16x32_bf16 v[88:91], v[150:153], v[190:193], v[88:91]
	v_mfma_f32_16x16x32_bf16 v[72:75], v[158:161], v[190:193], v[72:75]
	v_mfma_f32_16x16x32_bf16 v[28:31], v[150:153], v[198:201], v[28:31]
	v_mfma_f32_16x16x32_bf16 v[24:27], v[158:161], v[198:201], v[24:27]
	v_mfma_f32_16x16x32_bf16 v[12:15], v[150:153], v[206:209], v[12:15]
	v_mfma_f32_16x16x32_bf16 v[8:11], v[158:161], v[206:209], v[8:11]
	v_mfma_f32_16x16x32_bf16 v[116:119], v[162:165], v[178:181], v[116:119]
	v_mfma_f32_16x16x32_bf16 v[112:115], v[170:173], v[178:181], v[112:115]
	v_mfma_f32_16x16x32_bf16 v[52:55], v[162:165], v[186:189], v[52:55]
	v_mfma_f32_16x16x32_bf16 v[48:51], v[170:173], v[186:189], v[48:51]
	v_mfma_f32_16x16x32_bf16 v[20:23], v[162:165], v[194:197], v[20:23]
	v_mfma_f32_16x16x32_bf16 v[16:19], v[170:173], v[194:197], v[16:19]
	v_mfma_f32_16x16x32_bf16 v[4:7], v[162:165], v[202:205], v[4:7]
	v_mfma_f32_16x16x32_bf16 v[0:3], v[170:173], v[202:205], v[0:3]
	v_mfma_f32_16x16x32_bf16 v[116:119], v[166:169], v[182:185], v[116:119]
	v_mfma_f32_16x16x32_bf16 v[112:115], v[174:177], v[182:185], v[112:115]
	v_mfma_f32_16x16x32_bf16 v[52:55], v[166:169], v[190:193], v[52:55]
	v_mfma_f32_16x16x32_bf16 v[48:51], v[174:177], v[190:193], v[48:51]
	v_mfma_f32_16x16x32_bf16 v[20:23], v[166:169], v[198:201], v[20:23]
	v_mfma_f32_16x16x32_bf16 v[16:19], v[174:177], v[198:201], v[16:19]
	v_mfma_f32_16x16x32_bf16 v[4:7], v[166:169], v[206:209], v[4:7]
	v_mfma_f32_16x16x32_bf16 v[0:3], v[174:177], v[206:209], v[0:3]
	s_barrier
	s_add_i32 s42, s42, 2
	s_add_u32 s38, s38, 0x100
	s_addc_u32 s39, s39, 0
	s_add_u32 s40, s40, 0x10000
	s_addc_u32 s41, s41, 0
	v_lshl_add_u64 v[136:137], v[136:137], 0, s[14:15]
	s_cmpk_gt_u32 s42, 0x7d
	v_lshl_add_u64 v[138:139], v[138:139], 0, s[14:15]
	s_cbranch_scc0 .LBB0_3793
	s_waitcnt vmcnt(0)
	s_cmpk_lt_u32 s22, 0x100
	s_cbranch_scc0 .LBB0_3796
	s_barrier
